# FFN-up epilogue: second-pass conv-weight loads issued with the first pass; per-row LDS reads of the finish loops issued one row ahead
# speedup vs baseline: 1.0227x; 1.0074x over previous
; template <bool SWAP, class Epi, bool THIN = false> ...
;     ...
;     if (w < full * 8 * NT) { const int sr = w / (8 * NT), rem = w - sr * 8 * NT; nt = rem >> 3; mt = sr * 8 + (rem & 7); }
;     else { const int w2 = w - full * 8 * NT, rl = MT - full * 8; nt = w2 / rl; mt = full * 8 + (w2 - nt * rl); }
;     unsigned ap[4], bp[4];
; #pragma unroll
;     for (int i = 0; i < 4; ++i) {
;       const int r = (tid >> 3) + 64 * i;
;       const int cs = tid & 7;
;       const int c = ((cs ^ ((r >> 1) & 7)) << 3);
;       const int sub = 2 * mt + (r >> 7);
;       const int g = sub / tpg, ti = sub - g * tpg;
;       int rig = ti * step - halo + (r & 127); rig = rig < 0 ? 0 : (rig > grows - 1 ? grows - 1 : rig);
;       ap[i] = (unsigned)((g * a_gstride + a_goff + rig) * lda + c);
;       int br = nt * 256 + r; br = br > N - 1 ? N - 1 : br;
;       bp[i] = (unsigned)(br * K + c);
;     }
;     const bool have_next = false;
;     f32x4 acc[4][8];
; #pragma unroll
;     for (int m = 0; m < 4; ++m)
; #pragma unroll
;       for (int n = 0; n < 8; ++n) acc[m][n] = (f32x4){0.f, 0.f, 0.f, 0.f};
;     if (!pre_issued) {
; #pragma unroll
;       for (int i = 0; i < 4; ++i) { GLDS16(A + (size_t)ap[i], smem + tid * 16 + i * 8192); GLDS16(Bt + (size_t)bp[i], smem + 32768 + tid * 16 + i * 8192); }
;     }
;     pre_issued = have_next;
;     for (int st = 0; st < ns; ++st) {
;       asm volatile("s_waitcnt vmcnt(0)" ::: "memory");
;       __builtin_amdgcn_s_barrier();
;       asm volatile("" ::: "memory");
;       if (st + 1 < ns) {
;         char* nb = smem + ((st + 1) & 1) * 65536;
;         const int ko = (st + 1) * 64;
; #pragma unroll
;         for (int i = 0; i < 4; ++i) { GLDS16(A + (size_t)(ap[i] + ko), nb + tid * 16 + i * 8192); GLDS16(Bt + (size_t)(bp[i] + ko), nb + 32768 + tid * 16 + i * 8192); }
;       }
;       const char* sa = smem + (st & 1) * 65536 + (wr * 64 + fr) * 128;
;       const char* sb = smem + (st & 1) * 65536 + 32768 + (wc * 128 + fr) * 128;
;       if constexpr (THIN) {
;         if (wc == 0) {
; #pragma unroll
;           for (int ks = 0; ks < 2; ++ks) {
;             bf16x8 af[4], bf[2];
; #pragma unroll
;             for (int m = 0; m < 4; ++m) af[m] = *(const bf16x8*)(sa + m * 2048 + (((ks * 4 + fq) ^ swz) << 4));
; #pragma unroll
;             for (int n = 0; n < 2; ++n) bf[n] = *(const bf16x8*)(sb + n * 2048 + (((ks * 4 + fq) ^ swz) << 4));
.LBB0_1749:
	s_mul_hi_i32 s4, s33, 0x2aaaaaab
	s_lshr_b32 s5, s4, 31
	s_ashr_i32 s4, s4, 3
	s_add_i32 s4, s4, s5
	s_lshl_b32 s5, s4, 4
	s_and_b32 s6, s46, 14
	s_or_b32 s5, s5, s6
	v_add_u32_e32 v2, s5, v143
	v_ashrrev_i32_e32 v3, 31, v2
	v_lshrrev_b32_e32 v3, 28, v3
	v_add_u32_e32 v3, v2, v3
	v_ashrrev_i32_e32 v3, 4, v3
	v_lshlrev_b32_e32 v4, 11, v3
	v_lshlrev_b32_e32 v2, 7, v2
	v_sub_u32_e32 v2, v2, v4
	v_or_b32_e32 v4, v2, v144
	v_min_i32_e32 v4, 0x7ff, v4
	s_mulk_i32 s4, 0xfa00
	v_lshlrev_b32_e32 v4, 9, v4
	v_cmp_lt_i32_e32 vcc, -1, v2
	s_add_i32 s4, s48, s4
	s_and_b32 s4, s4, 0xffffff00
	v_cndmask_b32_e32 v2, 0, v4, vcc
	v_lshl_add_u32 v2, v3, 20, v2
	v_or_b32_e32 v130, v2, v141
	v_add_u32_e32 v2, s4, v140
	v_min_i32_e32 v2, 0x5ff, v2
	v_lshl_or_b32 v4, v2, 9, v141
	v_add_u32_e32 v2, s5, v146
	v_ashrrev_i32_e32 v3, 31, v2
	v_lshrrev_b32_e32 v3, 28, v3
	v_add_u32_e32 v3, v2, v3
	v_ashrrev_i32_e32 v3, 4, v3
	v_lshlrev_b32_e32 v5, 11, v3
	v_lshlrev_b32_e32 v2, 7, v2
	v_sub_u32_e32 v2, v2, v5
	v_or_b32_e32 v5, v2, v147
	v_min_i32_e32 v5, 0x7ff, v5
	v_lshlrev_b32_e32 v5, 9, v5
	v_cmp_lt_i32_e32 vcc, -1, v2
	v_readfirstlane_b32 s44, v142
	s_mov_b32 m0, s44
	v_cndmask_b32_e32 v2, 0, v5, vcc
	v_lshl_add_u32 v2, v3, 20, v2
	v_or_b32_e32 v6, v2, v141
	v_add_u32_e32 v2, s4, v145
	v_min_i32_e32 v2, 0x5ff, v2
	v_lshl_or_b32 v8, v2, 9, v141
	v_add_u32_e32 v2, s5, v149
	v_ashrrev_i32_e32 v3, 31, v2
	v_lshrrev_b32_e32 v3, 28, v3
	v_add_u32_e32 v3, v2, v3
	v_ashrrev_i32_e32 v3, 4, v3
	v_lshlrev_b32_e32 v5, 11, v3
	v_lshlrev_b32_e32 v2, 7, v2
	v_sub_u32_e32 v2, v2, v5
	v_or_b32_e32 v5, v2, v144
	v_min_i32_e32 v5, 0x7ff, v5
	v_lshlrev_b32_e32 v5, 9, v5
	v_cmp_lt_i32_e32 vcc, -1, v2
	v_readfirstlane_b32 s14, v153
	v_mov_b32_e32 v7, v131
	v_cndmask_b32_e32 v2, 0, v5, vcc
	v_lshl_add_u32 v2, v3, 20, v2
	v_or_b32_e32 v10, v2, v141
	v_add_u32_e32 v2, s4, v148
	v_min_i32_e32 v2, 0x5ff, v2
	v_lshl_or_b32 v12, v2, 9, v141
	v_add_u32_e32 v2, s5, v151
	v_ashrrev_i32_e32 v3, 31, v2
	v_lshrrev_b32_e32 v3, 28, v3
	v_add_u32_e32 v3, v2, v3
	v_ashrrev_i32_e32 v3, 4, v3
	v_lshlrev_b32_e32 v5, 11, v3
	v_lshlrev_b32_e32 v2, 7, v2
	v_sub_u32_e32 v2, v2, v5
	v_or_b32_e32 v5, v2, v152
	v_min_i32_e32 v5, 0x7ff, v5
	v_lshlrev_b32_e32 v5, 9, v5
	v_cmp_lt_i32_e32 vcc, -1, v2
	v_readfirstlane_b32 s15, v154
	v_lshl_add_u64 v[6:7], v[6:7], 1, s[24:25]
	v_cndmask_b32_e32 v2, 0, v5, vcc
	v_lshl_add_u32 v2, v3, 20, v2
	v_or_b32_e32 v14, v2, v141
	v_add_u32_e32 v2, s4, v150
	v_min_i32_e32 v2, 0x5ff, v2
	v_lshl_or_b32 v16, v2, 9, v141
	v_lshl_add_u64 v[2:3], v[130:131], 1, s[24:25]
	v_mov_b32_e32 v5, v131
	global_load_lds_dwordx4 v[2:3], off
	v_lshl_add_u64 v[4:5], v[4:5], 1, s[26:27]
	s_mov_b32 m0, s14
	v_mov_b32_e32 v9, v131
	global_load_lds_dwordx4 v[4:5], off
	s_mov_b32 m0, s15
	v_readfirstlane_b32 s16, v155
	global_load_lds_dwordx4 v[6:7], off
	v_lshl_add_u64 v[8:9], v[8:9], 1, s[26:27]
	s_mov_b32 m0, s16
	v_mov_b32_e32 v11, v131
	v_readfirstlane_b32 s17, v156
	global_load_lds_dwordx4 v[8:9], off
	v_lshl_add_u64 v[10:11], v[10:11], 1, s[24:25]
	s_mov_b32 m0, s17
	v_mov_b32_e32 v13, v131
	v_readfirstlane_b32 s18, v157
	global_load_lds_dwordx4 v[10:11], off
	v_lshl_add_u64 v[12:13], v[12:13], 1, s[26:27]
	s_mov_b32 m0, s18
	v_mov_b32_e32 v15, v131
	v_readfirstlane_b32 s19, v158
	global_load_lds_dwordx4 v[12:13], off
	v_lshl_add_u64 v[14:15], v[14:15], 1, s[24:25]
	s_mov_b32 m0, s19
	v_mov_b32_e32 v17, v131
	v_readfirstlane_b32 s45, v159
	global_load_lds_dwordx4 v[14:15], off
	v_lshl_add_u64 v[16:17], v[16:17], 1, s[26:27]
	s_mov_b32 m0, s45
	v_readfirstlane_b32 s13, v160
	global_load_lds_dwordx4 v[16:17], off
	s_waitcnt vmcnt(0)
	s_barrier
	v_lshl_add_u64 v[18:19], v[2:3], 0, s[28:29]
	s_mov_b32 m0, s13
	v_readfirstlane_b32 s8, v161
	global_load_lds_dwordx4 v[18:19], off
	v_lshl_add_u64 v[18:19], v[4:5], 0, s[28:29]
	s_mov_b32 m0, s8
	v_readfirstlane_b32 s7, v162
	global_load_lds_dwordx4 v[18:19], off
	v_lshl_add_u64 v[18:19], v[6:7], 0, s[28:29]
	s_mov_b32 m0, s7
	v_readfirstlane_b32 s6, v163
	global_load_lds_dwordx4 v[18:19], off
	v_lshl_add_u64 v[18:19], v[8:9], 0, s[28:29]
	s_mov_b32 m0, s6
	v_readfirstlane_b32 s9, v164
	global_load_lds_dwordx4 v[18:19], off
	v_lshl_add_u64 v[18:19], v[10:11], 0, s[28:29]
	s_mov_b32 m0, s9
	v_readfirstlane_b32 s10, v165
	global_load_lds_dwordx4 v[18:19], off
	v_lshl_add_u64 v[18:19], v[12:13], 0, s[28:29]
	s_mov_b32 m0, s10
	v_readfirstlane_b32 s11, v166
	global_load_lds_dwordx4 v[18:19], off
	v_lshl_add_u64 v[18:19], v[14:15], 0, s[28:29]
	s_mov_b32 m0, s11
	v_readfirstlane_b32 s12, v167
	global_load_lds_dwordx4 v[18:19], off
	v_lshl_add_u64 v[18:19], v[16:17], 0, s[28:29]
	s_mov_b32 m0, s12
	s_nop 0
	global_load_lds_dwordx4 v[18:19], off
	ds_read_b128 v[18:21], v168
	ds_read_b128 v[22:25], v168 offset:2048
	ds_read_b128 v[26:29], v168 offset:4096
	ds_read_b128 v[30:33], v168 offset:6144
	ds_read_b128 v[34:37], v169 offset:32768
	ds_read_b128 v[38:41], v169 offset:34816
	ds_read_b128 v[42:45], v169 offset:36864
	ds_read_b128 v[46:49], v169 offset:38912
	ds_read_b128 v[74:77], v169 offset:40960
	ds_read_b128 v[78:81], v169 offset:43008
	s_waitcnt lgkmcnt(0)
; template <bool SWAP, class Epi, bool THIN = false> ...
;     ...
;     for (int st = 0; st < ns; ++st) {
;       asm volatile("s_waitcnt vmcnt(0)" ::: "memory");
;       __builtin_amdgcn_s_barrier();
;       asm volatile("" ::: "memory");
;       if (st + 1 < ns) {
;         char* nb = smem + ((st + 1) & 1) * 65536;
;         const int ko = (st + 1) * 64;
; #pragma unroll
;         for (int i = 0; i < 4; ++i) { GLDS16(A + (size_t)(ap[i] + ko), nb + tid * 16 + i * 8192); GLDS16(Bt + (size_t)(bp[i] + ko), nb + 32768 + tid * 16 + i * 8192); }
;       }
;       const char* sa = smem + (st & 1) * 65536 + (wr * 64 + fr) * 128;
;       const char* sb = smem + (st & 1) * 65536 + 32768 + (wc * 128 + fr) * 128;
;       if constexpr (THIN) {
;         if (wc == 0) {
; #pragma unroll
;           for (int ks = 0; ks < 2; ++ks) {
;             bf16x8 af[4], bf[2];
; #pragma unroll
;             for (int m = 0; m < 4; ++m) af[m] = *(const bf16x8*)(sa + m * 2048 + (((ks * 4 + fq) ^ swz) << 4));
; #pragma unroll
;             for (int n = 0; n < 2; ++n) bf[n] = *(const bf16x8*)(sb + n * 2048 + (((ks * 4 + fq) ^ swz) << 4));
; #pragma unroll
;             for (int m = 0; m < 4; ++m)
; #pragma unroll
;               for (int n = 0; n < 2; ++n)
;                 acc[m][n] = SWAP ? __builtin_amdgcn_mfma_f32_16x16x32_bf16(bf[n], af[m], acc[m][n], 0, 0, 0)
;                                  : __builtin_amdgcn_mfma_f32_16x16x32_bf16(af[m], bf[n], acc[m][n], 0, 0, 0);
;           }
;         }
;       } else {
;       bf16x8 afA[4], afB[4], bfb[2][2];
; #pragma unroll
;       for (int m = 0; m < 4; ++m) afA[m] = *(const bf16x8*)(sa + m * 2048 + ((fq ^ swz) << 4));
; #pragma unroll
;       for (int n = 0; n < 2; ++n) bfb[0][n] = *(const bf16x8*)(sb + n * 2048 + ((fq ^ swz) << 4));
; #pragma unroll
;       for (int gq = 0; gq < 8; ++gq) {
;         const int ks = gq >> 2, nh = gq & 3;
;         if (gq < 7) {
;           const int ks2 = (gq + 1) >> 2, nh2 = (gq + 1) & 3;
; #pragma unroll
;           for (int n = 0; n < 2; ++n) bfb[(gq + 1) & 1][n] = *(const bf16x8*)(sb + (nh2 * 2 + n) * 2048 + (((ks2 * 4 + fq) ^ swz) << 4));
;         }
;         if (gq == 3) {
; #pragma unroll
;           for (int m = 0; m < 4; ++m) afB[m] = *(const bf16x8*)(sa + m * 2048 + (((4 + fq) ^ swz) << 4));
;         }
;         __builtin_amdgcn_sched_barrier(0);
; #pragma unroll
	v_mfma_f32_16x16x32_bf16 v[50:53], v[34:37], v[18:21], 0
	v_mfma_f32_16x16x32_bf16 v[54:57], v[38:41], v[18:21], 0
	v_mfma_f32_16x16x32_bf16 v[58:61], v[34:37], v[22:25], 0
	v_mfma_f32_16x16x32_bf16 v[62:65], v[38:41], v[22:25], 0
	v_mfma_f32_16x16x32_bf16 v[66:69], v[34:37], v[26:29], 0
	v_mfma_f32_16x16x32_bf16 v[70:73], v[38:41], v[26:29], 0
	v_mfma_f32_16x16x32_bf16 v[34:37], v[34:37], v[30:33], 0
	v_mfma_f32_16x16x32_bf16 v[38:41], v[38:41], v[30:33], 0
	ds_read_b128 v[106:109], v169 offset:45056
	ds_read_b128 v[110:113], v169 offset:47104
	v_mfma_f32_16x16x32_bf16 v[82:85], v[42:45], v[18:21], 0
	v_mfma_f32_16x16x32_bf16 v[86:89], v[46:49], v[18:21], 0
	v_mfma_f32_16x16x32_bf16 v[90:93], v[42:45], v[22:25], 0
	v_mfma_f32_16x16x32_bf16 v[94:97], v[46:49], v[22:25], 0
	v_mfma_f32_16x16x32_bf16 v[98:101], v[42:45], v[26:29], 0
	v_mfma_f32_16x16x32_bf16 v[102:105], v[46:49], v[26:29], 0
	v_mfma_f32_16x16x32_bf16 v[42:45], v[42:45], v[30:33], 0
	v_mfma_f32_16x16x32_bf16 v[46:49], v[46:49], v[30:33], 0
	ds_read_b128 v[178:181], v170 offset:32768
	ds_read_b128 v[182:185], v170 offset:34816
	ds_read_b128 v[186:189], v171
	ds_read_b128 v[190:193], v171 offset:2048
	ds_read_b128 v[194:197], v171 offset:4096
	ds_read_b128 v[198:201], v171 offset:6144
	v_mfma_f32_16x16x32_bf16 v[114:117], v[74:77], v[18:21], 0
	v_mfma_f32_16x16x32_bf16 v[118:121], v[78:81], v[18:21], 0
	v_mfma_f32_16x16x32_bf16 v[122:125], v[74:77], v[22:25], 0
	v_mfma_f32_16x16x32_bf16 v[126:129], v[78:81], v[22:25], 0
	v_mfma_f32_16x16x32_bf16 v[132:135], v[74:77], v[26:29], 0
	v_mfma_f32_16x16x32_bf16 v[136:139], v[78:81], v[26:29], 0
	v_mfma_f32_16x16x32_bf16 v[74:77], v[74:77], v[30:33], 0
	v_mfma_f32_16x16x32_bf16 v[78:81], v[78:81], v[30:33], 0
	ds_read_b128 v[214:217], v170 offset:36864
	ds_read_b128 v[218:221], v170 offset:38912
	s_waitcnt lgkmcnt(0)
	v_mfma_f32_16x16x32_bf16 v[202:205], v[106:109], v[18:21], 0
	v_mfma_f32_16x16x32_bf16 v[18:21], v[110:113], v[18:21], 0
	v_mfma_f32_16x16x32_bf16 v[206:209], v[106:109], v[22:25], 0
	v_mfma_f32_16x16x32_bf16 v[22:25], v[110:113], v[22:25], 0
	v_mfma_f32_16x16x32_bf16 v[210:213], v[106:109], v[26:29], 0
	v_mfma_f32_16x16x32_bf16 v[26:29], v[110:113], v[26:29], 0
	v_mfma_f32_16x16x32_bf16 v[106:109], v[106:109], v[30:33], 0
	v_mfma_f32_16x16x32_bf16 v[30:33], v[110:113], v[30:33], 0
	v_mfma_f32_16x16x32_bf16 v[50:53], v[178:181], v[186:189], v[50:53]
	v_mfma_f32_16x16x32_bf16 v[58:61], v[178:181], v[190:193], v[58:61]
	v_mfma_f32_16x16x32_bf16 v[66:69], v[178:181], v[194:197], v[66:69]
	v_mfma_f32_16x16x32_bf16 v[34:37], v[178:181], v[198:201], v[34:37]
	ds_read_b128 v[110:113], v170 offset:40960
	ds_read_b128 v[178:181], v170 offset:43008
	v_mfma_f32_16x16x32_bf16 v[54:57], v[182:185], v[186:189], v[54:57]
	v_mfma_f32_16x16x32_bf16 v[62:65], v[182:185], v[190:193], v[62:65]
	v_mfma_f32_16x16x32_bf16 v[70:73], v[182:185], v[194:197], v[70:73]
	v_mfma_f32_16x16x32_bf16 v[38:41], v[182:185], v[198:201], v[38:41]
	v_mfma_f32_16x16x32_bf16 v[82:85], v[214:217], v[186:189], v[82:85]
	v_mfma_f32_16x16x32_bf16 v[90:93], v[214:217], v[190:193], v[90:93]
	v_mfma_f32_16x16x32_bf16 v[98:101], v[214:217], v[194:197], v[98:101]
	v_mfma_f32_16x16x32_bf16 v[42:45], v[214:217], v[198:201], v[42:45]
	ds_read_b128 v[182:185], v170 offset:45056
	ds_read_b128 v[214:217], v170 offset:47104
	v_mfma_f32_16x16x32_bf16 v[86:89], v[218:221], v[186:189], v[86:89]
	v_mfma_f32_16x16x32_bf16 v[94:97], v[218:221], v[190:193], v[94:97]
	v_mfma_f32_16x16x32_bf16 v[102:105], v[218:221], v[194:197], v[102:105]
	v_mfma_f32_16x16x32_bf16 v[46:49], v[218:221], v[198:201], v[46:49]
	s_waitcnt lgkmcnt(0)
	v_mfma_f32_16x16x32_bf16 v[114:117], v[110:113], v[186:189], v[114:117]
	v_mfma_f32_16x16x32_bf16 v[118:121], v[178:181], v[186:189], v[118:121]
	v_mfma_f32_16x16x32_bf16 v[122:125], v[110:113], v[190:193], v[122:125]
	v_mfma_f32_16x16x32_bf16 v[126:129], v[178:181], v[190:193], v[126:129]
	v_mfma_f32_16x16x32_bf16 v[132:135], v[110:113], v[194:197], v[132:135]
	v_mfma_f32_16x16x32_bf16 v[136:139], v[178:181], v[194:197], v[136:139]
	v_mfma_f32_16x16x32_bf16 v[74:77], v[110:113], v[198:201], v[74:77]
	v_mfma_f32_16x16x32_bf16 v[78:81], v[178:181], v[198:201], v[78:81]
	s_mov_b32 m0, s44
	v_mfma_f32_16x16x32_bf16 v[110:113], v[182:185], v[186:189], v[202:205]
	s_waitcnt vmcnt(0)
	s_barrier
; template <bool SWAP, class Epi, bool THIN = false> ...
;     ...
;     for (int st = 0; st < ns; ++st) {
;       asm volatile("s_waitcnt vmcnt(0)" ::: "memory");
;       __builtin_amdgcn_s_barrier();
;       asm volatile("" ::: "memory");
;       if (st + 1 < ns) {
;         char* nb = smem + ((st + 1) & 1) * 65536;
;         const int ko = (st + 1) * 64;
; #pragma unroll
;         for (int i = 0; i < 4; ++i) { GLDS16(A + (size_t)(ap[i] + ko), nb + tid * 16 + i * 8192); GLDS16(Bt + (size_t)(bp[i] + ko), nb + 32768 + tid * 16 + i * 8192); }
;       }
;       const char* sa = smem + (st & 1) * 65536 + (wr * 64 + fr) * 128;
;       const char* sb = smem + (st & 1) * 65536 + 32768 + (wc * 128 + fr) * 128;
;       if constexpr (THIN) {
;         if (wc == 0) {
; #pragma unroll
;           for (int ks = 0; ks < 2; ++ks) {
;             bf16x8 af[4], bf[2];
; #pragma unroll
;             for (int m = 0; m < 4; ++m) af[m] = *(const bf16x8*)(sa + m * 2048 + (((ks * 4 + fq) ^ swz) << 4));
; #pragma unroll
;             for (int n = 0; n < 2; ++n) bf[n] = *(const bf16x8*)(sb + n * 2048 + (((ks * 4 + fq) ^ swz) << 4));
; #pragma unroll
;             for (int m = 0; m < 4; ++m)
; #pragma unroll
;               for (int n = 0; n < 2; ++n)
;                 acc[m][n] = SWAP ? __builtin_amdgcn_mfma_f32_16x16x32_bf16(bf[n], af[m], acc[m][n], 0, 0, 0)
;                                  : __builtin_amdgcn_mfma_f32_16x16x32_bf16(af[m], bf[n], acc[m][n], 0, 0, 0);
;           }
;         }
;       } else {
;       bf16x8 afA[4], afB[4], bfb[2][2];
; #pragma unroll
;       for (int m = 0; m < 4; ++m) afA[m] = *(const bf16x8*)(sa + m * 2048 + ((fq ^ swz) << 4));
; #pragma unroll
;       for (int n = 0; n < 2; ++n) bfb[0][n] = *(const bf16x8*)(sb + n * 2048 + ((fq ^ swz) << 4));
; #pragma unroll
;       for (int gq = 0; gq < 8; ++gq) {
;         const int ks = gq >> 2, nh = gq & 3;
;         if (gq < 7) {
;           const int ks2 = (gq + 1) >> 2, nh2 = (gq + 1) & 3;
; #pragma unroll
;           for (int n = 0; n < 2; ++n) bfb[(gq + 1) & 1][n] = *(const bf16x8*)(sb + (nh2 * 2 + n) * 2048 + (((ks2 * 4 + fq) ^ swz) << 4));
;         }
;         if (gq == 3) {
; #pragma unroll
;           for (int m = 0; m < 4; ++m) afB[m] = *(const bf16x8*)(sa + m * 2048 + (((4 + fq) ^ swz) << 4));
;         }
;         __builtin_amdgcn_sched_barrier(0);
; #pragma unroll
	v_mfma_f32_16x16x32_bf16 v[18:21], v[214:217], v[186:189], v[18:21]
	v_lshl_add_u64 v[186:187], v[2:3], 0, s[30:31]
	global_load_lds_dwordx4 v[186:187], off
	v_lshl_add_u64 v[186:187], v[4:5], 0, s[30:31]
	s_mov_b32 m0, s14
	v_mfma_f32_16x16x32_bf16 v[178:181], v[182:185], v[190:193], v[206:209]
	global_load_lds_dwordx4 v[186:187], off
	s_mov_b32 m0, s15
	v_mfma_f32_16x16x32_bf16 v[22:25], v[214:217], v[190:193], v[22:25]
	v_lshl_add_u64 v[190:191], v[6:7], 0, s[30:31]
	global_load_lds_dwordx4 v[190:191], off
	v_lshl_add_u64 v[190:191], v[8:9], 0, s[30:31]
	s_mov_b32 m0, s16
	v_mfma_f32_16x16x32_bf16 v[186:189], v[182:185], v[194:197], v[210:213]
	global_load_lds_dwordx4 v[190:191], off
	v_lshl_add_u64 v[190:191], v[10:11], 0, s[30:31]
	s_mov_b32 m0, s17
	v_mfma_f32_16x16x32_bf16 v[26:29], v[214:217], v[194:197], v[26:29]
	global_load_lds_dwordx4 v[190:191], off
	v_lshl_add_u64 v[190:191], v[12:13], 0, s[30:31]
	s_mov_b32 m0, s18
	v_mfma_f32_16x16x32_bf16 v[106:109], v[182:185], v[198:201], v[106:109]
	global_load_lds_dwordx4 v[190:191], off
	v_lshl_add_u64 v[190:191], v[14:15], 0, s[30:31]
	s_mov_b32 m0, s19
	v_mfma_f32_16x16x32_bf16 v[30:33], v[214:217], v[198:201], v[30:33]
	global_load_lds_dwordx4 v[190:191], off
	v_lshl_add_u64 v[190:191], v[16:17], 0, s[30:31]
	s_mov_b32 m0, s45
	s_nop 0
	global_load_lds_dwordx4 v[190:191], off
	ds_read_b128 v[182:185], v172
	ds_read_b128 v[190:193], v172 offset:2048
	ds_read_b128 v[194:197], v172 offset:4096
	ds_read_b128 v[202:205], v172 offset:6144
	ds_read_b128 v[206:209], v173
	ds_read_b128 v[210:213], v173 offset:2048
	ds_read_b128 v[218:221], v173 offset:4096
	ds_read_b128 v[222:225], v173 offset:6144
	s_waitcnt lgkmcnt(0)
	v_mfma_f32_16x16x32_bf16 v[50:53], v[206:209], v[182:185], v[50:53]
	v_mfma_f32_16x16x32_bf16 v[58:61], v[206:209], v[190:193], v[58:61]
	v_mfma_f32_16x16x32_bf16 v[66:69], v[206:209], v[194:197], v[66:69]
	v_mfma_f32_16x16x32_bf16 v[34:37], v[206:209], v[202:205], v[34:37]
	ds_read_b128 v[198:201], v173 offset:8192
	ds_read_b128 v[206:209], v173 offset:10240
	v_mfma_f32_16x16x32_bf16 v[54:57], v[210:213], v[182:185], v[54:57]
	v_mfma_f32_16x16x32_bf16 v[62:65], v[210:213], v[190:193], v[62:65]
	v_mfma_f32_16x16x32_bf16 v[70:73], v[210:213], v[194:197], v[70:73]
	v_mfma_f32_16x16x32_bf16 v[38:41], v[210:213], v[202:205], v[38:41]
	ds_read_b128 v[210:213], v173 offset:12288
	ds_read_b128 v[214:217], v173 offset:14336
	v_mfma_f32_16x16x32_bf16 v[82:85], v[218:221], v[182:185], v[82:85]
	v_mfma_f32_16x16x32_bf16 v[86:89], v[222:225], v[182:185], v[86:89]
	v_mfma_f32_16x16x32_bf16 v[90:93], v[218:221], v[190:193], v[90:93]
	v_mfma_f32_16x16x32_bf16 v[94:97], v[222:225], v[190:193], v[94:97]
	v_mfma_f32_16x16x32_bf16 v[98:101], v[218:221], v[194:197], v[98:101]
	v_mfma_f32_16x16x32_bf16 v[102:105], v[222:225], v[194:197], v[102:105]
	v_mfma_f32_16x16x32_bf16 v[42:45], v[218:221], v[202:205], v[42:45]
	v_mfma_f32_16x16x32_bf16 v[46:49], v[222:225], v[202:205], v[46:49]
	s_waitcnt lgkmcnt(0)
	v_mfma_f32_16x16x32_bf16 v[114:117], v[198:201], v[182:185], v[114:117]
	ds_read_b128 v[218:221], v174
	ds_read_b128 v[222:225], v174 offset:2048
	v_mfma_f32_16x16x32_bf16 v[122:125], v[198:201], v[190:193], v[122:125]
	v_mfma_f32_16x16x32_bf16 v[132:135], v[198:201], v[194:197], v[132:135]
	v_mfma_f32_16x16x32_bf16 v[74:77], v[198:201], v[202:205], v[74:77]
	ds_read_b128 v[198:201], v175
	ds_read_b128 v[226:229], v175 offset:2048
	ds_read_b128 v[230:233], v175 offset:4096
	ds_read_b128 v[234:237], v175 offset:6144
	v_mfma_f32_16x16x32_bf16 v[118:121], v[206:209], v[182:185], v[118:121]
	v_mfma_f32_16x16x32_bf16 v[126:129], v[206:209], v[190:193], v[126:129]
	v_mfma_f32_16x16x32_bf16 v[136:139], v[206:209], v[194:197], v[136:139]
	v_mfma_f32_16x16x32_bf16 v[78:81], v[206:209], v[202:205], v[78:81]
	v_mfma_f32_16x16x32_bf16 v[110:113], v[210:213], v[182:185], v[110:113]
	v_mfma_f32_16x16x32_bf16 v[18:21], v[214:217], v[182:185], v[18:21]
	v_mfma_f32_16x16x32_bf16 v[178:181], v[210:213], v[190:193], v[178:181]
	v_mfma_f32_16x16x32_bf16 v[22:25], v[214:217], v[190:193], v[22:25]
	v_mfma_f32_16x16x32_bf16 v[182:185], v[210:213], v[194:197], v[186:189]
	s_nop 2
	ds_read_b128 v[186:189], v174 offset:4096
	ds_read_b128 v[190:193], v174 offset:6144
	v_mfma_f32_16x16x32_bf16 v[26:29], v[214:217], v[194:197], v[26:29]
	v_mfma_f32_16x16x32_bf16 v[106:109], v[210:213], v[202:205], v[106:109]
	v_mfma_f32_16x16x32_bf16 v[30:33], v[214:217], v[202:205], v[30:33]
	ds_read_b128 v[194:197], v174 offset:8192
	ds_read_b128 v[202:205], v174 offset:10240
	s_waitcnt lgkmcnt(0)
	v_mfma_f32_16x16x32_bf16 v[50:53], v[218:221], v[198:201], v[50:53]
	v_mfma_f32_16x16x32_bf16 v[54:57], v[222:225], v[198:201], v[54:57]
	v_mfma_f32_16x16x32_bf16 v[58:61], v[218:221], v[226:229], v[58:61]
	v_mfma_f32_16x16x32_bf16 v[62:65], v[222:225], v[226:229], v[62:65]
	v_mfma_f32_16x16x32_bf16 v[66:69], v[218:221], v[230:233], v[66:69]
	v_mfma_f32_16x16x32_bf16 v[70:73], v[222:225], v[230:233], v[70:73]
	v_mfma_f32_16x16x32_bf16 v[34:37], v[218:221], v[234:237], v[34:37]
	v_mfma_f32_16x16x32_bf16 v[38:41], v[222:225], v[234:237], v[38:41]
	v_mfma_f32_16x16x32_bf16 v[82:85], v[186:189], v[198:201], v[82:85]
	v_mfma_f32_16x16x32_bf16 v[90:93], v[186:189], v[226:229], v[90:93]
	v_mfma_f32_16x16x32_bf16 v[98:101], v[186:189], v[230:233], v[98:101]
	v_mfma_f32_16x16x32_bf16 v[42:45], v[186:189], v[234:237], v[42:45]
	ds_read_b128 v[186:189], v174 offset:12288
	ds_read_b128 v[206:209], v174 offset:14336
	v_mfma_f32_16x16x32_bf16 v[86:89], v[190:193], v[198:201], v[86:89]
	v_mfma_f32_16x16x32_bf16 v[94:97], v[190:193], v[226:229], v[94:97]
	v_mfma_f32_16x16x32_bf16 v[102:105], v[190:193], v[230:233], v[102:105]
	v_mfma_f32_16x16x32_bf16 v[46:49], v[190:193], v[234:237], v[46:49]
	v_mfma_f32_16x16x32_bf16 v[114:117], v[194:197], v[198:201], v[114:117]
	v_mfma_f32_16x16x32_bf16 v[118:121], v[202:205], v[198:201], v[118:121]
	v_mfma_f32_16x16x32_bf16 v[122:125], v[194:197], v[226:229], v[122:125]
	v_mfma_f32_16x16x32_bf16 v[126:129], v[202:205], v[226:229], v[126:129]
	v_mfma_f32_16x16x32_bf16 v[132:135], v[194:197], v[230:233], v[132:135]
	v_mfma_f32_16x16x32_bf16 v[136:139], v[202:205], v[230:233], v[136:139]
	v_mfma_f32_16x16x32_bf16 v[74:77], v[194:197], v[234:237], v[74:77]
	v_mfma_f32_16x16x32_bf16 v[78:81], v[202:205], v[234:237], v[78:81]
	s_mov_b32 m0, s13
	s_waitcnt vmcnt(0)
	s_barrier
; template <bool SWAP, class Epi, bool THIN = false> ...
;     ...
;     for (int st = 0; st < ns; ++st) {
;       asm volatile("s_waitcnt vmcnt(0)" ::: "memory");
;       __builtin_amdgcn_s_barrier();
;       asm volatile("" ::: "memory");
;       if (st + 1 < ns) {
;         char* nb = smem + ((st + 1) & 1) * 65536;
;         const int ko = (st + 1) * 64;
; #pragma unroll
;         for (int i = 0; i < 4; ++i) { GLDS16(A + (size_t)(ap[i] + ko), nb + tid * 16 + i * 8192); GLDS16(Bt + (size_t)(bp[i] + ko), nb + 32768 + tid * 16 + i * 8192); }
;       }
;       const char* sa = smem + (st & 1) * 65536 + (wr * 64 + fr) * 128;
;       const char* sb = smem + (st & 1) * 65536 + 32768 + (wc * 128 + fr) * 128;
;       if constexpr (THIN) {
;         if (wc == 0) {
; #pragma unroll
;           for (int ks = 0; ks < 2; ++ks) {
;             bf16x8 af[4], bf[2];
; #pragma unroll
;             for (int m = 0; m < 4; ++m) af[m] = *(const bf16x8*)(sa + m * 2048 + (((ks * 4 + fq) ^ swz) << 4));
; #pragma unroll
;             for (int n = 0; n < 2; ++n) bf[n] = *(const bf16x8*)(sb + n * 2048 + (((ks * 4 + fq) ^ swz) << 4));
; #pragma unroll
;             for (int m = 0; m < 4; ++m)
; #pragma unroll
;               for (int n = 0; n < 2; ++n)
;                 acc[m][n] = SWAP ? __builtin_amdgcn_mfma_f32_16x16x32_bf16(bf[n], af[m], acc[m][n], 0, 0, 0)
;                                  : __builtin_amdgcn_mfma_f32_16x16x32_bf16(af[m], bf[n], acc[m][n], 0, 0, 0);
;           }
;         }
;       } else {
;       bf16x8 afA[4], afB[4], bfb[2][2];
; #pragma unroll
;       for (int m = 0; m < 4; ++m) afA[m] = *(const bf16x8*)(sa + m * 2048 + ((fq ^ swz) << 4));
; #pragma unroll
;       for (int n = 0; n < 2; ++n) bfb[0][n] = *(const bf16x8*)(sb + n * 2048 + ((fq ^ swz) << 4));
; #pragma unroll
;       for (int gq = 0; gq < 8; ++gq) {
;         const int ks = gq >> 2, nh = gq & 3;
;         if (gq < 7) {
;           const int ks2 = (gq + 1) >> 2, nh2 = (gq + 1) & 3;
; #pragma unroll
;           for (int n = 0; n < 2; ++n) bfb[(gq + 1) & 1][n] = *(const bf16x8*)(sb + (nh2 * 2 + n) * 2048 + (((ks2 * 4 + fq) ^ swz) << 4));
;         }
;         if (gq == 3) {
; #pragma unroll
;           for (int m = 0; m < 4; ++m) afB[m] = *(const bf16x8*)(sa + m * 2048 + (((4 + fq) ^ swz) << 4));
;         }
;         __builtin_amdgcn_sched_barrier(0);
; #pragma unroll
	v_lshl_add_u64 v[190:191], v[2:3], 0, s[34:35]
	global_load_lds_dwordx4 v[190:191], off
	v_lshl_add_u64 v[190:191], v[4:5], 0, s[34:35]
	s_mov_b32 m0, s8
	s_waitcnt lgkmcnt(0)
	v_mfma_f32_16x16x32_bf16 v[110:113], v[186:189], v[198:201], v[110:113]
	global_load_lds_dwordx4 v[190:191], off
	v_lshl_add_u64 v[190:191], v[6:7], 0, s[34:35]
	s_mov_b32 m0, s7
	v_mfma_f32_16x16x32_bf16 v[18:21], v[206:209], v[198:201], v[18:21]
	global_load_lds_dwordx4 v[190:191], off
	v_lshl_add_u64 v[190:191], v[8:9], 0, s[34:35]
	s_mov_b32 m0, s6
	v_mfma_f32_16x16x32_bf16 v[178:181], v[186:189], v[226:229], v[178:181]
	global_load_lds_dwordx4 v[190:191], off
	v_lshl_add_u64 v[190:191], v[10:11], 0, s[34:35]
	s_mov_b32 m0, s9
	v_mfma_f32_16x16x32_bf16 v[182:185], v[186:189], v[230:233], v[182:185]
	global_load_lds_dwordx4 v[190:191], off
	v_lshl_add_u64 v[190:191], v[12:13], 0, s[34:35]
	s_mov_b32 m0, s10
	v_mfma_f32_16x16x32_bf16 v[106:109], v[186:189], v[234:237], v[106:109]
	global_load_lds_dwordx4 v[190:191], off
	v_lshl_add_u64 v[190:191], v[14:15], 0, s[34:35]
	s_mov_b32 m0, s11
	v_mfma_f32_16x16x32_bf16 v[22:25], v[206:209], v[226:229], v[22:25]
	global_load_lds_dwordx4 v[190:191], off
	v_lshl_add_u64 v[190:191], v[16:17], 0, s[34:35]
	s_mov_b32 m0, s12
	v_mfma_f32_16x16x32_bf16 v[26:29], v[206:209], v[230:233], v[26:29]
	global_load_lds_dwordx4 v[190:191], off
	ds_read_b128 v[186:189], v168
	ds_read_b128 v[190:193], v168 offset:2048
	ds_read_b128 v[194:197], v168 offset:4096
	ds_read_b128 v[198:201], v168 offset:6144
	ds_read_b128 v[202:205], v169 offset:32768
	ds_read_b128 v[210:213], v169 offset:34816
	ds_read_b128 v[214:217], v169 offset:36864
	ds_read_b128 v[218:221], v169 offset:38912
	v_mfma_f32_16x16x32_bf16 v[30:33], v[206:209], v[234:237], v[30:33]
	s_waitcnt lgkmcnt(0)
	v_mfma_f32_16x16x32_bf16 v[50:53], v[202:205], v[186:189], v[50:53]
	v_mfma_f32_16x16x32_bf16 v[58:61], v[202:205], v[190:193], v[58:61]
	v_mfma_f32_16x16x32_bf16 v[66:69], v[202:205], v[194:197], v[66:69]
	v_mfma_f32_16x16x32_bf16 v[34:37], v[202:205], v[198:201], v[34:37]
	ds_read_b128 v[202:205], v169 offset:40960
	ds_read_b128 v[206:209], v169 offset:43008
	v_mfma_f32_16x16x32_bf16 v[54:57], v[210:213], v[186:189], v[54:57]
	v_mfma_f32_16x16x32_bf16 v[62:65], v[210:213], v[190:193], v[62:65]
	v_mfma_f32_16x16x32_bf16 v[70:73], v[210:213], v[194:197], v[70:73]
	v_mfma_f32_16x16x32_bf16 v[38:41], v[210:213], v[198:201], v[38:41]
	v_mfma_f32_16x16x32_bf16 v[82:85], v[214:217], v[186:189], v[82:85]
	v_mfma_f32_16x16x32_bf16 v[90:93], v[214:217], v[190:193], v[90:93]
	v_mfma_f32_16x16x32_bf16 v[98:101], v[214:217], v[194:197], v[98:101]
	v_mfma_f32_16x16x32_bf16 v[42:45], v[214:217], v[198:201], v[42:45]
	ds_read_b128 v[210:213], v169 offset:45056
	ds_read_b128 v[214:217], v169 offset:47104
	v_mfma_f32_16x16x32_bf16 v[86:89], v[218:221], v[186:189], v[86:89]
	v_mfma_f32_16x16x32_bf16 v[94:97], v[218:221], v[190:193], v[94:97]
	v_mfma_f32_16x16x32_bf16 v[102:105], v[218:221], v[194:197], v[102:105]
	v_mfma_f32_16x16x32_bf16 v[46:49], v[218:221], v[198:201], v[46:49]
	s_waitcnt lgkmcnt(0)
	v_mfma_f32_16x16x32_bf16 v[114:117], v[202:205], v[186:189], v[114:117]
	ds_read_b128 v[218:221], v170 offset:32768
	ds_read_b128 v[222:225], v170 offset:34816
	v_mfma_f32_16x16x32_bf16 v[122:125], v[202:205], v[190:193], v[122:125]
	v_mfma_f32_16x16x32_bf16 v[132:135], v[202:205], v[194:197], v[132:135]
	v_mfma_f32_16x16x32_bf16 v[74:77], v[202:205], v[198:201], v[74:77]
	ds_read_b128 v[202:205], v171
	ds_read_b128 v[226:229], v171 offset:2048
	ds_read_b128 v[230:233], v171 offset:4096
	ds_read_b128 v[234:237], v171 offset:6144
	v_mfma_f32_16x16x32_bf16 v[118:121], v[206:209], v[186:189], v[118:121]
	v_mfma_f32_16x16x32_bf16 v[126:129], v[206:209], v[190:193], v[126:129]
	v_mfma_f32_16x16x32_bf16 v[136:139], v[206:209], v[194:197], v[136:139]
	v_mfma_f32_16x16x32_bf16 v[78:81], v[206:209], v[198:201], v[78:81]
	v_mfma_f32_16x16x32_bf16 v[110:113], v[210:213], v[186:189], v[110:113]
	v_mfma_f32_16x16x32_bf16 v[18:21], v[214:217], v[186:189], v[18:21]
	v_mfma_f32_16x16x32_bf16 v[178:181], v[210:213], v[190:193], v[178:181]
	v_mfma_f32_16x16x32_bf16 v[22:25], v[214:217], v[190:193], v[22:25]
	ds_read_b128 v[186:189], v170 offset:36864
	ds_read_b128 v[190:193], v170 offset:38912
	v_mfma_f32_16x16x32_bf16 v[26:29], v[214:217], v[194:197], v[26:29]
	v_mfma_f32_16x16x32_bf16 v[106:109], v[210:213], v[198:201], v[106:109]
	v_mfma_f32_16x16x32_bf16 v[30:33], v[214:217], v[198:201], v[30:33]
	v_mfma_f32_16x16x32_bf16 v[182:185], v[210:213], v[194:197], v[182:185]
	ds_read_b128 v[194:197], v170 offset:40960
	ds_read_b128 v[198:201], v170 offset:43008
	s_waitcnt lgkmcnt(0)
	v_mfma_f32_16x16x32_bf16 v[50:53], v[218:221], v[202:205], v[50:53]
	v_mfma_f32_16x16x32_bf16 v[54:57], v[222:225], v[202:205], v[54:57]
	v_mfma_f32_16x16x32_bf16 v[58:61], v[218:221], v[226:229], v[58:61]
	v_mfma_f32_16x16x32_bf16 v[62:65], v[222:225], v[226:229], v[62:65]
	v_mfma_f32_16x16x32_bf16 v[66:69], v[218:221], v[230:233], v[66:69]
	v_mfma_f32_16x16x32_bf16 v[70:73], v[222:225], v[230:233], v[70:73]
	v_mfma_f32_16x16x32_bf16 v[34:37], v[218:221], v[234:237], v[34:37]
	v_mfma_f32_16x16x32_bf16 v[38:41], v[222:225], v[234:237], v[38:41]
	v_mfma_f32_16x16x32_bf16 v[82:85], v[186:189], v[202:205], v[82:85]
	v_mfma_f32_16x16x32_bf16 v[90:93], v[186:189], v[226:229], v[90:93]
	v_mfma_f32_16x16x32_bf16 v[98:101], v[186:189], v[230:233], v[98:101]
	v_mfma_f32_16x16x32_bf16 v[42:45], v[186:189], v[234:237], v[42:45]
	ds_read_b128 v[186:189], v170 offset:45056
	ds_read_b128 v[206:209], v170 offset:47104
	v_mfma_f32_16x16x32_bf16 v[86:89], v[190:193], v[202:205], v[86:89]
	v_mfma_f32_16x16x32_bf16 v[94:97], v[190:193], v[226:229], v[94:97]
	v_mfma_f32_16x16x32_bf16 v[102:105], v[190:193], v[230:233], v[102:105]
	v_mfma_f32_16x16x32_bf16 v[46:49], v[190:193], v[234:237], v[46:49]
	v_mfma_f32_16x16x32_bf16 v[114:117], v[194:197], v[202:205], v[114:117]
	v_mfma_f32_16x16x32_bf16 v[118:121], v[198:201], v[202:205], v[118:121]
	v_mfma_f32_16x16x32_bf16 v[122:125], v[194:197], v[226:229], v[122:125]
	v_mfma_f32_16x16x32_bf16 v[126:129], v[198:201], v[226:229], v[126:129]
	v_mfma_f32_16x16x32_bf16 v[132:135], v[194:197], v[230:233], v[132:135]
	v_mfma_f32_16x16x32_bf16 v[136:139], v[198:201], v[230:233], v[136:139]
	v_mfma_f32_16x16x32_bf16 v[74:77], v[194:197], v[234:237], v[74:77]
	v_mfma_f32_16x16x32_bf16 v[78:81], v[198:201], v[234:237], v[78:81]
	s_mov_b32 m0, s44
	s_waitcnt vmcnt(0)
	s_barrier
; template <bool SWAP, class Epi, bool THIN = false> ...
;     ...
;     for (int st = 0; st < ns; ++st) {
;       asm volatile("s_waitcnt vmcnt(0)" ::: "memory");
;       __builtin_amdgcn_s_barrier();
;       asm volatile("" ::: "memory");
;       if (st + 1 < ns) {
;         char* nb = smem + ((st + 1) & 1) * 65536;
;         const int ko = (st + 1) * 64;
; #pragma unroll
;         for (int i = 0; i < 4; ++i) { GLDS16(A + (size_t)(ap[i] + ko), nb + tid * 16 + i * 8192); GLDS16(Bt + (size_t)(bp[i] + ko), nb + 32768 + tid * 16 + i * 8192); }
;       }
;       const char* sa = smem + (st & 1) * 65536 + (wr * 64 + fr) * 128;
;       const char* sb = smem + (st & 1) * 65536 + 32768 + (wc * 128 + fr) * 128;
;       if constexpr (THIN) {
;         if (wc == 0) {
; #pragma unroll
;           for (int ks = 0; ks < 2; ++ks) {
;             bf16x8 af[4], bf[2];
; #pragma unroll
;             for (int m = 0; m < 4; ++m) af[m] = *(const bf16x8*)(sa + m * 2048 + (((ks * 4 + fq) ^ swz) << 4));
; #pragma unroll
;             for (int n = 0; n < 2; ++n) bf[n] = *(const bf16x8*)(sb + n * 2048 + (((ks * 4 + fq) ^ swz) << 4));
; #pragma unroll
;             for (int m = 0; m < 4; ++m)
; #pragma unroll
;               for (int n = 0; n < 2; ++n)
;                 acc[m][n] = SWAP ? __builtin_amdgcn_mfma_f32_16x16x32_bf16(bf[n], af[m], acc[m][n], 0, 0, 0)
;                                  : __builtin_amdgcn_mfma_f32_16x16x32_bf16(af[m], bf[n], acc[m][n], 0, 0, 0);
;           }
;         }
;       } else {
;       bf16x8 afA[4], afB[4], bfb[2][2];
; #pragma unroll
;       for (int m = 0; m < 4; ++m) afA[m] = *(const bf16x8*)(sa + m * 2048 + ((fq ^ swz) << 4));
; #pragma unroll
;       for (int n = 0; n < 2; ++n) bfb[0][n] = *(const bf16x8*)(sb + n * 2048 + ((fq ^ swz) << 4));
; #pragma unroll
;       for (int gq = 0; gq < 8; ++gq) {
;         const int ks = gq >> 2, nh = gq & 3;
;         if (gq < 7) {
;           const int ks2 = (gq + 1) >> 2, nh2 = (gq + 1) & 3;
; #pragma unroll
;           for (int n = 0; n < 2; ++n) bfb[(gq + 1) & 1][n] = *(const bf16x8*)(sb + (nh2 * 2 + n) * 2048 + (((ks2 * 4 + fq) ^ swz) << 4));
;         }
;         if (gq == 3) {
; #pragma unroll
;           for (int m = 0; m < 4; ++m) afB[m] = *(const bf16x8*)(sa + m * 2048 + (((4 + fq) ^ swz) << 4));
;         }
;         __builtin_amdgcn_sched_barrier(0);
; #pragma unroll
	v_lshl_add_u64 v[190:191], v[2:3], 0, s[36:37]
	global_load_lds_dwordx4 v[190:191], off
	v_lshl_add_u64 v[190:191], v[4:5], 0, s[36:37]
	s_mov_b32 m0, s14
	s_waitcnt lgkmcnt(0)
	v_mfma_f32_16x16x32_bf16 v[110:113], v[186:189], v[202:205], v[110:113]
	global_load_lds_dwordx4 v[190:191], off
	v_lshl_add_u64 v[190:191], v[6:7], 0, s[36:37]
	s_mov_b32 m0, s15
	v_mfma_f32_16x16x32_bf16 v[18:21], v[206:209], v[202:205], v[18:21]
	global_load_lds_dwordx4 v[190:191], off
	v_lshl_add_u64 v[190:191], v[8:9], 0, s[36:37]
	s_mov_b32 m0, s16
	v_mfma_f32_16x16x32_bf16 v[178:181], v[186:189], v[226:229], v[178:181]
	global_load_lds_dwordx4 v[190:191], off
	v_lshl_add_u64 v[190:191], v[10:11], 0, s[36:37]
	s_mov_b32 m0, s17
	v_mfma_f32_16x16x32_bf16 v[182:185], v[186:189], v[230:233], v[182:185]
	global_load_lds_dwordx4 v[190:191], off
	v_lshl_add_u64 v[190:191], v[12:13], 0, s[36:37]
	s_mov_b32 m0, s18
	v_mfma_f32_16x16x32_bf16 v[106:109], v[186:189], v[234:237], v[106:109]
	global_load_lds_dwordx4 v[190:191], off
	v_lshl_add_u64 v[190:191], v[14:15], 0, s[36:37]
	s_mov_b32 m0, s19
	v_mfma_f32_16x16x32_bf16 v[22:25], v[206:209], v[226:229], v[22:25]
	global_load_lds_dwordx4 v[190:191], off
	v_lshl_add_u64 v[190:191], v[16:17], 0, s[36:37]
	s_mov_b32 m0, s45
	v_mfma_f32_16x16x32_bf16 v[26:29], v[206:209], v[230:233], v[26:29]
	global_load_lds_dwordx4 v[190:191], off
	ds_read_b128 v[186:189], v172
	ds_read_b128 v[190:193], v172 offset:2048
	ds_read_b128 v[194:197], v172 offset:4096
	ds_read_b128 v[198:201], v172 offset:6144
	ds_read_b128 v[202:205], v173
	ds_read_b128 v[210:213], v173 offset:2048
	ds_read_b128 v[214:217], v173 offset:4096
	ds_read_b128 v[218:221], v173 offset:6144
	v_mfma_f32_16x16x32_bf16 v[30:33], v[206:209], v[234:237], v[30:33]
	s_waitcnt lgkmcnt(0)
	v_mfma_f32_16x16x32_bf16 v[50:53], v[202:205], v[186:189], v[50:53]
	v_mfma_f32_16x16x32_bf16 v[58:61], v[202:205], v[190:193], v[58:61]
	v_mfma_f32_16x16x32_bf16 v[66:69], v[202:205], v[194:197], v[66:69]
	v_mfma_f32_16x16x32_bf16 v[34:37], v[202:205], v[198:201], v[34:37]
	ds_read_b128 v[202:205], v173 offset:8192
	ds_read_b128 v[206:209], v173 offset:10240
	v_mfma_f32_16x16x32_bf16 v[54:57], v[210:213], v[186:189], v[54:57]
	v_mfma_f32_16x16x32_bf16 v[62:65], v[210:213], v[190:193], v[62:65]
	v_mfma_f32_16x16x32_bf16 v[70:73], v[210:213], v[194:197], v[70:73]
	v_mfma_f32_16x16x32_bf16 v[38:41], v[210:213], v[198:201], v[38:41]
	v_mfma_f32_16x16x32_bf16 v[82:85], v[214:217], v[186:189], v[82:85]
	v_mfma_f32_16x16x32_bf16 v[90:93], v[214:217], v[190:193], v[90:93]
	v_mfma_f32_16x16x32_bf16 v[98:101], v[214:217], v[194:197], v[98:101]
	v_mfma_f32_16x16x32_bf16 v[42:45], v[214:217], v[198:201], v[42:45]
	ds_read_b128 v[210:213], v173 offset:12288
	ds_read_b128 v[214:217], v173 offset:14336
	v_mfma_f32_16x16x32_bf16 v[86:89], v[218:221], v[186:189], v[86:89]
	v_mfma_f32_16x16x32_bf16 v[94:97], v[218:221], v[190:193], v[94:97]
	v_mfma_f32_16x16x32_bf16 v[102:105], v[218:221], v[194:197], v[102:105]
	v_mfma_f32_16x16x32_bf16 v[46:49], v[218:221], v[198:201], v[46:49]
	s_waitcnt lgkmcnt(0)
	v_mfma_f32_16x16x32_bf16 v[114:117], v[202:205], v[186:189], v[114:117]
	ds_read_b128 v[218:221], v174
	ds_read_b128 v[222:225], v174 offset:2048
	v_mfma_f32_16x16x32_bf16 v[122:125], v[202:205], v[190:193], v[122:125]
	v_mfma_f32_16x16x32_bf16 v[132:135], v[202:205], v[194:197], v[132:135]
	v_mfma_f32_16x16x32_bf16 v[74:77], v[202:205], v[198:201], v[74:77]
	ds_read_b128 v[202:205], v175
	ds_read_b128 v[226:229], v175 offset:2048
	ds_read_b128 v[230:233], v175 offset:4096
	ds_read_b128 v[234:237], v175 offset:6144
	v_mfma_f32_16x16x32_bf16 v[118:121], v[206:209], v[186:189], v[118:121]
	v_mfma_f32_16x16x32_bf16 v[126:129], v[206:209], v[190:193], v[126:129]
	v_mfma_f32_16x16x32_bf16 v[136:139], v[206:209], v[194:197], v[136:139]
	v_mfma_f32_16x16x32_bf16 v[78:81], v[206:209], v[198:201], v[78:81]
	v_mfma_f32_16x16x32_bf16 v[110:113], v[210:213], v[186:189], v[110:113]
	v_mfma_f32_16x16x32_bf16 v[18:21], v[214:217], v[186:189], v[18:21]
	v_mfma_f32_16x16x32_bf16 v[178:181], v[210:213], v[190:193], v[178:181]
	v_mfma_f32_16x16x32_bf16 v[22:25], v[214:217], v[190:193], v[22:25]
	ds_read_b128 v[186:189], v174 offset:4096
	ds_read_b128 v[190:193], v174 offset:6144
	v_mfma_f32_16x16x32_bf16 v[26:29], v[214:217], v[194:197], v[26:29]
	v_mfma_f32_16x16x32_bf16 v[106:109], v[210:213], v[198:201], v[106:109]
	v_mfma_f32_16x16x32_bf16 v[30:33], v[214:217], v[198:201], v[30:33]
	v_mfma_f32_16x16x32_bf16 v[182:185], v[210:213], v[194:197], v[182:185]
	ds_read_b128 v[194:197], v174 offset:8192
	ds_read_b128 v[198:201], v174 offset:10240
	s_waitcnt lgkmcnt(0)
	v_mfma_f32_16x16x32_bf16 v[50:53], v[218:221], v[202:205], v[50:53]
	v_mfma_f32_16x16x32_bf16 v[54:57], v[222:225], v[202:205], v[54:57]
	v_mfma_f32_16x16x32_bf16 v[58:61], v[218:221], v[226:229], v[58:61]
	v_mfma_f32_16x16x32_bf16 v[62:65], v[222:225], v[226:229], v[62:65]
	v_mfma_f32_16x16x32_bf16 v[66:69], v[218:221], v[230:233], v[66:69]
	v_mfma_f32_16x16x32_bf16 v[70:73], v[222:225], v[230:233], v[70:73]
	v_mfma_f32_16x16x32_bf16 v[34:37], v[218:221], v[234:237], v[34:37]
	v_mfma_f32_16x16x32_bf16 v[38:41], v[222:225], v[234:237], v[38:41]
	v_mfma_f32_16x16x32_bf16 v[82:85], v[186:189], v[202:205], v[82:85]
	v_mfma_f32_16x16x32_bf16 v[90:93], v[186:189], v[226:229], v[90:93]
	v_mfma_f32_16x16x32_bf16 v[98:101], v[186:189], v[230:233], v[98:101]
	v_mfma_f32_16x16x32_bf16 v[42:45], v[186:189], v[234:237], v[42:45]
	ds_read_b128 v[186:189], v174 offset:12288
	ds_read_b128 v[206:209], v174 offset:14336
	v_mfma_f32_16x16x32_bf16 v[86:89], v[190:193], v[202:205], v[86:89]
	v_mfma_f32_16x16x32_bf16 v[94:97], v[190:193], v[226:229], v[94:97]
	v_mfma_f32_16x16x32_bf16 v[102:105], v[190:193], v[230:233], v[102:105]
	v_mfma_f32_16x16x32_bf16 v[46:49], v[190:193], v[234:237], v[46:49]
	v_mfma_f32_16x16x32_bf16 v[114:117], v[194:197], v[202:205], v[114:117]
	v_mfma_f32_16x16x32_bf16 v[118:121], v[198:201], v[202:205], v[118:121]
	v_mfma_f32_16x16x32_bf16 v[122:125], v[194:197], v[226:229], v[122:125]
	v_mfma_f32_16x16x32_bf16 v[126:129], v[198:201], v[226:229], v[126:129]
	v_mfma_f32_16x16x32_bf16 v[132:135], v[194:197], v[230:233], v[132:135]
	v_mfma_f32_16x16x32_bf16 v[136:139], v[198:201], v[230:233], v[136:139]
	v_mfma_f32_16x16x32_bf16 v[74:77], v[194:197], v[234:237], v[74:77]
	v_mfma_f32_16x16x32_bf16 v[78:81], v[198:201], v[234:237], v[78:81]
	s_mov_b32 m0, s13
	s_waitcnt vmcnt(0)
	s_barrier
; template <bool SWAP, class Epi, bool THIN = false> ...
;     ...
;     for (int st = 0; st < ns; ++st) {
;       asm volatile("s_waitcnt vmcnt(0)" ::: "memory");
;       __builtin_amdgcn_s_barrier();
;       asm volatile("" ::: "memory");
;       if (st + 1 < ns) {
;         char* nb = smem + ((st + 1) & 1) * 65536;
;         const int ko = (st + 1) * 64;
; #pragma unroll
;         for (int i = 0; i < 4; ++i) { GLDS16(A + (size_t)(ap[i] + ko), nb + tid * 16 + i * 8192); GLDS16(Bt + (size_t)(bp[i] + ko), nb + 32768 + tid * 16 + i * 8192); }
;       }
;       const char* sa = smem + (st & 1) * 65536 + (wr * 64 + fr) * 128;
;       const char* sb = smem + (st & 1) * 65536 + 32768 + (wc * 128 + fr) * 128;
;       if constexpr (THIN) {
;         if (wc == 0) {
; #pragma unroll
;           for (int ks = 0; ks < 2; ++ks) {
;             bf16x8 af[4], bf[2];
; #pragma unroll
;             for (int m = 0; m < 4; ++m) af[m] = *(const bf16x8*)(sa + m * 2048 + (((ks * 4 + fq) ^ swz) << 4));
; #pragma unroll
;             for (int n = 0; n < 2; ++n) bf[n] = *(const bf16x8*)(sb + n * 2048 + (((ks * 4 + fq) ^ swz) << 4));
; #pragma unroll
;             for (int m = 0; m < 4; ++m)
; #pragma unroll
;               for (int n = 0; n < 2; ++n)
;                 acc[m][n] = SWAP ? __builtin_amdgcn_mfma_f32_16x16x32_bf16(bf[n], af[m], acc[m][n], 0, 0, 0)
;                                  : __builtin_amdgcn_mfma_f32_16x16x32_bf16(af[m], bf[n], acc[m][n], 0, 0, 0);
;           }
;         }
;       } else {
;       bf16x8 afA[4], afB[4], bfb[2][2];
; #pragma unroll
;       for (int m = 0; m < 4; ++m) afA[m] = *(const bf16x8*)(sa + m * 2048 + ((fq ^ swz) << 4));
; #pragma unroll
;       for (int n = 0; n < 2; ++n) bfb[0][n] = *(const bf16x8*)(sb + n * 2048 + ((fq ^ swz) << 4));
; #pragma unroll
;       for (int gq = 0; gq < 8; ++gq) {
;         const int ks = gq >> 2, nh = gq & 3;
;         if (gq < 7) {
;           const int ks2 = (gq + 1) >> 2, nh2 = (gq + 1) & 3;
; #pragma unroll
;           for (int n = 0; n < 2; ++n) bfb[(gq + 1) & 1][n] = *(const bf16x8*)(sb + (nh2 * 2 + n) * 2048 + (((ks2 * 4 + fq) ^ swz) << 4));
;         }
;         if (gq == 3) {
; #pragma unroll
;           for (int m = 0; m < 4; ++m) afB[m] = *(const bf16x8*)(sa + m * 2048 + (((4 + fq) ^ swz) << 4));
;         }
;         __builtin_amdgcn_sched_barrier(0);
; #pragma unroll
	v_lshl_add_u64 v[190:191], v[2:3], 0, s[38:39]
	global_load_lds_dwordx4 v[190:191], off
	v_lshl_add_u64 v[190:191], v[4:5], 0, s[38:39]
	s_mov_b32 m0, s8
	s_waitcnt lgkmcnt(0)
	v_mfma_f32_16x16x32_bf16 v[110:113], v[186:189], v[202:205], v[110:113]
	global_load_lds_dwordx4 v[190:191], off
	v_lshl_add_u64 v[190:191], v[6:7], 0, s[38:39]
	s_mov_b32 m0, s7
	v_mfma_f32_16x16x32_bf16 v[18:21], v[206:209], v[202:205], v[18:21]
	global_load_lds_dwordx4 v[190:191], off
	v_lshl_add_u64 v[190:191], v[8:9], 0, s[38:39]
	s_mov_b32 m0, s6
	v_mfma_f32_16x16x32_bf16 v[178:181], v[186:189], v[226:229], v[178:181]
	global_load_lds_dwordx4 v[190:191], off
	v_lshl_add_u64 v[190:191], v[10:11], 0, s[38:39]
	s_mov_b32 m0, s9
	v_mfma_f32_16x16x32_bf16 v[182:185], v[186:189], v[230:233], v[182:185]
	global_load_lds_dwordx4 v[190:191], off
	v_lshl_add_u64 v[190:191], v[12:13], 0, s[38:39]
	s_mov_b32 m0, s10
	v_mfma_f32_16x16x32_bf16 v[106:109], v[186:189], v[234:237], v[106:109]
	global_load_lds_dwordx4 v[190:191], off
	v_lshl_add_u64 v[190:191], v[14:15], 0, s[38:39]
	s_mov_b32 m0, s11
	v_mfma_f32_16x16x32_bf16 v[22:25], v[206:209], v[226:229], v[22:25]
	global_load_lds_dwordx4 v[190:191], off
	v_lshl_add_u64 v[190:191], v[16:17], 0, s[38:39]
	s_mov_b32 m0, s12
	v_mfma_f32_16x16x32_bf16 v[26:29], v[206:209], v[230:233], v[26:29]
	global_load_lds_dwordx4 v[190:191], off
	ds_read_b128 v[186:189], v168
	ds_read_b128 v[190:193], v168 offset:2048
	ds_read_b128 v[194:197], v168 offset:4096
	ds_read_b128 v[198:201], v168 offset:6144
	ds_read_b128 v[202:205], v169 offset:32768
	ds_read_b128 v[210:213], v169 offset:34816
	ds_read_b128 v[214:217], v169 offset:36864
	ds_read_b128 v[218:221], v169 offset:38912
	v_mfma_f32_16x16x32_bf16 v[30:33], v[206:209], v[234:237], v[30:33]
	s_waitcnt lgkmcnt(0)
	v_mfma_f32_16x16x32_bf16 v[50:53], v[202:205], v[186:189], v[50:53]
	v_mfma_f32_16x16x32_bf16 v[58:61], v[202:205], v[190:193], v[58:61]
	v_mfma_f32_16x16x32_bf16 v[66:69], v[202:205], v[194:197], v[66:69]
	v_mfma_f32_16x16x32_bf16 v[34:37], v[202:205], v[198:201], v[34:37]
	ds_read_b128 v[202:205], v169 offset:40960
	ds_read_b128 v[206:209], v169 offset:43008
	v_mfma_f32_16x16x32_bf16 v[54:57], v[210:213], v[186:189], v[54:57]
	v_mfma_f32_16x16x32_bf16 v[62:65], v[210:213], v[190:193], v[62:65]
	v_mfma_f32_16x16x32_bf16 v[70:73], v[210:213], v[194:197], v[70:73]
	v_mfma_f32_16x16x32_bf16 v[38:41], v[210:213], v[198:201], v[38:41]
	v_mfma_f32_16x16x32_bf16 v[82:85], v[214:217], v[186:189], v[82:85]
	v_mfma_f32_16x16x32_bf16 v[90:93], v[214:217], v[190:193], v[90:93]
	v_mfma_f32_16x16x32_bf16 v[98:101], v[214:217], v[194:197], v[98:101]
	v_mfma_f32_16x16x32_bf16 v[42:45], v[214:217], v[198:201], v[42:45]
	ds_read_b128 v[210:213], v169 offset:45056
	ds_read_b128 v[214:217], v169 offset:47104
	v_mfma_f32_16x16x32_bf16 v[86:89], v[218:221], v[186:189], v[86:89]
	v_mfma_f32_16x16x32_bf16 v[94:97], v[218:221], v[190:193], v[94:97]
	v_mfma_f32_16x16x32_bf16 v[102:105], v[218:221], v[194:197], v[102:105]
	v_mfma_f32_16x16x32_bf16 v[46:49], v[218:221], v[198:201], v[46:49]
	s_waitcnt lgkmcnt(0)
	v_mfma_f32_16x16x32_bf16 v[114:117], v[202:205], v[186:189], v[114:117]
	ds_read_b128 v[218:221], v170 offset:32768
	ds_read_b128 v[222:225], v170 offset:34816
	v_mfma_f32_16x16x32_bf16 v[122:125], v[202:205], v[190:193], v[122:125]
	v_mfma_f32_16x16x32_bf16 v[132:135], v[202:205], v[194:197], v[132:135]
	v_mfma_f32_16x16x32_bf16 v[74:77], v[202:205], v[198:201], v[74:77]
	ds_read_b128 v[202:205], v171
	ds_read_b128 v[226:229], v171 offset:2048
	ds_read_b128 v[230:233], v171 offset:4096
	ds_read_b128 v[234:237], v171 offset:6144
	v_mfma_f32_16x16x32_bf16 v[118:121], v[206:209], v[186:189], v[118:121]
	v_mfma_f32_16x16x32_bf16 v[126:129], v[206:209], v[190:193], v[126:129]
	v_mfma_f32_16x16x32_bf16 v[136:139], v[206:209], v[194:197], v[136:139]
	v_mfma_f32_16x16x32_bf16 v[78:81], v[206:209], v[198:201], v[78:81]
	v_mfma_f32_16x16x32_bf16 v[110:113], v[210:213], v[186:189], v[110:113]
	v_mfma_f32_16x16x32_bf16 v[18:21], v[214:217], v[186:189], v[18:21]
	v_mfma_f32_16x16x32_bf16 v[178:181], v[210:213], v[190:193], v[178:181]
	v_mfma_f32_16x16x32_bf16 v[22:25], v[214:217], v[190:193], v[22:25]
	ds_read_b128 v[186:189], v170 offset:36864
	ds_read_b128 v[190:193], v170 offset:38912
	v_mfma_f32_16x16x32_bf16 v[26:29], v[214:217], v[194:197], v[26:29]
	v_mfma_f32_16x16x32_bf16 v[106:109], v[210:213], v[198:201], v[106:109]
	v_mfma_f32_16x16x32_bf16 v[30:33], v[214:217], v[198:201], v[30:33]
	v_mfma_f32_16x16x32_bf16 v[182:185], v[210:213], v[194:197], v[182:185]
	ds_read_b128 v[194:197], v170 offset:40960
	ds_read_b128 v[198:201], v170 offset:43008
	s_waitcnt lgkmcnt(0)
	v_mfma_f32_16x16x32_bf16 v[50:53], v[218:221], v[202:205], v[50:53]
	v_mfma_f32_16x16x32_bf16 v[54:57], v[222:225], v[202:205], v[54:57]
	v_mfma_f32_16x16x32_bf16 v[58:61], v[218:221], v[226:229], v[58:61]
	v_mfma_f32_16x16x32_bf16 v[62:65], v[222:225], v[226:229], v[62:65]
	v_mfma_f32_16x16x32_bf16 v[66:69], v[218:221], v[230:233], v[66:69]
	v_mfma_f32_16x16x32_bf16 v[70:73], v[222:225], v[230:233], v[70:73]
	v_mfma_f32_16x16x32_bf16 v[34:37], v[218:221], v[234:237], v[34:37]
	v_mfma_f32_16x16x32_bf16 v[38:41], v[222:225], v[234:237], v[38:41]
	v_mfma_f32_16x16x32_bf16 v[82:85], v[186:189], v[202:205], v[82:85]
	v_mfma_f32_16x16x32_bf16 v[90:93], v[186:189], v[226:229], v[90:93]
	v_mfma_f32_16x16x32_bf16 v[98:101], v[186:189], v[230:233], v[98:101]
	v_mfma_f32_16x16x32_bf16 v[42:45], v[186:189], v[234:237], v[42:45]
	ds_read_b128 v[186:189], v170 offset:45056
	ds_read_b128 v[206:209], v170 offset:47104
	v_mfma_f32_16x16x32_bf16 v[86:89], v[190:193], v[202:205], v[86:89]
	v_mfma_f32_16x16x32_bf16 v[94:97], v[190:193], v[226:229], v[94:97]
	v_mfma_f32_16x16x32_bf16 v[102:105], v[190:193], v[230:233], v[102:105]
	v_mfma_f32_16x16x32_bf16 v[46:49], v[190:193], v[234:237], v[46:49]
	v_mfma_f32_16x16x32_bf16 v[114:117], v[194:197], v[202:205], v[114:117]
	v_mfma_f32_16x16x32_bf16 v[118:121], v[198:201], v[202:205], v[118:121]
	v_mfma_f32_16x16x32_bf16 v[122:125], v[194:197], v[226:229], v[122:125]
	v_mfma_f32_16x16x32_bf16 v[126:129], v[198:201], v[226:229], v[126:129]
	v_mfma_f32_16x16x32_bf16 v[132:135], v[194:197], v[230:233], v[132:135]
	v_mfma_f32_16x16x32_bf16 v[136:139], v[198:201], v[230:233], v[136:139]
	v_mfma_f32_16x16x32_bf16 v[74:77], v[194:197], v[234:237], v[74:77]
	v_mfma_f32_16x16x32_bf16 v[78:81], v[198:201], v[234:237], v[78:81]
	v_readfirstlane_b32 s6, v142
	s_waitcnt vmcnt(0)
	s_barrier
; template <bool SWAP, class Epi, bool THIN = false> ...
;     ...
;     for (int st = 0; st < ns; ++st) {
;       asm volatile("s_waitcnt vmcnt(0)" ::: "memory");
;       __builtin_amdgcn_s_barrier();
;       asm volatile("" ::: "memory");
;       if (st + 1 < ns) {
;         char* nb = smem + ((st + 1) & 1) * 65536;
;         const int ko = (st + 1) * 64;
; #pragma unroll
;         for (int i = 0; i < 4; ++i) { GLDS16(A + (size_t)(ap[i] + ko), nb + tid * 16 + i * 8192); GLDS16(Bt + (size_t)(bp[i] + ko), nb + 32768 + tid * 16 + i * 8192); }
;       }
;       const char* sa = smem + (st & 1) * 65536 + (wr * 64 + fr) * 128;
;       const char* sb = smem + (st & 1) * 65536 + 32768 + (wc * 128 + fr) * 128;
;       if constexpr (THIN) {
;         if (wc == 0) {
; #pragma unroll
;           for (int ks = 0; ks < 2; ++ks) {
;             bf16x8 af[4], bf[2];
; #pragma unroll
;             for (int m = 0; m < 4; ++m) af[m] = *(const bf16x8*)(sa + m * 2048 + (((ks * 4 + fq) ^ swz) << 4));
; #pragma unroll
;             for (int n = 0; n < 2; ++n) bf[n] = *(const bf16x8*)(sb + n * 2048 + (((ks * 4 + fq) ^ swz) << 4));
; #pragma unroll
;             for (int m = 0; m < 4; ++m)
; #pragma unroll
;               for (int n = 0; n < 2; ++n)
;                 acc[m][n] = SWAP ? __builtin_amdgcn_mfma_f32_16x16x32_bf16(bf[n], af[m], acc[m][n], 0, 0, 0)
;                                  : __builtin_amdgcn_mfma_f32_16x16x32_bf16(af[m], bf[n], acc[m][n], 0, 0, 0);
;           }
;         }
;       } else {
;       bf16x8 afA[4], afB[4], bfb[2][2];
; #pragma unroll
;       for (int m = 0; m < 4; ++m) afA[m] = *(const bf16x8*)(sa + m * 2048 + ((fq ^ swz) << 4));
; #pragma unroll
;       for (int n = 0; n < 2; ++n) bfb[0][n] = *(const bf16x8*)(sb + n * 2048 + ((fq ^ swz) << 4));
; #pragma unroll
;       for (int gq = 0; gq < 8; ++gq) {
;         const int ks = gq >> 2, nh = gq & 3;
;         if (gq < 7) {
;           const int ks2 = (gq + 1) >> 2, nh2 = (gq + 1) & 3;
; #pragma unroll
;           for (int n = 0; n < 2; ++n) bfb[(gq + 1) & 1][n] = *(const bf16x8*)(sb + (nh2 * 2 + n) * 2048 + (((ks2 * 4 + fq) ^ swz) << 4));
;         }
;         if (gq == 3) {
; #pragma unroll
;           for (int m = 0; m < 4; ++m) afB[m] = *(const bf16x8*)(sa + m * 2048 + (((4 + fq) ^ swz) << 4));
;         }
;         __builtin_amdgcn_sched_barrier(0);
; #pragma unroll
	v_lshl_add_u64 v[190:191], v[2:3], 0, s[40:41]
	s_mov_b32 m0, s6
	v_readfirstlane_b32 s6, v153
	global_load_lds_dwordx4 v[190:191], off
	v_lshl_add_u64 v[190:191], v[4:5], 0, s[40:41]
	s_mov_b32 m0, s6
	v_readfirstlane_b32 s6, v154
	global_load_lds_dwordx4 v[190:191], off
	v_lshl_add_u64 v[190:191], v[6:7], 0, s[40:41]
	s_mov_b32 m0, s6
	v_readfirstlane_b32 s6, v155
	global_load_lds_dwordx4 v[190:191], off
	v_lshl_add_u64 v[190:191], v[8:9], 0, s[40:41]
	s_mov_b32 m0, s6
	v_readfirstlane_b32 s6, v156
	global_load_lds_dwordx4 v[190:191], off
	v_lshl_add_u64 v[190:191], v[10:11], 0, s[40:41]
	s_mov_b32 m0, s6
	v_readfirstlane_b32 s6, v157
	global_load_lds_dwordx4 v[190:191], off
	v_lshl_add_u64 v[190:191], v[12:13], 0, s[40:41]
	s_mov_b32 m0, s6
	v_readfirstlane_b32 s6, v158
	global_load_lds_dwordx4 v[190:191], off
	v_lshl_add_u64 v[190:191], v[14:15], 0, s[40:41]
	s_mov_b32 m0, s6
	v_readfirstlane_b32 s6, v159
	global_load_lds_dwordx4 v[190:191], off
	v_lshl_add_u64 v[190:191], v[16:17], 0, s[40:41]
	s_mov_b32 m0, s6
	s_waitcnt lgkmcnt(0)
	v_mfma_f32_16x16x32_bf16 v[110:113], v[186:189], v[202:205], v[110:113]
	global_load_lds_dwordx4 v[190:191], off
	v_mfma_f32_16x16x32_bf16 v[18:21], v[206:209], v[202:205], v[18:21]
	v_mfma_f32_16x16x32_bf16 v[178:181], v[186:189], v[226:229], v[178:181]
	v_mfma_f32_16x16x32_bf16 v[182:185], v[186:189], v[230:233], v[182:185]
	v_mfma_f32_16x16x32_bf16 v[106:109], v[186:189], v[234:237], v[106:109]
	ds_read_b128 v[186:189], v172
	ds_read_b128 v[190:193], v172 offset:2048
	ds_read_b128 v[194:197], v172 offset:4096
	ds_read_b128 v[198:201], v172 offset:6144
	ds_read_b128 v[202:205], v173
	ds_read_b128 v[210:213], v173 offset:2048
	ds_read_b128 v[214:217], v173 offset:4096
	ds_read_b128 v[218:221], v173 offset:6144
	v_mfma_f32_16x16x32_bf16 v[22:25], v[206:209], v[226:229], v[22:25]
	v_mfma_f32_16x16x32_bf16 v[26:29], v[206:209], v[230:233], v[26:29]
	v_mfma_f32_16x16x32_bf16 v[30:33], v[206:209], v[234:237], v[30:33]
	s_waitcnt lgkmcnt(0)
	v_mfma_f32_16x16x32_bf16 v[50:53], v[202:205], v[186:189], v[50:53]
	v_mfma_f32_16x16x32_bf16 v[58:61], v[202:205], v[190:193], v[58:61]
	v_mfma_f32_16x16x32_bf16 v[66:69], v[202:205], v[194:197], v[66:69]
	v_mfma_f32_16x16x32_bf16 v[34:37], v[202:205], v[198:201], v[34:37]
	ds_read_b128 v[202:205], v173 offset:8192
	ds_read_b128 v[206:209], v173 offset:10240
	v_mfma_f32_16x16x32_bf16 v[54:57], v[210:213], v[186:189], v[54:57]
	v_mfma_f32_16x16x32_bf16 v[62:65], v[210:213], v[190:193], v[62:65]
	v_mfma_f32_16x16x32_bf16 v[70:73], v[210:213], v[194:197], v[70:73]
	v_mfma_f32_16x16x32_bf16 v[38:41], v[210:213], v[198:201], v[38:41]
	v_mfma_f32_16x16x32_bf16 v[82:85], v[214:217], v[186:189], v[82:85]
	v_mfma_f32_16x16x32_bf16 v[90:93], v[214:217], v[190:193], v[90:93]
	v_mfma_f32_16x16x32_bf16 v[98:101], v[214:217], v[194:197], v[98:101]
	v_mfma_f32_16x16x32_bf16 v[42:45], v[214:217], v[198:201], v[42:45]
	ds_read_b128 v[210:213], v173 offset:12288
	ds_read_b128 v[214:217], v173 offset:14336
	v_mfma_f32_16x16x32_bf16 v[86:89], v[218:221], v[186:189], v[86:89]
	v_mfma_f32_16x16x32_bf16 v[94:97], v[218:221], v[190:193], v[94:97]
	v_mfma_f32_16x16x32_bf16 v[102:105], v[218:221], v[194:197], v[102:105]
	v_mfma_f32_16x16x32_bf16 v[46:49], v[218:221], v[198:201], v[46:49]
	s_waitcnt lgkmcnt(0)
	v_mfma_f32_16x16x32_bf16 v[114:117], v[202:205], v[186:189], v[114:117]
	ds_read_b128 v[218:221], v174
	ds_read_b128 v[222:225], v174 offset:2048
	v_mfma_f32_16x16x32_bf16 v[122:125], v[202:205], v[190:193], v[122:125]
	v_mfma_f32_16x16x32_bf16 v[132:135], v[202:205], v[194:197], v[132:135]
	v_mfma_f32_16x16x32_bf16 v[74:77], v[202:205], v[198:201], v[74:77]
	ds_read_b128 v[202:205], v175
	ds_read_b128 v[226:229], v175 offset:2048
	ds_read_b128 v[230:233], v175 offset:4096
	ds_read_b128 v[234:237], v175 offset:6144
	v_mfma_f32_16x16x32_bf16 v[118:121], v[206:209], v[186:189], v[118:121]
	v_mfma_f32_16x16x32_bf16 v[126:129], v[206:209], v[190:193], v[126:129]
	v_mfma_f32_16x16x32_bf16 v[136:139], v[206:209], v[194:197], v[136:139]
	v_mfma_f32_16x16x32_bf16 v[78:81], v[206:209], v[198:201], v[78:81]
	v_mfma_f32_16x16x32_bf16 v[110:113], v[210:213], v[186:189], v[110:113]
	v_mfma_f32_16x16x32_bf16 v[18:21], v[214:217], v[186:189], v[18:21]
	v_mfma_f32_16x16x32_bf16 v[178:181], v[210:213], v[190:193], v[178:181]
	v_mfma_f32_16x16x32_bf16 v[22:25], v[214:217], v[190:193], v[22:25]
	ds_read_b128 v[186:189], v174 offset:4096
	ds_read_b128 v[190:193], v174 offset:6144
	v_mfma_f32_16x16x32_bf16 v[26:29], v[214:217], v[194:197], v[26:29]
	v_mfma_f32_16x16x32_bf16 v[106:109], v[210:213], v[198:201], v[106:109]
	v_mfma_f32_16x16x32_bf16 v[30:33], v[214:217], v[198:201], v[30:33]
	v_mfma_f32_16x16x32_bf16 v[182:185], v[210:213], v[194:197], v[182:185]
	ds_read_b128 v[194:197], v174 offset:8192
	ds_read_b128 v[198:201], v174 offset:10240
	s_waitcnt lgkmcnt(0)
	v_mfma_f32_16x16x32_bf16 v[50:53], v[218:221], v[202:205], v[50:53]
	v_mfma_f32_16x16x32_bf16 v[54:57], v[222:225], v[202:205], v[54:57]
	v_mfma_f32_16x16x32_bf16 v[58:61], v[218:221], v[226:229], v[58:61]
	v_mfma_f32_16x16x32_bf16 v[62:65], v[222:225], v[226:229], v[62:65]
	v_mfma_f32_16x16x32_bf16 v[66:69], v[218:221], v[230:233], v[66:69]
	v_mfma_f32_16x16x32_bf16 v[70:73], v[222:225], v[230:233], v[70:73]
	v_mfma_f32_16x16x32_bf16 v[34:37], v[218:221], v[234:237], v[34:37]
	v_mfma_f32_16x16x32_bf16 v[38:41], v[222:225], v[234:237], v[38:41]
	v_mfma_f32_16x16x32_bf16 v[82:85], v[186:189], v[202:205], v[82:85]
	v_mfma_f32_16x16x32_bf16 v[90:93], v[186:189], v[226:229], v[90:93]
	v_mfma_f32_16x16x32_bf16 v[98:101], v[186:189], v[230:233], v[98:101]
	v_mfma_f32_16x16x32_bf16 v[42:45], v[186:189], v[234:237], v[42:45]
	ds_read_b128 v[186:189], v174 offset:12288
	ds_read_b128 v[206:209], v174 offset:14336
	v_mfma_f32_16x16x32_bf16 v[86:89], v[190:193], v[202:205], v[86:89]
	v_mfma_f32_16x16x32_bf16 v[94:97], v[190:193], v[226:229], v[94:97]
	v_mfma_f32_16x16x32_bf16 v[102:105], v[190:193], v[230:233], v[102:105]
	v_mfma_f32_16x16x32_bf16 v[46:49], v[190:193], v[234:237], v[46:49]
	v_mfma_f32_16x16x32_bf16 v[114:117], v[194:197], v[202:205], v[114:117]
	v_mfma_f32_16x16x32_bf16 v[118:121], v[198:201], v[202:205], v[118:121]
	v_mfma_f32_16x16x32_bf16 v[122:125], v[194:197], v[226:229], v[122:125]
	v_mfma_f32_16x16x32_bf16 v[126:129], v[198:201], v[226:229], v[126:129]
	v_mfma_f32_16x16x32_bf16 v[132:135], v[194:197], v[230:233], v[132:135]
	v_mfma_f32_16x16x32_bf16 v[136:139], v[198:201], v[230:233], v[136:139]
	v_mfma_f32_16x16x32_bf16 v[74:77], v[194:197], v[234:237], v[74:77]
	v_mfma_f32_16x16x32_bf16 v[78:81], v[198:201], v[234:237], v[78:81]
	v_readfirstlane_b32 s6, v160
	s_waitcnt vmcnt(0)
	s_barrier
; template <bool SWAP, class Epi, bool THIN = false> ...
;     ...
;     for (int st = 0; st < ns; ++st) {
;       asm volatile("s_waitcnt vmcnt(0)" ::: "memory");
;       __builtin_amdgcn_s_barrier();
;       asm volatile("" ::: "memory");
;       if (st + 1 < ns) {
;         char* nb = smem + ((st + 1) & 1) * 65536;
;         const int ko = (st + 1) * 64;
; #pragma unroll
;         for (int i = 0; i < 4; ++i) { GLDS16(A + (size_t)(ap[i] + ko), nb + tid * 16 + i * 8192); GLDS16(Bt + (size_t)(bp[i] + ko), nb + 32768 + tid * 16 + i * 8192); }
;       }
;       const char* sa = smem + (st & 1) * 65536 + (wr * 64 + fr) * 128;
;       const char* sb = smem + (st & 1) * 65536 + 32768 + (wc * 128 + fr) * 128;
;       if constexpr (THIN) {
;         if (wc == 0) {
; #pragma unroll
;           for (int ks = 0; ks < 2; ++ks) {
;             bf16x8 af[4], bf[2];
; #pragma unroll
;             for (int m = 0; m < 4; ++m) af[m] = *(const bf16x8*)(sa + m * 2048 + (((ks * 4 + fq) ^ swz) << 4));
; #pragma unroll
;             for (int n = 0; n < 2; ++n) bf[n] = *(const bf16x8*)(sb + n * 2048 + (((ks * 4 + fq) ^ swz) << 4));
; #pragma unroll
;             for (int m = 0; m < 4; ++m)
; #pragma unroll
;               for (int n = 0; n < 2; ++n)
;                 acc[m][n] = SWAP ? __builtin_amdgcn_mfma_f32_16x16x32_bf16(bf[n], af[m], acc[m][n], 0, 0, 0)
;                                  : __builtin_amdgcn_mfma_f32_16x16x32_bf16(af[m], bf[n], acc[m][n], 0, 0, 0);
;           }
;         }
;       } else {
;       bf16x8 afA[4], afB[4], bfb[2][2];
; #pragma unroll
;       for (int m = 0; m < 4; ++m) afA[m] = *(const bf16x8*)(sa + m * 2048 + ((fq ^ swz) << 4));
; #pragma unroll
;       for (int n = 0; n < 2; ++n) bfb[0][n] = *(const bf16x8*)(sb + n * 2048 + ((fq ^ swz) << 4));
; #pragma unroll
;       for (int gq = 0; gq < 8; ++gq) {
;         const int ks = gq >> 2, nh = gq & 3;
;         if (gq < 7) {
;           const int ks2 = (gq + 1) >> 2, nh2 = (gq + 1) & 3;
; #pragma unroll
;           for (int n = 0; n < 2; ++n) bfb[(gq + 1) & 1][n] = *(const bf16x8*)(sb + (nh2 * 2 + n) * 2048 + (((ks2 * 4 + fq) ^ swz) << 4));
;         }
;         if (gq == 3) {
; #pragma unroll
;           for (int m = 0; m < 4; ++m) afB[m] = *(const bf16x8*)(sa + m * 2048 + (((4 + fq) ^ swz) << 4));
;         }
;         __builtin_amdgcn_sched_barrier(0);
; #pragma unroll
	v_lshl_add_u64 v[2:3], v[2:3], 0, s[42:43]
	s_mov_b32 m0, s6
	v_readfirstlane_b32 s6, v161
	global_load_lds_dwordx4 v[2:3], off
	v_lshl_add_u64 v[190:191], v[4:5], 0, s[42:43]
	s_mov_b32 m0, s6
	v_readfirstlane_b32 s6, v162
	global_load_lds_dwordx4 v[190:191], off
	v_lshl_add_u64 v[6:7], v[6:7], 0, s[42:43]
	s_mov_b32 m0, s6
	v_readfirstlane_b32 s6, v163
	global_load_lds_dwordx4 v[6:7], off
	v_lshl_add_u64 v[6:7], v[8:9], 0, s[42:43]
	s_mov_b32 m0, s6
	v_readfirstlane_b32 s6, v164
	global_load_lds_dwordx4 v[6:7], off
	v_lshl_add_u64 v[6:7], v[10:11], 0, s[42:43]
	s_mov_b32 m0, s6
	v_readfirstlane_b32 s6, v165
	global_load_lds_dwordx4 v[6:7], off
	v_lshl_add_u64 v[6:7], v[12:13], 0, s[42:43]
	s_mov_b32 m0, s6
	v_readfirstlane_b32 s6, v166
	global_load_lds_dwordx4 v[6:7], off
	v_lshl_add_u64 v[6:7], v[14:15], 0, s[42:43]
	s_mov_b32 m0, s6
	v_readfirstlane_b32 s6, v167
	global_load_lds_dwordx4 v[6:7], off
	v_lshl_add_u64 v[6:7], v[16:17], 0, s[42:43]
	s_mov_b32 m0, s6
	s_waitcnt lgkmcnt(0)
	v_mfma_f32_16x16x32_bf16 v[110:113], v[186:189], v[202:205], v[110:113]
	global_load_lds_dwordx4 v[6:7], off
	v_mfma_f32_16x16x32_bf16 v[178:181], v[186:189], v[226:229], v[178:181]
	v_mfma_f32_16x16x32_bf16 v[2:5], v[186:189], v[230:233], v[182:185]
	v_mfma_f32_16x16x32_bf16 v[6:9], v[186:189], v[234:237], v[106:109]
	ds_read_b128 v[10:13], v168
	ds_read_b128 v[14:17], v168 offset:2048
	s_nop 0
	ds_read_b128 v[106:109], v168 offset:4096
	ds_read_b128 v[182:185], v168 offset:6144
	ds_read_b128 v[186:189], v169 offset:32768
	ds_read_b128 v[190:193], v169 offset:34816
	ds_read_b128 v[194:197], v169 offset:36864
	ds_read_b128 v[198:201], v169 offset:38912
	v_mfma_f32_16x16x32_bf16 v[18:21], v[206:209], v[202:205], v[18:21]
	v_mfma_f32_16x16x32_bf16 v[22:25], v[206:209], v[226:229], v[22:25]
	v_mfma_f32_16x16x32_bf16 v[26:29], v[206:209], v[230:233], v[26:29]
	v_mfma_f32_16x16x32_bf16 v[30:33], v[206:209], v[234:237], v[30:33]
	s_waitcnt lgkmcnt(0)
	v_mfma_f32_16x16x32_bf16 v[50:53], v[186:189], v[10:13], v[50:53]
	v_mfma_f32_16x16x32_bf16 v[58:61], v[186:189], v[14:17], v[58:61]
	v_mfma_f32_16x16x32_bf16 v[66:69], v[186:189], v[106:109], v[66:69]
	v_mfma_f32_16x16x32_bf16 v[34:37], v[186:189], v[182:185], v[34:37]
	ds_read_b128 v[186:189], v169 offset:40960
	ds_read_b128 v[202:205], v169 offset:43008
	v_mfma_f32_16x16x32_bf16 v[54:57], v[190:193], v[10:13], v[54:57]
	v_mfma_f32_16x16x32_bf16 v[62:65], v[190:193], v[14:17], v[62:65]
	v_mfma_f32_16x16x32_bf16 v[70:73], v[190:193], v[106:109], v[70:73]
	v_mfma_f32_16x16x32_bf16 v[38:41], v[190:193], v[182:185], v[38:41]
	v_mfma_f32_16x16x32_bf16 v[82:85], v[194:197], v[10:13], v[82:85]
	v_mfma_f32_16x16x32_bf16 v[90:93], v[194:197], v[14:17], v[90:93]
	v_mfma_f32_16x16x32_bf16 v[98:101], v[194:197], v[106:109], v[98:101]
	v_mfma_f32_16x16x32_bf16 v[42:45], v[194:197], v[182:185], v[42:45]
	ds_read_b128 v[190:193], v169 offset:45056
	ds_read_b128 v[194:197], v169 offset:47104
	v_mfma_f32_16x16x32_bf16 v[86:89], v[198:201], v[10:13], v[86:89]
	v_mfma_f32_16x16x32_bf16 v[94:97], v[198:201], v[14:17], v[94:97]
	v_mfma_f32_16x16x32_bf16 v[102:105], v[198:201], v[106:109], v[102:105]
	v_mfma_f32_16x16x32_bf16 v[46:49], v[198:201], v[182:185], v[46:49]
	s_waitcnt lgkmcnt(0)
	v_mfma_f32_16x16x32_bf16 v[114:117], v[186:189], v[10:13], v[114:117]
	ds_read_b128 v[198:201], v170 offset:32768
	ds_read_b128 v[206:209], v170 offset:34816
	v_mfma_f32_16x16x32_bf16 v[122:125], v[186:189], v[14:17], v[122:125]
	v_mfma_f32_16x16x32_bf16 v[132:135], v[186:189], v[106:109], v[132:135]
	v_mfma_f32_16x16x32_bf16 v[74:77], v[186:189], v[182:185], v[74:77]
	ds_read_b128 v[186:189], v171
	ds_read_b128 v[210:213], v171 offset:2048
	ds_read_b128 v[214:217], v171 offset:4096
	ds_read_b128 v[218:221], v171 offset:6144
	v_mfma_f32_16x16x32_bf16 v[118:121], v[202:205], v[10:13], v[118:121]
	v_mfma_f32_16x16x32_bf16 v[126:129], v[202:205], v[14:17], v[126:129]
	v_mfma_f32_16x16x32_bf16 v[136:139], v[202:205], v[106:109], v[136:139]
	v_mfma_f32_16x16x32_bf16 v[78:81], v[202:205], v[182:185], v[78:81]
	v_mfma_f32_16x16x32_bf16 v[110:113], v[190:193], v[10:13], v[110:113]
	v_mfma_f32_16x16x32_bf16 v[10:13], v[194:197], v[10:13], v[18:21]
	v_mfma_f32_16x16x32_bf16 v[18:21], v[190:193], v[14:17], v[178:181]
	v_mfma_f32_16x16x32_bf16 v[14:17], v[194:197], v[14:17], v[22:25]
	v_mfma_f32_16x16x32_bf16 v[2:5], v[190:193], v[106:109], v[2:5]
	v_mfma_f32_16x16x32_bf16 v[22:25], v[194:197], v[106:109], v[26:29]
	s_nop 2
	ds_read_b128 v[26:29], v170 offset:36864
	ds_read_b128 v[106:109], v170 offset:38912
	v_mfma_f32_16x16x32_bf16 v[6:9], v[190:193], v[182:185], v[6:9]
	v_mfma_f32_16x16x32_bf16 v[30:33], v[194:197], v[182:185], v[30:33]
	ds_read_b128 v[178:181], v170 offset:40960
	ds_read_b128 v[182:185], v170 offset:43008
	s_waitcnt lgkmcnt(0)
	v_mfma_f32_16x16x32_bf16 v[50:53], v[198:201], v[186:189], v[50:53]
	v_mfma_f32_16x16x32_bf16 v[54:57], v[206:209], v[186:189], v[54:57]
	v_mfma_f32_16x16x32_bf16 v[58:61], v[198:201], v[210:213], v[58:61]
	v_mfma_f32_16x16x32_bf16 v[62:65], v[206:209], v[210:213], v[62:65]
	v_mfma_f32_16x16x32_bf16 v[66:69], v[198:201], v[214:217], v[66:69]
	v_mfma_f32_16x16x32_bf16 v[70:73], v[206:209], v[214:217], v[70:73]
	v_mfma_f32_16x16x32_bf16 v[34:37], v[198:201], v[218:221], v[34:37]
	v_mfma_f32_16x16x32_bf16 v[38:41], v[206:209], v[218:221], v[38:41]
	v_mfma_f32_16x16x32_bf16 v[82:85], v[26:29], v[186:189], v[82:85]
	v_mfma_f32_16x16x32_bf16 v[90:93], v[26:29], v[210:213], v[90:93]
	v_mfma_f32_16x16x32_bf16 v[98:101], v[26:29], v[214:217], v[98:101]
	v_mfma_f32_16x16x32_bf16 v[26:29], v[26:29], v[218:221], v[42:45]
	s_nop 2
	ds_read_b128 v[42:45], v170 offset:45056
	ds_read_b128 v[190:193], v170 offset:47104
	v_mfma_f32_16x16x32_bf16 v[86:89], v[106:109], v[186:189], v[86:89]
	v_mfma_f32_16x16x32_bf16 v[94:97], v[106:109], v[210:213], v[94:97]
	v_mfma_f32_16x16x32_bf16 v[102:105], v[106:109], v[214:217], v[102:105]
	v_mfma_f32_16x16x32_bf16 v[46:49], v[106:109], v[218:221], v[46:49]
	v_mfma_f32_16x16x32_bf16 v[106:109], v[178:181], v[186:189], v[114:117]
	v_mfma_f32_16x16x32_bf16 v[114:117], v[182:185], v[186:189], v[118:121]
	v_mfma_f32_16x16x32_bf16 v[118:121], v[178:181], v[210:213], v[122:125]
	v_mfma_f32_16x16x32_bf16 v[122:125], v[182:185], v[210:213], v[126:129]
	v_mfma_f32_16x16x32_bf16 v[126:129], v[178:181], v[214:217], v[132:135]
	v_mfma_f32_16x16x32_bf16 v[132:135], v[182:185], v[214:217], v[136:139]
	v_mfma_f32_16x16x32_bf16 v[74:77], v[178:181], v[218:221], v[74:77]
	v_mfma_f32_16x16x32_bf16 v[78:81], v[182:185], v[218:221], v[78:81]
	s_waitcnt vmcnt(0)
	s_barrier
; template <bool SWAP, class Epi, bool THIN = false> ...
;     ...
;     for (int st = 0; st < ns; ++st) {
;       asm volatile("s_waitcnt vmcnt(0)" ::: "memory");
;       __builtin_amdgcn_s_barrier();
;       asm volatile("" ::: "memory");
;       if (st + 1 < ns) {
;         char* nb = smem + ((st + 1) & 1) * 65536;
;         const int ko = (st + 1) * 64;
; #pragma unroll
;         for (int i = 0; i < 4; ++i) { GLDS16(A + (size_t)(ap[i] + ko), nb + tid * 16 + i * 8192); GLDS16(Bt + (size_t)(bp[i] + ko), nb + 32768 + tid * 16 + i * 8192); }
;       }
;       const char* sa = smem + (st & 1) * 65536 + (wr * 64 + fr) * 128;
;       const char* sb = smem + (st & 1) * 65536 + 32768 + (wc * 128 + fr) * 128;
;       if constexpr (THIN) {
;         if (wc == 0) {
; #pragma unroll
;           for (int ks = 0; ks < 2; ++ks) {
;             bf16x8 af[4], bf[2];
; #pragma unroll
;             for (int m = 0; m < 4; ++m) af[m] = *(const bf16x8*)(sa + m * 2048 + (((ks * 4 + fq) ^ swz) << 4));
; #pragma unroll
;             for (int n = 0; n < 2; ++n) bf[n] = *(const bf16x8*)(sb + n * 2048 + (((ks * 4 + fq) ^ swz) << 4));
; #pragma unroll
;             for (int m = 0; m < 4; ++m)
; #pragma unroll
;               for (int n = 0; n < 2; ++n)
;                 acc[m][n] = SWAP ? __builtin_amdgcn_mfma_f32_16x16x32_bf16(bf[n], af[m], acc[m][n], 0, 0, 0)
;                                  : __builtin_amdgcn_mfma_f32_16x16x32_bf16(af[m], bf[n], acc[m][n], 0, 0, 0);
;           }
;         }
;       } else {
;       bf16x8 afA[4], afB[4], bfb[2][2];
; #pragma unroll
;       for (int m = 0; m < 4; ++m) afA[m] = *(const bf16x8*)(sa + m * 2048 + ((fq ^ swz) << 4));
; #pragma unroll
;       for (int n = 0; n < 2; ++n) bfb[0][n] = *(const bf16x8*)(sb + n * 2048 + ((fq ^ swz) << 4));
; #pragma unroll
;       for (int gq = 0; gq < 8; ++gq) {
;         const int ks = gq >> 2, nh = gq & 3;
;         if (gq < 7) {
;           const int ks2 = (gq + 1) >> 2, nh2 = (gq + 1) & 3;
; #pragma unroll
;           for (int n = 0; n < 2; ++n) bfb[(gq + 1) & 1][n] = *(const bf16x8*)(sb + (nh2 * 2 + n) * 2048 + (((ks2 * 4 + fq) ^ swz) << 4));
;         }
;         if (gq == 3) {
; #pragma unroll
;           for (int m = 0; m < 4; ++m) afB[m] = *(const bf16x8*)(sa + m * 2048 + (((4 + fq) ^ swz) << 4));
;         }
;         __builtin_amdgcn_sched_barrier(0);
; #pragma unroll
	s_waitcnt lgkmcnt(0)
	v_mfma_f32_16x16x32_bf16 v[110:113], v[42:45], v[186:189], v[110:113]
	v_mfma_f32_16x16x32_bf16 v[10:13], v[190:193], v[186:189], v[10:13]
	ds_read_b128 v[136:139], v172
	ds_read_b128 v[178:181], v172 offset:2048
	ds_read_b128 v[182:185], v172 offset:4096
	ds_read_b128 v[186:189], v172 offset:6144
	v_mfma_f32_16x16x32_bf16 v[18:21], v[42:45], v[210:213], v[18:21]
	v_mfma_f32_16x16x32_bf16 v[2:5], v[42:45], v[214:217], v[2:5]
	v_mfma_f32_16x16x32_bf16 v[6:9], v[42:45], v[218:221], v[6:9]
	ds_read_b128 v[42:45], v173
	ds_read_b128 v[194:197], v173 offset:2048
	ds_read_b128 v[198:201], v173 offset:4096
	ds_read_b128 v[202:205], v173 offset:6144
	v_mfma_f32_16x16x32_bf16 v[14:17], v[190:193], v[210:213], v[14:17]
	v_mfma_f32_16x16x32_bf16 v[22:25], v[190:193], v[214:217], v[22:25]
	v_mfma_f32_16x16x32_bf16 v[30:33], v[190:193], v[218:221], v[30:33]
	s_waitcnt lgkmcnt(0)
	v_mfma_f32_16x16x32_bf16 v[50:53], v[42:45], v[136:139], v[50:53]
	v_mfma_f32_16x16x32_bf16 v[58:61], v[42:45], v[178:181], v[58:61]
	v_mfma_f32_16x16x32_bf16 v[66:69], v[42:45], v[182:185], v[66:69]
	v_mfma_f32_16x16x32_bf16 v[34:37], v[42:45], v[186:189], v[34:37]
	ds_read_b128 v[42:45], v173 offset:8192
	ds_read_b128 v[190:193], v173 offset:10240
	v_mfma_f32_16x16x32_bf16 v[54:57], v[194:197], v[136:139], v[54:57]
	v_mfma_f32_16x16x32_bf16 v[62:65], v[194:197], v[178:181], v[62:65]
	v_mfma_f32_16x16x32_bf16 v[70:73], v[194:197], v[182:185], v[70:73]
	v_mfma_f32_16x16x32_bf16 v[38:41], v[194:197], v[186:189], v[38:41]
	v_mfma_f32_16x16x32_bf16 v[82:85], v[198:201], v[136:139], v[82:85]
	v_mfma_f32_16x16x32_bf16 v[194:197], v[198:201], v[178:181], v[90:93]
	v_mfma_f32_16x16x32_bf16 v[98:101], v[198:201], v[182:185], v[98:101]
	v_mfma_f32_16x16x32_bf16 v[198:201], v[198:201], v[186:189], v[26:29]
	s_nop 2
	ds_read_b128 v[26:29], v173 offset:12288
	ds_read_b128 v[90:93], v173 offset:14336
	v_mfma_f32_16x16x32_bf16 v[86:89], v[202:205], v[136:139], v[86:89]
	v_mfma_f32_16x16x32_bf16 v[102:105], v[202:205], v[182:185], v[102:105]
	v_mfma_f32_16x16x32_bf16 v[46:49], v[202:205], v[186:189], v[46:49]
	v_mfma_f32_16x16x32_bf16 v[206:209], v[202:205], v[178:181], v[94:97]
	s_waitcnt lgkmcnt(0)
	v_mfma_f32_16x16x32_bf16 v[202:205], v[190:193], v[136:139], v[114:117]
	v_mfma_f32_16x16x32_bf16 v[210:213], v[42:45], v[178:181], v[118:121]
	s_nop 1
	ds_read_b128 v[114:117], v174
	ds_read_b128 v[118:121], v174 offset:2048
	ds_read_b128 v[226:229], v175
	ds_read_b128 v[230:233], v175 offset:2048
	ds_read_b128 v[234:237], v175 offset:4096
	ds_read_b128 v[238:241], v175 offset:6144
	v_mfma_f32_16x16x32_bf16 v[106:109], v[42:45], v[136:139], v[106:109]
	v_mfma_f32_16x16x32_bf16 v[132:135], v[190:193], v[182:185], v[132:135]
	v_mfma_f32_16x16x32_bf16 v[214:217], v[190:193], v[178:181], v[122:125]
	v_mfma_f32_16x16x32_bf16 v[218:221], v[42:45], v[182:185], v[126:129]
	v_mfma_f32_16x16x32_bf16 v[222:225], v[42:45], v[186:189], v[74:77]
	v_mfma_f32_16x16x32_bf16 v[190:193], v[190:193], v[186:189], v[78:81]
	v_mfma_f32_16x16x32_bf16 v[242:245], v[26:29], v[136:139], v[110:113]
	v_mfma_f32_16x16x32_bf16 v[136:139], v[90:93], v[136:139], v[10:13]
	v_mfma_f32_16x16x32_bf16 v[246:249], v[26:29], v[178:181], v[18:21]
	v_mfma_f32_16x16x32_bf16 v[178:181], v[90:93], v[178:181], v[14:17]
	s_nop 0
	ds_read_b128 v[10:13], v174 offset:4096
	s_nop 0
	ds_read_b128 v[14:17], v174 offset:6144
	v_mfma_f32_16x16x32_bf16 v[2:5], v[26:29], v[182:185], v[2:5]
	v_mfma_f32_16x16x32_bf16 v[6:9], v[26:29], v[186:189], v[6:9]
	v_mfma_f32_16x16x32_bf16 v[182:185], v[90:93], v[182:185], v[22:25]
	v_mfma_f32_16x16x32_bf16 v[186:189], v[90:93], v[186:189], v[30:33]
	s_waitcnt lgkmcnt(0)
	v_mfma_f32_16x16x32_bf16 v[90:93], v[118:121], v[230:233], v[62:65]
	v_mfma_f32_16x16x32_bf16 v[62:65], v[114:117], v[234:237], v[66:69]
	v_mfma_f32_16x16x32_bf16 v[30:33], v[114:117], v[238:241], v[34:37]
	s_nop 2
	ds_read_b128 v[34:37], v174 offset:8192
	ds_read_b128 v[66:69], v174 offset:10240
	v_mfma_f32_16x16x32_bf16 v[126:129], v[114:117], v[226:229], v[50:53]
	v_mfma_f32_16x16x32_bf16 v[122:125], v[118:121], v[226:229], v[54:57]
	v_mfma_f32_16x16x32_bf16 v[94:97], v[114:117], v[230:233], v[58:61]
	v_mfma_f32_16x16x32_bf16 v[58:61], v[118:121], v[234:237], v[70:73]
	v_mfma_f32_16x16x32_bf16 v[26:29], v[118:121], v[238:241], v[38:41]
	v_mfma_f32_16x16x32_bf16 v[114:117], v[14:17], v[226:229], v[86:89]
	v_mfma_f32_16x16x32_bf16 v[86:89], v[10:13], v[230:233], v[194:197]
	v_mfma_f32_16x16x32_bf16 v[22:25], v[10:13], v[238:241], v[198:201]
	s_nop 1
	ds_read_b128 v[194:197], v174 offset:12288
	ds_read_b128 v[198:201], v174 offset:14336
	v_mfma_f32_16x16x32_bf16 v[118:121], v[10:13], v[226:229], v[82:85]
	v_mfma_f32_16x16x32_bf16 v[82:85], v[14:17], v[230:233], v[206:209]
	v_mfma_f32_16x16x32_bf16 v[54:57], v[10:13], v[234:237], v[98:101]
	v_mfma_f32_16x16x32_bf16 v[50:53], v[14:17], v[234:237], v[102:105]
	v_mfma_f32_16x16x32_bf16 v[18:21], v[14:17], v[238:241], v[46:49]
	s_waitcnt lgkmcnt(0)
	v_mfma_f32_16x16x32_bf16 v[110:113], v[34:37], v[226:229], v[106:109]
	v_mfma_f32_16x16x32_bf16 v[106:109], v[66:69], v[226:229], v[202:205]
	v_mfma_f32_16x16x32_bf16 v[78:81], v[34:37], v[230:233], v[210:213]
	v_mfma_f32_16x16x32_bf16 v[74:77], v[66:69], v[230:233], v[214:217]
	v_mfma_f32_16x16x32_bf16 v[46:49], v[34:37], v[234:237], v[218:221]
	v_mfma_f32_16x16x32_bf16 v[42:45], v[66:69], v[234:237], v[132:135]
	v_mfma_f32_16x16x32_bf16 v[14:17], v[34:37], v[238:241], v[222:225]
	v_mfma_f32_16x16x32_bf16 v[10:13], v[66:69], v[238:241], v[190:193]
	v_mov_b32_e32 v130, v1
	s_waitcnt vmcnt(0)
	s_barrier
; __device__ __forceinline__ int get_tid512() { int t = threadIdx.x; asm volatile("" : "+v"(t)); return t; }
; __device__ __forceinline__ unsigned pack2(float a, float b) { unsigned r; asm("v_cvt_pk_bf16_f32 %0, %1, %2" : "=v"(r) : "v"(a), "v"(b)); return r; }
;   __device__ __forceinline__ void c4(int g, int rig, int col, f32x4 v) const {
;     const size_t row = (size_t)g * ostride + rig;
;     float s = 1.f;
;     if (NP > 0) {
;       float t = 0.f;
; #pragma unroll
;       for (int q = 0; q < NP; ++q) t += part[(size_t)q * pstride + row];
;       s = rsqrtf(t * inv_n + 1e-6f);
;     }
;     uint2 u; u.x = pack2(v[0] * s, v[1] * s); u.y = pack2(v[2] * s, v[3] * s);
;     *(uint2*)(out + row * ld + col) = u;
;   }
; template <bool SWAP, class Epi, bool THIN = false> ...
;     ...
;     __syncthreads();
;     const int te = get_tid512();
;     const int fr_e = te & 15, fq_e = (te & 63) >> 4, wr_e = te >> 7, wc_e = (te >> 6) & 1;
;     const int sub = 2 * mt + (wr_e >> 1);
;     const int g = sub / tpg, ti = sub - g * tpg;
;     const int rig0 = ti * step - halo;
;     const int rw = (wr_e & 1) * 64;
;     if constexpr (Epi::KIND == 0) {
; #pragma unroll
;       for (int m = 0; m < 4; ++m) {
;         const int rig = rig0 + rw + m * 16 + fr_e;
;         if constexpr (Epi::ROWSUM) {
;           float ss = 0.f;
; #pragma unroll
;           for (int n = 0; n < 8; ++n) {
;             const int col = nt * 256 + wc_e * 128 + n * 16 + fq_e * 4;
;             if (col < N) ss += epi.c4(g, rig, col, acc[m][n]);
;           }
;           ss += __shfl_xor(ss, 16); ss += __shfl_xor(ss, 32);
;           if (fq_e == 0) epi.rowsum(g, rig, nt * 2 + wc_e, ss);
;         } else {
; #pragma unroll
;           for (int n = 0; n < 8; ++n) {
;             const int col = nt * 256 + wc_e * 128 + n * 16 + fq_e * 4;
;             if (col < N) epi.c4(g, rig, col, acc[m][n]);
;           }
;         }
	v_mfma_f32_16x16x32_bf16 v[38:41], v[194:197], v[234:237], v[2:5]
	v_ashrrev_i32_e32 v34, 8, v130
	v_add_u32_e32 v34, s5, v34
	v_ashrrev_i32_e32 v35, 31, v34
	v_lshrrev_b32_e32 v35, 28, v35
	v_add_u32_e32 v35, v34, v35
	v_ashrrev_i32_e32 v134, 4, v35
	v_lshlrev_b32_e32 v35, 11, v134
	v_lshlrev_b32_e32 v34, 7, v34
	v_lshrrev_b32_e32 v3, 1, v130
	v_and_b32_e32 v132, 15, v130
	v_sub_u32_e32 v2, v34, v35
	v_and_b32_e32 v3, 64, v3
	v_mfma_f32_16x16x32_bf16 v[98:101], v[198:201], v[226:229], v[136:139]
	v_ashrrev_i32_e32 v135, 31, v134
	s_nop 1
	v_or3_b32 v136, v2, v3, v132
	v_lshlrev_b32_e32 v2, 1, v130
	v_lshrrev_b32_e32 v3, 2, v130
	v_and_b32_e32 v2, 0x80, v2
	v_and_b32_e32 v3, 12, v3
	v_mfma_f32_16x16x32_bf16 v[102:105], v[194:197], v[226:229], v[242:245]
	v_or3_b32 v132, v3, v2, s4
	v_ashrrev_i32_e32 v137, 31, v136
	v_lshlrev_b64 v[138:139], 11, v[134:135]
	v_mfma_f32_16x16x32_bf16 v[70:73], v[194:197], v[230:233], v[246:249]
	v_cmp_gt_i32_e64 s[4:5], s50, v132
	v_ashrrev_i32_e32 v133, 31, v132
	v_lshl_add_u64 v[134:135], v[138:139], 0, v[136:137]
	v_mfma_f32_16x16x32_bf16 v[66:69], v[198:201], v[230:233], v[178:181]
	v_mfma_f32_16x16x32_bf16 v[34:37], v[198:201], v[234:237], v[182:185]
	v_mfma_f32_16x16x32_bf16 v[6:9], v[194:197], v[238:241], v[6:9]
	v_mfma_f32_16x16x32_bf16 v[2:5], v[198:201], v[238:241], v[186:189]
	v_lshl_add_u64 v[178:179], v[134:135], 2, s[22:23]
	v_add_co_u32_e32 v180, vcc, 0x10000, v178
	s_nop 1
	v_addc_co_u32_e32 v181, vcc, 0, v179, vcc
	v_add_co_u32_e32 v182, vcc, 0x20000, v178
	s_nop 1
	v_addc_co_u32_e32 v183, vcc, 0, v179, vcc
	v_add_co_u32_e32 v184, vcc, 0x30000, v178
	s_nop 1
	v_addc_co_u32_e32 v185, vcc, 0, v179, vcc
	global_load_dword v130, v[178:179], off
	global_load_dword v137, v[180:181], off
	global_load_dword v177, v[182:183], off
	s_nop 0
	global_load_dword v180, v[184:185], off
	v_mov_b64_e32 v[178:179], s[20:21]
	v_mad_u64_u32 v[178:179], s[8:9], v134, s56, v[178:179]
	v_mad_i32_i24 v179, v135, s56, v179
	s_waitcnt vmcnt(3)
	v_add_f32_e32 v130, 0, v130
	s_waitcnt vmcnt(2)
	v_add_f32_e32 v130, v130, v137
	s_waitcnt vmcnt(1)
	v_add_f32_e32 v130, v130, v177
	s_waitcnt vmcnt(0)
	v_add_f32_e32 v130, v130, v180
	v_fmamk_f32 v130, v130, 0x3b000000, v176
	v_mul_f32_e32 v137, 0x4b800000, v130
	v_cmp_gt_f32_e32 vcc, s51, v130
	s_nop 1
	v_cndmask_b32_e32 v130, v130, v137, vcc
	v_rsq_f32_e32 v130, v130
	s_nop 0
	v_mul_f32_e32 v137, 0x45800000, v130
	v_cndmask_b32_e32 v130, v130, v137, vcc
	v_mov_b32_e32 v251, v130
	v_mul_f32_e32 v126, v126, v130
	v_mul_f32_e32 v127, v127, v130
	v_mul_f32_e32 v128, v128, v130
	v_mul_f32_e32 v129, v129, v130
	v_cvt_pk_bf16_f32 v126, v126, v127
	v_cvt_pk_bf16_f32 v127, v128, v129
	v_lshl_add_u64 v[128:129], v[132:133], 1, v[178:179]
	global_store_dwordx2 v[128:129], v[126:127], off
	v_or_b32_e32 v126, 16, v132
	v_mov_b64_e32 v[126:127], s[20:21]
	v_mad_u64_u32 v[126:127], s[10:11], v134, s56, v[126:127]
	v_mad_i32_i24 v127, v135, s56, v127
	v_mul_f32_e32 v122, v122, v251
	v_mul_f32_e32 v123, v123, v251
	v_mul_f32_e32 v124, v124, v251
	v_mul_f32_e32 v125, v125, v251
	v_cvt_pk_bf16_f32 v122, v122, v123
	v_cvt_pk_bf16_f32 v123, v124, v125
	v_lshl_add_u64 v[124:125], v[132:133], 1, v[126:127]
	global_store_dwordx2 v[124:125], v[122:123], off offset:32
	v_or_b32_e32 v122, 32, v132
	v_mov_b64_e32 v[122:123], s[20:21]
	v_mad_u64_u32 v[122:123], s[12:13], v134, s56, v[122:123]
	v_mad_i32_i24 v123, v135, s56, v123
	v_mul_f32_e32 v118, v118, v251
	v_mul_f32_e32 v119, v119, v251
	v_mul_f32_e32 v120, v120, v251
	v_mul_f32_e32 v121, v121, v251
	v_cvt_pk_bf16_f32 v118, v118, v119
	v_cvt_pk_bf16_f32 v119, v120, v121
	v_lshl_add_u64 v[120:121], v[132:133], 1, v[122:123]
	global_store_dwordx2 v[120:121], v[118:119], off offset:64
	v_or_b32_e32 v118, 48, v132
	v_mov_b64_e32 v[118:119], s[20:21]
	v_mad_u64_u32 v[118:119], s[14:15], v134, s56, v[118:119]
	v_mad_i32_i24 v119, v135, s56, v119
	v_mul_f32_e32 v114, v114, v251
	v_mul_f32_e32 v115, v115, v251
	v_mul_f32_e32 v116, v116, v251
	v_mul_f32_e32 v117, v117, v251
	v_cvt_pk_bf16_f32 v114, v114, v115
	v_cvt_pk_bf16_f32 v115, v116, v117
	v_lshl_add_u64 v[116:117], v[132:133], 1, v[118:119]
	global_store_dwordx2 v[116:117], v[114:115], off offset:96
	v_or_b32_e32 v114, 64, v132
	v_mov_b64_e32 v[114:115], s[20:21]
	v_mad_u64_u32 v[114:115], s[16:17], v134, s56, v[114:115]
	v_mad_i32_i24 v115, v135, s56, v115
	v_mul_f32_e32 v110, v110, v251
	v_mul_f32_e32 v111, v111, v251
	v_mul_f32_e32 v112, v112, v251
	v_mul_f32_e32 v113, v113, v251
	v_cvt_pk_bf16_f32 v110, v110, v111
	v_cvt_pk_bf16_f32 v111, v112, v113
	v_lshl_add_u64 v[112:113], v[132:133], 1, v[114:115]
	global_store_dwordx2 v[112:113], v[110:111], off offset:128
	v_or_b32_e32 v110, 0x50, v132
	v_mov_b64_e32 v[110:111], s[20:21]
	v_mad_u64_u32 v[110:111], s[18:19], v134, s56, v[110:111]
	v_mad_i32_i24 v111, v135, s56, v111
	v_mul_f32_e32 v106, v106, v251
	v_mul_f32_e32 v107, v107, v251
	v_mul_f32_e32 v108, v108, v251
	v_mul_f32_e32 v109, v109, v251
	v_cvt_pk_bf16_f32 v106, v106, v107
	v_cvt_pk_bf16_f32 v107, v108, v109
	v_lshl_add_u64 v[108:109], v[132:133], 1, v[110:111]
	global_store_dwordx2 v[108:109], v[106:107], off offset:160
	v_or_b32_e32 v106, 0x60, v132
	v_mov_b64_e32 v[106:107], s[20:21]
	v_mad_u64_u32 v[106:107], s[44:45], v134, s56, v[106:107]
	v_mad_i32_i24 v107, v135, s56, v107
	v_mul_f32_e32 v102, v102, v251
	v_mul_f32_e32 v103, v103, v251
	v_mul_f32_e32 v104, v104, v251
	v_mul_f32_e32 v105, v105, v251
	v_cvt_pk_bf16_f32 v102, v102, v103
	v_cvt_pk_bf16_f32 v103, v104, v105
	v_lshl_add_u64 v[104:105], v[132:133], 1, v[106:107]
	global_store_dwordx2 v[104:105], v[102:103], off offset:192
	v_or_b32_e32 v102, 0x70, v132
	v_mov_b64_e32 v[102:103], s[20:21]
	v_mad_u64_u32 v[102:103], s[58:59], v134, s56, v[102:103]
	v_mad_i32_i24 v103, v135, s56, v103
	v_mul_f32_e32 v98, v98, v251
	v_mul_f32_e32 v99, v99, v251
	v_mul_f32_e32 v100, v100, v251
	v_mul_f32_e32 v101, v101, v251
	v_cvt_pk_bf16_f32 v98, v98, v99
	v_cvt_pk_bf16_f32 v99, v100, v101
	v_lshl_add_u64 v[100:101], v[132:133], 1, v[102:103]
	global_store_dwordx2 v[100:101], v[98:99], off offset:224
	v_or_b32_e32 v98, 16, v136
	v_ashrrev_i32_e32 v99, 31, v98
	v_lshl_add_u64 v[98:99], v[138:139], 0, v[98:99]
	v_lshl_add_u64 v[100:101], v[134:135], 2, s[22:23]
	v_add_co_u32_e32 v102, vcc, 0x10000, v100
	s_nop 1
	v_addc_co_u32_e32 v103, vcc, 0, v101, vcc
	v_add_co_u32_e32 v104, vcc, 0x20000, v100
	s_nop 1
	v_addc_co_u32_e32 v105, vcc, 0, v101, vcc
	v_add_co_u32_e32 v106, vcc, 0x30000, v100
	s_nop 1
	v_addc_co_u32_e32 v107, vcc, 0, v101, vcc
	global_load_dword v108, v[100:101], off offset:64
	s_nop 0
	global_load_dword v102, v[102:103], off offset:64
	s_nop 0
	global_load_dword v103, v[104:105], off offset:64
	s_nop 0
	global_load_dword v104, v[106:107], off offset:64
	v_mov_b64_e32 v[100:101], s[20:21]
	v_mad_u64_u32 v[100:101], s[58:59], v98, s56, v[100:101]
	v_mad_i32_i24 v101, v99, s56, v101
	s_waitcnt vmcnt(3)
; __device__ __forceinline__ unsigned pack2(float a, float b) { unsigned r; asm("v_cvt_pk_bf16_f32 %0, %1, %2" : "=v"(r) : "v"(a), "v"(b)); return r; }
;   __device__ __forceinline__ void c4(int g, int rig, int col, f32x4 v) const {
;     const size_t row = (size_t)g * ostride + rig;
;     float s = 1.f;
;     if (NP > 0) {
;       float t = 0.f;
; #pragma unroll
;       for (int q = 0; q < NP; ++q) t += part[(size_t)q * pstride + row];
;       s = rsqrtf(t * inv_n + 1e-6f);
;     }
;     uint2 u; u.x = pack2(v[0] * s, v[1] * s); u.y = pack2(v[2] * s, v[3] * s);
;     *(uint2*)(out + row * ld + col) = u;
;   }
; template <bool SWAP, class Epi, bool THIN = false> ...
;     ...
;     if constexpr (Epi::KIND == 0) {
; #pragma unroll
;       for (int m = 0; m < 4; ++m) {
;         const int rig = rig0 + rw + m * 16 + fr_e;
;         if constexpr (Epi::ROWSUM) {
;           float ss = 0.f;
; #pragma unroll
;           for (int n = 0; n < 8; ++n) {
;             const int col = nt * 256 + wc_e * 128 + n * 16 + fq_e * 4;
;             if (col < N) ss += epi.c4(g, rig, col, acc[m][n]);
;           }
;           ss += __shfl_xor(ss, 16); ss += __shfl_xor(ss, 32);
;           if (fq_e == 0) epi.rowsum(g, rig, nt * 2 + wc_e, ss);
;         } else {
; #pragma unroll
;           for (int n = 0; n < 8; ++n) {
;             const int col = nt * 256 + wc_e * 128 + n * 16 + fq_e * 4;
;             if (col < N) epi.c4(g, rig, col, acc[m][n]);
;           }
;         }
	v_add_f32_e32 v105, 0, v108
	s_waitcnt vmcnt(2)
	v_add_f32_e32 v102, v105, v102
	s_waitcnt vmcnt(1)
	v_add_f32_e32 v102, v102, v103
	s_waitcnt vmcnt(0)
	v_add_f32_e32 v102, v102, v104
	v_fmamk_f32 v102, v102, 0x3b000000, v176
	v_mul_f32_e32 v103, 0x4b800000, v102
	v_cmp_gt_f32_e32 vcc, s51, v102
	s_nop 1
	v_cndmask_b32_e32 v102, v102, v103, vcc
	v_rsq_f32_e32 v102, v102
	s_nop 0
	v_mul_f32_e32 v103, 0x45800000, v102
	v_cndmask_b32_e32 v102, v102, v103, vcc
	v_mov_b32_e32 v251, v102
	v_mul_f32_e32 v94, v94, v102
	v_mul_f32_e32 v95, v95, v102
	v_mul_f32_e32 v96, v96, v102
	v_mul_f32_e32 v97, v97, v102
	v_cvt_pk_bf16_f32 v94, v94, v95
	v_cvt_pk_bf16_f32 v95, v96, v97
	v_lshl_add_u64 v[96:97], v[132:133], 1, v[100:101]
	global_store_dwordx2 v[96:97], v[94:95], off
	v_mov_b64_e32 v[94:95], s[20:21]
	v_mad_u64_u32 v[94:95], s[58:59], v98, s56, v[94:95]
	v_mad_i32_i24 v95, v99, s56, v95
	v_mul_f32_e32 v90, v90, v251
	v_mul_f32_e32 v91, v91, v251
	v_mul_f32_e32 v92, v92, v251
	v_mul_f32_e32 v93, v93, v251
	v_cvt_pk_bf16_f32 v90, v90, v91
	v_cvt_pk_bf16_f32 v91, v92, v93
	v_lshl_add_u64 v[92:93], v[132:133], 1, v[94:95]
	global_store_dwordx2 v[92:93], v[90:91], off offset:32
	v_mov_b64_e32 v[90:91], s[20:21]
	v_mad_u64_u32 v[90:91], s[58:59], v98, s56, v[90:91]
	v_mad_i32_i24 v91, v99, s56, v91
	v_mul_f32_e32 v86, v86, v251
	v_mul_f32_e32 v87, v87, v251
	v_mul_f32_e32 v88, v88, v251
	v_mul_f32_e32 v89, v89, v251
	v_cvt_pk_bf16_f32 v86, v86, v87
	v_cvt_pk_bf16_f32 v87, v88, v89
	v_lshl_add_u64 v[88:89], v[132:133], 1, v[90:91]
	global_store_dwordx2 v[88:89], v[86:87], off offset:64
	v_mov_b64_e32 v[86:87], s[20:21]
	v_mad_u64_u32 v[86:87], s[58:59], v98, s56, v[86:87]
	v_mad_i32_i24 v87, v99, s56, v87
	v_mul_f32_e32 v82, v82, v251
	v_mul_f32_e32 v83, v83, v251
	v_mul_f32_e32 v84, v84, v251
	v_mul_f32_e32 v85, v85, v251
	v_cvt_pk_bf16_f32 v82, v82, v83
	v_cvt_pk_bf16_f32 v83, v84, v85
	v_lshl_add_u64 v[84:85], v[132:133], 1, v[86:87]
	global_store_dwordx2 v[84:85], v[82:83], off offset:96
	v_mov_b64_e32 v[82:83], s[20:21]
	v_mad_u64_u32 v[82:83], s[58:59], v98, s56, v[82:83]
	v_mad_i32_i24 v83, v99, s56, v83
	v_mul_f32_e32 v78, v78, v251
	v_mul_f32_e32 v79, v79, v251
	v_mul_f32_e32 v80, v80, v251
	v_mul_f32_e32 v81, v81, v251
	v_cvt_pk_bf16_f32 v78, v78, v79
	v_cvt_pk_bf16_f32 v79, v80, v81
	v_lshl_add_u64 v[80:81], v[132:133], 1, v[82:83]
	global_store_dwordx2 v[80:81], v[78:79], off offset:128
	v_mov_b64_e32 v[78:79], s[20:21]
	v_mad_u64_u32 v[78:79], s[58:59], v98, s56, v[78:79]
	v_mad_i32_i24 v79, v99, s56, v79
	v_mul_f32_e32 v74, v74, v251
	v_mul_f32_e32 v75, v75, v251
	v_mul_f32_e32 v76, v76, v251
	v_mul_f32_e32 v77, v77, v251
	v_cvt_pk_bf16_f32 v74, v74, v75
	v_cvt_pk_bf16_f32 v75, v76, v77
	v_lshl_add_u64 v[76:77], v[132:133], 1, v[78:79]
	global_store_dwordx2 v[76:77], v[74:75], off offset:160
	v_mov_b64_e32 v[74:75], s[20:21]
	v_mad_u64_u32 v[74:75], s[58:59], v98, s56, v[74:75]
	v_mad_i32_i24 v75, v99, s56, v75
	v_mul_f32_e32 v70, v70, v251
	v_mul_f32_e32 v71, v71, v251
	v_mul_f32_e32 v72, v72, v251
	v_mul_f32_e32 v73, v73, v251
	v_cvt_pk_bf16_f32 v70, v70, v71
	v_cvt_pk_bf16_f32 v71, v72, v73
	v_lshl_add_u64 v[72:73], v[132:133], 1, v[74:75]
	global_store_dwordx2 v[72:73], v[70:71], off offset:192
	v_mov_b64_e32 v[70:71], s[20:21]
	v_mad_u64_u32 v[70:71], s[58:59], v98, s56, v[70:71]
	v_mad_i32_i24 v71, v99, s56, v71
	v_mul_f32_e32 v66, v66, v251
	v_mul_f32_e32 v67, v67, v251
	v_mul_f32_e32 v68, v68, v251
	v_mul_f32_e32 v69, v69, v251
	v_cvt_pk_bf16_f32 v66, v66, v67
	v_cvt_pk_bf16_f32 v67, v68, v69
	v_lshl_add_u64 v[68:69], v[132:133], 1, v[70:71]
	global_store_dwordx2 v[68:69], v[66:67], off offset:224
	v_or_b32_e32 v66, 32, v136
	v_ashrrev_i32_e32 v67, 31, v66
	v_lshl_add_u64 v[66:67], v[138:139], 0, v[66:67]
	v_lshl_add_u64 v[68:69], v[134:135], 2, s[22:23]
	v_add_co_u32_e32 v70, vcc, 0x10000, v68
	s_nop 1
	v_addc_co_u32_e32 v71, vcc, 0, v69, vcc
	v_add_co_u32_e32 v72, vcc, 0x20000, v68
	s_nop 1
	v_addc_co_u32_e32 v73, vcc, 0, v69, vcc
	v_add_co_u32_e32 v74, vcc, 0x30000, v68
	s_nop 1
	v_addc_co_u32_e32 v75, vcc, 0, v69, vcc
	global_load_dword v76, v[68:69], off offset:128
	s_nop 0
	global_load_dword v70, v[70:71], off offset:128
	s_nop 0
	global_load_dword v71, v[72:73], off offset:128
	s_nop 0
	global_load_dword v72, v[74:75], off offset:128
	v_mov_b64_e32 v[68:69], s[20:21]
	v_mad_u64_u32 v[68:69], s[58:59], v66, s56, v[68:69]
	v_mad_i32_i24 v69, v67, s56, v69
	s_waitcnt vmcnt(3)
	v_add_f32_e32 v73, 0, v76
	s_waitcnt vmcnt(2)
	v_add_f32_e32 v70, v73, v70
	s_waitcnt vmcnt(1)
	v_add_f32_e32 v70, v70, v71
	s_waitcnt vmcnt(0)
; __device__ __forceinline__ unsigned pack2(float a, float b) { unsigned r; asm("v_cvt_pk_bf16_f32 %0, %1, %2" : "=v"(r) : "v"(a), "v"(b)); return r; }
;   __device__ __forceinline__ void c4(int g, int rig, int col, f32x4 v) const {
;     const size_t row = (size_t)g * ostride + rig;
;     float s = 1.f;
;     if (NP > 0) {
;       float t = 0.f;
; #pragma unroll
;       for (int q = 0; q < NP; ++q) t += part[(size_t)q * pstride + row];
;       s = rsqrtf(t * inv_n + 1e-6f);
;     }
;     uint2 u; u.x = pack2(v[0] * s, v[1] * s); u.y = pack2(v[2] * s, v[3] * s);
;     *(uint2*)(out + row * ld + col) = u;
;   }
; template <bool SWAP, class Epi, bool THIN = false> ...
;     ...
;     if constexpr (Epi::KIND == 0) {
; #pragma unroll
;       for (int m = 0; m < 4; ++m) {
;         const int rig = rig0 + rw + m * 16 + fr_e;
;         if constexpr (Epi::ROWSUM) {
;           float ss = 0.f;
; #pragma unroll
;           for (int n = 0; n < 8; ++n) {
;             const int col = nt * 256 + wc_e * 128 + n * 16 + fq_e * 4;
;             if (col < N) ss += epi.c4(g, rig, col, acc[m][n]);
;           }
;           ss += __shfl_xor(ss, 16); ss += __shfl_xor(ss, 32);
;           if (fq_e == 0) epi.rowsum(g, rig, nt * 2 + wc_e, ss);
;         } else {
; #pragma unroll
;           for (int n = 0; n < 8; ++n) {
;             const int col = nt * 256 + wc_e * 128 + n * 16 + fq_e * 4;
;             if (col < N) epi.c4(g, rig, col, acc[m][n]);
;           }
;         }
	v_add_f32_e32 v70, v70, v72
	v_fmamk_f32 v70, v70, 0x3b000000, v176
	v_mul_f32_e32 v71, 0x4b800000, v70
	v_cmp_gt_f32_e32 vcc, s51, v70
	s_nop 1
	v_cndmask_b32_e32 v70, v70, v71, vcc
	v_rsq_f32_e32 v70, v70
	s_nop 0
	v_mul_f32_e32 v71, 0x45800000, v70
	v_cndmask_b32_e32 v70, v70, v71, vcc
	v_mov_b32_e32 v251, v70
	v_mul_f32_e32 v62, v62, v70
	v_mul_f32_e32 v63, v63, v70
	v_mul_f32_e32 v64, v64, v70
	v_mul_f32_e32 v65, v65, v70
	v_cvt_pk_bf16_f32 v62, v62, v63
	v_cvt_pk_bf16_f32 v63, v64, v65
	v_lshl_add_u64 v[64:65], v[132:133], 1, v[68:69]
	global_store_dwordx2 v[64:65], v[62:63], off
	v_mov_b64_e32 v[62:63], s[20:21]
	v_mad_u64_u32 v[62:63], s[58:59], v66, s56, v[62:63]
	v_mad_i32_i24 v63, v67, s56, v63
	v_mul_f32_e32 v58, v58, v251
	v_mul_f32_e32 v59, v59, v251
	v_mul_f32_e32 v60, v60, v251
	v_mul_f32_e32 v61, v61, v251
	v_cvt_pk_bf16_f32 v58, v58, v59
	v_cvt_pk_bf16_f32 v59, v60, v61
	v_lshl_add_u64 v[60:61], v[132:133], 1, v[62:63]
	global_store_dwordx2 v[60:61], v[58:59], off offset:32
	v_mov_b64_e32 v[58:59], s[20:21]
	v_mad_u64_u32 v[58:59], s[58:59], v66, s56, v[58:59]
	v_mad_i32_i24 v59, v67, s56, v59
	v_mul_f32_e32 v54, v54, v251
	v_mul_f32_e32 v55, v55, v251
	v_mul_f32_e32 v56, v56, v251
	v_mul_f32_e32 v57, v57, v251
	v_cvt_pk_bf16_f32 v54, v54, v55
	v_cvt_pk_bf16_f32 v55, v56, v57
	v_lshl_add_u64 v[56:57], v[132:133], 1, v[58:59]
	global_store_dwordx2 v[56:57], v[54:55], off offset:64
	v_mov_b64_e32 v[54:55], s[20:21]
	v_mad_u64_u32 v[54:55], s[58:59], v66, s56, v[54:55]
	v_mad_i32_i24 v55, v67, s56, v55
	v_mul_f32_e32 v50, v50, v251
	v_mul_f32_e32 v51, v51, v251
	v_mul_f32_e32 v52, v52, v251
	v_mul_f32_e32 v53, v53, v251
	v_cvt_pk_bf16_f32 v50, v50, v51
	v_cvt_pk_bf16_f32 v51, v52, v53
	v_lshl_add_u64 v[52:53], v[132:133], 1, v[54:55]
	global_store_dwordx2 v[52:53], v[50:51], off offset:96
	v_mov_b64_e32 v[50:51], s[20:21]
	v_mad_u64_u32 v[50:51], s[58:59], v66, s56, v[50:51]
	v_mad_i32_i24 v51, v67, s56, v51
	v_mul_f32_e32 v46, v46, v251
	v_mul_f32_e32 v47, v47, v251
	v_mul_f32_e32 v48, v48, v251
	v_mul_f32_e32 v49, v49, v251
	v_cvt_pk_bf16_f32 v46, v46, v47
	v_cvt_pk_bf16_f32 v47, v48, v49
	v_lshl_add_u64 v[48:49], v[132:133], 1, v[50:51]
	global_store_dwordx2 v[48:49], v[46:47], off offset:128
	v_mov_b64_e32 v[46:47], s[20:21]
	v_mad_u64_u32 v[46:47], s[58:59], v66, s56, v[46:47]
	v_mad_i32_i24 v47, v67, s56, v47
	v_mul_f32_e32 v42, v42, v251
	v_mul_f32_e32 v43, v43, v251
	v_mul_f32_e32 v44, v44, v251
	v_mul_f32_e32 v45, v45, v251
	v_cvt_pk_bf16_f32 v42, v42, v43
	v_cvt_pk_bf16_f32 v43, v44, v45
	v_lshl_add_u64 v[44:45], v[132:133], 1, v[46:47]
	global_store_dwordx2 v[44:45], v[42:43], off offset:160
	v_mov_b64_e32 v[42:43], s[20:21]
	v_mad_u64_u32 v[42:43], s[58:59], v66, s56, v[42:43]
	v_mad_i32_i24 v43, v67, s56, v43
	v_mul_f32_e32 v38, v38, v251
	v_mul_f32_e32 v39, v39, v251
	v_mul_f32_e32 v40, v40, v251
	v_mul_f32_e32 v41, v41, v251
	v_cvt_pk_bf16_f32 v38, v38, v39
	v_cvt_pk_bf16_f32 v39, v40, v41
	v_lshl_add_u64 v[40:41], v[132:133], 1, v[42:43]
	global_store_dwordx2 v[40:41], v[38:39], off offset:192
	v_mov_b64_e32 v[38:39], s[20:21]
	v_mad_u64_u32 v[38:39], s[58:59], v66, s56, v[38:39]
	v_mad_i32_i24 v39, v67, s56, v39
	v_mul_f32_e32 v34, v34, v251
	v_mul_f32_e32 v35, v35, v251
	v_mul_f32_e32 v36, v36, v251
	v_mul_f32_e32 v37, v37, v251
	v_cvt_pk_bf16_f32 v34, v34, v35
	v_cvt_pk_bf16_f32 v35, v36, v37
	v_lshl_add_u64 v[36:37], v[132:133], 1, v[38:39]
	global_store_dwordx2 v[36:37], v[34:35], off offset:224
	v_or_b32_e32 v34, 48, v136
	v_ashrrev_i32_e32 v35, 31, v34
	v_lshl_add_u64 v[34:35], v[138:139], 0, v[34:35]
	v_lshl_add_u64 v[36:37], v[134:135], 2, s[22:23]
	v_add_co_u32_e32 v38, vcc, 0x10000, v36
	s_nop 1
	v_addc_co_u32_e32 v39, vcc, 0, v37, vcc
	v_add_co_u32_e32 v40, vcc, 0x20000, v36
	s_nop 1
	v_addc_co_u32_e32 v41, vcc, 0, v37, vcc
	v_add_co_u32_e32 v42, vcc, 0x30000, v36
	s_nop 1
	v_addc_co_u32_e32 v43, vcc, 0, v37, vcc
	global_load_dword v44, v[36:37], off offset:192
	s_nop 0
	global_load_dword v38, v[38:39], off offset:192
	s_nop 0
	global_load_dword v39, v[40:41], off offset:192
	s_nop 0
	global_load_dword v40, v[42:43], off offset:192
	v_mov_b64_e32 v[36:37], s[20:21]
	v_mad_u64_u32 v[36:37], s[4:5], v34, s56, v[36:37]
	v_mad_i32_i24 v37, v35, s56, v37
	s_waitcnt vmcnt(3)
; __device__ __forceinline__ unsigned pack2(float a, float b) { unsigned r; asm("v_cvt_pk_bf16_f32 %0, %1, %2" : "=v"(r) : "v"(a), "v"(b)); return r; }
;   __device__ __forceinline__ void c4(int g, int rig, int col, f32x4 v) const {
;     const size_t row = (size_t)g * ostride + rig;
;     float s = 1.f;
;     if (NP > 0) {
;       float t = 0.f;
; #pragma unroll
;       for (int q = 0; q < NP; ++q) t += part[(size_t)q * pstride + row];
;       s = rsqrtf(t * inv_n + 1e-6f);
;     }
;     uint2 u; u.x = pack2(v[0] * s, v[1] * s); u.y = pack2(v[2] * s, v[3] * s);
;     *(uint2*)(out + row * ld + col) = u;
;   }
; template <bool SWAP, class Epi, bool THIN = false> ...
;     ...
;     if constexpr (Epi::KIND == 0) {
; #pragma unroll
;       for (int m = 0; m < 4; ++m) {
;         const int rig = rig0 + rw + m * 16 + fr_e;
;         if constexpr (Epi::ROWSUM) {
;           float ss = 0.f;
; #pragma unroll
;           for (int n = 0; n < 8; ++n) {
;             const int col = nt * 256 + wc_e * 128 + n * 16 + fq_e * 4;
;             if (col < N) ss += epi.c4(g, rig, col, acc[m][n]);
;           }
;           ss += __shfl_xor(ss, 16); ss += __shfl_xor(ss, 32);
;           if (fq_e == 0) epi.rowsum(g, rig, nt * 2 + wc_e, ss);
;         } else {
; #pragma unroll
;           for (int n = 0; n < 8; ++n) {
;             const int col = nt * 256 + wc_e * 128 + n * 16 + fq_e * 4;
;             if (col < N) epi.c4(g, rig, col, acc[m][n]);
;           }
;         }
	v_add_f32_e32 v41, 0, v44
	s_waitcnt vmcnt(2)
	v_add_f32_e32 v38, v41, v38
	s_waitcnt vmcnt(1)
	v_add_f32_e32 v38, v38, v39
	s_waitcnt vmcnt(0)
	v_add_f32_e32 v38, v38, v40
	v_fmamk_f32 v38, v38, 0x3b000000, v176
	v_mul_f32_e32 v39, 0x4b800000, v38
	v_cmp_gt_f32_e32 vcc, s51, v38
	s_nop 1
	v_cndmask_b32_e32 v38, v38, v39, vcc
	v_rsq_f32_e32 v38, v38
	s_nop 0
	v_mul_f32_e32 v39, 0x45800000, v38
	v_cndmask_b32_e32 v38, v38, v39, vcc
	v_mov_b32_e32 v251, v38
	v_mul_f32_e32 v30, v30, v38
	v_mul_f32_e32 v31, v31, v38
	v_mul_f32_e32 v32, v32, v38
	v_mul_f32_e32 v33, v33, v38
	v_cvt_pk_bf16_f32 v30, v30, v31
	v_cvt_pk_bf16_f32 v31, v32, v33
	v_lshl_add_u64 v[32:33], v[132:133], 1, v[36:37]
	global_store_dwordx2 v[32:33], v[30:31], off
	v_mov_b64_e32 v[30:31], s[20:21]
	v_mad_u64_u32 v[30:31], s[6:7], v34, s56, v[30:31]
	v_mad_i32_i24 v31, v35, s56, v31
	v_mul_f32_e32 v26, v26, v251
	v_mul_f32_e32 v27, v27, v251
	v_mul_f32_e32 v28, v28, v251
	v_mul_f32_e32 v29, v29, v251
	v_cvt_pk_bf16_f32 v26, v26, v27
	v_cvt_pk_bf16_f32 v27, v28, v29
	v_lshl_add_u64 v[28:29], v[132:133], 1, v[30:31]
	global_store_dwordx2 v[28:29], v[26:27], off offset:32
	v_mov_b64_e32 v[26:27], s[20:21]
	v_mad_u64_u32 v[26:27], s[6:7], v34, s56, v[26:27]
	v_mad_i32_i24 v27, v35, s56, v27
	v_mul_f32_e32 v22, v22, v251
	v_mul_f32_e32 v23, v23, v251
	v_mul_f32_e32 v24, v24, v251
	v_mul_f32_e32 v25, v25, v251
	v_cvt_pk_bf16_f32 v22, v22, v23
	v_cvt_pk_bf16_f32 v23, v24, v25
	v_lshl_add_u64 v[24:25], v[132:133], 1, v[26:27]
	global_store_dwordx2 v[24:25], v[22:23], off offset:64
	v_mov_b64_e32 v[22:23], s[20:21]
	v_mad_u64_u32 v[22:23], s[6:7], v34, s56, v[22:23]
	v_mad_i32_i24 v23, v35, s56, v23
	v_mul_f32_e32 v18, v18, v251
	v_mul_f32_e32 v19, v19, v251
	v_mul_f32_e32 v20, v20, v251
	v_mul_f32_e32 v21, v21, v251
	v_cvt_pk_bf16_f32 v18, v18, v19
	v_cvt_pk_bf16_f32 v19, v20, v21
	v_lshl_add_u64 v[20:21], v[132:133], 1, v[22:23]
	global_store_dwordx2 v[20:21], v[18:19], off offset:96
	v_mov_b64_e32 v[18:19], s[20:21]
	v_mad_u64_u32 v[18:19], s[6:7], v34, s56, v[18:19]
	v_mad_i32_i24 v19, v35, s56, v19
	v_mul_f32_e32 v14, v14, v251
	v_mul_f32_e32 v15, v15, v251
	v_mul_f32_e32 v16, v16, v251
	v_mul_f32_e32 v17, v17, v251
	v_cvt_pk_bf16_f32 v14, v14, v15
	v_cvt_pk_bf16_f32 v15, v16, v17
	v_lshl_add_u64 v[16:17], v[132:133], 1, v[18:19]
	global_store_dwordx2 v[16:17], v[14:15], off offset:128
	v_mov_b64_e32 v[14:15], s[20:21]
	v_mad_u64_u32 v[14:15], s[6:7], v34, s56, v[14:15]
	v_mad_i32_i24 v15, v35, s56, v15
	v_mul_f32_e32 v10, v10, v251
	v_mul_f32_e32 v11, v11, v251
	v_mul_f32_e32 v12, v12, v251
	v_mul_f32_e32 v13, v13, v251
	v_cvt_pk_bf16_f32 v10, v10, v11
	v_cvt_pk_bf16_f32 v11, v12, v13
	v_lshl_add_u64 v[12:13], v[132:133], 1, v[14:15]
	global_store_dwordx2 v[12:13], v[10:11], off offset:160
	v_mov_b64_e32 v[10:11], s[20:21]
	v_mad_u64_u32 v[10:11], s[6:7], v34, s56, v[10:11]
	v_mad_i32_i24 v11, v35, s56, v11
	v_mul_f32_e32 v6, v6, v251
	v_mul_f32_e32 v7, v7, v251
	v_mul_f32_e32 v8, v8, v251
	v_mul_f32_e32 v9, v9, v251
	v_cvt_pk_bf16_f32 v6, v6, v7
	v_cvt_pk_bf16_f32 v7, v8, v9
	v_lshl_add_u64 v[8:9], v[132:133], 1, v[10:11]
	global_store_dwordx2 v[8:9], v[6:7], off offset:192
	v_mov_b64_e32 v[6:7], s[20:21]
	v_mad_u64_u32 v[6:7], s[6:7], v34, s56, v[6:7]
	v_mad_i32_i24 v7, v35, s56, v7
	v_mul_f32_e32 v2, v2, v251
	v_mul_f32_e32 v3, v3, v251
	v_mul_f32_e32 v4, v4, v251
	v_mul_f32_e32 v5, v5, v251
	v_cvt_pk_bf16_f32 v2, v2, v3
	v_cvt_pk_bf16_f32 v3, v4, v5
	v_lshl_add_u64 v[4:5], v[132:133], 1, v[6:7]
	global_store_dwordx2 v[4:5], v[2:3], off offset:224
	s_branch .LBB0_1748

; #define GLDS16(gp, lp) __builtin_amdgcn_global_load_lds((const unsigned*)(gp), (__attribute__((address_space(3))) unsigned*)(lp), 16, 0, 0)
; template <bool SWAP, class Epi, bool THIN = false> ...
;     ...
;   for (; v < voff + ntiles; v += grid) {
;     const int w = v - voff;
;     int mt, nt;
;     if (w < full * 8 * NT) { const int sr = w / (8 * NT), rem = w - sr * 8 * NT; nt = rem >> 3; mt = sr * 8 + (rem & 7); }
;     else { const int w2 = w - full * 8 * NT, rl = MT - full * 8; nt = w2 / rl; mt = full * 8 + (w2 - nt * rl); }
;     unsigned ap[4], bp[4];
; #pragma unroll
;     for (int i = 0; i < 4; ++i) {
;       const int r = (tid >> 3) + 64 * i;
;       const int cs = tid & 7;
;       const int c = ((cs ^ ((r >> 1) & 7)) << 3);
;       const int sub = 2 * mt + (r >> 7);
;       const int g = sub / tpg, ti = sub - g * tpg;
;       int rig = ti * step - halo + (r & 127); rig = rig < 0 ? 0 : (rig > grows - 1 ? grows - 1 : rig);
;       ap[i] = (unsigned)((g * a_gstride + a_goff + rig) * lda + c);
;       int br = nt * 256 + r; br = br > N - 1 ? N - 1 : br;
;       bp[i] = (unsigned)(br * K + c);
;     }
;     const bool have_next = false;
;     f32x4 acc[4][8];
; #pragma unroll
;     for (int m = 0; m < 4; ++m)
; #pragma unroll
;       for (int n = 0; n < 8; ++n) acc[m][n] = (f32x4){0.f, 0.f, 0.f, 0.f};
;     if (!pre_issued) {
; #pragma unroll
;       for (int i = 0; i < 4; ++i) { GLDS16(A + (size_t)ap[i], smem + tid * 16 + i * 8192); GLDS16(Bt + (size_t)bp[i], smem + 32768 + tid * 16 + i * 8192); }
;     }
;     pre_issued = have_next;
;     for (int st = 0; st < ns; ++st) {
;       asm volatile("s_waitcnt vmcnt(0)" ::: "memory");
;       __builtin_amdgcn_s_barrier();
;       asm volatile("" ::: "memory");
;       if (st + 1 < ns) {
;         char* nb = smem + ((st + 1) & 1) * 65536;
;         const int ko = (st + 1) * 64;
; #pragma unroll
;         for (int i = 0; i < 4; ++i) { GLDS16(A + (size_t)(ap[i] + ko), nb + tid * 16 + i * 8192); GLDS16(Bt + (size_t)(bp[i] + ko), nb + 32768 + tid * 16 + i * 8192); }
.LBB0_1818:
	s_add_i32 s4, s33, 0xfffffe80
	s_ashr_i32 s5, s4, 31
	s_lshr_b32 s5, s5, 27
	s_add_i32 s4, s4, s5
	s_ashr_i32 s4, s4, 5
	s_lshl_b32 s5, s4, 4
	s_and_b32 s6, s38, 14
	s_or_b32 s5, s5, s6
	v_add_u32_e32 v2, s5, v139
	v_mul_hi_i32 v3, v2, s42
	v_lshrrev_b32_e32 v4, 31, v3
	v_ashrrev_i32_e32 v3, 2, v3
	v_add_u32_e32 v4, v3, v4
	v_mad_u64_u32 v[2:3], s[6:7], v4, s43, v[2:3]
	v_lshl_or_b32 v3, v2, 7, v140
	v_min_i32_e32 v3, 0x8ff, v3
	v_cmp_lt_i32_e32 vcc, -1, v2
	s_lshl_b32 s4, s4, 10
	s_sub_i32 s4, s40, s4
	v_cndmask_b32_e32 v2, 0, v3, vcc
	v_mad_u64_u32 v[2:3], s[6:7], v4, s44, v[2:3]
	s_and_b32 s4, s4, 0xffffff00
	v_mad_u64_u32 v[2:3], s[6:7], v2, s45, v[130:131]
	v_add_u32_e32 v3, s4, v131
	v_min_i32_e32 v3, 0x3ff, v3
	v_add_u32_e32 v4, s5, v142
	v_lshl_or_b32 v132, v3, 8, v130
	v_mul_hi_i32 v3, v4, s42
	v_lshrrev_b32_e32 v5, 31, v3
	v_ashrrev_i32_e32 v3, 2, v3
	v_add_u32_e32 v3, v3, v5
	v_mad_u64_u32 v[4:5], s[6:7], v3, s43, v[4:5]
	v_lshl_or_b32 v5, v4, 7, v143
	v_min_i32_e32 v5, 0x8ff, v5
	v_cmp_lt_i32_e32 vcc, -1, v4
	v_add_u32_e32 v6, s5, v145
	v_add_u32_e32 v8, s5, v147
	v_cndmask_b32_e32 v4, 0, v5, vcc
	v_mad_u64_u32 v[4:5], s[6:7], v3, s44, v[4:5]
	v_add_u32_e32 v3, s4, v141
	v_min_i32_e32 v3, 0x3ff, v3
	v_mad_u64_u32 v[4:5], s[6:7], v4, s45, v[130:131]
	v_lshl_or_b32 v12, v3, 8, v130
	v_mul_hi_i32 v3, v6, s42
	v_lshrrev_b32_e32 v5, 31, v3
	v_ashrrev_i32_e32 v3, 2, v3
	v_add_u32_e32 v3, v3, v5
	v_mad_u64_u32 v[6:7], s[6:7], v3, s43, v[6:7]
	v_lshl_or_b32 v5, v6, 7, v140
	v_min_i32_e32 v5, 0x8ff, v5
	v_cmp_lt_i32_e32 vcc, -1, v6
	v_readfirstlane_b32 s37, v138
	s_mov_b32 m0, s37
	v_cndmask_b32_e32 v6, 0, v5, vcc
	v_mad_u64_u32 v[6:7], s[6:7], v3, s44, v[6:7]
	v_add_u32_e32 v3, s4, v144
	v_min_i32_e32 v3, 0x3ff, v3
	v_lshl_or_b32 v14, v3, 8, v130
	v_mul_hi_i32 v3, v8, s42
	v_lshrrev_b32_e32 v5, 31, v3
	v_ashrrev_i32_e32 v3, 2, v3
	v_add_u32_e32 v3, v3, v5
	v_mad_u64_u32 v[8:9], s[6:7], v3, s43, v[8:9]
	v_lshl_or_b32 v5, v8, 7, v148
	v_min_i32_e32 v5, 0x8ff, v5
	v_cmp_lt_i32_e32 vcc, -1, v8
	v_readfirstlane_b32 s15, v149
	v_readfirstlane_b32 s14, v150
	v_cndmask_b32_e32 v8, 0, v5, vcc
	v_mad_u64_u32 v[8:9], s[6:7], v3, s44, v[8:9]
	v_add_u32_e32 v3, s4, v146
	v_min_i32_e32 v3, 0x3ff, v3
	v_lshl_or_b32 v16, v3, 8, v130
	v_mov_b32_e32 v3, v133
	v_lshl_add_u64 v[10:11], v[2:3], 1, s[28:29]
	global_load_lds_dwordx4 v[10:11], off
	v_lshl_add_u64 v[10:11], v[132:133], 1, s[20:21]
	s_mov_b32 m0, s15
	v_mov_b32_e32 v5, v133
	v_mad_u64_u32 v[6:7], s[6:7], v6, s45, v[130:131]
	global_load_lds_dwordx4 v[10:11], off
	v_lshl_add_u64 v[18:19], v[4:5], 1, s[28:29]
	s_mov_b32 m0, s14
	v_mov_b32_e32 v13, v133
	v_readfirstlane_b32 s17, v151
	global_load_lds_dwordx4 v[18:19], off
	v_lshl_add_u64 v[12:13], v[12:13], 1, s[20:21]
	s_mov_b32 m0, s17
	v_mov_b32_e32 v7, v133
	v_readfirstlane_b32 s16, v152
	v_mad_u64_u32 v[8:9], s[6:7], v8, s45, v[130:131]
	global_load_lds_dwordx4 v[12:13], off
	v_lshl_add_u64 v[18:19], v[6:7], 1, s[28:29]
	s_mov_b32 m0, s16
	v_mov_b32_e32 v15, v133
	v_readfirstlane_b32 s19, v153
	global_load_lds_dwordx4 v[18:19], off
	v_lshl_add_u64 v[14:15], v[14:15], 1, s[20:21]
	s_mov_b32 m0, s19
	v_mov_b32_e32 v9, v133
	v_readfirstlane_b32 s18, v154
	global_load_lds_dwordx4 v[14:15], off
	v_lshl_add_u64 v[18:19], v[8:9], 1, s[28:29]
	s_mov_b32 m0, s18
	v_mov_b32_e32 v17, v133
	v_readfirstlane_b32 s36, v155
	global_load_lds_dwordx4 v[18:19], off
	v_lshl_add_u64 v[16:17], v[16:17], 1, s[20:21]
	s_mov_b32 m0, s36
	v_add_u32_e32 v132, 64, v2
	global_load_lds_dwordx4 v[16:17], off
	v_readfirstlane_b32 s13, v156
	s_waitcnt vmcnt(0)
	s_barrier
	v_lshl_add_u64 v[18:19], v[132:133], 1, s[28:29]
	s_mov_b32 m0, s13
	v_readfirstlane_b32 s8, v157
	global_load_lds_dwordx4 v[18:19], off
	v_lshl_add_u64 v[18:19], v[10:11], 0, s[24:25]
	s_mov_b32 m0, s8
	v_add_u32_e32 v132, 64, v4
	v_readfirstlane_b32 s7, v158
	global_load_lds_dwordx4 v[18:19], off
	v_lshl_add_u64 v[18:19], v[132:133], 1, s[28:29]
	s_mov_b32 m0, s7
	v_readfirstlane_b32 s6, v159
	global_load_lds_dwordx4 v[18:19], off
	v_lshl_add_u64 v[18:19], v[12:13], 0, s[24:25]
	s_mov_b32 m0, s6
	v_add_u32_e32 v132, 64, v6
	v_readfirstlane_b32 s9, v160
	global_load_lds_dwordx4 v[18:19], off
	v_lshl_add_u64 v[18:19], v[132:133], 1, s[28:29]
	s_mov_b32 m0, s9
	v_readfirstlane_b32 s10, v161
	global_load_lds_dwordx4 v[18:19], off
	v_lshl_add_u64 v[18:19], v[14:15], 0, s[24:25]
	s_mov_b32 m0, s10
	v_add_u32_e32 v132, 64, v8
	v_readfirstlane_b32 s11, v162
	global_load_lds_dwordx4 v[18:19], off
	v_lshl_add_u64 v[18:19], v[132:133], 1, s[28:29]
	s_mov_b32 m0, s11
	v_readfirstlane_b32 s12, v163
	global_load_lds_dwordx4 v[18:19], off
	v_lshl_add_u64 v[18:19], v[16:17], 0, s[24:25]
	s_mov_b32 m0, s12
	s_nop 0
	global_load_lds_dwordx4 v[18:19], off
	ds_read_b128 v[18:21], v164
	ds_read_b128 v[22:25], v164 offset:2048
	ds_read_b128 v[26:29], v164 offset:4096
	ds_read_b128 v[30:33], v164 offset:6144
	ds_read_b128 v[34:37], v165 offset:32768
	ds_read_b128 v[38:41], v165 offset:34816
	ds_read_b128 v[42:45], v165 offset:36864
	ds_read_b128 v[46:49], v165 offset:38912
	ds_read_b128 v[74:77], v165 offset:40960
	ds_read_b128 v[78:81], v165 offset:43008
	s_waitcnt lgkmcnt(0)
; template <bool SWAP, class Epi, bool THIN = false> ...
;     ...
;       bf16x8 afA[4], afB[4], bfb[2][2];
; #pragma unroll
;       for (int m = 0; m < 4; ++m) afA[m] = *(const bf16x8*)(sa + m * 2048 + ((fq ^ swz) << 4));
; #pragma unroll
;       for (int n = 0; n < 2; ++n) bfb[0][n] = *(const bf16x8*)(sb + n * 2048 + ((fq ^ swz) << 4));
; #pragma unroll
;       for (int gq = 0; gq < 8; ++gq) {
;         const int ks = gq >> 2, nh = gq & 3;
;         if (gq < 7) {
;           const int ks2 = (gq + 1) >> 2, nh2 = (gq + 1) & 3;
; #pragma unroll
;           for (int n = 0; n < 2; ++n) bfb[(gq + 1) & 1][n] = *(const bf16x8*)(sb + (nh2 * 2 + n) * 2048 + (((ks2 * 4 + fq) ^ swz) << 4));
;         }
;         if (gq == 3) {
; #pragma unroll
;           for (int m = 0; m < 4; ++m) afB[m] = *(const bf16x8*)(sa + m * 2048 + (((4 + fq) ^ swz) << 4));
;         }
;         __builtin_amdgcn_sched_barrier(0);
; #pragma unroll
;         for (int m = 0; m < 4; ++m)
; #pragma unroll
;           for (int n = 0; n < 2; ++n) {
;             const bf16x8 av = ks ? afB[m] : afA[m];
;             acc[m][nh * 2 + n] = SWAP ? __builtin_amdgcn_mfma_f32_16x16x32_bf16(bfb[gq & 1][n], av, acc[m][nh * 2 + n], 0, 0, 0)
;                                       : __builtin_amdgcn_mfma_f32_16x16x32_bf16(av, bfb[gq & 1][n], acc[m][nh * 2 + n], 0, 0, 0);
;           }
;       }
	v_mfma_f32_16x16x32_bf16 v[50:53], v[34:37], v[18:21], 0
	v_mfma_f32_16x16x32_bf16 v[54:57], v[38:41], v[18:21], 0
	v_mfma_f32_16x16x32_bf16 v[58:61], v[34:37], v[22:25], 0
	v_mfma_f32_16x16x32_bf16 v[62:65], v[38:41], v[22:25], 0
	v_mfma_f32_16x16x32_bf16 v[66:69], v[34:37], v[26:29], 0
	v_mfma_f32_16x16x32_bf16 v[70:73], v[38:41], v[26:29], 0
	v_mfma_f32_16x16x32_bf16 v[34:37], v[34:37], v[30:33], 0
	v_mfma_f32_16x16x32_bf16 v[38:41], v[38:41], v[30:33], 0
	ds_read_b128 v[106:109], v165 offset:45056
	ds_read_b128 v[110:113], v165 offset:47104
	v_mfma_f32_16x16x32_bf16 v[82:85], v[42:45], v[18:21], 0
	v_mfma_f32_16x16x32_bf16 v[86:89], v[46:49], v[18:21], 0
	v_mfma_f32_16x16x32_bf16 v[90:93], v[42:45], v[22:25], 0
	v_mfma_f32_16x16x32_bf16 v[94:97], v[46:49], v[22:25], 0
	v_mfma_f32_16x16x32_bf16 v[98:101], v[42:45], v[26:29], 0
	v_mfma_f32_16x16x32_bf16 v[102:105], v[46:49], v[26:29], 0
	v_mfma_f32_16x16x32_bf16 v[42:45], v[42:45], v[30:33], 0
	v_mfma_f32_16x16x32_bf16 v[46:49], v[46:49], v[30:33], 0
	ds_read_b128 v[178:181], v166 offset:32768
	ds_read_b128 v[182:185], v166 offset:34816
	ds_read_b128 v[186:189], v167
	ds_read_b128 v[190:193], v167 offset:2048
	ds_read_b128 v[194:197], v167 offset:4096
	ds_read_b128 v[198:201], v167 offset:6144
	v_mfma_f32_16x16x32_bf16 v[114:117], v[74:77], v[18:21], 0
	v_mfma_f32_16x16x32_bf16 v[118:121], v[78:81], v[18:21], 0
	v_mfma_f32_16x16x32_bf16 v[122:125], v[74:77], v[22:25], 0
	v_mfma_f32_16x16x32_bf16 v[126:129], v[78:81], v[22:25], 0
	v_mfma_f32_16x16x32_bf16 v[134:137], v[74:77], v[26:29], 0
	v_mfma_f32_16x16x32_bf16 v[174:177], v[78:81], v[26:29], 0
	v_mfma_f32_16x16x32_bf16 v[74:77], v[74:77], v[30:33], 0
	v_mfma_f32_16x16x32_bf16 v[78:81], v[78:81], v[30:33], 0
	ds_read_b128 v[214:217], v166 offset:36864
	ds_read_b128 v[218:221], v166 offset:38912
	s_waitcnt lgkmcnt(0)
	v_mfma_f32_16x16x32_bf16 v[202:205], v[106:109], v[18:21], 0
	v_mfma_f32_16x16x32_bf16 v[18:21], v[110:113], v[18:21], 0
	v_mfma_f32_16x16x32_bf16 v[206:209], v[106:109], v[22:25], 0
	v_mfma_f32_16x16x32_bf16 v[22:25], v[110:113], v[22:25], 0
	v_mfma_f32_16x16x32_bf16 v[210:213], v[106:109], v[26:29], 0
	v_mfma_f32_16x16x32_bf16 v[26:29], v[110:113], v[26:29], 0
	v_mfma_f32_16x16x32_bf16 v[106:109], v[106:109], v[30:33], 0
	v_mfma_f32_16x16x32_bf16 v[30:33], v[110:113], v[30:33], 0
	v_mfma_f32_16x16x32_bf16 v[50:53], v[178:181], v[186:189], v[50:53]
	v_mfma_f32_16x16x32_bf16 v[58:61], v[178:181], v[190:193], v[58:61]
	v_mfma_f32_16x16x32_bf16 v[66:69], v[178:181], v[194:197], v[66:69]
	v_mfma_f32_16x16x32_bf16 v[34:37], v[178:181], v[198:201], v[34:37]
	ds_read_b128 v[110:113], v166 offset:40960
	ds_read_b128 v[178:181], v166 offset:43008
	v_mfma_f32_16x16x32_bf16 v[54:57], v[182:185], v[186:189], v[54:57]
	v_mfma_f32_16x16x32_bf16 v[62:65], v[182:185], v[190:193], v[62:65]
	v_mfma_f32_16x16x32_bf16 v[70:73], v[182:185], v[194:197], v[70:73]
	v_mfma_f32_16x16x32_bf16 v[38:41], v[182:185], v[198:201], v[38:41]
	v_mfma_f32_16x16x32_bf16 v[82:85], v[214:217], v[186:189], v[82:85]
	v_mfma_f32_16x16x32_bf16 v[90:93], v[214:217], v[190:193], v[90:93]
	v_mfma_f32_16x16x32_bf16 v[98:101], v[214:217], v[194:197], v[98:101]
	v_mfma_f32_16x16x32_bf16 v[42:45], v[214:217], v[198:201], v[42:45]
	ds_read_b128 v[182:185], v166 offset:45056
	ds_read_b128 v[214:217], v166 offset:47104
	v_mfma_f32_16x16x32_bf16 v[86:89], v[218:221], v[186:189], v[86:89]
	v_mfma_f32_16x16x32_bf16 v[94:97], v[218:221], v[190:193], v[94:97]
	v_mfma_f32_16x16x32_bf16 v[102:105], v[218:221], v[194:197], v[102:105]
	v_mfma_f32_16x16x32_bf16 v[46:49], v[218:221], v[198:201], v[46:49]
	s_waitcnt lgkmcnt(0)
	v_mfma_f32_16x16x32_bf16 v[114:117], v[110:113], v[186:189], v[114:117]
	v_mfma_f32_16x16x32_bf16 v[118:121], v[178:181], v[186:189], v[118:121]
	v_mfma_f32_16x16x32_bf16 v[122:125], v[110:113], v[190:193], v[122:125]
	v_mfma_f32_16x16x32_bf16 v[126:129], v[178:181], v[190:193], v[126:129]
	v_mfma_f32_16x16x32_bf16 v[134:137], v[110:113], v[194:197], v[134:137]
	v_mfma_f32_16x16x32_bf16 v[74:77], v[110:113], v[198:201], v[74:77]
	v_mfma_f32_16x16x32_bf16 v[78:81], v[178:181], v[198:201], v[78:81]
	v_mfma_f32_16x16x32_bf16 v[174:177], v[178:181], v[194:197], v[174:177]
	v_add_u32_e32 v132, 0x80, v2
	s_mov_b32 m0, s37
	v_mfma_f32_16x16x32_bf16 v[110:113], v[182:185], v[186:189], v[202:205]
	s_waitcnt vmcnt(0)
	s_barrier
; template <bool SWAP, class Epi, bool THIN = false> ...
;     ...
;     for (int st = 0; st < ns; ++st) {
;       asm volatile("s_waitcnt vmcnt(0)" ::: "memory");
;       __builtin_amdgcn_s_barrier();
;       asm volatile("" ::: "memory");
;       if (st + 1 < ns) {
;         char* nb = smem + ((st + 1) & 1) * 65536;
;         const int ko = (st + 1) * 64;
; #pragma unroll
;         for (int i = 0; i < 4; ++i) { GLDS16(A + (size_t)(ap[i] + ko), nb + tid * 16 + i * 8192); GLDS16(Bt + (size_t)(bp[i] + ko), nb + 32768 + tid * 16 + i * 8192); }
;       }
;       const char* sa = smem + (st & 1) * 65536 + (wr * 64 + fr) * 128;
;       const char* sb = smem + (st & 1) * 65536 + 32768 + (wc * 128 + fr) * 128;
;       if constexpr (THIN) {
;         if (wc == 0) {
; #pragma unroll
;           for (int ks = 0; ks < 2; ++ks) {
;             bf16x8 af[4], bf[2];
; #pragma unroll
;             for (int m = 0; m < 4; ++m) af[m] = *(const bf16x8*)(sa + m * 2048 + (((ks * 4 + fq) ^ swz) << 4));
; #pragma unroll
;             for (int n = 0; n < 2; ++n) bf[n] = *(const bf16x8*)(sb + n * 2048 + (((ks * 4 + fq) ^ swz) << 4));
; #pragma unroll
;             for (int m = 0; m < 4; ++m)
; #pragma unroll
;               for (int n = 0; n < 2; ++n)
;                 acc[m][n] = SWAP ? __builtin_amdgcn_mfma_f32_16x16x32_bf16(bf[n], af[m], acc[m][n], 0, 0, 0)
;                                  : __builtin_amdgcn_mfma_f32_16x16x32_bf16(af[m], bf[n], acc[m][n], 0, 0, 0);
;           }
;         }
;       } else {
;       bf16x8 afA[4], afB[4], bfb[2][2];
; #pragma unroll
;       for (int m = 0; m < 4; ++m) afA[m] = *(const bf16x8*)(sa + m * 2048 + ((fq ^ swz) << 4));
; #pragma unroll
;       for (int n = 0; n < 2; ++n) bfb[0][n] = *(const bf16x8*)(sb + n * 2048 + ((fq ^ swz) << 4));
; #pragma unroll
;       for (int gq = 0; gq < 8; ++gq) {
;         const int ks = gq >> 2, nh = gq & 3;
;         if (gq < 7) {
;           const int ks2 = (gq + 1) >> 2, nh2 = (gq + 1) & 3;
; #pragma unroll
;           for (int n = 0; n < 2; ++n) bfb[(gq + 1) & 1][n] = *(const bf16x8*)(sb + (nh2 * 2 + n) * 2048 + (((ks2 * 4 + fq) ^ swz) << 4));
;         }
;         if (gq == 3) {
; #pragma unroll
;           for (int m = 0; m < 4; ++m) afB[m] = *(const bf16x8*)(sa + m * 2048 + (((4 + fq) ^ swz) << 4));
;         }
;         __builtin_amdgcn_sched_barrier(0);
; #pragma unroll
	v_mfma_f32_16x16x32_bf16 v[18:21], v[214:217], v[186:189], v[18:21]
	v_lshl_add_u64 v[186:187], v[132:133], 1, s[28:29]
	global_load_lds_dwordx4 v[186:187], off
	v_lshl_add_u64 v[186:187], v[10:11], 0, s[30:31]
	s_mov_b32 m0, s15
	v_add_u32_e32 v132, 0x80, v4
	v_mfma_f32_16x16x32_bf16 v[178:181], v[182:185], v[190:193], v[206:209]
	global_load_lds_dwordx4 v[186:187], off
	s_mov_b32 m0, s14
	v_mfma_f32_16x16x32_bf16 v[22:25], v[214:217], v[190:193], v[22:25]
	v_lshl_add_u64 v[190:191], v[132:133], 1, s[28:29]
	global_load_lds_dwordx4 v[190:191], off
	v_lshl_add_u64 v[190:191], v[12:13], 0, s[30:31]
	s_mov_b32 m0, s17
	v_add_u32_e32 v132, 0x80, v6
	global_load_lds_dwordx4 v[190:191], off
	v_lshl_add_u64 v[190:191], v[132:133], 1, s[28:29]
	s_mov_b32 m0, s16
	v_add_u32_e32 v132, 0x80, v8
	global_load_lds_dwordx4 v[190:191], off
	v_lshl_add_u64 v[190:191], v[14:15], 0, s[30:31]
	s_mov_b32 m0, s19
	v_mfma_f32_16x16x32_bf16 v[186:189], v[182:185], v[194:197], v[210:213]
	global_load_lds_dwordx4 v[190:191], off
	v_lshl_add_u64 v[190:191], v[132:133], 1, s[28:29]
	s_mov_b32 m0, s18
	v_mfma_f32_16x16x32_bf16 v[26:29], v[214:217], v[194:197], v[26:29]
	global_load_lds_dwordx4 v[190:191], off
	v_lshl_add_u64 v[190:191], v[16:17], 0, s[30:31]
	s_mov_b32 m0, s36
	v_mfma_f32_16x16x32_bf16 v[106:109], v[182:185], v[198:201], v[106:109]
	global_load_lds_dwordx4 v[190:191], off
	ds_read_b128 v[182:185], v168
	ds_read_b128 v[190:193], v168 offset:2048
	ds_read_b128 v[194:197], v168 offset:4096
	ds_read_b128 v[202:205], v168 offset:6144
	ds_read_b128 v[206:209], v169
	ds_read_b128 v[210:213], v169 offset:2048
	ds_read_b128 v[218:221], v169 offset:4096
	ds_read_b128 v[222:225], v169 offset:6144
	v_mfma_f32_16x16x32_bf16 v[30:33], v[214:217], v[198:201], v[30:33]
	s_waitcnt lgkmcnt(0)
	v_mfma_f32_16x16x32_bf16 v[50:53], v[206:209], v[182:185], v[50:53]
	v_mfma_f32_16x16x32_bf16 v[58:61], v[206:209], v[190:193], v[58:61]
	v_mfma_f32_16x16x32_bf16 v[66:69], v[206:209], v[194:197], v[66:69]
	v_mfma_f32_16x16x32_bf16 v[34:37], v[206:209], v[202:205], v[34:37]
	ds_read_b128 v[198:201], v169 offset:8192
	ds_read_b128 v[206:209], v169 offset:10240
	v_mfma_f32_16x16x32_bf16 v[54:57], v[210:213], v[182:185], v[54:57]
	v_mfma_f32_16x16x32_bf16 v[62:65], v[210:213], v[190:193], v[62:65]
	v_mfma_f32_16x16x32_bf16 v[70:73], v[210:213], v[194:197], v[70:73]
	v_mfma_f32_16x16x32_bf16 v[38:41], v[210:213], v[202:205], v[38:41]
	ds_read_b128 v[210:213], v169 offset:12288
	ds_read_b128 v[214:217], v169 offset:14336
	v_mfma_f32_16x16x32_bf16 v[82:85], v[218:221], v[182:185], v[82:85]
	v_mfma_f32_16x16x32_bf16 v[86:89], v[222:225], v[182:185], v[86:89]
	v_mfma_f32_16x16x32_bf16 v[90:93], v[218:221], v[190:193], v[90:93]
	v_mfma_f32_16x16x32_bf16 v[94:97], v[222:225], v[190:193], v[94:97]
	v_mfma_f32_16x16x32_bf16 v[98:101], v[218:221], v[194:197], v[98:101]
	v_mfma_f32_16x16x32_bf16 v[102:105], v[222:225], v[194:197], v[102:105]
	v_mfma_f32_16x16x32_bf16 v[42:45], v[218:221], v[202:205], v[42:45]
	v_mfma_f32_16x16x32_bf16 v[46:49], v[222:225], v[202:205], v[46:49]
	s_waitcnt lgkmcnt(0)
	v_mfma_f32_16x16x32_bf16 v[114:117], v[198:201], v[182:185], v[114:117]
	ds_read_b128 v[218:221], v170
	ds_read_b128 v[222:225], v170 offset:2048
	v_mfma_f32_16x16x32_bf16 v[122:125], v[198:201], v[190:193], v[122:125]
	v_mfma_f32_16x16x32_bf16 v[134:137], v[198:201], v[194:197], v[134:137]
	v_mfma_f32_16x16x32_bf16 v[74:77], v[198:201], v[202:205], v[74:77]
	ds_read_b128 v[198:201], v171
	ds_read_b128 v[226:229], v171 offset:2048
	ds_read_b128 v[230:233], v171 offset:4096
	ds_read_b128 v[234:237], v171 offset:6144
	v_mfma_f32_16x16x32_bf16 v[118:121], v[206:209], v[182:185], v[118:121]
	v_mfma_f32_16x16x32_bf16 v[126:129], v[206:209], v[190:193], v[126:129]
	v_mfma_f32_16x16x32_bf16 v[78:81], v[206:209], v[202:205], v[78:81]
	v_mfma_f32_16x16x32_bf16 v[174:177], v[206:209], v[194:197], v[174:177]
	v_mfma_f32_16x16x32_bf16 v[110:113], v[210:213], v[182:185], v[110:113]
	v_mfma_f32_16x16x32_bf16 v[18:21], v[214:217], v[182:185], v[18:21]
	v_mfma_f32_16x16x32_bf16 v[178:181], v[210:213], v[190:193], v[178:181]
	v_mfma_f32_16x16x32_bf16 v[22:25], v[214:217], v[190:193], v[22:25]
	v_mfma_f32_16x16x32_bf16 v[182:185], v[210:213], v[194:197], v[186:189]
	s_nop 2
	ds_read_b128 v[186:189], v170 offset:4096
	ds_read_b128 v[190:193], v170 offset:6144
	v_mfma_f32_16x16x32_bf16 v[26:29], v[214:217], v[194:197], v[26:29]
	v_mfma_f32_16x16x32_bf16 v[106:109], v[210:213], v[202:205], v[106:109]
	v_mfma_f32_16x16x32_bf16 v[30:33], v[214:217], v[202:205], v[30:33]
	ds_read_b128 v[194:197], v170 offset:8192
	ds_read_b128 v[202:205], v170 offset:10240
	s_waitcnt lgkmcnt(0)
	v_mfma_f32_16x16x32_bf16 v[50:53], v[218:221], v[198:201], v[50:53]
	v_mfma_f32_16x16x32_bf16 v[54:57], v[222:225], v[198:201], v[54:57]
	v_mfma_f32_16x16x32_bf16 v[58:61], v[218:221], v[226:229], v[58:61]
	v_mfma_f32_16x16x32_bf16 v[62:65], v[222:225], v[226:229], v[62:65]
	v_mfma_f32_16x16x32_bf16 v[66:69], v[218:221], v[230:233], v[66:69]
	v_mfma_f32_16x16x32_bf16 v[70:73], v[222:225], v[230:233], v[70:73]
	v_mfma_f32_16x16x32_bf16 v[34:37], v[218:221], v[234:237], v[34:37]
	v_mfma_f32_16x16x32_bf16 v[38:41], v[222:225], v[234:237], v[38:41]
	v_mfma_f32_16x16x32_bf16 v[82:85], v[186:189], v[198:201], v[82:85]
	v_mfma_f32_16x16x32_bf16 v[90:93], v[186:189], v[226:229], v[90:93]
	v_mfma_f32_16x16x32_bf16 v[98:101], v[186:189], v[230:233], v[98:101]
	v_mfma_f32_16x16x32_bf16 v[42:45], v[186:189], v[234:237], v[42:45]
	ds_read_b128 v[186:189], v170 offset:12288
	ds_read_b128 v[206:209], v170 offset:14336
	v_mfma_f32_16x16x32_bf16 v[86:89], v[190:193], v[198:201], v[86:89]
	v_mfma_f32_16x16x32_bf16 v[94:97], v[190:193], v[226:229], v[94:97]
	v_mfma_f32_16x16x32_bf16 v[102:105], v[190:193], v[230:233], v[102:105]
	v_mfma_f32_16x16x32_bf16 v[46:49], v[190:193], v[234:237], v[46:49]
	v_mfma_f32_16x16x32_bf16 v[114:117], v[194:197], v[198:201], v[114:117]
	v_mfma_f32_16x16x32_bf16 v[118:121], v[202:205], v[198:201], v[118:121]
	v_mfma_f32_16x16x32_bf16 v[122:125], v[194:197], v[226:229], v[122:125]
	v_mfma_f32_16x16x32_bf16 v[126:129], v[202:205], v[226:229], v[126:129]
	v_mfma_f32_16x16x32_bf16 v[134:137], v[194:197], v[230:233], v[134:137]
	v_mfma_f32_16x16x32_bf16 v[74:77], v[194:197], v[234:237], v[74:77]
	v_mfma_f32_16x16x32_bf16 v[78:81], v[202:205], v[234:237], v[78:81]
	v_mfma_f32_16x16x32_bf16 v[174:177], v[202:205], v[230:233], v[174:177]
	v_add_u32_e32 v132, 0xc0, v2
	s_mov_b32 m0, s13
	s_waitcnt vmcnt(0)
	s_barrier
; template <bool SWAP, class Epi, bool THIN = false> ...
;     ...
;     for (int st = 0; st < ns; ++st) {
;       asm volatile("s_waitcnt vmcnt(0)" ::: "memory");
;       __builtin_amdgcn_s_barrier();
;       asm volatile("" ::: "memory");
;       if (st + 1 < ns) {
;         char* nb = smem + ((st + 1) & 1) * 65536;
;         const int ko = (st + 1) * 64;
; #pragma unroll
;         for (int i = 0; i < 4; ++i) { GLDS16(A + (size_t)(ap[i] + ko), nb + tid * 16 + i * 8192); GLDS16(Bt + (size_t)(bp[i] + ko), nb + 32768 + tid * 16 + i * 8192); }
;       }
;       const char* sa = smem + (st & 1) * 65536 + (wr * 64 + fr) * 128;
;       const char* sb = smem + (st & 1) * 65536 + 32768 + (wc * 128 + fr) * 128;
;       if constexpr (THIN) {
;         if (wc == 0) {
; #pragma unroll
;           for (int ks = 0; ks < 2; ++ks) {
;             bf16x8 af[4], bf[2];
; #pragma unroll
;             for (int m = 0; m < 4; ++m) af[m] = *(const bf16x8*)(sa + m * 2048 + (((ks * 4 + fq) ^ swz) << 4));
; #pragma unroll
;             for (int n = 0; n < 2; ++n) bf[n] = *(const bf16x8*)(sb + n * 2048 + (((ks * 4 + fq) ^ swz) << 4));
; #pragma unroll
;             for (int m = 0; m < 4; ++m)
; #pragma unroll
;               for (int n = 0; n < 2; ++n)
;                 acc[m][n] = SWAP ? __builtin_amdgcn_mfma_f32_16x16x32_bf16(bf[n], af[m], acc[m][n], 0, 0, 0)
;                                  : __builtin_amdgcn_mfma_f32_16x16x32_bf16(af[m], bf[n], acc[m][n], 0, 0, 0);
;           }
;         }
;       } else {
;       bf16x8 afA[4], afB[4], bfb[2][2];
; #pragma unroll
;       for (int m = 0; m < 4; ++m) afA[m] = *(const bf16x8*)(sa + m * 2048 + ((fq ^ swz) << 4));
; #pragma unroll
;       for (int n = 0; n < 2; ++n) bfb[0][n] = *(const bf16x8*)(sb + n * 2048 + ((fq ^ swz) << 4));
; #pragma unroll
;       for (int gq = 0; gq < 8; ++gq) {
;         const int ks = gq >> 2, nh = gq & 3;
;         if (gq < 7) {
;           const int ks2 = (gq + 1) >> 2, nh2 = (gq + 1) & 3;
; #pragma unroll
;           for (int n = 0; n < 2; ++n) bfb[(gq + 1) & 1][n] = *(const bf16x8*)(sb + (nh2 * 2 + n) * 2048 + (((ks2 * 4 + fq) ^ swz) << 4));
;         }
;         if (gq == 3) {
; #pragma unroll
;           for (int m = 0; m < 4; ++m) afB[m] = *(const bf16x8*)(sa + m * 2048 + (((4 + fq) ^ swz) << 4));
;         }
;         __builtin_amdgcn_sched_barrier(0);
; #pragma unroll
	v_lshl_add_u64 v[2:3], v[132:133], 1, s[28:29]
	global_load_lds_dwordx4 v[2:3], off
	v_lshl_add_u64 v[2:3], v[10:11], 0, s[34:35]
	s_mov_b32 m0, s8
	v_add_u32_e32 v132, 0xc0, v4
	global_load_lds_dwordx4 v[2:3], off
	v_lshl_add_u64 v[10:11], v[132:133], 1, s[28:29]
	s_mov_b32 m0, s7
	v_add_u32_e32 v132, 0xc0, v6
	global_load_lds_dwordx4 v[10:11], off
	v_lshl_add_u64 v[10:11], v[12:13], 0, s[34:35]
	s_mov_b32 m0, s6
	v_lshl_add_u64 v[6:7], v[132:133], 1, s[28:29]
	global_load_lds_dwordx4 v[10:11], off
	s_mov_b32 m0, s9
	v_add_u32_e32 v132, 0xc0, v8
	global_load_lds_dwordx4 v[6:7], off
	v_lshl_add_u64 v[6:7], v[14:15], 0, s[34:35]
	s_mov_b32 m0, s10
	s_waitcnt lgkmcnt(0)
	v_mfma_f32_16x16x32_bf16 v[110:113], v[186:189], v[198:201], v[110:113]
	global_load_lds_dwordx4 v[6:7], off
	v_lshl_add_u64 v[6:7], v[132:133], 1, s[28:29]
	s_mov_b32 m0, s11
	v_mfma_f32_16x16x32_bf16 v[18:21], v[206:209], v[198:201], v[18:21]
	global_load_lds_dwordx4 v[6:7], off
	v_lshl_add_u64 v[6:7], v[16:17], 0, s[34:35]
	s_mov_b32 m0, s12
	v_mfma_f32_16x16x32_bf16 v[178:181], v[186:189], v[226:229], v[178:181]
	global_load_lds_dwordx4 v[6:7], off
	v_mfma_f32_16x16x32_bf16 v[2:5], v[186:189], v[230:233], v[182:185]
	v_mfma_f32_16x16x32_bf16 v[6:9], v[186:189], v[234:237], v[106:109]
	ds_read_b128 v[10:13], v164
	ds_read_b128 v[14:17], v164 offset:2048
	s_nop 0
	ds_read_b128 v[106:109], v164 offset:4096
	ds_read_b128 v[182:185], v164 offset:6144
	ds_read_b128 v[186:189], v165 offset:32768
	ds_read_b128 v[190:193], v165 offset:34816
	ds_read_b128 v[194:197], v165 offset:36864
	ds_read_b128 v[198:201], v165 offset:38912
	v_mfma_f32_16x16x32_bf16 v[22:25], v[206:209], v[226:229], v[22:25]
	v_mfma_f32_16x16x32_bf16 v[26:29], v[206:209], v[230:233], v[26:29]
	v_mfma_f32_16x16x32_bf16 v[30:33], v[206:209], v[234:237], v[30:33]
	s_waitcnt lgkmcnt(0)
	v_mfma_f32_16x16x32_bf16 v[50:53], v[186:189], v[10:13], v[50:53]
	v_mfma_f32_16x16x32_bf16 v[58:61], v[186:189], v[14:17], v[58:61]
	v_mfma_f32_16x16x32_bf16 v[66:69], v[186:189], v[106:109], v[66:69]
	v_mfma_f32_16x16x32_bf16 v[34:37], v[186:189], v[182:185], v[34:37]
	ds_read_b128 v[186:189], v165 offset:40960
	ds_read_b128 v[202:205], v165 offset:43008
	v_mfma_f32_16x16x32_bf16 v[54:57], v[190:193], v[10:13], v[54:57]
	v_mfma_f32_16x16x32_bf16 v[62:65], v[190:193], v[14:17], v[62:65]
	v_mfma_f32_16x16x32_bf16 v[70:73], v[190:193], v[106:109], v[70:73]
	v_mfma_f32_16x16x32_bf16 v[38:41], v[190:193], v[182:185], v[38:41]
	v_mfma_f32_16x16x32_bf16 v[82:85], v[194:197], v[10:13], v[82:85]
	v_mfma_f32_16x16x32_bf16 v[90:93], v[194:197], v[14:17], v[90:93]
	v_mfma_f32_16x16x32_bf16 v[98:101], v[194:197], v[106:109], v[98:101]
	v_mfma_f32_16x16x32_bf16 v[42:45], v[194:197], v[182:185], v[42:45]
	ds_read_b128 v[190:193], v165 offset:45056
	ds_read_b128 v[194:197], v165 offset:47104
	v_mfma_f32_16x16x32_bf16 v[86:89], v[198:201], v[10:13], v[86:89]
	v_mfma_f32_16x16x32_bf16 v[94:97], v[198:201], v[14:17], v[94:97]
	v_mfma_f32_16x16x32_bf16 v[102:105], v[198:201], v[106:109], v[102:105]
	v_mfma_f32_16x16x32_bf16 v[46:49], v[198:201], v[182:185], v[46:49]
	s_waitcnt lgkmcnt(0)
	v_mfma_f32_16x16x32_bf16 v[114:117], v[186:189], v[10:13], v[114:117]
	ds_read_b128 v[198:201], v166 offset:32768
	ds_read_b128 v[206:209], v166 offset:34816
	v_mfma_f32_16x16x32_bf16 v[122:125], v[186:189], v[14:17], v[122:125]
	v_mfma_f32_16x16x32_bf16 v[134:137], v[186:189], v[106:109], v[134:137]
	v_mfma_f32_16x16x32_bf16 v[74:77], v[186:189], v[182:185], v[74:77]
	ds_read_b128 v[186:189], v167
	ds_read_b128 v[210:213], v167 offset:2048
	ds_read_b128 v[214:217], v167 offset:4096
	ds_read_b128 v[218:221], v167 offset:6144
	v_mfma_f32_16x16x32_bf16 v[118:121], v[202:205], v[10:13], v[118:121]
	v_mfma_f32_16x16x32_bf16 v[126:129], v[202:205], v[14:17], v[126:129]
	v_mfma_f32_16x16x32_bf16 v[78:81], v[202:205], v[182:185], v[78:81]
	v_mfma_f32_16x16x32_bf16 v[174:177], v[202:205], v[106:109], v[174:177]
	v_mfma_f32_16x16x32_bf16 v[110:113], v[190:193], v[10:13], v[110:113]
	v_mfma_f32_16x16x32_bf16 v[10:13], v[194:197], v[10:13], v[18:21]
	v_mfma_f32_16x16x32_bf16 v[18:21], v[190:193], v[14:17], v[178:181]
	v_mfma_f32_16x16x32_bf16 v[14:17], v[194:197], v[14:17], v[22:25]
	v_mfma_f32_16x16x32_bf16 v[2:5], v[190:193], v[106:109], v[2:5]
	v_mfma_f32_16x16x32_bf16 v[22:25], v[194:197], v[106:109], v[26:29]
	s_nop 2
	ds_read_b128 v[26:29], v166 offset:36864
	ds_read_b128 v[106:109], v166 offset:38912
	v_mfma_f32_16x16x32_bf16 v[6:9], v[190:193], v[182:185], v[6:9]
	v_mfma_f32_16x16x32_bf16 v[30:33], v[194:197], v[182:185], v[30:33]
	ds_read_b128 v[178:181], v166 offset:40960
	ds_read_b128 v[182:185], v166 offset:43008
	s_waitcnt lgkmcnt(0)
	v_mfma_f32_16x16x32_bf16 v[50:53], v[198:201], v[186:189], v[50:53]
	v_mfma_f32_16x16x32_bf16 v[54:57], v[206:209], v[186:189], v[54:57]
	v_mfma_f32_16x16x32_bf16 v[58:61], v[198:201], v[210:213], v[58:61]
	v_mfma_f32_16x16x32_bf16 v[62:65], v[206:209], v[210:213], v[62:65]
	v_mfma_f32_16x16x32_bf16 v[66:69], v[198:201], v[214:217], v[66:69]
	v_mfma_f32_16x16x32_bf16 v[70:73], v[206:209], v[214:217], v[70:73]
	v_mfma_f32_16x16x32_bf16 v[34:37], v[198:201], v[218:221], v[34:37]
	v_mfma_f32_16x16x32_bf16 v[38:41], v[206:209], v[218:221], v[38:41]
	v_mfma_f32_16x16x32_bf16 v[82:85], v[26:29], v[186:189], v[82:85]
	v_mfma_f32_16x16x32_bf16 v[90:93], v[26:29], v[210:213], v[90:93]
	v_mfma_f32_16x16x32_bf16 v[98:101], v[26:29], v[214:217], v[98:101]
	v_mfma_f32_16x16x32_bf16 v[26:29], v[26:29], v[218:221], v[42:45]
	s_nop 2
	ds_read_b128 v[42:45], v166 offset:45056
	ds_read_b128 v[190:193], v166 offset:47104
	v_mfma_f32_16x16x32_bf16 v[86:89], v[106:109], v[186:189], v[86:89]
	v_mfma_f32_16x16x32_bf16 v[94:97], v[106:109], v[210:213], v[94:97]
	v_mfma_f32_16x16x32_bf16 v[102:105], v[106:109], v[214:217], v[102:105]
	v_mfma_f32_16x16x32_bf16 v[46:49], v[106:109], v[218:221], v[46:49]
	v_mfma_f32_16x16x32_bf16 v[106:109], v[178:181], v[186:189], v[114:117]
	v_mfma_f32_16x16x32_bf16 v[114:117], v[182:185], v[186:189], v[118:121]
	v_mfma_f32_16x16x32_bf16 v[118:121], v[178:181], v[210:213], v[122:125]
	v_mfma_f32_16x16x32_bf16 v[122:125], v[182:185], v[210:213], v[126:129]
	v_mfma_f32_16x16x32_bf16 v[126:129], v[178:181], v[214:217], v[134:137]
	v_mfma_f32_16x16x32_bf16 v[134:137], v[182:185], v[214:217], v[174:177]
	v_mfma_f32_16x16x32_bf16 v[74:77], v[178:181], v[218:221], v[74:77]
	v_mfma_f32_16x16x32_bf16 v[78:81], v[182:185], v[218:221], v[78:81]
	s_waitcnt vmcnt(0)
	s_barrier
; template <bool SWAP, class Epi, bool THIN = false> ...
;     ...
;     for (int st = 0; st < ns; ++st) {
;       asm volatile("s_waitcnt vmcnt(0)" ::: "memory");
;       __builtin_amdgcn_s_barrier();
;       asm volatile("" ::: "memory");
;       if (st + 1 < ns) {
;         char* nb = smem + ((st + 1) & 1) * 65536;
;         const int ko = (st + 1) * 64;
; #pragma unroll
;         for (int i = 0; i < 4; ++i) { GLDS16(A + (size_t)(ap[i] + ko), nb + tid * 16 + i * 8192); GLDS16(Bt + (size_t)(bp[i] + ko), nb + 32768 + tid * 16 + i * 8192); }
;       }
;       const char* sa = smem + (st & 1) * 65536 + (wr * 64 + fr) * 128;
;       const char* sb = smem + (st & 1) * 65536 + 32768 + (wc * 128 + fr) * 128;
;       if constexpr (THIN) {
;         if (wc == 0) {
; #pragma unroll
;           for (int ks = 0; ks < 2; ++ks) {
;             bf16x8 af[4], bf[2];
; #pragma unroll
;             for (int m = 0; m < 4; ++m) af[m] = *(const bf16x8*)(sa + m * 2048 + (((ks * 4 + fq) ^ swz) << 4));
; #pragma unroll
;             for (int n = 0; n < 2; ++n) bf[n] = *(const bf16x8*)(sb + n * 2048 + (((ks * 4 + fq) ^ swz) << 4));
; #pragma unroll
;             for (int m = 0; m < 4; ++m)
; #pragma unroll
;               for (int n = 0; n < 2; ++n)
;                 acc[m][n] = SWAP ? __builtin_amdgcn_mfma_f32_16x16x32_bf16(bf[n], af[m], acc[m][n], 0, 0, 0)
;                                  : __builtin_amdgcn_mfma_f32_16x16x32_bf16(af[m], bf[n], acc[m][n], 0, 0, 0);
;           }
;         }
;       } else {
;       bf16x8 afA[4], afB[4], bfb[2][2];
; #pragma unroll
;       for (int m = 0; m < 4; ++m) afA[m] = *(const bf16x8*)(sa + m * 2048 + ((fq ^ swz) << 4));
; #pragma unroll
;       for (int n = 0; n < 2; ++n) bfb[0][n] = *(const bf16x8*)(sb + n * 2048 + ((fq ^ swz) << 4));
; #pragma unroll
;       for (int gq = 0; gq < 8; ++gq) {
;         const int ks = gq >> 2, nh = gq & 3;
;         if (gq < 7) {
;           const int ks2 = (gq + 1) >> 2, nh2 = (gq + 1) & 3;
; #pragma unroll
;           for (int n = 0; n < 2; ++n) bfb[(gq + 1) & 1][n] = *(const bf16x8*)(sb + (nh2 * 2 + n) * 2048 + (((ks2 * 4 + fq) ^ swz) << 4));
;         }
;         if (gq == 3) {
; #pragma unroll
;           for (int m = 0; m < 4; ++m) afB[m] = *(const bf16x8*)(sa + m * 2048 + (((4 + fq) ^ swz) << 4));
;         }
;         __builtin_amdgcn_sched_barrier(0);
; #pragma unroll
	s_waitcnt lgkmcnt(0)
	v_mfma_f32_16x16x32_bf16 v[110:113], v[42:45], v[186:189], v[110:113]
	v_mfma_f32_16x16x32_bf16 v[10:13], v[190:193], v[186:189], v[10:13]
	ds_read_b128 v[174:177], v168
	ds_read_b128 v[178:181], v168 offset:2048
	ds_read_b128 v[182:185], v168 offset:4096
	ds_read_b128 v[186:189], v168 offset:6144
	v_mfma_f32_16x16x32_bf16 v[18:21], v[42:45], v[210:213], v[18:21]
	v_mfma_f32_16x16x32_bf16 v[2:5], v[42:45], v[214:217], v[2:5]
	v_mfma_f32_16x16x32_bf16 v[6:9], v[42:45], v[218:221], v[6:9]
	ds_read_b128 v[42:45], v169
	ds_read_b128 v[194:197], v169 offset:2048
	ds_read_b128 v[198:201], v169 offset:4096
	ds_read_b128 v[202:205], v169 offset:6144
	v_mfma_f32_16x16x32_bf16 v[14:17], v[190:193], v[210:213], v[14:17]
	v_mfma_f32_16x16x32_bf16 v[22:25], v[190:193], v[214:217], v[22:25]
	v_mfma_f32_16x16x32_bf16 v[30:33], v[190:193], v[218:221], v[30:33]
	s_waitcnt lgkmcnt(0)
	v_mfma_f32_16x16x32_bf16 v[50:53], v[42:45], v[174:177], v[50:53]
	v_mfma_f32_16x16x32_bf16 v[58:61], v[42:45], v[178:181], v[58:61]
	v_mfma_f32_16x16x32_bf16 v[66:69], v[42:45], v[182:185], v[66:69]
	v_mfma_f32_16x16x32_bf16 v[34:37], v[42:45], v[186:189], v[34:37]
	ds_read_b128 v[42:45], v169 offset:8192
	ds_read_b128 v[190:193], v169 offset:10240
	v_mfma_f32_16x16x32_bf16 v[54:57], v[194:197], v[174:177], v[54:57]
	v_mfma_f32_16x16x32_bf16 v[62:65], v[194:197], v[178:181], v[62:65]
	v_mfma_f32_16x16x32_bf16 v[70:73], v[194:197], v[182:185], v[70:73]
	v_mfma_f32_16x16x32_bf16 v[38:41], v[194:197], v[186:189], v[38:41]
	v_mfma_f32_16x16x32_bf16 v[82:85], v[198:201], v[174:177], v[82:85]
	v_mfma_f32_16x16x32_bf16 v[194:197], v[198:201], v[178:181], v[90:93]
	v_mfma_f32_16x16x32_bf16 v[98:101], v[198:201], v[182:185], v[98:101]
	v_mfma_f32_16x16x32_bf16 v[198:201], v[198:201], v[186:189], v[26:29]
	s_nop 2
	ds_read_b128 v[26:29], v169 offset:12288
	ds_read_b128 v[90:93], v169 offset:14336
	v_mfma_f32_16x16x32_bf16 v[86:89], v[202:205], v[174:177], v[86:89]
	v_mfma_f32_16x16x32_bf16 v[102:105], v[202:205], v[182:185], v[102:105]
	v_mfma_f32_16x16x32_bf16 v[46:49], v[202:205], v[186:189], v[46:49]
	v_mfma_f32_16x16x32_bf16 v[206:209], v[202:205], v[178:181], v[94:97]
	s_waitcnt lgkmcnt(0)
	v_mfma_f32_16x16x32_bf16 v[202:205], v[190:193], v[174:177], v[114:117]
	v_mfma_f32_16x16x32_bf16 v[210:213], v[42:45], v[178:181], v[118:121]
	s_nop 1
	ds_read_b128 v[114:117], v170
	ds_read_b128 v[118:121], v170 offset:2048
	ds_read_b128 v[226:229], v171
	ds_read_b128 v[230:233], v171 offset:2048
	ds_read_b128 v[234:237], v171 offset:4096
	ds_read_b128 v[238:241], v171 offset:6144
	v_mfma_f32_16x16x32_bf16 v[106:109], v[42:45], v[174:177], v[106:109]
	v_mfma_f32_16x16x32_bf16 v[134:137], v[190:193], v[182:185], v[134:137]
	v_mfma_f32_16x16x32_bf16 v[214:217], v[190:193], v[178:181], v[122:125]
	v_mfma_f32_16x16x32_bf16 v[218:221], v[42:45], v[182:185], v[126:129]
	v_mfma_f32_16x16x32_bf16 v[222:225], v[42:45], v[186:189], v[74:77]
	v_mfma_f32_16x16x32_bf16 v[190:193], v[190:193], v[186:189], v[78:81]
	v_mfma_f32_16x16x32_bf16 v[242:245], v[26:29], v[174:177], v[110:113]
	v_mfma_f32_16x16x32_bf16 v[174:177], v[90:93], v[174:177], v[10:13]
	v_mfma_f32_16x16x32_bf16 v[246:249], v[26:29], v[178:181], v[18:21]
	v_mfma_f32_16x16x32_bf16 v[178:181], v[90:93], v[178:181], v[14:17]
	s_nop 0
	ds_read_b128 v[10:13], v170 offset:4096
	s_nop 0
	ds_read_b128 v[14:17], v170 offset:6144
	v_mfma_f32_16x16x32_bf16 v[2:5], v[26:29], v[182:185], v[2:5]
	v_mfma_f32_16x16x32_bf16 v[6:9], v[26:29], v[186:189], v[6:9]
	v_mfma_f32_16x16x32_bf16 v[182:185], v[90:93], v[182:185], v[22:25]
	v_mfma_f32_16x16x32_bf16 v[186:189], v[90:93], v[186:189], v[30:33]
	s_waitcnt lgkmcnt(0)
	v_mfma_f32_16x16x32_bf16 v[90:93], v[118:121], v[230:233], v[62:65]
	v_mfma_f32_16x16x32_bf16 v[62:65], v[114:117], v[234:237], v[66:69]
	v_mfma_f32_16x16x32_bf16 v[30:33], v[114:117], v[238:241], v[34:37]
	s_nop 2
	ds_read_b128 v[34:37], v170 offset:8192
	ds_read_b128 v[66:69], v170 offset:10240
	v_mfma_f32_16x16x32_bf16 v[126:129], v[114:117], v[226:229], v[50:53]
	v_mfma_f32_16x16x32_bf16 v[122:125], v[118:121], v[226:229], v[54:57]
	v_mfma_f32_16x16x32_bf16 v[94:97], v[114:117], v[230:233], v[58:61]
	v_mfma_f32_16x16x32_bf16 v[58:61], v[118:121], v[234:237], v[70:73]
	v_mfma_f32_16x16x32_bf16 v[26:29], v[118:121], v[238:241], v[38:41]
	v_mfma_f32_16x16x32_bf16 v[114:117], v[14:17], v[226:229], v[86:89]
	v_mfma_f32_16x16x32_bf16 v[86:89], v[10:13], v[230:233], v[194:197]
	v_mfma_f32_16x16x32_bf16 v[22:25], v[10:13], v[238:241], v[198:201]
	s_nop 1
	ds_read_b128 v[194:197], v170 offset:12288
	ds_read_b128 v[198:201], v170 offset:14336
	v_mfma_f32_16x16x32_bf16 v[118:121], v[10:13], v[226:229], v[82:85]
	v_mfma_f32_16x16x32_bf16 v[82:85], v[14:17], v[230:233], v[206:209]
	v_mfma_f32_16x16x32_bf16 v[54:57], v[10:13], v[234:237], v[98:101]
	v_mfma_f32_16x16x32_bf16 v[50:53], v[14:17], v[234:237], v[102:105]
	v_mfma_f32_16x16x32_bf16 v[18:21], v[14:17], v[238:241], v[46:49]
	s_waitcnt lgkmcnt(0)
	v_mfma_f32_16x16x32_bf16 v[110:113], v[34:37], v[226:229], v[106:109]
	v_mfma_f32_16x16x32_bf16 v[106:109], v[66:69], v[226:229], v[202:205]
	v_mfma_f32_16x16x32_bf16 v[78:81], v[34:37], v[230:233], v[210:213]
	v_mfma_f32_16x16x32_bf16 v[74:77], v[66:69], v[230:233], v[214:217]
	v_mfma_f32_16x16x32_bf16 v[46:49], v[34:37], v[234:237], v[218:221]
	v_mfma_f32_16x16x32_bf16 v[42:45], v[66:69], v[234:237], v[134:137]
	v_mfma_f32_16x16x32_bf16 v[14:17], v[34:37], v[238:241], v[222:225]
	v_mfma_f32_16x16x32_bf16 v[10:13], v[66:69], v[238:241], v[190:193]
	s_nop 0
	v_mov_b32_e32 v134, v1
	s_waitcnt vmcnt(0)
	s_barrier
; __device__ __forceinline__ int get_tid512() { int t = threadIdx.x; asm volatile("" : "+v"(t)); return t; }
; __device__ __forceinline__ unsigned pack2(float a, float b) { unsigned r; asm("v_cvt_pk_bf16_f32 %0, %1, %2" : "=v"(r) : "v"(a), "v"(b)); return r; }
;   __device__ __forceinline__ void c4(int g, int rig, int col, f32x4 v) const {
;     const size_t row = (size_t)g * ostride + rig;
;     float s = 1.f;
;     if (NP > 0) {
;       float t = 0.f;
; #pragma unroll
;       for (int q = 0; q < NP; ++q) t += part[(size_t)q * pstride + row];
;       s = rsqrtf(t * inv_n + 1e-6f);
;     }
;     uint2 u; u.x = pack2(v[0] * s, v[1] * s); u.y = pack2(v[2] * s, v[3] * s);
;     *(uint2*)(out + row * ld + col) = u;
;   }
; template <bool SWAP, class Epi, bool THIN = false> ...
;     ...
;     __syncthreads();
;     const int te = get_tid512();
;     const int fr_e = te & 15, fq_e = (te & 63) >> 4, wr_e = te >> 7, wc_e = (te >> 6) & 1;
;     const int sub = 2 * mt + (wr_e >> 1);
;     const int g = sub / tpg, ti = sub - g * tpg;
;     const int rig0 = ti * step - halo;
;     const int rw = (wr_e & 1) * 64;
;     if constexpr (Epi::KIND == 0) {
; #pragma unroll
;       for (int m = 0; m < 4; ++m) {
;         const int rig = rig0 + rw + m * 16 + fr_e;
;         if constexpr (Epi::ROWSUM) {
;           float ss = 0.f;
; #pragma unroll
;           for (int n = 0; n < 8; ++n) {
;             const int col = nt * 256 + wc_e * 128 + n * 16 + fq_e * 4;
;             if (col < N) ss += epi.c4(g, rig, col, acc[m][n]);
;           }
;           ss += __shfl_xor(ss, 16); ss += __shfl_xor(ss, 32);
;           if (fq_e == 0) epi.rowsum(g, rig, nt * 2 + wc_e, ss);
;         } else {
; #pragma unroll
;           for (int n = 0; n < 8; ++n) {
;             const int col = nt * 256 + wc_e * 128 + n * 16 + fq_e * 4;
;             if (col < N) epi.c4(g, rig, col, acc[m][n]);
;           }
;         }
;       }
	v_mfma_f32_16x16x32_bf16 v[38:41], v[194:197], v[234:237], v[2:5]
	v_ashrrev_i32_e32 v35, 8, v134
	v_add_u32_e32 v35, s5, v35
	v_mul_hi_i32 v36, v35, s42
	v_lshrrev_b32_e32 v37, 31, v36
	v_ashrrev_i32_e32 v36, 2, v36
	v_add_u32_e32 v132, v36, v37
	v_mul_lo_u32 v36, v132, s43
	v_lshrrev_b32_e32 v2, 1, v134
	v_and_b32_e32 v34, 15, v134
	v_add_lshl_u32 v35, v36, v35, 7
	v_and_b32_e32 v2, 64, v2
	v_or3_b32 v136, v35, v2, v34
	v_lshlrev_b32_e32 v2, 1, v134
	v_lshrrev_b32_e32 v3, 2, v134
	v_and_b32_e32 v2, 0x80, v2
	v_and_b32_e32 v3, 12, v3
	v_mfma_f32_16x16x32_bf16 v[102:105], v[194:197], v[226:229], v[242:245]
	v_or3_b32 v134, v3, v2, s4
	v_ashrrev_i32_e32 v137, 31, v136
	v_cmp_gt_i32_e64 s[10:11], s46, v134
	v_mfma_f32_16x16x32_bf16 v[98:101], v[198:201], v[226:229], v[174:177]
	v_ashrrev_i32_e32 v135, 31, v134
	v_mfma_f32_16x16x32_bf16 v[70:73], v[194:197], v[230:233], v[246:249]
	v_mfma_f32_16x16x32_bf16 v[66:69], v[198:201], v[230:233], v[178:181]
	v_mfma_f32_16x16x32_bf16 v[34:37], v[198:201], v[234:237], v[182:185]
	v_mfma_f32_16x16x32_bf16 v[6:9], v[194:197], v[238:241], v[6:9]
	v_mfma_f32_16x16x32_bf16 v[2:5], v[198:201], v[238:241], v[186:189]
	v_mad_i64_i32 v[174:175], s[6:7], v132, s44, v[136:137]
	v_lshl_add_u64 v[176:177], v[174:175], 2, s[26:27]
	v_add_co_u32_e32 v178, vcc, 0x12000, v176
	v_lshlrev_b64 v[174:175], 11, v[174:175]
	s_nop 0
	v_addc_co_u32_e32 v179, vcc, 0, v177, vcc
	global_load_dword v173, v[176:177], off
	s_nop 0
	global_load_dword v176, v[178:179], off
	v_lshl_add_u64 v[174:175], s[22:23], 0, v[174:175]
	s_waitcnt vmcnt(1)
	v_add_f32_e32 v173, 0, v173
	s_waitcnt vmcnt(0)
	v_add_f32_e32 v173, v173, v176
	v_fmamk_f32 v173, v173, 0x3b800000, v172
	v_mul_f32_e32 v176, 0x4b800000, v173
	v_cmp_gt_f32_e32 vcc, s47, v173
	s_nop 1
	v_cndmask_b32_e32 v173, v173, v176, vcc
	v_rsq_f32_e32 v173, v173
	s_nop 0
	v_mul_f32_e32 v176, 0x45800000, v173
	v_cndmask_b32_e32 v173, v173, v176, vcc
	v_mov_b32_e32 v251, v173
	v_mul_f32_e32 v126, v126, v173
	v_mul_f32_e32 v127, v127, v173
	v_mul_f32_e32 v128, v128, v173
	v_mul_f32_e32 v129, v129, v173
	v_cvt_pk_bf16_f32 v126, v126, v127
	v_cvt_pk_bf16_f32 v127, v128, v129
	v_lshl_add_u64 v[128:129], v[134:135], 1, v[174:175]
	global_store_dwordx2 v[128:129], v[126:127], off
	v_or_b32_e32 v126, 16, v134
	v_mad_i64_i32 v[126:127], s[6:7], v132, s44, v[136:137]
	v_lshlrev_b64 v[126:127], 11, v[126:127]
	s_nop 0
	v_lshl_add_u64 v[126:127], s[22:23], 0, v[126:127]
	v_mul_f32_e32 v122, v122, v251
	v_mul_f32_e32 v123, v123, v251
	v_mul_f32_e32 v124, v124, v251
	v_mul_f32_e32 v125, v125, v251
	v_cvt_pk_bf16_f32 v122, v122, v123
	v_cvt_pk_bf16_f32 v123, v124, v125
	v_lshl_add_u64 v[124:125], v[134:135], 1, v[126:127]
	global_store_dwordx2 v[124:125], v[122:123], off offset:32
	v_or_b32_e32 v122, 32, v134
	v_mad_i64_i32 v[122:123], s[6:7], v132, s44, v[136:137]
	v_lshlrev_b64 v[122:123], 11, v[122:123]
	s_nop 0
	v_lshl_add_u64 v[122:123], s[22:23], 0, v[122:123]
	v_mul_f32_e32 v118, v118, v251
	v_mul_f32_e32 v119, v119, v251
	v_mul_f32_e32 v120, v120, v251
	v_mul_f32_e32 v121, v121, v251
	v_cvt_pk_bf16_f32 v118, v118, v119
	v_cvt_pk_bf16_f32 v119, v120, v121
	v_lshl_add_u64 v[120:121], v[134:135], 1, v[122:123]
	global_store_dwordx2 v[120:121], v[118:119], off offset:64
	v_or_b32_e32 v118, 48, v134
	v_mad_i64_i32 v[118:119], s[6:7], v132, s44, v[136:137]
	v_lshlrev_b64 v[118:119], 11, v[118:119]
	s_nop 0
	v_lshl_add_u64 v[118:119], s[22:23], 0, v[118:119]
	v_mul_f32_e32 v114, v114, v251
	v_mul_f32_e32 v115, v115, v251
	v_mul_f32_e32 v116, v116, v251
	v_mul_f32_e32 v117, v117, v251
	v_cvt_pk_bf16_f32 v114, v114, v115
	v_cvt_pk_bf16_f32 v115, v116, v117
	v_lshl_add_u64 v[116:117], v[134:135], 1, v[118:119]
	global_store_dwordx2 v[116:117], v[114:115], off offset:96
	v_or_b32_e32 v114, 64, v134
	v_mad_i64_i32 v[114:115], s[6:7], v132, s44, v[136:137]
	v_lshlrev_b64 v[114:115], 11, v[114:115]
	s_nop 0
	v_lshl_add_u64 v[114:115], s[22:23], 0, v[114:115]
	v_mul_f32_e32 v110, v110, v251
	v_mul_f32_e32 v111, v111, v251
	v_mul_f32_e32 v112, v112, v251
	v_mul_f32_e32 v113, v113, v251
	v_cvt_pk_bf16_f32 v110, v110, v111
	v_cvt_pk_bf16_f32 v111, v112, v113
	v_lshl_add_u64 v[112:113], v[134:135], 1, v[114:115]
	global_store_dwordx2 v[112:113], v[110:111], off offset:128
	v_or_b32_e32 v110, 0x50, v134
	v_mad_i64_i32 v[110:111], s[6:7], v132, s44, v[136:137]
	v_lshlrev_b64 v[110:111], 11, v[110:111]
	s_nop 0
	v_lshl_add_u64 v[110:111], s[22:23], 0, v[110:111]
	v_mul_f32_e32 v106, v106, v251
	v_mul_f32_e32 v107, v107, v251
	v_mul_f32_e32 v108, v108, v251
	v_mul_f32_e32 v109, v109, v251
	v_cvt_pk_bf16_f32 v106, v106, v107
	v_cvt_pk_bf16_f32 v107, v108, v109
	v_lshl_add_u64 v[108:109], v[134:135], 1, v[110:111]
	global_store_dwordx2 v[108:109], v[106:107], off offset:160
	v_or_b32_e32 v106, 0x60, v134
	v_mad_i64_i32 v[106:107], s[36:37], v132, s44, v[136:137]
	v_lshlrev_b64 v[106:107], 11, v[106:107]
	s_nop 0
	v_lshl_add_u64 v[106:107], s[22:23], 0, v[106:107]
	v_mul_f32_e32 v102, v102, v251
	v_mul_f32_e32 v103, v103, v251
	v_mul_f32_e32 v104, v104, v251
	v_mul_f32_e32 v105, v105, v251
	v_cvt_pk_bf16_f32 v102, v102, v103
	v_cvt_pk_bf16_f32 v103, v104, v105
	v_lshl_add_u64 v[104:105], v[134:135], 1, v[106:107]
	global_store_dwordx2 v[104:105], v[102:103], off offset:192
	v_or_b32_e32 v102, 0x70, v134
	v_mad_i64_i32 v[102:103], s[48:49], v132, s44, v[136:137]
	v_lshlrev_b64 v[102:103], 11, v[102:103]
	s_nop 0
	v_lshl_add_u64 v[102:103], s[22:23], 0, v[102:103]
	v_mul_f32_e32 v98, v98, v251
	v_mul_f32_e32 v99, v99, v251
	v_mul_f32_e32 v100, v100, v251
	v_mul_f32_e32 v101, v101, v251
	v_cvt_pk_bf16_f32 v98, v98, v99
	v_cvt_pk_bf16_f32 v99, v100, v101
	v_lshl_add_u64 v[100:101], v[134:135], 1, v[102:103]
	global_store_dwordx2 v[100:101], v[98:99], off offset:224
	v_or_b32_e32 v98, 16, v136
	v_ashrrev_i32_e32 v99, 31, v98
	v_mad_i64_i32 v[100:101], s[48:49], v132, s44, v[136:137]
	v_lshl_add_u64 v[100:101], v[100:101], 2, s[26:27]
	v_add_co_u32_e32 v102, vcc, 0x12000, v100
	s_nop 1
	v_addc_co_u32_e32 v103, vcc, 0, v101, vcc
	global_load_dword v100, v[100:101], off offset:64
	s_nop 0
	global_load_dword v101, v[102:103], off offset:64
	s_waitcnt vmcnt(1)
; __device__ __forceinline__ int get_tid512() { int t = threadIdx.x; asm volatile("" : "+v"(t)); return t; }
; __device__ __forceinline__ unsigned pack2(float a, float b) { unsigned r; asm("v_cvt_pk_bf16_f32 %0, %1, %2" : "=v"(r) : "v"(a), "v"(b)); return r; }
;   __device__ __forceinline__ void c4(int g, int rig, int col, f32x4 v) const {
;     const size_t row = (size_t)g * ostride + rig;
;     float s = 1.f;
;     if (NP > 0) {
;       float t = 0.f;
; #pragma unroll
;       for (int q = 0; q < NP; ++q) t += part[(size_t)q * pstride + row];
;       s = rsqrtf(t * inv_n + 1e-6f);
;     }
;     uint2 u; u.x = pack2(v[0] * s, v[1] * s); u.y = pack2(v[2] * s, v[3] * s);
;     *(uint2*)(out + row * ld + col) = u;
;   }
; template <bool SWAP, class Epi, bool THIN = false> ...
;     ...
;     __syncthreads();
;     const int te = get_tid512();
;     const int fr_e = te & 15, fq_e = (te & 63) >> 4, wr_e = te >> 7, wc_e = (te >> 6) & 1;
;     const int sub = 2 * mt + (wr_e >> 1);
;     const int g = sub / tpg, ti = sub - g * tpg;
;     const int rig0 = ti * step - halo;
;     const int rw = (wr_e & 1) * 64;
;     if constexpr (Epi::KIND == 0) {
; #pragma unroll
;       for (int m = 0; m < 4; ++m) {
;         const int rig = rig0 + rw + m * 16 + fr_e;
;         if constexpr (Epi::ROWSUM) {
;           float ss = 0.f;
; #pragma unroll
;           for (int n = 0; n < 8; ++n) {
;             const int col = nt * 256 + wc_e * 128 + n * 16 + fq_e * 4;
;             if (col < N) ss += epi.c4(g, rig, col, acc[m][n]);
;           }
;           ss += __shfl_xor(ss, 16); ss += __shfl_xor(ss, 32);
;           if (fq_e == 0) epi.rowsum(g, rig, nt * 2 + wc_e, ss);
;         } else {
; #pragma unroll
;           for (int n = 0; n < 8; ++n) {
;             const int col = nt * 256 + wc_e * 128 + n * 16 + fq_e * 4;
;             if (col < N) epi.c4(g, rig, col, acc[m][n]);
;           }
;         }
;       }
	v_add_f32_e32 v100, 0, v100
	s_waitcnt vmcnt(0)
	v_add_f32_e32 v100, v100, v101
	v_fmamk_f32 v100, v100, 0x3b800000, v172
	v_mul_f32_e32 v101, 0x4b800000, v100
	v_cmp_gt_f32_e32 vcc, s47, v100
	s_nop 1
	v_cndmask_b32_e32 v100, v100, v101, vcc
	v_rsq_f32_e32 v102, v100
	v_mad_i64_i32 v[100:101], s[48:49], v132, s44, v[98:99]
	v_lshlrev_b64 v[100:101], 11, v[100:101]
	v_mul_f32_e32 v103, 0x45800000, v102
	v_cndmask_b32_e32 v102, v102, v103, vcc
	v_lshl_add_u64 v[100:101], s[22:23], 0, v[100:101]
	v_mov_b32_e32 v251, v102
	v_mul_f32_e32 v94, v94, v102
	v_mul_f32_e32 v95, v95, v102
	v_mul_f32_e32 v96, v96, v102
	v_mul_f32_e32 v97, v97, v102
	v_cvt_pk_bf16_f32 v94, v94, v95
	v_cvt_pk_bf16_f32 v95, v96, v97
	v_lshl_add_u64 v[96:97], v[134:135], 1, v[100:101]
	global_store_dwordx2 v[96:97], v[94:95], off
	v_mad_i64_i32 v[94:95], s[48:49], v132, s44, v[98:99]
	v_lshlrev_b64 v[94:95], 11, v[94:95]
	v_lshl_add_u64 v[94:95], s[22:23], 0, v[94:95]
	v_mul_f32_e32 v90, v90, v251
	v_mul_f32_e32 v91, v91, v251
	v_mul_f32_e32 v92, v92, v251
	v_mul_f32_e32 v93, v93, v251
	v_cvt_pk_bf16_f32 v90, v90, v91
	v_cvt_pk_bf16_f32 v91, v92, v93
	v_lshl_add_u64 v[92:93], v[134:135], 1, v[94:95]
	global_store_dwordx2 v[92:93], v[90:91], off offset:32
	v_mad_i64_i32 v[90:91], s[48:49], v132, s44, v[98:99]
	v_lshlrev_b64 v[90:91], 11, v[90:91]
	v_lshl_add_u64 v[90:91], s[22:23], 0, v[90:91]
	v_mul_f32_e32 v86, v86, v251
	v_mul_f32_e32 v87, v87, v251
	v_mul_f32_e32 v88, v88, v251
	v_mul_f32_e32 v89, v89, v251
	v_cvt_pk_bf16_f32 v86, v86, v87
	v_cvt_pk_bf16_f32 v87, v88, v89
	v_lshl_add_u64 v[88:89], v[134:135], 1, v[90:91]
	global_store_dwordx2 v[88:89], v[86:87], off offset:64
	v_mad_i64_i32 v[86:87], s[48:49], v132, s44, v[98:99]
	v_lshlrev_b64 v[86:87], 11, v[86:87]
	v_lshl_add_u64 v[86:87], s[22:23], 0, v[86:87]
	v_mul_f32_e32 v82, v82, v251
	v_mul_f32_e32 v83, v83, v251
	v_mul_f32_e32 v84, v84, v251
	v_mul_f32_e32 v85, v85, v251
	v_cvt_pk_bf16_f32 v82, v82, v83
	v_cvt_pk_bf16_f32 v83, v84, v85
	v_lshl_add_u64 v[84:85], v[134:135], 1, v[86:87]
	global_store_dwordx2 v[84:85], v[82:83], off offset:96
	v_mad_i64_i32 v[82:83], s[48:49], v132, s44, v[98:99]
	v_lshlrev_b64 v[82:83], 11, v[82:83]
	v_lshl_add_u64 v[82:83], s[22:23], 0, v[82:83]
	v_mul_f32_e32 v78, v78, v251
	v_mul_f32_e32 v79, v79, v251
	v_mul_f32_e32 v80, v80, v251
	v_mul_f32_e32 v81, v81, v251
	v_cvt_pk_bf16_f32 v78, v78, v79
	v_cvt_pk_bf16_f32 v79, v80, v81
	v_lshl_add_u64 v[80:81], v[134:135], 1, v[82:83]
	global_store_dwordx2 v[80:81], v[78:79], off offset:128
	v_mad_i64_i32 v[78:79], s[48:49], v132, s44, v[98:99]
	v_lshlrev_b64 v[78:79], 11, v[78:79]
	v_lshl_add_u64 v[78:79], s[22:23], 0, v[78:79]
	v_mul_f32_e32 v74, v74, v251
	v_mul_f32_e32 v75, v75, v251
	v_mul_f32_e32 v76, v76, v251
	v_mul_f32_e32 v77, v77, v251
	v_cvt_pk_bf16_f32 v74, v74, v75
	v_cvt_pk_bf16_f32 v75, v76, v77
	v_lshl_add_u64 v[76:77], v[134:135], 1, v[78:79]
	global_store_dwordx2 v[76:77], v[74:75], off offset:160
	v_mad_i64_i32 v[74:75], s[48:49], v132, s44, v[98:99]
	v_lshlrev_b64 v[74:75], 11, v[74:75]
	v_lshl_add_u64 v[74:75], s[22:23], 0, v[74:75]
	v_mul_f32_e32 v70, v70, v251
	v_mul_f32_e32 v71, v71, v251
	v_mul_f32_e32 v72, v72, v251
	v_mul_f32_e32 v73, v73, v251
	v_cvt_pk_bf16_f32 v70, v70, v71
	v_cvt_pk_bf16_f32 v71, v72, v73
	v_lshl_add_u64 v[72:73], v[134:135], 1, v[74:75]
	global_store_dwordx2 v[72:73], v[70:71], off offset:192
	v_mad_i64_i32 v[70:71], s[48:49], v132, s44, v[98:99]
	v_lshlrev_b64 v[70:71], 11, v[70:71]
	v_lshl_add_u64 v[70:71], s[22:23], 0, v[70:71]
	v_mul_f32_e32 v66, v66, v251
	v_mul_f32_e32 v67, v67, v251
	v_mul_f32_e32 v68, v68, v251
	v_mul_f32_e32 v69, v69, v251
	v_cvt_pk_bf16_f32 v66, v66, v67
	v_cvt_pk_bf16_f32 v67, v68, v69
	v_lshl_add_u64 v[68:69], v[134:135], 1, v[70:71]
	global_store_dwordx2 v[68:69], v[66:67], off offset:224
	v_or_b32_e32 v66, 32, v136
	v_ashrrev_i32_e32 v67, 31, v66
	v_mad_i64_i32 v[68:69], s[48:49], v132, s44, v[136:137]
	v_lshl_add_u64 v[68:69], v[68:69], 2, s[26:27]
	v_add_co_u32_e32 v70, vcc, 0x12000, v68
	s_nop 1
	v_addc_co_u32_e32 v71, vcc, 0, v69, vcc
	global_load_dword v68, v[68:69], off offset:128
	s_nop 0
	global_load_dword v69, v[70:71], off offset:128
	s_waitcnt vmcnt(1)
	v_add_f32_e32 v68, 0, v68
	s_waitcnt vmcnt(0)
; __device__ __forceinline__ int get_tid512() { int t = threadIdx.x; asm volatile("" : "+v"(t)); return t; }
; __device__ __forceinline__ unsigned pack2(float a, float b) { unsigned r; asm("v_cvt_pk_bf16_f32 %0, %1, %2" : "=v"(r) : "v"(a), "v"(b)); return r; }
;   __device__ __forceinline__ void c4(int g, int rig, int col, f32x4 v) const {
;     const size_t row = (size_t)g * ostride + rig;
;     float s = 1.f;
;     if (NP > 0) {
;       float t = 0.f;
; #pragma unroll
;       for (int q = 0; q < NP; ++q) t += part[(size_t)q * pstride + row];
;       s = rsqrtf(t * inv_n + 1e-6f);
;     }
;     uint2 u; u.x = pack2(v[0] * s, v[1] * s); u.y = pack2(v[2] * s, v[3] * s);
;     *(uint2*)(out + row * ld + col) = u;
;   }
; template <bool SWAP, class Epi, bool THIN = false> ...
;     ...
;     __syncthreads();
;     const int te = get_tid512();
;     const int fr_e = te & 15, fq_e = (te & 63) >> 4, wr_e = te >> 7, wc_e = (te >> 6) & 1;
;     const int sub = 2 * mt + (wr_e >> 1);
;     const int g = sub / tpg, ti = sub - g * tpg;
;     const int rig0 = ti * step - halo;
;     const int rw = (wr_e & 1) * 64;
;     if constexpr (Epi::KIND == 0) {
; #pragma unroll
;       for (int m = 0; m < 4; ++m) {
;         const int rig = rig0 + rw + m * 16 + fr_e;
;         if constexpr (Epi::ROWSUM) {
;           float ss = 0.f;
; #pragma unroll
;           for (int n = 0; n < 8; ++n) {
;             const int col = nt * 256 + wc_e * 128 + n * 16 + fq_e * 4;
;             if (col < N) ss += epi.c4(g, rig, col, acc[m][n]);
;           }
;           ss += __shfl_xor(ss, 16); ss += __shfl_xor(ss, 32);
;           if (fq_e == 0) epi.rowsum(g, rig, nt * 2 + wc_e, ss);
;         } else {
; #pragma unroll
;           for (int n = 0; n < 8; ++n) {
;             const int col = nt * 256 + wc_e * 128 + n * 16 + fq_e * 4;
;             if (col < N) epi.c4(g, rig, col, acc[m][n]);
;           }
;         }
;       }
	v_add_f32_e32 v68, v68, v69
	v_fmamk_f32 v68, v68, 0x3b800000, v172
	v_mul_f32_e32 v69, 0x4b800000, v68
	v_cmp_gt_f32_e32 vcc, s47, v68
	s_nop 1
	v_cndmask_b32_e32 v68, v68, v69, vcc
	v_rsq_f32_e32 v70, v68
	v_mad_i64_i32 v[68:69], s[48:49], v132, s44, v[66:67]
	v_lshlrev_b64 v[68:69], 11, v[68:69]
	v_mul_f32_e32 v71, 0x45800000, v70
	v_cndmask_b32_e32 v70, v70, v71, vcc
	v_lshl_add_u64 v[68:69], s[22:23], 0, v[68:69]
	v_mov_b32_e32 v251, v70
	v_mul_f32_e32 v62, v62, v70
	v_mul_f32_e32 v63, v63, v70
	v_mul_f32_e32 v64, v64, v70
	v_mul_f32_e32 v65, v65, v70
	v_cvt_pk_bf16_f32 v62, v62, v63
	v_cvt_pk_bf16_f32 v63, v64, v65
	v_lshl_add_u64 v[64:65], v[134:135], 1, v[68:69]
	global_store_dwordx2 v[64:65], v[62:63], off
	v_mad_i64_i32 v[62:63], s[48:49], v132, s44, v[66:67]
	v_lshlrev_b64 v[62:63], 11, v[62:63]
	v_lshl_add_u64 v[62:63], s[22:23], 0, v[62:63]
	v_mul_f32_e32 v58, v58, v251
	v_mul_f32_e32 v59, v59, v251
	v_mul_f32_e32 v60, v60, v251
	v_mul_f32_e32 v61, v61, v251
	v_cvt_pk_bf16_f32 v58, v58, v59
	v_cvt_pk_bf16_f32 v59, v60, v61
	v_lshl_add_u64 v[60:61], v[134:135], 1, v[62:63]
	global_store_dwordx2 v[60:61], v[58:59], off offset:32
	v_mad_i64_i32 v[58:59], s[48:49], v132, s44, v[66:67]
	v_lshlrev_b64 v[58:59], 11, v[58:59]
	v_lshl_add_u64 v[58:59], s[22:23], 0, v[58:59]
	v_mul_f32_e32 v54, v54, v251
	v_mul_f32_e32 v55, v55, v251
	v_mul_f32_e32 v56, v56, v251
	v_mul_f32_e32 v57, v57, v251
	v_cvt_pk_bf16_f32 v54, v54, v55
	v_cvt_pk_bf16_f32 v55, v56, v57
	v_lshl_add_u64 v[56:57], v[134:135], 1, v[58:59]
	global_store_dwordx2 v[56:57], v[54:55], off offset:64
	v_mad_i64_i32 v[54:55], s[48:49], v132, s44, v[66:67]
	v_lshlrev_b64 v[54:55], 11, v[54:55]
	v_lshl_add_u64 v[54:55], s[22:23], 0, v[54:55]
	v_mul_f32_e32 v50, v50, v251
	v_mul_f32_e32 v51, v51, v251
	v_mul_f32_e32 v52, v52, v251
	v_mul_f32_e32 v53, v53, v251
	v_cvt_pk_bf16_f32 v50, v50, v51
	v_cvt_pk_bf16_f32 v51, v52, v53
	v_lshl_add_u64 v[52:53], v[134:135], 1, v[54:55]
	global_store_dwordx2 v[52:53], v[50:51], off offset:96
	v_mad_i64_i32 v[50:51], s[48:49], v132, s44, v[66:67]
	v_lshlrev_b64 v[50:51], 11, v[50:51]
	v_lshl_add_u64 v[50:51], s[22:23], 0, v[50:51]
	v_mul_f32_e32 v46, v46, v251
	v_mul_f32_e32 v47, v47, v251
	v_mul_f32_e32 v48, v48, v251
	v_mul_f32_e32 v49, v49, v251
	v_cvt_pk_bf16_f32 v46, v46, v47
	v_cvt_pk_bf16_f32 v47, v48, v49
	v_lshl_add_u64 v[48:49], v[134:135], 1, v[50:51]
	global_store_dwordx2 v[48:49], v[46:47], off offset:128
	v_mad_i64_i32 v[46:47], s[48:49], v132, s44, v[66:67]
	v_lshlrev_b64 v[46:47], 11, v[46:47]
	v_lshl_add_u64 v[46:47], s[22:23], 0, v[46:47]
	v_mul_f32_e32 v42, v42, v251
	v_mul_f32_e32 v43, v43, v251
	v_mul_f32_e32 v44, v44, v251
	v_mul_f32_e32 v45, v45, v251
	v_cvt_pk_bf16_f32 v42, v42, v43
	v_cvt_pk_bf16_f32 v43, v44, v45
	v_lshl_add_u64 v[44:45], v[134:135], 1, v[46:47]
	global_store_dwordx2 v[44:45], v[42:43], off offset:160
	v_mad_i64_i32 v[42:43], s[48:49], v132, s44, v[66:67]
	v_lshlrev_b64 v[42:43], 11, v[42:43]
	v_lshl_add_u64 v[42:43], s[22:23], 0, v[42:43]
	v_mul_f32_e32 v38, v38, v251
	v_mul_f32_e32 v39, v39, v251
	v_mul_f32_e32 v40, v40, v251
	v_mul_f32_e32 v41, v41, v251
	v_cvt_pk_bf16_f32 v38, v38, v39
	v_cvt_pk_bf16_f32 v39, v40, v41
	v_lshl_add_u64 v[40:41], v[134:135], 1, v[42:43]
	global_store_dwordx2 v[40:41], v[38:39], off offset:192
	v_mad_i64_i32 v[38:39], s[48:49], v132, s44, v[66:67]
	v_lshlrev_b64 v[38:39], 11, v[38:39]
	v_lshl_add_u64 v[38:39], s[22:23], 0, v[38:39]
	v_mul_f32_e32 v34, v34, v251
	v_mul_f32_e32 v35, v35, v251
	v_mul_f32_e32 v36, v36, v251
	v_mul_f32_e32 v37, v37, v251
	v_cvt_pk_bf16_f32 v34, v34, v35
	v_cvt_pk_bf16_f32 v35, v36, v37
	v_lshl_add_u64 v[36:37], v[134:135], 1, v[38:39]
	global_store_dwordx2 v[36:37], v[34:35], off offset:224
	v_or_b32_e32 v34, 48, v136
	v_ashrrev_i32_e32 v35, 31, v34
	v_mad_i64_i32 v[36:37], s[10:11], v132, s44, v[136:137]
	v_lshl_add_u64 v[36:37], v[36:37], 2, s[26:27]
	v_add_co_u32_e32 v38, vcc, 0x12000, v36
	s_nop 1
	v_addc_co_u32_e32 v39, vcc, 0, v37, vcc
	global_load_dword v36, v[36:37], off offset:192
	s_nop 0
	global_load_dword v37, v[38:39], off offset:192
	s_waitcnt vmcnt(1)
; __device__ __forceinline__ int get_tid512() { int t = threadIdx.x; asm volatile("" : "+v"(t)); return t; }
; __device__ __forceinline__ unsigned pack2(float a, float b) { unsigned r; asm("v_cvt_pk_bf16_f32 %0, %1, %2" : "=v"(r) : "v"(a), "v"(b)); return r; }
;   __device__ __forceinline__ void c4(int g, int rig, int col, f32x4 v) const {
;     const size_t row = (size_t)g * ostride + rig;
;     float s = 1.f;
;     if (NP > 0) {
;       float t = 0.f;
; #pragma unroll
;       for (int q = 0; q < NP; ++q) t += part[(size_t)q * pstride + row];
;       s = rsqrtf(t * inv_n + 1e-6f);
;     }
;     uint2 u; u.x = pack2(v[0] * s, v[1] * s); u.y = pack2(v[2] * s, v[3] * s);
;     *(uint2*)(out + row * ld + col) = u;
;   }
; template <bool SWAP, class Epi, bool THIN = false> ...
;     ...
;     __syncthreads();
;     const int te = get_tid512();
;     const int fr_e = te & 15, fq_e = (te & 63) >> 4, wr_e = te >> 7, wc_e = (te >> 6) & 1;
;     const int sub = 2 * mt + (wr_e >> 1);
;     const int g = sub / tpg, ti = sub - g * tpg;
;     const int rig0 = ti * step - halo;
;     const int rw = (wr_e & 1) * 64;
;     if constexpr (Epi::KIND == 0) {
; #pragma unroll
;       for (int m = 0; m < 4; ++m) {
;         const int rig = rig0 + rw + m * 16 + fr_e;
;         if constexpr (Epi::ROWSUM) {
;           float ss = 0.f;
; #pragma unroll
;           for (int n = 0; n < 8; ++n) {
;             const int col = nt * 256 + wc_e * 128 + n * 16 + fq_e * 4;
;             if (col < N) ss += epi.c4(g, rig, col, acc[m][n]);
;           }
;           ss += __shfl_xor(ss, 16); ss += __shfl_xor(ss, 32);
;           if (fq_e == 0) epi.rowsum(g, rig, nt * 2 + wc_e, ss);
;         } else {
; #pragma unroll
;           for (int n = 0; n < 8; ++n) {
;             const int col = nt * 256 + wc_e * 128 + n * 16 + fq_e * 4;
;             if (col < N) epi.c4(g, rig, col, acc[m][n]);
;           }
;         }
;       }
	v_add_f32_e32 v36, 0, v36
	s_waitcnt vmcnt(0)
	v_add_f32_e32 v36, v36, v37
	v_fmamk_f32 v36, v36, 0x3b800000, v172
	v_mul_f32_e32 v37, 0x4b800000, v36
	v_cmp_gt_f32_e32 vcc, s47, v36
	s_nop 1
	v_cndmask_b32_e32 v36, v36, v37, vcc
	v_rsq_f32_e32 v38, v36
	v_mad_i64_i32 v[36:37], s[10:11], v132, s44, v[34:35]
	v_lshlrev_b64 v[36:37], 11, v[36:37]
	v_mul_f32_e32 v39, 0x45800000, v38
	v_cndmask_b32_e32 v38, v38, v39, vcc
	v_lshl_add_u64 v[36:37], s[22:23], 0, v[36:37]
	v_mov_b32_e32 v251, v38
	v_mul_f32_e32 v30, v30, v38
	v_mul_f32_e32 v31, v31, v38
	v_mul_f32_e32 v32, v32, v38
	v_mul_f32_e32 v33, v33, v38
	v_cvt_pk_bf16_f32 v30, v30, v31
	v_cvt_pk_bf16_f32 v31, v32, v33
	v_lshl_add_u64 v[32:33], v[134:135], 1, v[36:37]
	global_store_dwordx2 v[32:33], v[30:31], off
	v_mad_i64_i32 v[30:31], s[12:13], v132, s44, v[34:35]
	v_lshlrev_b64 v[30:31], 11, v[30:31]
	v_lshl_add_u64 v[30:31], s[22:23], 0, v[30:31]
	v_mul_f32_e32 v26, v26, v251
	v_mul_f32_e32 v27, v27, v251
	v_mul_f32_e32 v28, v28, v251
	v_mul_f32_e32 v29, v29, v251
	v_cvt_pk_bf16_f32 v26, v26, v27
	v_cvt_pk_bf16_f32 v27, v28, v29
	v_lshl_add_u64 v[28:29], v[134:135], 1, v[30:31]
	global_store_dwordx2 v[28:29], v[26:27], off offset:32
	v_mad_i64_i32 v[26:27], s[12:13], v132, s44, v[34:35]
	v_lshlrev_b64 v[26:27], 11, v[26:27]
	v_lshl_add_u64 v[26:27], s[22:23], 0, v[26:27]
	v_mul_f32_e32 v22, v22, v251
	v_mul_f32_e32 v23, v23, v251
	v_mul_f32_e32 v24, v24, v251
	v_mul_f32_e32 v25, v25, v251
	v_cvt_pk_bf16_f32 v22, v22, v23
	v_cvt_pk_bf16_f32 v23, v24, v25
	v_lshl_add_u64 v[24:25], v[134:135], 1, v[26:27]
	global_store_dwordx2 v[24:25], v[22:23], off offset:64
	v_mad_i64_i32 v[22:23], s[12:13], v132, s44, v[34:35]
	v_lshlrev_b64 v[22:23], 11, v[22:23]
	v_lshl_add_u64 v[22:23], s[22:23], 0, v[22:23]
	v_mul_f32_e32 v18, v18, v251
	v_mul_f32_e32 v19, v19, v251
	v_mul_f32_e32 v20, v20, v251
	v_mul_f32_e32 v21, v21, v251
	v_cvt_pk_bf16_f32 v18, v18, v19
	v_cvt_pk_bf16_f32 v19, v20, v21
	v_lshl_add_u64 v[20:21], v[134:135], 1, v[22:23]
	global_store_dwordx2 v[20:21], v[18:19], off offset:96
	v_mad_i64_i32 v[18:19], s[12:13], v132, s44, v[34:35]
	v_lshlrev_b64 v[18:19], 11, v[18:19]
	v_lshl_add_u64 v[18:19], s[22:23], 0, v[18:19]
	v_mul_f32_e32 v14, v14, v251
	v_mul_f32_e32 v15, v15, v251
	v_mul_f32_e32 v16, v16, v251
	v_mul_f32_e32 v17, v17, v251
	v_cvt_pk_bf16_f32 v14, v14, v15
	v_cvt_pk_bf16_f32 v15, v16, v17
	v_lshl_add_u64 v[16:17], v[134:135], 1, v[18:19]
	global_store_dwordx2 v[16:17], v[14:15], off offset:128
	v_mad_i64_i32 v[14:15], s[8:9], v132, s44, v[34:35]
	v_lshlrev_b64 v[14:15], 11, v[14:15]
	v_lshl_add_u64 v[14:15], s[22:23], 0, v[14:15]
	v_mul_f32_e32 v10, v10, v251
	v_mul_f32_e32 v11, v11, v251
	v_mul_f32_e32 v12, v12, v251
	v_mul_f32_e32 v13, v13, v251
	v_cvt_pk_bf16_f32 v10, v10, v11
	v_cvt_pk_bf16_f32 v11, v12, v13
	v_lshl_add_u64 v[12:13], v[134:135], 1, v[14:15]
	global_store_dwordx2 v[12:13], v[10:11], off offset:160
	v_mad_i64_i32 v[10:11], s[6:7], v132, s44, v[34:35]
	v_lshlrev_b64 v[10:11], 11, v[10:11]
	v_lshl_add_u64 v[10:11], s[22:23], 0, v[10:11]
	v_mul_f32_e32 v6, v6, v251
	v_mul_f32_e32 v7, v7, v251
	v_mul_f32_e32 v8, v8, v251
	v_mul_f32_e32 v9, v9, v251
	v_cvt_pk_bf16_f32 v6, v6, v7
	v_cvt_pk_bf16_f32 v7, v8, v9
	v_lshl_add_u64 v[8:9], v[134:135], 1, v[10:11]
	global_store_dwordx2 v[8:9], v[6:7], off offset:192
	v_mad_i64_i32 v[6:7], s[4:5], v132, s44, v[34:35]
	v_lshlrev_b64 v[6:7], 11, v[6:7]
	v_lshl_add_u64 v[6:7], s[22:23], 0, v[6:7]
	v_mul_f32_e32 v2, v2, v251
	v_mul_f32_e32 v3, v3, v251
	v_mul_f32_e32 v4, v4, v251
	v_mul_f32_e32 v5, v5, v251
	v_cvt_pk_bf16_f32 v2, v2, v3
	v_cvt_pk_bf16_f32 v3, v4, v5
	v_lshl_add_u64 v[4:5], v[134:135], 1, v[6:7]
	global_store_dwordx2 v[4:5], v[2:3], off offset:224
	s_branch .LBB0_1817

; template <bool SWAP, class Epi, bool THIN = false> ...
;     ...
;     unsigned ap[4], bp[4];
; #pragma unroll
;     for (int i = 0; i < 4; ++i) {
;       const int r = (tid >> 3) + 64 * i;
;       const int cs = tid & 7;
;       const int c = ((cs ^ ((r >> 1) & 7)) << 3);
;       const int sub = 2 * mt + (r >> 7);
;       const int g = sub / tpg, ti = sub - g * tpg;
;       int rig = ti * step - halo + (r & 127); rig = rig < 0 ? 0 : (rig > grows - 1 ? grows - 1 : rig);
;       ap[i] = (unsigned)((g * a_gstride + a_goff + rig) * lda + c);
;       int br = nt * 256 + r; br = br > N - 1 ? N - 1 : br;
;       bp[i] = (unsigned)(br * K + c);
;     }
;     const bool have_next = false;
;     f32x4 acc[4][8];
; #pragma unroll
;     for (int m = 0; m < 4; ++m)
; #pragma unroll
;       for (int n = 0; n < 8; ++n) acc[m][n] = (f32x4){0.f, 0.f, 0.f, 0.f};
;     if (!pre_issued) {
; #pragma unroll
;       for (int i = 0; i < 4; ++i) { GLDS16(A + (size_t)ap[i], smem + tid * 16 + i * 8192); GLDS16(Bt + (size_t)bp[i], smem + 32768 + tid * 16 + i * 8192); }
;     }
;     pre_issued = have_next;
;     for (int st = 0; st < ns; ++st) {
;       asm volatile("s_waitcnt vmcnt(0)" ::: "memory");
;       __builtin_amdgcn_s_barrier();
;       asm volatile("" ::: "memory");
;       if (st + 1 < ns) {
;         char* nb = smem + ((st + 1) & 1) * 65536;
;         const int ko = (st + 1) * 64;
; #pragma unroll
;         for (int i = 0; i < 4; ++i) { GLDS16(A + (size_t)(ap[i] + ko), nb + tid * 16 + i * 8192); GLDS16(Bt + (size_t)(bp[i] + ko), nb + 32768 + tid * 16 + i * 8192); }
;     ...
;       bf16x8 afA[4], afB[4], bfb[2][2];
; #pragma unroll
;       for (int m = 0; m < 4; ++m) afA[m] = *(const bf16x8*)(sa + m * 2048 + ((fq ^ swz) << 4));
; #pragma unroll
;       for (int n = 0; n < 2; ++n) bfb[0][n] = *(const bf16x8*)(sb + n * 2048 + ((fq ^ swz) << 4));
; #pragma unroll
;       for (int gq = 0; gq < 8; ++gq) {
;         const int ks = gq >> 2, nh = gq & 3;
;         if (gq < 7) {
;           const int ks2 = (gq + 1) >> 2, nh2 = (gq + 1) & 3;
; #pragma unroll
;           for (int n = 0; n < 2; ++n) bfb[(gq + 1) & 1][n] = *(const bf16x8*)(sb + (nh2 * 2 + n) * 2048 + (((ks2 * 4 + fq) ^ swz) << 4));
;         }
;         if (gq == 3) {
; #pragma unroll
;           for (int m = 0; m < 4; ++m) afB[m] = *(const bf16x8*)(sa + m * 2048 + (((4 + fq) ^ swz) << 4));
;         }
.LBB0_1887:
	s_add_i32 s4, s3, 0xfffffd60
	s_ashr_i32 s5, s4, 31
	s_lshr_b32 s5, s5, 27
	s_add_i32 s4, s4, s5
	s_ashr_i32 s4, s4, 5
	s_lshl_b32 s5, s4, 4
	s_and_b32 s6, s33, 14
	s_or_b32 s5, s5, s6
	v_add_u32_e32 v2, s5, v149
	v_mul_hi_i32 v3, v2, s51
	v_lshrrev_b32_e32 v4, 31, v3
	v_ashrrev_i32_e32 v3, 2, v3
	v_add_u32_e32 v4, v3, v4
	v_mad_u64_u32 v[2:3], s[6:7], v4, s56, v[2:3]
	v_lshl_or_b32 v3, v2, 7, v150
	v_min_i32_e32 v3, 0x8ff, v3
	v_cmp_lt_i32_e32 vcc, -1, v2
	s_lshl_b32 s4, s4, 10
	s_sub_i32 s4, s49, s4
	v_cndmask_b32_e32 v2, 0, v3, vcc
	v_mad_u64_u32 v[2:3], s[6:7], v4, s57, v[2:3]
	s_and_b32 s4, s4, 0xffffff00
	v_mad_u64_u32 v[2:3], s[6:7], v2, s58, v[130:131]
	v_add_u32_e32 v3, s4, v131
	v_min_i32_e32 v3, 0x3ff, v3
	v_add_u32_e32 v4, s5, v152
	v_lshl_or_b32 v132, v3, 8, v130
	v_mul_hi_i32 v3, v4, s51
	v_lshrrev_b32_e32 v5, 31, v3
	v_ashrrev_i32_e32 v3, 2, v3
	v_add_u32_e32 v3, v3, v5
	v_mad_u64_u32 v[4:5], s[6:7], v3, s56, v[4:5]
	v_lshl_or_b32 v5, v4, 7, v153
	v_min_i32_e32 v5, 0x8ff, v5
	v_cmp_lt_i32_e32 vcc, -1, v4
	v_add_u32_e32 v6, s5, v155
	v_add_u32_e32 v8, s5, v157
	v_cndmask_b32_e32 v4, 0, v5, vcc
	v_mad_u64_u32 v[4:5], s[6:7], v3, s57, v[4:5]
	v_add_u32_e32 v3, s4, v151
	v_min_i32_e32 v3, 0x3ff, v3
	v_mad_u64_u32 v[4:5], s[6:7], v4, s58, v[130:131]
	v_lshl_or_b32 v12, v3, 8, v130
	v_mul_hi_i32 v3, v6, s51
	v_lshrrev_b32_e32 v5, 31, v3
	v_ashrrev_i32_e32 v3, 2, v3
	v_add_u32_e32 v3, v3, v5
	v_mad_u64_u32 v[6:7], s[6:7], v3, s56, v[6:7]
	v_lshl_or_b32 v5, v6, 7, v150
	v_min_i32_e32 v5, 0x8ff, v5
	v_cmp_lt_i32_e32 vcc, -1, v6
	v_readfirstlane_b32 s21, v148
	s_mov_b32 m0, s21
	v_cndmask_b32_e32 v6, 0, v5, vcc
	v_mad_u64_u32 v[6:7], s[6:7], v3, s57, v[6:7]
	v_add_u32_e32 v3, s4, v154
	v_min_i32_e32 v3, 0x3ff, v3
	v_lshl_or_b32 v14, v3, 8, v130
	v_mul_hi_i32 v3, v8, s51
	v_lshrrev_b32_e32 v5, 31, v3
	v_ashrrev_i32_e32 v3, 2, v3
	v_add_u32_e32 v3, v3, v5
	v_mad_u64_u32 v[8:9], s[6:7], v3, s56, v[8:9]
	v_lshl_or_b32 v5, v8, 7, v158
	v_min_i32_e32 v5, 0x8ff, v5
	v_cmp_lt_i32_e32 vcc, -1, v8
	v_readfirstlane_b32 s15, v159
	v_readfirstlane_b32 s14, v160
	v_cndmask_b32_e32 v8, 0, v5, vcc
	v_mad_u64_u32 v[8:9], s[6:7], v3, s57, v[8:9]
	v_add_u32_e32 v3, s4, v156
	v_min_i32_e32 v3, 0x3ff, v3
	v_lshl_or_b32 v16, v3, 8, v130
	v_mov_b32_e32 v3, v133
	v_lshl_add_u64 v[10:11], v[2:3], 1, s[28:29]
	global_load_lds_dwordx4 v[10:11], off
	v_lshl_add_u64 v[10:11], v[132:133], 1, s[34:35]
	s_mov_b32 m0, s15
	v_mov_b32_e32 v5, v133
	v_mad_u64_u32 v[6:7], s[6:7], v6, s58, v[130:131]
	global_load_lds_dwordx4 v[10:11], off
	v_lshl_add_u64 v[18:19], v[4:5], 1, s[28:29]
	s_mov_b32 m0, s14
	v_mov_b32_e32 v13, v133
	v_readfirstlane_b32 s17, v161
	global_load_lds_dwordx4 v[18:19], off
	v_lshl_add_u64 v[12:13], v[12:13], 1, s[34:35]
	s_mov_b32 m0, s17
	v_mov_b32_e32 v7, v133
	v_readfirstlane_b32 s16, v162
	v_mad_u64_u32 v[8:9], s[6:7], v8, s58, v[130:131]
	global_load_lds_dwordx4 v[12:13], off
	v_lshl_add_u64 v[18:19], v[6:7], 1, s[28:29]
	s_mov_b32 m0, s16
	v_mov_b32_e32 v15, v133
	v_readfirstlane_b32 s19, v163
	global_load_lds_dwordx4 v[18:19], off
	v_lshl_add_u64 v[14:15], v[14:15], 1, s[34:35]
	s_mov_b32 m0, s19
	v_mov_b32_e32 v9, v133
	v_readfirstlane_b32 s18, v164
	global_load_lds_dwordx4 v[14:15], off
	v_lshl_add_u64 v[18:19], v[8:9], 1, s[28:29]
	s_mov_b32 m0, s18
	v_mov_b32_e32 v17, v133
	v_readfirstlane_b32 s20, v165
	global_load_lds_dwordx4 v[18:19], off
	v_lshl_add_u64 v[16:17], v[16:17], 1, s[34:35]
	s_mov_b32 m0, s20
	v_add_u32_e32 v132, 64, v2
	global_load_lds_dwordx4 v[16:17], off
	v_readfirstlane_b32 s13, v166
	s_waitcnt vmcnt(0)
	s_barrier
	v_lshl_add_u64 v[18:19], v[132:133], 1, s[28:29]
	s_mov_b32 m0, s13
	v_readfirstlane_b32 s8, v167
	global_load_lds_dwordx4 v[18:19], off
	v_lshl_add_u64 v[18:19], v[10:11], 0, s[38:39]
	s_mov_b32 m0, s8
	v_add_u32_e32 v132, 64, v4
	v_readfirstlane_b32 s7, v168
	global_load_lds_dwordx4 v[18:19], off
	v_lshl_add_u64 v[18:19], v[132:133], 1, s[28:29]
	s_mov_b32 m0, s7
	v_readfirstlane_b32 s6, v169
	global_load_lds_dwordx4 v[18:19], off
	v_lshl_add_u64 v[18:19], v[12:13], 0, s[38:39]
	s_mov_b32 m0, s6
	v_add_u32_e32 v132, 64, v6
	v_readfirstlane_b32 s9, v170
	global_load_lds_dwordx4 v[18:19], off
	v_lshl_add_u64 v[18:19], v[132:133], 1, s[28:29]
	s_mov_b32 m0, s9
	v_readfirstlane_b32 s10, v171
	global_load_lds_dwordx4 v[18:19], off
	v_lshl_add_u64 v[18:19], v[14:15], 0, s[38:39]
	s_mov_b32 m0, s10
	v_add_u32_e32 v132, 64, v8
	v_readfirstlane_b32 s11, v172
	global_load_lds_dwordx4 v[18:19], off
	v_lshl_add_u64 v[18:19], v[132:133], 1, s[28:29]
	s_mov_b32 m0, s11
	v_readfirstlane_b32 s12, v173
	global_load_lds_dwordx4 v[18:19], off
	v_lshl_add_u64 v[18:19], v[16:17], 0, s[38:39]
	s_mov_b32 m0, s12
	s_nop 0
	global_load_lds_dwordx4 v[18:19], off
	ds_read_b128 v[18:21], v174
	ds_read_b128 v[22:25], v174 offset:2048
	ds_read_b128 v[26:29], v174 offset:4096
	ds_read_b128 v[30:33], v174 offset:6144
	ds_read_b128 v[34:37], v175 offset:32768
	ds_read_b128 v[38:41], v175 offset:34816
	ds_read_b128 v[42:45], v175 offset:36864
	ds_read_b128 v[46:49], v175 offset:38912
	ds_read_b128 v[74:77], v175 offset:40960
	ds_read_b128 v[78:81], v175 offset:43008
	s_waitcnt lgkmcnt(0)
; template <bool SWAP, class Epi, bool THIN = false> ...
;     ...
;     for (int st = 0; st < ns; ++st) {
;       asm volatile("s_waitcnt vmcnt(0)" ::: "memory");
;       __builtin_amdgcn_s_barrier();
;       asm volatile("" ::: "memory");
;     ...
;       bf16x8 afA[4], afB[4], bfb[2][2];
; #pragma unroll
;       for (int m = 0; m < 4; ++m) afA[m] = *(const bf16x8*)(sa + m * 2048 + ((fq ^ swz) << 4));
; #pragma unroll
;       for (int n = 0; n < 2; ++n) bfb[0][n] = *(const bf16x8*)(sb + n * 2048 + ((fq ^ swz) << 4));
; #pragma unroll
;       for (int gq = 0; gq < 8; ++gq) {
;         const int ks = gq >> 2, nh = gq & 3;
;         if (gq < 7) {
;           const int ks2 = (gq + 1) >> 2, nh2 = (gq + 1) & 3;
; #pragma unroll
;           for (int n = 0; n < 2; ++n) bfb[(gq + 1) & 1][n] = *(const bf16x8*)(sb + (nh2 * 2 + n) * 2048 + (((ks2 * 4 + fq) ^ swz) << 4));
;         }
;         if (gq == 3) {
; #pragma unroll
;           for (int m = 0; m < 4; ++m) afB[m] = *(const bf16x8*)(sa + m * 2048 + (((4 + fq) ^ swz) << 4));
;         }
;         __builtin_amdgcn_sched_barrier(0);
; #pragma unroll
;         for (int m = 0; m < 4; ++m)
; #pragma unroll
;           for (int n = 0; n < 2; ++n) {
;             const bf16x8 av = ks ? afB[m] : afA[m];
;             acc[m][nh * 2 + n] = SWAP ? __builtin_amdgcn_mfma_f32_16x16x32_bf16(bfb[gq & 1][n], av, acc[m][nh * 2 + n], 0, 0, 0)
;                                       : __builtin_amdgcn_mfma_f32_16x16x32_bf16(av, bfb[gq & 1][n], acc[m][nh * 2 + n], 0, 0, 0);
;           }
;       }
	v_mfma_f32_16x16x32_bf16 v[50:53], v[18:21], v[34:37], 0
	v_mfma_f32_16x16x32_bf16 v[54:57], v[18:21], v[38:41], 0
	v_mfma_f32_16x16x32_bf16 v[58:61], v[22:25], v[34:37], 0
	v_mfma_f32_16x16x32_bf16 v[62:65], v[22:25], v[38:41], 0
	v_mfma_f32_16x16x32_bf16 v[66:69], v[26:29], v[34:37], 0
	v_mfma_f32_16x16x32_bf16 v[70:73], v[26:29], v[38:41], 0
	v_mfma_f32_16x16x32_bf16 v[34:37], v[30:33], v[34:37], 0
	v_mfma_f32_16x16x32_bf16 v[38:41], v[30:33], v[38:41], 0
	ds_read_b128 v[106:109], v175 offset:45056
	ds_read_b128 v[110:113], v175 offset:47104
	v_mfma_f32_16x16x32_bf16 v[82:85], v[18:21], v[42:45], 0
	v_mfma_f32_16x16x32_bf16 v[86:89], v[18:21], v[46:49], 0
	v_mfma_f32_16x16x32_bf16 v[90:93], v[22:25], v[42:45], 0
	v_mfma_f32_16x16x32_bf16 v[94:97], v[22:25], v[46:49], 0
	v_mfma_f32_16x16x32_bf16 v[98:101], v[26:29], v[42:45], 0
	v_mfma_f32_16x16x32_bf16 v[102:105], v[26:29], v[46:49], 0
	v_mfma_f32_16x16x32_bf16 v[42:45], v[30:33], v[42:45], 0
	v_mfma_f32_16x16x32_bf16 v[46:49], v[30:33], v[46:49], 0
	ds_read_b128 v[142:145], v176 offset:32768
	ds_read_b128 v[182:185], v176 offset:34816
	ds_read_b128 v[186:189], v177
	ds_read_b128 v[190:193], v177 offset:2048
	ds_read_b128 v[194:197], v177 offset:4096
	ds_read_b128 v[198:201], v177 offset:6144
	v_mfma_f32_16x16x32_bf16 v[114:117], v[18:21], v[74:77], 0
	v_mfma_f32_16x16x32_bf16 v[118:121], v[18:21], v[78:81], 0
	v_mfma_f32_16x16x32_bf16 v[122:125], v[22:25], v[74:77], 0
	v_mfma_f32_16x16x32_bf16 v[126:129], v[22:25], v[78:81], 0
	v_mfma_f32_16x16x32_bf16 v[134:137], v[26:29], v[74:77], 0
	v_mfma_f32_16x16x32_bf16 v[138:141], v[26:29], v[78:81], 0
	v_mfma_f32_16x16x32_bf16 v[74:77], v[30:33], v[74:77], 0
	v_mfma_f32_16x16x32_bf16 v[78:81], v[30:33], v[78:81], 0
	ds_read_b128 v[214:217], v176 offset:36864
	ds_read_b128 v[218:221], v176 offset:38912
	s_waitcnt lgkmcnt(0)
	v_mfma_f32_16x16x32_bf16 v[202:205], v[18:21], v[106:109], 0
	v_mfma_f32_16x16x32_bf16 v[18:21], v[18:21], v[110:113], 0
	v_mfma_f32_16x16x32_bf16 v[206:209], v[22:25], v[106:109], 0
	v_mfma_f32_16x16x32_bf16 v[22:25], v[22:25], v[110:113], 0
	v_mfma_f32_16x16x32_bf16 v[210:213], v[26:29], v[106:109], 0
	v_mfma_f32_16x16x32_bf16 v[26:29], v[26:29], v[110:113], 0
	v_mfma_f32_16x16x32_bf16 v[106:109], v[30:33], v[106:109], 0
	v_mfma_f32_16x16x32_bf16 v[30:33], v[30:33], v[110:113], 0
	v_mfma_f32_16x16x32_bf16 v[50:53], v[186:189], v[142:145], v[50:53]
	v_mfma_f32_16x16x32_bf16 v[58:61], v[190:193], v[142:145], v[58:61]
	v_mfma_f32_16x16x32_bf16 v[66:69], v[194:197], v[142:145], v[66:69]
	v_mfma_f32_16x16x32_bf16 v[34:37], v[198:201], v[142:145], v[34:37]
	ds_read_b128 v[110:113], v176 offset:40960
	ds_read_b128 v[142:145], v176 offset:43008
	v_mfma_f32_16x16x32_bf16 v[54:57], v[186:189], v[182:185], v[54:57]
	v_mfma_f32_16x16x32_bf16 v[62:65], v[190:193], v[182:185], v[62:65]
	v_mfma_f32_16x16x32_bf16 v[70:73], v[194:197], v[182:185], v[70:73]
	v_mfma_f32_16x16x32_bf16 v[38:41], v[198:201], v[182:185], v[38:41]
	v_mfma_f32_16x16x32_bf16 v[82:85], v[186:189], v[214:217], v[82:85]
	v_mfma_f32_16x16x32_bf16 v[90:93], v[190:193], v[214:217], v[90:93]
	v_mfma_f32_16x16x32_bf16 v[98:101], v[194:197], v[214:217], v[98:101]
	v_mfma_f32_16x16x32_bf16 v[42:45], v[198:201], v[214:217], v[42:45]
	ds_read_b128 v[182:185], v176 offset:45056
	ds_read_b128 v[214:217], v176 offset:47104
	v_mfma_f32_16x16x32_bf16 v[86:89], v[186:189], v[218:221], v[86:89]
	v_mfma_f32_16x16x32_bf16 v[94:97], v[190:193], v[218:221], v[94:97]
	v_mfma_f32_16x16x32_bf16 v[102:105], v[194:197], v[218:221], v[102:105]
	v_mfma_f32_16x16x32_bf16 v[46:49], v[198:201], v[218:221], v[46:49]
	s_waitcnt lgkmcnt(0)
	v_mfma_f32_16x16x32_bf16 v[114:117], v[186:189], v[110:113], v[114:117]
	v_mfma_f32_16x16x32_bf16 v[118:121], v[186:189], v[142:145], v[118:121]
	v_mfma_f32_16x16x32_bf16 v[122:125], v[190:193], v[110:113], v[122:125]
	v_mfma_f32_16x16x32_bf16 v[126:129], v[190:193], v[142:145], v[126:129]
	v_mfma_f32_16x16x32_bf16 v[134:137], v[194:197], v[110:113], v[134:137]
	v_mfma_f32_16x16x32_bf16 v[138:141], v[194:197], v[142:145], v[138:141]
	v_mfma_f32_16x16x32_bf16 v[74:77], v[198:201], v[110:113], v[74:77]
	v_mfma_f32_16x16x32_bf16 v[78:81], v[198:201], v[142:145], v[78:81]
	v_add_u32_e32 v132, 0x80, v2
	s_mov_b32 m0, s21
	s_waitcnt vmcnt(0)
	s_barrier
; #define GLDS16(gp, lp) __builtin_amdgcn_global_load_lds((const unsigned*)(gp), (__attribute__((address_space(3))) unsigned*)(lp), 16, 0, 0)
; template <bool SWAP, class Epi, bool THIN = false> ...
;     ...
;       if (st + 1 < ns) {
;         char* nb = smem + ((st + 1) & 1) * 65536;
;         const int ko = (st + 1) * 64;
; #pragma unroll
;         for (int i = 0; i < 4; ++i) { GLDS16(A + (size_t)(ap[i] + ko), nb + tid * 16 + i * 8192); GLDS16(Bt + (size_t)(bp[i] + ko), nb + 32768 + tid * 16 + i * 8192); }
;     ...
;       bf16x8 afA[4], afB[4], bfb[2][2];
; #pragma unroll
;       for (int m = 0; m < 4; ++m) afA[m] = *(const bf16x8*)(sa + m * 2048 + ((fq ^ swz) << 4));
; #pragma unroll
;       for (int n = 0; n < 2; ++n) bfb[0][n] = *(const bf16x8*)(sb + n * 2048 + ((fq ^ swz) << 4));
; #pragma unroll
;       for (int gq = 0; gq < 8; ++gq) {
;         const int ks = gq >> 2, nh = gq & 3;
;         if (gq < 7) {
;           const int ks2 = (gq + 1) >> 2, nh2 = (gq + 1) & 3;
; #pragma unroll
;           for (int n = 0; n < 2; ++n) bfb[(gq + 1) & 1][n] = *(const bf16x8*)(sb + (nh2 * 2 + n) * 2048 + (((ks2 * 4 + fq) ^ swz) << 4));
;         }
;         if (gq == 3) {
; #pragma unroll
;           for (int m = 0; m < 4; ++m) afB[m] = *(const bf16x8*)(sa + m * 2048 + (((4 + fq) ^ swz) << 4));
;         }
;         __builtin_amdgcn_sched_barrier(0);
; #pragma unroll
;         for (int m = 0; m < 4; ++m)
; #pragma unroll
;           for (int n = 0; n < 2; ++n) {
;             const bf16x8 av = ks ? afB[m] : afA[m];
;             acc[m][nh * 2 + n] = SWAP ? __builtin_amdgcn_mfma_f32_16x16x32_bf16(bfb[gq & 1][n], av, acc[m][nh * 2 + n], 0, 0, 0)
;                                       : __builtin_amdgcn_mfma_f32_16x16x32_bf16(av, bfb[gq & 1][n], acc[m][nh * 2 + n], 0, 0, 0);
;           }
;       }
	v_lshl_add_u64 v[146:147], v[132:133], 1, s[28:29]
	global_load_lds_dwordx4 v[146:147], off
	v_lshl_add_u64 v[146:147], v[10:11], 0, s[40:41]
	s_mov_b32 m0, s15
	v_add_u32_e32 v132, 0x80, v4
	global_load_lds_dwordx4 v[146:147], off
	v_lshl_add_u64 v[146:147], v[132:133], 1, s[28:29]
	s_mov_b32 m0, s14
	v_add_u32_e32 v132, 0x80, v6
	global_load_lds_dwordx4 v[146:147], off
	v_lshl_add_u64 v[146:147], v[12:13], 0, s[40:41]
	s_mov_b32 m0, s17
	v_mfma_f32_16x16x32_bf16 v[110:113], v[186:189], v[182:185], v[202:205]
	global_load_lds_dwordx4 v[146:147], off
	v_lshl_add_u64 v[146:147], v[132:133], 1, s[28:29]
	s_mov_b32 m0, s16
	v_add_u32_e32 v132, 0x80, v8
	global_load_lds_dwordx4 v[146:147], off
	v_lshl_add_u64 v[146:147], v[14:15], 0, s[40:41]
	s_mov_b32 m0, s19
	v_mfma_f32_16x16x32_bf16 v[18:21], v[186:189], v[214:217], v[18:21]
	global_load_lds_dwordx4 v[146:147], off
	v_lshl_add_u64 v[146:147], v[132:133], 1, s[28:29]
	s_mov_b32 m0, s18
	v_mfma_f32_16x16x32_bf16 v[142:145], v[190:193], v[182:185], v[206:209]
	global_load_lds_dwordx4 v[146:147], off
	v_lshl_add_u64 v[146:147], v[16:17], 0, s[40:41]
	s_mov_b32 m0, s20
	v_mfma_f32_16x16x32_bf16 v[22:25], v[190:193], v[214:217], v[22:25]
	global_load_lds_dwordx4 v[146:147], off
	v_mfma_f32_16x16x32_bf16 v[186:189], v[194:197], v[182:185], v[210:213]
	v_mfma_f32_16x16x32_bf16 v[26:29], v[194:197], v[214:217], v[26:29]
	v_mfma_f32_16x16x32_bf16 v[106:109], v[198:201], v[182:185], v[106:109]
	ds_read_b128 v[182:185], v178
	ds_read_b128 v[190:193], v178 offset:2048
	ds_read_b128 v[194:197], v178 offset:4096
	ds_read_b128 v[202:205], v178 offset:6144
	ds_read_b128 v[206:209], v179
	ds_read_b128 v[210:213], v179 offset:2048
	ds_read_b128 v[218:221], v179 offset:4096
	ds_read_b128 v[222:225], v179 offset:6144
	v_mfma_f32_16x16x32_bf16 v[30:33], v[198:201], v[214:217], v[30:33]
	s_waitcnt lgkmcnt(0)
	v_mfma_f32_16x16x32_bf16 v[50:53], v[182:185], v[206:209], v[50:53]
	v_mfma_f32_16x16x32_bf16 v[58:61], v[190:193], v[206:209], v[58:61]
	v_mfma_f32_16x16x32_bf16 v[66:69], v[194:197], v[206:209], v[66:69]
	v_mfma_f32_16x16x32_bf16 v[34:37], v[202:205], v[206:209], v[34:37]
	ds_read_b128 v[198:201], v179 offset:8192
	ds_read_b128 v[206:209], v179 offset:10240
	v_mfma_f32_16x16x32_bf16 v[54:57], v[182:185], v[210:213], v[54:57]
	v_mfma_f32_16x16x32_bf16 v[62:65], v[190:193], v[210:213], v[62:65]
	v_mfma_f32_16x16x32_bf16 v[70:73], v[194:197], v[210:213], v[70:73]
	v_mfma_f32_16x16x32_bf16 v[38:41], v[202:205], v[210:213], v[38:41]
	ds_read_b128 v[210:213], v179 offset:12288
	ds_read_b128 v[214:217], v179 offset:14336
	v_mfma_f32_16x16x32_bf16 v[82:85], v[182:185], v[218:221], v[82:85]
	v_mfma_f32_16x16x32_bf16 v[86:89], v[182:185], v[222:225], v[86:89]
	v_mfma_f32_16x16x32_bf16 v[90:93], v[190:193], v[218:221], v[90:93]
	v_mfma_f32_16x16x32_bf16 v[94:97], v[190:193], v[222:225], v[94:97]
	v_mfma_f32_16x16x32_bf16 v[98:101], v[194:197], v[218:221], v[98:101]
	v_mfma_f32_16x16x32_bf16 v[102:105], v[194:197], v[222:225], v[102:105]
	v_mfma_f32_16x16x32_bf16 v[42:45], v[202:205], v[218:221], v[42:45]
	v_mfma_f32_16x16x32_bf16 v[46:49], v[202:205], v[222:225], v[46:49]
	s_waitcnt lgkmcnt(0)
	v_mfma_f32_16x16x32_bf16 v[114:117], v[182:185], v[198:201], v[114:117]
	ds_read_b128 v[218:221], v180
	ds_read_b128 v[222:225], v180 offset:2048
	v_mfma_f32_16x16x32_bf16 v[122:125], v[190:193], v[198:201], v[122:125]
	v_mfma_f32_16x16x32_bf16 v[134:137], v[194:197], v[198:201], v[134:137]
	v_mfma_f32_16x16x32_bf16 v[74:77], v[202:205], v[198:201], v[74:77]
	ds_read_b128 v[198:201], v181
	ds_read_b128 v[226:229], v181 offset:2048
	ds_read_b128 v[230:233], v181 offset:4096
	ds_read_b128 v[234:237], v181 offset:6144
	v_mfma_f32_16x16x32_bf16 v[118:121], v[182:185], v[206:209], v[118:121]
	v_mfma_f32_16x16x32_bf16 v[126:129], v[190:193], v[206:209], v[126:129]
	v_mfma_f32_16x16x32_bf16 v[138:141], v[194:197], v[206:209], v[138:141]
	v_mfma_f32_16x16x32_bf16 v[78:81], v[202:205], v[206:209], v[78:81]
	v_mfma_f32_16x16x32_bf16 v[110:113], v[182:185], v[210:213], v[110:113]
	v_mfma_f32_16x16x32_bf16 v[18:21], v[182:185], v[214:217], v[18:21]
	v_mfma_f32_16x16x32_bf16 v[142:145], v[190:193], v[210:213], v[142:145]
	v_mfma_f32_16x16x32_bf16 v[22:25], v[190:193], v[214:217], v[22:25]
	v_mfma_f32_16x16x32_bf16 v[182:185], v[194:197], v[210:213], v[186:189]
	s_nop 2
	ds_read_b128 v[186:189], v180 offset:4096
	ds_read_b128 v[190:193], v180 offset:6144
	v_mfma_f32_16x16x32_bf16 v[26:29], v[194:197], v[214:217], v[26:29]
	v_mfma_f32_16x16x32_bf16 v[106:109], v[202:205], v[210:213], v[106:109]
	v_mfma_f32_16x16x32_bf16 v[30:33], v[202:205], v[214:217], v[30:33]
	ds_read_b128 v[194:197], v180 offset:8192
	ds_read_b128 v[202:205], v180 offset:10240
	s_waitcnt lgkmcnt(0)
	v_mfma_f32_16x16x32_bf16 v[50:53], v[198:201], v[218:221], v[50:53]
	v_mfma_f32_16x16x32_bf16 v[54:57], v[198:201], v[222:225], v[54:57]
	v_mfma_f32_16x16x32_bf16 v[58:61], v[226:229], v[218:221], v[58:61]
	v_mfma_f32_16x16x32_bf16 v[62:65], v[226:229], v[222:225], v[62:65]
	v_mfma_f32_16x16x32_bf16 v[66:69], v[230:233], v[218:221], v[66:69]
	v_mfma_f32_16x16x32_bf16 v[70:73], v[230:233], v[222:225], v[70:73]
	v_mfma_f32_16x16x32_bf16 v[34:37], v[234:237], v[218:221], v[34:37]
	v_mfma_f32_16x16x32_bf16 v[38:41], v[234:237], v[222:225], v[38:41]
	v_mfma_f32_16x16x32_bf16 v[82:85], v[198:201], v[186:189], v[82:85]
	v_mfma_f32_16x16x32_bf16 v[90:93], v[226:229], v[186:189], v[90:93]
	v_mfma_f32_16x16x32_bf16 v[98:101], v[230:233], v[186:189], v[98:101]
	v_mfma_f32_16x16x32_bf16 v[42:45], v[234:237], v[186:189], v[42:45]
	ds_read_b128 v[186:189], v180 offset:12288
	ds_read_b128 v[206:209], v180 offset:14336
	v_mfma_f32_16x16x32_bf16 v[86:89], v[198:201], v[190:193], v[86:89]
	v_mfma_f32_16x16x32_bf16 v[94:97], v[226:229], v[190:193], v[94:97]
	v_mfma_f32_16x16x32_bf16 v[102:105], v[230:233], v[190:193], v[102:105]
	v_mfma_f32_16x16x32_bf16 v[46:49], v[234:237], v[190:193], v[46:49]
	v_mfma_f32_16x16x32_bf16 v[114:117], v[198:201], v[194:197], v[114:117]
	v_mfma_f32_16x16x32_bf16 v[118:121], v[198:201], v[202:205], v[118:121]
	v_mfma_f32_16x16x32_bf16 v[122:125], v[226:229], v[194:197], v[122:125]
	v_mfma_f32_16x16x32_bf16 v[126:129], v[226:229], v[202:205], v[126:129]
	v_mfma_f32_16x16x32_bf16 v[134:137], v[230:233], v[194:197], v[134:137]
	v_mfma_f32_16x16x32_bf16 v[138:141], v[230:233], v[202:205], v[138:141]
	v_mfma_f32_16x16x32_bf16 v[74:77], v[234:237], v[194:197], v[74:77]
	v_mfma_f32_16x16x32_bf16 v[78:81], v[234:237], v[202:205], v[78:81]
	v_add_u32_e32 v132, 0xc0, v2
	s_mov_b32 m0, s13
	s_waitcnt vmcnt(0)
	s_barrier
; #define GLDS16(gp, lp) __builtin_amdgcn_global_load_lds((const unsigned*)(gp), (__attribute__((address_space(3))) unsigned*)(lp), 16, 0, 0)
; template <bool SWAP, class Epi, bool THIN = false> ...
;     ...
;       if (st + 1 < ns) {
;         char* nb = smem + ((st + 1) & 1) * 65536;
;         const int ko = (st + 1) * 64;
; #pragma unroll
;         for (int i = 0; i < 4; ++i) { GLDS16(A + (size_t)(ap[i] + ko), nb + tid * 16 + i * 8192); GLDS16(Bt + (size_t)(bp[i] + ko), nb + 32768 + tid * 16 + i * 8192); }
;     ...
;       bf16x8 afA[4], afB[4], bfb[2][2];
; #pragma unroll
;       for (int m = 0; m < 4; ++m) afA[m] = *(const bf16x8*)(sa + m * 2048 + ((fq ^ swz) << 4));
; #pragma unroll
;       for (int n = 0; n < 2; ++n) bfb[0][n] = *(const bf16x8*)(sb + n * 2048 + ((fq ^ swz) << 4));
; #pragma unroll
;       for (int gq = 0; gq < 8; ++gq) {
;         const int ks = gq >> 2, nh = gq & 3;
;         if (gq < 7) {
;           const int ks2 = (gq + 1) >> 2, nh2 = (gq + 1) & 3;
; #pragma unroll
;           for (int n = 0; n < 2; ++n) bfb[(gq + 1) & 1][n] = *(const bf16x8*)(sb + (nh2 * 2 + n) * 2048 + (((ks2 * 4 + fq) ^ swz) << 4));
;         }
;         if (gq == 3) {
; #pragma unroll
;           for (int m = 0; m < 4; ++m) afB[m] = *(const bf16x8*)(sa + m * 2048 + (((4 + fq) ^ swz) << 4));
;         }
;         __builtin_amdgcn_sched_barrier(0);
; #pragma unroll
;         for (int m = 0; m < 4; ++m)
; #pragma unroll
;           for (int n = 0; n < 2; ++n) {
;             const bf16x8 av = ks ? afB[m] : afA[m];
;             acc[m][nh * 2 + n] = SWAP ? __builtin_amdgcn_mfma_f32_16x16x32_bf16(bfb[gq & 1][n], av, acc[m][nh * 2 + n], 0, 0, 0)
;                                       : __builtin_amdgcn_mfma_f32_16x16x32_bf16(av, bfb[gq & 1][n], acc[m][nh * 2 + n], 0, 0, 0);
;           }
;       }
	v_lshl_add_u64 v[2:3], v[132:133], 1, s[28:29]
	global_load_lds_dwordx4 v[2:3], off
	v_lshl_add_u64 v[2:3], v[10:11], 0, s[42:43]
	s_mov_b32 m0, s8
	v_add_u32_e32 v132, 0xc0, v4
	global_load_lds_dwordx4 v[2:3], off
	v_lshl_add_u64 v[10:11], v[132:133], 1, s[28:29]
	s_mov_b32 m0, s7
	v_add_u32_e32 v132, 0xc0, v6
	global_load_lds_dwordx4 v[10:11], off
	v_lshl_add_u64 v[10:11], v[12:13], 0, s[42:43]
	s_mov_b32 m0, s6
	v_lshl_add_u64 v[6:7], v[132:133], 1, s[28:29]
	global_load_lds_dwordx4 v[10:11], off
	s_mov_b32 m0, s9
	v_add_u32_e32 v132, 0xc0, v8
	global_load_lds_dwordx4 v[6:7], off
	v_lshl_add_u64 v[6:7], v[14:15], 0, s[42:43]
	s_mov_b32 m0, s10
	s_waitcnt lgkmcnt(0)
	v_mfma_f32_16x16x32_bf16 v[110:113], v[198:201], v[186:189], v[110:113]
	global_load_lds_dwordx4 v[6:7], off
	v_lshl_add_u64 v[6:7], v[132:133], 1, s[28:29]
	s_mov_b32 m0, s11
	v_mfma_f32_16x16x32_bf16 v[18:21], v[198:201], v[206:209], v[18:21]
	global_load_lds_dwordx4 v[6:7], off
	v_lshl_add_u64 v[6:7], v[16:17], 0, s[42:43]
	s_mov_b32 m0, s12
	v_mfma_f32_16x16x32_bf16 v[142:145], v[226:229], v[186:189], v[142:145]
	global_load_lds_dwordx4 v[6:7], off
	v_mfma_f32_16x16x32_bf16 v[2:5], v[230:233], v[186:189], v[182:185]
	v_mfma_f32_16x16x32_bf16 v[6:9], v[234:237], v[186:189], v[106:109]
	ds_read_b128 v[10:13], v174
	ds_read_b128 v[14:17], v174 offset:2048
	s_nop 0
	ds_read_b128 v[106:109], v174 offset:4096
	ds_read_b128 v[182:185], v174 offset:6144
	ds_read_b128 v[186:189], v175 offset:32768
	ds_read_b128 v[190:193], v175 offset:34816
	ds_read_b128 v[194:197], v175 offset:36864
	ds_read_b128 v[198:201], v175 offset:38912
	v_mfma_f32_16x16x32_bf16 v[22:25], v[226:229], v[206:209], v[22:25]
	v_mfma_f32_16x16x32_bf16 v[26:29], v[230:233], v[206:209], v[26:29]
	v_mfma_f32_16x16x32_bf16 v[30:33], v[234:237], v[206:209], v[30:33]
	s_waitcnt lgkmcnt(0)
	v_mfma_f32_16x16x32_bf16 v[50:53], v[10:13], v[186:189], v[50:53]
	v_mfma_f32_16x16x32_bf16 v[58:61], v[14:17], v[186:189], v[58:61]
	v_mfma_f32_16x16x32_bf16 v[66:69], v[106:109], v[186:189], v[66:69]
	v_mfma_f32_16x16x32_bf16 v[34:37], v[182:185], v[186:189], v[34:37]
	ds_read_b128 v[186:189], v175 offset:40960
	ds_read_b128 v[202:205], v175 offset:43008
	v_mfma_f32_16x16x32_bf16 v[54:57], v[10:13], v[190:193], v[54:57]
	v_mfma_f32_16x16x32_bf16 v[62:65], v[14:17], v[190:193], v[62:65]
	v_mfma_f32_16x16x32_bf16 v[70:73], v[106:109], v[190:193], v[70:73]
	v_mfma_f32_16x16x32_bf16 v[38:41], v[182:185], v[190:193], v[38:41]
	v_mfma_f32_16x16x32_bf16 v[82:85], v[10:13], v[194:197], v[82:85]
	v_mfma_f32_16x16x32_bf16 v[90:93], v[14:17], v[194:197], v[90:93]
	v_mfma_f32_16x16x32_bf16 v[98:101], v[106:109], v[194:197], v[98:101]
	v_mfma_f32_16x16x32_bf16 v[42:45], v[182:185], v[194:197], v[42:45]
	ds_read_b128 v[190:193], v175 offset:45056
	ds_read_b128 v[194:197], v175 offset:47104
	v_mfma_f32_16x16x32_bf16 v[86:89], v[10:13], v[198:201], v[86:89]
	v_mfma_f32_16x16x32_bf16 v[94:97], v[14:17], v[198:201], v[94:97]
	v_mfma_f32_16x16x32_bf16 v[102:105], v[106:109], v[198:201], v[102:105]
	v_mfma_f32_16x16x32_bf16 v[46:49], v[182:185], v[198:201], v[46:49]
	s_waitcnt lgkmcnt(0)
	v_mfma_f32_16x16x32_bf16 v[114:117], v[10:13], v[186:189], v[114:117]
	ds_read_b128 v[198:201], v176 offset:32768
	ds_read_b128 v[206:209], v176 offset:34816
	v_mfma_f32_16x16x32_bf16 v[122:125], v[14:17], v[186:189], v[122:125]
	v_mfma_f32_16x16x32_bf16 v[134:137], v[106:109], v[186:189], v[134:137]
	v_mfma_f32_16x16x32_bf16 v[74:77], v[182:185], v[186:189], v[74:77]
	ds_read_b128 v[186:189], v177
	ds_read_b128 v[210:213], v177 offset:2048
	ds_read_b128 v[214:217], v177 offset:4096
	ds_read_b128 v[218:221], v177 offset:6144
	v_mfma_f32_16x16x32_bf16 v[118:121], v[10:13], v[202:205], v[118:121]
	v_mfma_f32_16x16x32_bf16 v[126:129], v[14:17], v[202:205], v[126:129]
	v_mfma_f32_16x16x32_bf16 v[138:141], v[106:109], v[202:205], v[138:141]
	v_mfma_f32_16x16x32_bf16 v[78:81], v[182:185], v[202:205], v[78:81]
	v_mfma_f32_16x16x32_bf16 v[110:113], v[10:13], v[190:193], v[110:113]
	v_mfma_f32_16x16x32_bf16 v[10:13], v[10:13], v[194:197], v[18:21]
	v_mfma_f32_16x16x32_bf16 v[18:21], v[14:17], v[190:193], v[142:145]
	v_mfma_f32_16x16x32_bf16 v[14:17], v[14:17], v[194:197], v[22:25]
	v_mfma_f32_16x16x32_bf16 v[2:5], v[106:109], v[190:193], v[2:5]
	v_mfma_f32_16x16x32_bf16 v[22:25], v[106:109], v[194:197], v[26:29]
	s_nop 2
	ds_read_b128 v[26:29], v176 offset:36864
	ds_read_b128 v[106:109], v176 offset:38912
	v_mfma_f32_16x16x32_bf16 v[6:9], v[182:185], v[190:193], v[6:9]
	v_mfma_f32_16x16x32_bf16 v[30:33], v[182:185], v[194:197], v[30:33]
	ds_read_b128 v[142:145], v176 offset:40960
	ds_read_b128 v[182:185], v176 offset:43008
	s_waitcnt lgkmcnt(0)
	v_mfma_f32_16x16x32_bf16 v[50:53], v[186:189], v[198:201], v[50:53]
	v_mfma_f32_16x16x32_bf16 v[54:57], v[186:189], v[206:209], v[54:57]
	v_mfma_f32_16x16x32_bf16 v[58:61], v[210:213], v[198:201], v[58:61]
	v_mfma_f32_16x16x32_bf16 v[62:65], v[210:213], v[206:209], v[62:65]
	v_mfma_f32_16x16x32_bf16 v[66:69], v[214:217], v[198:201], v[66:69]
	v_mfma_f32_16x16x32_bf16 v[70:73], v[214:217], v[206:209], v[70:73]
	v_mfma_f32_16x16x32_bf16 v[34:37], v[218:221], v[198:201], v[34:37]
	v_mfma_f32_16x16x32_bf16 v[38:41], v[218:221], v[206:209], v[38:41]
	v_mfma_f32_16x16x32_bf16 v[82:85], v[186:189], v[26:29], v[82:85]
	v_mfma_f32_16x16x32_bf16 v[90:93], v[210:213], v[26:29], v[90:93]
	v_mfma_f32_16x16x32_bf16 v[98:101], v[214:217], v[26:29], v[98:101]
	v_mfma_f32_16x16x32_bf16 v[26:29], v[218:221], v[26:29], v[42:45]
	s_nop 2
	ds_read_b128 v[42:45], v176 offset:45056
	ds_read_b128 v[190:193], v176 offset:47104
	v_mfma_f32_16x16x32_bf16 v[86:89], v[186:189], v[106:109], v[86:89]
	v_mfma_f32_16x16x32_bf16 v[94:97], v[210:213], v[106:109], v[94:97]
	v_mfma_f32_16x16x32_bf16 v[102:105], v[214:217], v[106:109], v[102:105]
	v_mfma_f32_16x16x32_bf16 v[46:49], v[218:221], v[106:109], v[46:49]
	v_mfma_f32_16x16x32_bf16 v[106:109], v[186:189], v[142:145], v[114:117]
	v_mfma_f32_16x16x32_bf16 v[114:117], v[186:189], v[182:185], v[118:121]
	v_mfma_f32_16x16x32_bf16 v[118:121], v[210:213], v[142:145], v[122:125]
	v_mfma_f32_16x16x32_bf16 v[122:125], v[210:213], v[182:185], v[126:129]
	v_mfma_f32_16x16x32_bf16 v[126:129], v[214:217], v[142:145], v[134:137]
	v_mfma_f32_16x16x32_bf16 v[134:137], v[214:217], v[182:185], v[138:141]
	v_mfma_f32_16x16x32_bf16 v[74:77], v[218:221], v[142:145], v[74:77]
	v_mfma_f32_16x16x32_bf16 v[78:81], v[218:221], v[182:185], v[78:81]
	s_waitcnt vmcnt(0)
	s_barrier
; template <bool SWAP, class Epi, bool THIN = false> ...
;     ...
;       bf16x8 afA[4], afB[4], bfb[2][2];
; #pragma unroll
;       for (int m = 0; m < 4; ++m) afA[m] = *(const bf16x8*)(sa + m * 2048 + ((fq ^ swz) << 4));
; #pragma unroll
;       for (int n = 0; n < 2; ++n) bfb[0][n] = *(const bf16x8*)(sb + n * 2048 + ((fq ^ swz) << 4));
; #pragma unroll
;       for (int gq = 0; gq < 8; ++gq) {
;         const int ks = gq >> 2, nh = gq & 3;
;         if (gq < 7) {
;           const int ks2 = (gq + 1) >> 2, nh2 = (gq + 1) & 3;
; #pragma unroll
;           for (int n = 0; n < 2; ++n) bfb[(gq + 1) & 1][n] = *(const bf16x8*)(sb + (nh2 * 2 + n) * 2048 + (((ks2 * 4 + fq) ^ swz) << 4));
;         }
;         if (gq == 3) {
; #pragma unroll
;           for (int m = 0; m < 4; ++m) afB[m] = *(const bf16x8*)(sa + m * 2048 + (((4 + fq) ^ swz) << 4));
;         }
;         __builtin_amdgcn_sched_barrier(0);
; #pragma unroll
;         for (int m = 0; m < 4; ++m)
; #pragma unroll
;           for (int n = 0; n < 2; ++n) {
;             const bf16x8 av = ks ? afB[m] : afA[m];
;             acc[m][nh * 2 + n] = SWAP ? __builtin_amdgcn_mfma_f32_16x16x32_bf16(bfb[gq & 1][n], av, acc[m][nh * 2 + n], 0, 0, 0)
;                                       : __builtin_amdgcn_mfma_f32_16x16x32_bf16(av, bfb[gq & 1][n], acc[m][nh * 2 + n], 0, 0, 0);
;           }
;       }
	s_waitcnt lgkmcnt(0)
	v_mfma_f32_16x16x32_bf16 v[110:113], v[186:189], v[42:45], v[110:113]
	v_mfma_f32_16x16x32_bf16 v[10:13], v[186:189], v[190:193], v[10:13]
	ds_read_b128 v[138:141], v178
	ds_read_b128 v[142:145], v178 offset:2048
	ds_read_b128 v[182:185], v178 offset:4096
	ds_read_b128 v[186:189], v178 offset:6144
	v_mfma_f32_16x16x32_bf16 v[18:21], v[210:213], v[42:45], v[18:21]
	v_mfma_f32_16x16x32_bf16 v[2:5], v[214:217], v[42:45], v[2:5]
	v_mfma_f32_16x16x32_bf16 v[6:9], v[218:221], v[42:45], v[6:9]
	ds_read_b128 v[42:45], v179
	ds_read_b128 v[194:197], v179 offset:2048
	ds_read_b128 v[198:201], v179 offset:4096
	ds_read_b128 v[202:205], v179 offset:6144
	v_mfma_f32_16x16x32_bf16 v[14:17], v[210:213], v[190:193], v[14:17]
	v_mfma_f32_16x16x32_bf16 v[22:25], v[214:217], v[190:193], v[22:25]
	v_mfma_f32_16x16x32_bf16 v[30:33], v[218:221], v[190:193], v[30:33]
	s_waitcnt lgkmcnt(0)
	v_mfma_f32_16x16x32_bf16 v[50:53], v[138:141], v[42:45], v[50:53]
	v_mfma_f32_16x16x32_bf16 v[58:61], v[142:145], v[42:45], v[58:61]
	v_mfma_f32_16x16x32_bf16 v[66:69], v[182:185], v[42:45], v[66:69]
	v_mfma_f32_16x16x32_bf16 v[34:37], v[186:189], v[42:45], v[34:37]
	ds_read_b128 v[42:45], v179 offset:8192
	ds_read_b128 v[190:193], v179 offset:10240
	v_mfma_f32_16x16x32_bf16 v[54:57], v[138:141], v[194:197], v[54:57]
	v_mfma_f32_16x16x32_bf16 v[62:65], v[142:145], v[194:197], v[62:65]
	v_mfma_f32_16x16x32_bf16 v[70:73], v[182:185], v[194:197], v[70:73]
	v_mfma_f32_16x16x32_bf16 v[38:41], v[186:189], v[194:197], v[38:41]
	v_mfma_f32_16x16x32_bf16 v[82:85], v[138:141], v[198:201], v[82:85]
	v_mfma_f32_16x16x32_bf16 v[194:197], v[142:145], v[198:201], v[90:93]
	v_mfma_f32_16x16x32_bf16 v[98:101], v[182:185], v[198:201], v[98:101]
	v_mfma_f32_16x16x32_bf16 v[198:201], v[186:189], v[198:201], v[26:29]
	s_nop 2
	ds_read_b128 v[26:29], v179 offset:12288
	ds_read_b128 v[90:93], v179 offset:14336
	v_mfma_f32_16x16x32_bf16 v[86:89], v[138:141], v[202:205], v[86:89]
	v_mfma_f32_16x16x32_bf16 v[102:105], v[182:185], v[202:205], v[102:105]
	v_mfma_f32_16x16x32_bf16 v[46:49], v[186:189], v[202:205], v[46:49]
	v_mfma_f32_16x16x32_bf16 v[206:209], v[142:145], v[202:205], v[94:97]
	s_waitcnt lgkmcnt(0)
	v_mfma_f32_16x16x32_bf16 v[202:205], v[138:141], v[190:193], v[114:117]
	v_mfma_f32_16x16x32_bf16 v[210:213], v[142:145], v[42:45], v[118:121]
	s_nop 1
	ds_read_b128 v[114:117], v180
	ds_read_b128 v[118:121], v180 offset:2048
	ds_read_b128 v[226:229], v181
	ds_read_b128 v[230:233], v181 offset:2048
	ds_read_b128 v[234:237], v181 offset:4096
	ds_read_b128 v[238:241], v181 offset:6144
	v_mfma_f32_16x16x32_bf16 v[106:109], v[138:141], v[42:45], v[106:109]
	v_mfma_f32_16x16x32_bf16 v[134:137], v[182:185], v[190:193], v[134:137]
	v_mfma_f32_16x16x32_bf16 v[214:217], v[142:145], v[190:193], v[122:125]
	v_mfma_f32_16x16x32_bf16 v[218:221], v[182:185], v[42:45], v[126:129]
	v_mfma_f32_16x16x32_bf16 v[222:225], v[186:189], v[42:45], v[74:77]
	v_mfma_f32_16x16x32_bf16 v[190:193], v[186:189], v[190:193], v[78:81]
	v_mfma_f32_16x16x32_bf16 v[242:245], v[138:141], v[26:29], v[110:113]
	v_mfma_f32_16x16x32_bf16 v[138:141], v[138:141], v[90:93], v[10:13]
	v_mfma_f32_16x16x32_bf16 v[246:249], v[142:145], v[26:29], v[18:21]
	v_mfma_f32_16x16x32_bf16 v[142:145], v[142:145], v[90:93], v[14:17]
	s_nop 0
	ds_read_b128 v[10:13], v180 offset:4096
	s_nop 0
	ds_read_b128 v[14:17], v180 offset:6144
	v_mfma_f32_16x16x32_bf16 v[2:5], v[182:185], v[26:29], v[2:5]
	v_mfma_f32_16x16x32_bf16 v[6:9], v[186:189], v[26:29], v[6:9]
	v_mfma_f32_16x16x32_bf16 v[182:185], v[182:185], v[90:93], v[22:25]
	v_mfma_f32_16x16x32_bf16 v[186:189], v[186:189], v[90:93], v[30:33]
	s_waitcnt lgkmcnt(0)
	v_mfma_f32_16x16x32_bf16 v[90:93], v[230:233], v[118:121], v[62:65]
	v_mfma_f32_16x16x32_bf16 v[62:65], v[234:237], v[114:117], v[66:69]
	v_mfma_f32_16x16x32_bf16 v[30:33], v[238:241], v[114:117], v[34:37]
	s_nop 2
	ds_read_b128 v[34:37], v180 offset:8192
	ds_read_b128 v[66:69], v180 offset:10240
	v_mfma_f32_16x16x32_bf16 v[126:129], v[226:229], v[114:117], v[50:53]
	v_mfma_f32_16x16x32_bf16 v[122:125], v[226:229], v[118:121], v[54:57]
	v_mfma_f32_16x16x32_bf16 v[94:97], v[230:233], v[114:117], v[58:61]
	v_mfma_f32_16x16x32_bf16 v[58:61], v[234:237], v[118:121], v[70:73]
	v_mfma_f32_16x16x32_bf16 v[26:29], v[238:241], v[118:121], v[38:41]
	v_mfma_f32_16x16x32_bf16 v[114:117], v[226:229], v[14:17], v[86:89]
	v_mfma_f32_16x16x32_bf16 v[86:89], v[230:233], v[10:13], v[194:197]
	v_mfma_f32_16x16x32_bf16 v[22:25], v[238:241], v[10:13], v[198:201]
	s_nop 1
	ds_read_b128 v[194:197], v180 offset:12288
	ds_read_b128 v[198:201], v180 offset:14336
	v_mfma_f32_16x16x32_bf16 v[118:121], v[226:229], v[10:13], v[82:85]
	v_mfma_f32_16x16x32_bf16 v[82:85], v[230:233], v[14:17], v[206:209]
	v_mfma_f32_16x16x32_bf16 v[54:57], v[234:237], v[10:13], v[98:101]
	v_mfma_f32_16x16x32_bf16 v[50:53], v[234:237], v[14:17], v[102:105]
	v_mfma_f32_16x16x32_bf16 v[18:21], v[238:241], v[14:17], v[46:49]
	s_waitcnt lgkmcnt(0)
	v_mfma_f32_16x16x32_bf16 v[110:113], v[226:229], v[34:37], v[106:109]
	v_mfma_f32_16x16x32_bf16 v[106:109], v[226:229], v[66:69], v[202:205]
	v_mfma_f32_16x16x32_bf16 v[78:81], v[230:233], v[34:37], v[210:213]
	v_mfma_f32_16x16x32_bf16 v[74:77], v[230:233], v[66:69], v[214:217]
	v_mfma_f32_16x16x32_bf16 v[46:49], v[234:237], v[34:37], v[218:221]
	v_mfma_f32_16x16x32_bf16 v[42:45], v[234:237], v[66:69], v[134:137]
	v_mfma_f32_16x16x32_bf16 v[14:17], v[238:241], v[34:37], v[222:225]
	v_mfma_f32_16x16x32_bf16 v[10:13], v[238:241], v[66:69], v[190:193]
	v_mov_b32_e32 v132, v1
	s_waitcnt vmcnt(0)
	s_barrier
; __device__ __forceinline__ int get_tid512() { int t = threadIdx.x; asm volatile("" : "+v"(t)); return t; }
; __device__ __forceinline__ unsigned pack2(float a, float b) { unsigned r; asm("v_cvt_pk_bf16_f32 %0, %1, %2" : "=v"(r) : "v"(a), "v"(b)); return r; }
;   __device__ __forceinline__ void r4(int g, int rig, int col, f32x4 v) const {
;     const size_t row = (size_t)g * 2304 + rig;
;     const f32x4 t = *(const f32x4*)(part + row) + *(const f32x4*)(part + 18432 + row);
;     f32x4 s;
; #pragma unroll
;     for (int j = 0; j < 4; ++j) s[j] = rsqrtf(t[j] * (1.0f / 256.0f) + 1e-6f);
;     uint2 u; u.x = pack2(v[0] * s[0], v[1] * s[1]); u.y = pack2(v[2] * s[2], v[3] * s[3]);
;     *(uint2*)(out + ((size_t)g * 1024 + col) * 2304 + rig) = u;
;   }
; template <bool SWAP, class Epi, bool THIN = false> ...
;     ...
;     __syncthreads();
;     const int te = get_tid512();
;     const int fr_e = te & 15, fq_e = (te & 63) >> 4, wr_e = te >> 7, wc_e = (te >> 6) & 1;
;     const int sub = 2 * mt + (wr_e >> 1);
;     const int g = sub / tpg, ti = sub - g * tpg;
;     const int rig0 = ti * step - halo;
;     const int rw = (wr_e & 1) * 64;
;     if constexpr (Epi::KIND == 0) {
; #pragma unroll
;       for (int m = 0; m < 4; ++m) {
;         const int rig = rig0 + rw + m * 16 + fr_e;
;         if constexpr (Epi::ROWSUM) {
;           float ss = 0.f;
; #pragma unroll
;           for (int n = 0; n < 8; ++n) {
;             const int col = nt * 256 + wc_e * 128 + n * 16 + fq_e * 4;
;             if (col < N) ss += epi.c4(g, rig, col, acc[m][n]);
;           }
;           ss += __shfl_xor(ss, 16); ss += __shfl_xor(ss, 32);
;           if (fq_e == 0) epi.rowsum(g, rig, nt * 2 + wc_e, ss);
;         } else {
; #pragma unroll
;           for (int n = 0; n < 8; ++n) {
;             const int col = nt * 256 + wc_e * 128 + n * 16 + fq_e * 4;
;             if (col < N) epi.c4(g, rig, col, acc[m][n]);
;           }
;         }
;       }
;     } else if constexpr (Epi::KIND == 1) {
; #pragma unroll
;       for (int m = 0; m < 4; ++m) {
;         const int rig = rig0 + rw + m * 16 + fq_e * 4;
; #pragma unroll
;         for (int n = 0; n < 8; ++n) {
;           const int col = nt * 256 + wc_e * 128 + n * 16 + fr_e;
;           if (col < N) epi.r4(g, rig, col, acc[m][n]);
;         }
;       }
	v_mfma_f32_16x16x32_bf16 v[66:69], v[230:233], v[198:201], v[142:145]
	v_ashrrev_i32_e32 v34, 8, v132
	v_add_u32_e32 v34, s5, v34
	v_mul_hi_i32 v35, v34, s51
	v_lshrrev_b32_e32 v36, 31, v35
	v_ashrrev_i32_e32 v35, 2, v35
	v_add_u32_e32 v144, v35, v36
	v_mul_lo_u32 v35, v144, s56
	v_mfma_f32_16x16x32_bf16 v[38:41], v[234:237], v[194:197], v[2:5]
	v_add_lshl_u32 v135, v35, v34, 7
	v_and_b32_e32 v134, 15, v132
	v_ashrrev_i32_e32 v145, 31, v144
	v_lshrrev_b32_e32 v2, 1, v132
	v_lshrrev_b32_e32 v3, 2, v132
	v_and_b32_e32 v2, 64, v2
	v_and_b32_e32 v3, 12, v3
	v_or3_b32 v142, v135, v2, v3
	v_lshlrev_b32_e32 v2, 1, v132
	v_and_b32_e32 v2, 0x80, v2
	v_mfma_f32_16x16x32_bf16 v[102:105], v[226:229], v[194:197], v[242:245]
	v_ashrrev_i32_e32 v143, 31, v142
	v_mfma_f32_16x16x32_bf16 v[98:101], v[226:229], v[198:201], v[138:141]
	v_mfma_f32_16x16x32_bf16 v[70:73], v[230:233], v[194:197], v[246:249]
	s_nop 1
	v_or3_b32 v140, v134, v2, s4
	v_mad_i64_i32 v[136:137], s[4:5], v144, s57, v[142:143]
	v_mfma_f32_16x16x32_bf16 v[34:37], v[234:237], v[198:201], v[182:185]
	v_lshlrev_b64 v[136:137], 2, v[136:137]
	v_lshlrev_b64 v[134:135], 10, v[144:145]
	v_lshl_add_u64 v[138:139], s[26:27], 0, v[136:137]
	v_mfma_f32_16x16x32_bf16 v[6:9], v[238:241], v[194:197], v[6:9]
	v_lshl_add_u64 v[146:147], s[36:37], 0, v[136:137]
	v_lshl_add_u64 v[136:137], v[142:143], 1, s[30:31]
	v_cmp_gt_i32_e32 vcc, s59, v140
	v_mfma_f32_16x16x32_bf16 v[2:5], v[238:241], v[198:201], v[186:189]
	v_ashrrev_i32_e32 v141, 31, v140
	global_load_dwordx4 v[182:185], v[138:139], off
	global_load_dwordx4 v[186:189], v[146:147], off
	v_mov_b64_e32 v[190:191], s[48:49]
	v_lshl_add_u64 v[192:193], v[134:135], 0, v[140:141]
	v_mad_u64_u32 v[194:195], s[4:5], v192, s61, v[136:137]
	v_mad_i32_i24 v195, v193, s61, v195
	s_waitcnt vmcnt(0)
	v_pk_add_f32 v[182:183], v[182:183], v[186:187]
	v_pk_add_f32 v[184:185], v[184:185], v[188:189]
	v_pk_fma_f32 v[182:183], v[182:183], s[44:45], v[190:191] op_sel_hi:[1,0,0]
	v_pk_fma_f32 v[184:185], v[184:185], s[44:45], v[190:191] op_sel_hi:[1,0,0]
	v_mul_f32_e32 v132, 0x4b800000, v182
	v_mul_f32_e32 v143, 0x4b800000, v183
	v_cmp_gt_f32_e64 s[4:5], s60, v182
	v_cmp_gt_f32_e64 s[6:7], s60, v183
	v_mul_f32_e32 v145, 0x4b800000, v184
	v_mul_f32_e32 v186, 0x4b800000, v185
	v_cndmask_b32_e64 v132, v182, v132, s[4:5]
	v_cndmask_b32_e64 v143, v183, v143, s[6:7]
	v_cmp_gt_f32_e64 s[8:9], s60, v184
	v_cmp_gt_f32_e64 s[10:11], s60, v185
	v_rsq_f32_e32 v132, v132
	v_cndmask_b32_e64 v145, v184, v145, s[8:9]
	v_cndmask_b32_e64 v182, v185, v186, s[10:11]
	v_rsq_f32_e32 v143, v143
	v_rsq_f32_e32 v145, v145
	v_rsq_f32_e32 v182, v182
	v_mul_f32_e32 v183, 0x45800000, v132
	v_mul_f32_e32 v184, 0x45800000, v143
	v_mul_f32_e32 v185, 0x45800000, v145
	v_mul_f32_e32 v186, 0x45800000, v182
	v_cndmask_b32_e64 v132, v132, v183, s[4:5]
	v_cndmask_b32_e64 v143, v143, v184, s[6:7]
	v_cndmask_b32_e64 v145, v145, v185, s[8:9]
	v_cndmask_b32_e64 v182, v182, v186, s[10:11]
	v_mov_b32_e32 v251, v132
	v_mov_b32_e32 v252, v143
	v_mov_b32_e32 v253, v145
	v_mov_b32_e32 v254, v182
	v_mul_f32_e32 v126, v126, v132
	v_mul_f32_e32 v127, v127, v143
	v_mul_f32_e32 v128, v128, v145
	v_mul_f32_e32 v129, v129, v182
	v_cvt_pk_bf16_f32 v126, v126, v127
	v_cvt_pk_bf16_f32 v127, v128, v129
	global_store_dwordx2 v[194:195], v[126:127], off
	v_or_b32_e32 v126, 16, v140
	v_ashrrev_i32_e32 v127, 31, v126
	v_lshl_add_u64 v[190:191], v[134:135], 0, v[126:127]
	v_mad_u64_u32 v[192:193], s[6:7], v190, s61, v[136:137]
	v_mad_i32_i24 v193, v191, s61, v193
	v_mul_f32_e32 v122, v122, v251
	v_mul_f32_e32 v123, v123, v252
	v_mul_f32_e32 v124, v124, v253
	v_mul_f32_e32 v125, v125, v254
	v_cvt_pk_bf16_f32 v122, v122, v123
	v_cvt_pk_bf16_f32 v123, v124, v125
	global_store_dwordx2 v[192:193], v[122:123], off
	v_or_b32_e32 v122, 32, v140
	v_ashrrev_i32_e32 v123, 31, v122
	v_lshl_add_u64 v[128:129], v[134:135], 0, v[122:123]
	v_mad_u64_u32 v[190:191], s[8:9], v128, s61, v[136:137]
	v_mad_i32_i24 v191, v129, s61, v191
	v_mul_f32_e32 v118, v118, v251
	v_mul_f32_e32 v119, v119, v252
	v_mul_f32_e32 v120, v120, v253
	v_mul_f32_e32 v121, v121, v254
	v_cvt_pk_bf16_f32 v118, v118, v119
	v_cvt_pk_bf16_f32 v119, v120, v121
	global_store_dwordx2 v[190:191], v[118:119], off
	v_or_b32_e32 v118, 48, v140
	v_ashrrev_i32_e32 v119, 31, v118
	v_lshl_add_u64 v[124:125], v[134:135], 0, v[118:119]
	v_mad_u64_u32 v[128:129], s[10:11], v124, s61, v[136:137]
	v_mad_i32_i24 v129, v125, s61, v129
	v_mul_f32_e32 v114, v114, v251
	v_mul_f32_e32 v115, v115, v252
	v_mul_f32_e32 v116, v116, v253
	v_mul_f32_e32 v117, v117, v254
	v_cvt_pk_bf16_f32 v114, v114, v115
	v_cvt_pk_bf16_f32 v115, v116, v117
	global_store_dwordx2 v[128:129], v[114:115], off
	v_or_b32_e32 v114, 64, v140
	v_ashrrev_i32_e32 v115, 31, v114
	v_lshl_add_u64 v[120:121], v[134:135], 0, v[114:115]
	v_mad_u64_u32 v[124:125], s[12:13], v120, s61, v[136:137]
	v_mad_i32_i24 v125, v121, s61, v125
	v_mul_f32_e32 v110, v110, v251
	v_mul_f32_e32 v111, v111, v252
	v_mul_f32_e32 v112, v112, v253
	v_mul_f32_e32 v113, v113, v254
	v_cvt_pk_bf16_f32 v110, v110, v111
	v_cvt_pk_bf16_f32 v111, v112, v113
	global_store_dwordx2 v[124:125], v[110:111], off
	v_or_b32_e32 v110, 0x50, v140
	v_ashrrev_i32_e32 v111, 31, v110
	v_lshl_add_u64 v[116:117], v[134:135], 0, v[110:111]
	v_mad_u64_u32 v[120:121], s[14:15], v116, s61, v[136:137]
	v_mad_i32_i24 v121, v117, s61, v121
	v_mul_f32_e32 v106, v106, v251
	v_mul_f32_e32 v107, v107, v252
	v_mul_f32_e32 v108, v108, v253
	v_mul_f32_e32 v109, v109, v254
	v_cvt_pk_bf16_f32 v106, v106, v107
	v_cvt_pk_bf16_f32 v107, v108, v109
	global_store_dwordx2 v[120:121], v[106:107], off
; __device__ __forceinline__ unsigned pack2(float a, float b) { unsigned r; asm("v_cvt_pk_bf16_f32 %0, %1, %2" : "=v"(r) : "v"(a), "v"(b)); return r; }
;   __device__ __forceinline__ void r4(int g, int rig, int col, f32x4 v) const {
;     const size_t row = (size_t)g * 2304 + rig;
;     const f32x4 t = *(const f32x4*)(part + row) + *(const f32x4*)(part + 18432 + row);
;     f32x4 s;
; #pragma unroll
;     for (int j = 0; j < 4; ++j) s[j] = rsqrtf(t[j] * (1.0f / 256.0f) + 1e-6f);
;     uint2 u; u.x = pack2(v[0] * s[0], v[1] * s[1]); u.y = pack2(v[2] * s[2], v[3] * s[3]);
;     *(uint2*)(out + ((size_t)g * 1024 + col) * 2304 + rig) = u;
;   }
; template <bool SWAP, class Epi, bool THIN = false> ...
;     ...
;     } else if constexpr (Epi::KIND == 1) {
; #pragma unroll
;       for (int m = 0; m < 4; ++m) {
;         const int rig = rig0 + rw + m * 16 + fq_e * 4;
; #pragma unroll
;         for (int n = 0; n < 8; ++n) {
;           const int col = nt * 256 + wc_e * 128 + n * 16 + fr_e;
;           if (col < N) epi.r4(g, rig, col, acc[m][n]);
;         }
;       }
	v_or_b32_e32 v106, 0x60, v140
	v_ashrrev_i32_e32 v107, 31, v106
	v_lshl_add_u64 v[112:113], v[134:135], 0, v[106:107]
	v_mad_u64_u32 v[116:117], s[16:17], v112, s61, v[136:137]
	v_mad_i32_i24 v117, v113, s61, v117
	v_mul_f32_e32 v102, v102, v251
	v_mul_f32_e32 v103, v103, v252
	v_mul_f32_e32 v104, v104, v253
	v_mul_f32_e32 v105, v105, v254
	v_cvt_pk_bf16_f32 v102, v102, v103
	v_cvt_pk_bf16_f32 v103, v104, v105
	global_store_dwordx2 v[116:117], v[102:103], off
	v_or_b32_e32 v102, 0x70, v140
	v_ashrrev_i32_e32 v103, 31, v102
	v_lshl_add_u64 v[108:109], v[134:135], 0, v[102:103]
	v_mad_u64_u32 v[112:113], s[18:19], v108, s61, v[136:137]
	v_mad_i32_i24 v113, v109, s61, v113
	v_mul_f32_e32 v98, v98, v251
	v_mul_f32_e32 v99, v99, v252
	v_mul_f32_e32 v100, v100, v253
	v_mul_f32_e32 v101, v101, v254
	v_cvt_pk_bf16_f32 v98, v98, v99
	v_cvt_pk_bf16_f32 v99, v100, v101
	global_store_dwordx2 v[112:113], v[98:99], off
	v_or_b32_e32 v100, 16, v142
	v_mad_i64_i32 v[98:99], s[18:19], v144, s57, 0
	v_ashrrev_i32_e32 v101, 31, v100
	v_lshl_add_u64 v[100:101], v[98:99], 0, v[100:101]
	v_lshl_add_u64 v[100:101], v[100:101], 2, s[36:37]
	global_load_dwordx4 v[144:147], v[138:139], off offset:64
	global_load_dwordx4 v[182:185], v[100:101], off
	v_mov_b64_e32 v[104:105], s[48:49]
	v_lshl_add_u64 v[108:109], v[134:135], 0, v[140:141]
	v_mad_u64_u32 v[112:113], s[18:19], v108, s61, v[136:137]
	v_mad_i32_i24 v113, v109, s61, v113
	s_waitcnt vmcnt(0)
	v_pk_add_f32 v[120:121], v[144:145], v[182:183]
	v_pk_add_f32 v[116:117], v[146:147], v[184:185]
	v_pk_fma_f32 v[120:121], v[120:121], s[44:45], v[104:105] op_sel_hi:[1,0,0]
	v_pk_fma_f32 v[104:105], v[116:117], s[44:45], v[104:105] op_sel_hi:[1,0,0]
	v_mul_f32_e32 v108, 0x4b800000, v120
	v_mul_f32_e32 v116, 0x4b800000, v121
	v_cmp_gt_f32_e64 s[18:19], s60, v120
	v_cmp_gt_f32_e64 s[20:21], s60, v121
	v_mul_f32_e32 v117, 0x4b800000, v104
	v_mul_f32_e32 v124, 0x4b800000, v105
	v_cndmask_b32_e64 v108, v120, v108, s[18:19]
	v_cndmask_b32_e64 v116, v121, v116, s[20:21]
	v_cmp_gt_f32_e64 s[22:23], s60, v104
	v_cmp_gt_f32_e64 s[24:25], s60, v105
	v_rsq_f32_e32 v108, v108
	v_cndmask_b32_e64 v104, v104, v117, s[22:23]
	v_cndmask_b32_e64 v105, v105, v124, s[24:25]
	v_rsq_f32_e32 v116, v116
	v_rsq_f32_e32 v104, v104
	v_rsq_f32_e32 v105, v105
	v_mul_f32_e32 v117, 0x45800000, v108
	v_mul_f32_e32 v120, 0x45800000, v116
	v_mul_f32_e32 v121, 0x45800000, v104
	v_mul_f32_e32 v124, 0x45800000, v105
	v_cndmask_b32_e64 v108, v108, v117, s[18:19]
	v_cndmask_b32_e64 v116, v116, v120, s[20:21]
	v_cndmask_b32_e64 v104, v104, v121, s[22:23]
	v_cndmask_b32_e64 v105, v105, v124, s[24:25]
	v_mov_b32_e32 v251, v108
	v_mov_b32_e32 v252, v116
	v_mov_b32_e32 v253, v104
	v_mov_b32_e32 v254, v105
	v_mul_f32_e32 v94, v94, v108
	v_mul_f32_e32 v95, v95, v116
	v_mul_f32_e32 v96, v96, v104
	v_mul_f32_e32 v97, v97, v105
	v_cvt_pk_bf16_f32 v94, v94, v95
	v_cvt_pk_bf16_f32 v95, v96, v97
	global_store_dwordx2 v[112:113], v[94:95], off offset:32
	v_lshl_add_u64 v[108:109], v[134:135], 0, v[126:127]
	v_mad_u64_u32 v[112:113], s[18:19], v108, s61, v[136:137]
	v_mad_i32_i24 v113, v109, s61, v113
	v_mul_f32_e32 v90, v90, v251
	v_mul_f32_e32 v91, v91, v252
	v_mul_f32_e32 v92, v92, v253
	v_mul_f32_e32 v93, v93, v254
	v_cvt_pk_bf16_f32 v90, v90, v91
	v_cvt_pk_bf16_f32 v91, v92, v93
	global_store_dwordx2 v[112:113], v[90:91], off offset:32
	v_lshl_add_u64 v[108:109], v[134:135], 0, v[122:123]
	v_mad_u64_u32 v[112:113], s[18:19], v108, s61, v[136:137]
	v_mad_i32_i24 v113, v109, s61, v113
	v_mul_f32_e32 v86, v86, v251
	v_mul_f32_e32 v87, v87, v252
	v_mul_f32_e32 v88, v88, v253
	v_mul_f32_e32 v89, v89, v254
	v_cvt_pk_bf16_f32 v86, v86, v87
	v_cvt_pk_bf16_f32 v87, v88, v89
	global_store_dwordx2 v[112:113], v[86:87], off offset:32
	v_lshl_add_u64 v[96:97], v[134:135], 0, v[118:119]
	v_mad_u64_u32 v[104:105], s[18:19], v96, s61, v[136:137]
	v_mad_i32_i24 v105, v97, s61, v105
	v_mul_f32_e32 v82, v82, v251
	v_mul_f32_e32 v83, v83, v252
	v_mul_f32_e32 v84, v84, v253
	v_mul_f32_e32 v85, v85, v254
	v_cvt_pk_bf16_f32 v82, v82, v83
	v_cvt_pk_bf16_f32 v83, v84, v85
	global_store_dwordx2 v[104:105], v[82:83], off offset:32
	v_lshl_add_u64 v[92:93], v[134:135], 0, v[114:115]
	v_mad_u64_u32 v[94:95], s[18:19], v92, s61, v[136:137]
	v_mad_i32_i24 v95, v93, s61, v95
	v_mul_f32_e32 v78, v78, v251
	v_mul_f32_e32 v79, v79, v252
	v_mul_f32_e32 v80, v80, v253
	v_mul_f32_e32 v81, v81, v254
	v_cvt_pk_bf16_f32 v78, v78, v79
	v_cvt_pk_bf16_f32 v79, v80, v81
	global_store_dwordx2 v[94:95], v[78:79], off offset:32
	v_lshl_add_u64 v[88:89], v[134:135], 0, v[110:111]
	v_mad_u64_u32 v[90:91], s[18:19], v88, s61, v[136:137]
	v_mad_i32_i24 v91, v89, s61, v91
	v_mul_f32_e32 v74, v74, v251
	v_mul_f32_e32 v75, v75, v252
	v_mul_f32_e32 v76, v76, v253
	v_mul_f32_e32 v77, v77, v254
	v_cvt_pk_bf16_f32 v74, v74, v75
	v_cvt_pk_bf16_f32 v75, v76, v77
	global_store_dwordx2 v[90:91], v[74:75], off offset:32
	v_lshl_add_u64 v[84:85], v[134:135], 0, v[106:107]
	v_mad_u64_u32 v[86:87], s[18:19], v84, s61, v[136:137]
	v_mad_i32_i24 v87, v85, s61, v87
	v_mul_f32_e32 v70, v70, v251
	v_mul_f32_e32 v71, v71, v252
	v_mul_f32_e32 v72, v72, v253
	v_mul_f32_e32 v73, v73, v254
	v_cvt_pk_bf16_f32 v70, v70, v71
	v_cvt_pk_bf16_f32 v71, v72, v73
	global_store_dwordx2 v[86:87], v[70:71], off offset:32
	v_lshl_add_u64 v[80:81], v[134:135], 0, v[102:103]
	v_mad_u64_u32 v[82:83], s[18:19], v80, s61, v[136:137]
	v_mad_i32_i24 v83, v81, s61, v83
	v_mul_f32_e32 v66, v66, v251
	v_mul_f32_e32 v67, v67, v252
	v_mul_f32_e32 v68, v68, v253
	v_mul_f32_e32 v69, v69, v254
	v_cvt_pk_bf16_f32 v66, v66, v67
	v_cvt_pk_bf16_f32 v67, v68, v69
	global_store_dwordx2 v[82:83], v[66:67], off offset:32
	v_or_b32_e32 v66, 32, v142
	v_ashrrev_i32_e32 v67, 31, v66
	v_lshl_add_u64 v[66:67], v[98:99], 0, v[66:67]
	v_lshl_add_u64 v[66:67], v[66:67], 2, s[36:37]
	global_load_dwordx4 v[68:71], v[138:139], off offset:128
	global_load_dwordx4 v[72:75], v[66:67], off
	v_mov_b64_e32 v[76:77], s[48:49]
	v_lshl_add_u64 v[78:79], v[134:135], 0, v[140:141]
	v_mad_u64_u32 v[80:81], s[18:19], v78, s61, v[136:137]
	v_mad_i32_i24 v81, v79, s61, v81
	s_waitcnt vmcnt(0)
; __device__ __forceinline__ unsigned pack2(float a, float b) { unsigned r; asm("v_cvt_pk_bf16_f32 %0, %1, %2" : "=v"(r) : "v"(a), "v"(b)); return r; }
;   __device__ __forceinline__ void r4(int g, int rig, int col, f32x4 v) const {
;     const size_t row = (size_t)g * 2304 + rig;
;     const f32x4 t = *(const f32x4*)(part + row) + *(const f32x4*)(part + 18432 + row);
;     f32x4 s;
; #pragma unroll
;     for (int j = 0; j < 4; ++j) s[j] = rsqrtf(t[j] * (1.0f / 256.0f) + 1e-6f);
;     uint2 u; u.x = pack2(v[0] * s[0], v[1] * s[1]); u.y = pack2(v[2] * s[2], v[3] * s[3]);
;     *(uint2*)(out + ((size_t)g * 1024 + col) * 2304 + rig) = u;
;   }
; template <bool SWAP, class Epi, bool THIN = false> ...
;     ...
;     } else if constexpr (Epi::KIND == 1) {
; #pragma unroll
;       for (int m = 0; m < 4; ++m) {
;         const int rig = rig0 + rw + m * 16 + fq_e * 4;
; #pragma unroll
;         for (int n = 0; n < 8; ++n) {
;           const int col = nt * 256 + wc_e * 128 + n * 16 + fr_e;
;           if (col < N) epi.r4(g, rig, col, acc[m][n]);
;         }
;       }
	v_pk_add_f32 v[68:69], v[68:69], v[72:73]
	v_pk_add_f32 v[70:71], v[70:71], v[74:75]
	v_pk_fma_f32 v[68:69], v[68:69], s[44:45], v[76:77] op_sel_hi:[1,0,0]
	v_pk_fma_f32 v[70:71], v[70:71], s[44:45], v[76:77] op_sel_hi:[1,0,0]
	v_mul_f32_e32 v72, 0x4b800000, v68
	v_mul_f32_e32 v73, 0x4b800000, v69
	v_cmp_gt_f32_e64 s[18:19], s60, v68
	v_cmp_gt_f32_e64 s[20:21], s60, v69
	v_mul_f32_e32 v74, 0x4b800000, v70
	v_mul_f32_e32 v75, 0x4b800000, v71
	v_cndmask_b32_e64 v68, v68, v72, s[18:19]
	v_cndmask_b32_e64 v69, v69, v73, s[20:21]
	v_cmp_gt_f32_e64 s[22:23], s60, v70
	v_cmp_gt_f32_e64 s[24:25], s60, v71
	v_rsq_f32_e32 v68, v68
	v_cndmask_b32_e64 v70, v70, v74, s[22:23]
	v_cndmask_b32_e64 v71, v71, v75, s[24:25]
	v_rsq_f32_e32 v69, v69
	v_rsq_f32_e32 v70, v70
	v_rsq_f32_e32 v71, v71
	v_mul_f32_e32 v72, 0x45800000, v68
	v_mul_f32_e32 v73, 0x45800000, v69
	v_mul_f32_e32 v74, 0x45800000, v70
	v_mul_f32_e32 v75, 0x45800000, v71
	v_cndmask_b32_e64 v68, v68, v72, s[18:19]
	v_cndmask_b32_e64 v69, v69, v73, s[20:21]
	v_cndmask_b32_e64 v70, v70, v74, s[22:23]
	v_cndmask_b32_e64 v71, v71, v75, s[24:25]
	v_mov_b32_e32 v251, v68
	v_mov_b32_e32 v252, v69
	v_mov_b32_e32 v253, v70
	v_mov_b32_e32 v254, v71
	v_mul_f32_e32 v62, v62, v68
	v_mul_f32_e32 v63, v63, v69
	v_mul_f32_e32 v64, v64, v70
	v_mul_f32_e32 v65, v65, v71
	v_cvt_pk_bf16_f32 v62, v62, v63
	v_cvt_pk_bf16_f32 v63, v64, v65
	global_store_dwordx2 v[80:81], v[62:63], off offset:64
	v_lshl_add_u64 v[74:75], v[134:135], 0, v[126:127]
	v_mad_u64_u32 v[76:77], s[18:19], v74, s61, v[136:137]
	v_mad_i32_i24 v77, v75, s61, v77
	v_mul_f32_e32 v58, v58, v251
	v_mul_f32_e32 v59, v59, v252
	v_mul_f32_e32 v60, v60, v253
	v_mul_f32_e32 v61, v61, v254
	v_cvt_pk_bf16_f32 v58, v58, v59
	v_cvt_pk_bf16_f32 v59, v60, v61
	global_store_dwordx2 v[76:77], v[58:59], off offset:64
	v_lshl_add_u64 v[70:71], v[134:135], 0, v[122:123]
	v_mad_u64_u32 v[72:73], s[18:19], v70, s61, v[136:137]
	v_mad_i32_i24 v73, v71, s61, v73
	v_mul_f32_e32 v54, v54, v251
	v_mul_f32_e32 v55, v55, v252
	v_mul_f32_e32 v56, v56, v253
	v_mul_f32_e32 v57, v57, v254
	v_cvt_pk_bf16_f32 v54, v54, v55
	v_cvt_pk_bf16_f32 v55, v56, v57
	global_store_dwordx2 v[72:73], v[54:55], off offset:64
	v_lshl_add_u64 v[64:65], v[134:135], 0, v[118:119]
	v_mad_u64_u32 v[68:69], s[18:19], v64, s61, v[136:137]
	v_mad_i32_i24 v69, v65, s61, v69
	v_mul_f32_e32 v50, v50, v251
	v_mul_f32_e32 v51, v51, v252
	v_mul_f32_e32 v52, v52, v253
	v_mul_f32_e32 v53, v53, v254
	v_cvt_pk_bf16_f32 v50, v50, v51
	v_cvt_pk_bf16_f32 v51, v52, v53
	global_store_dwordx2 v[68:69], v[50:51], off offset:64
	v_lshl_add_u64 v[60:61], v[134:135], 0, v[114:115]
	v_mad_u64_u32 v[62:63], s[18:19], v60, s61, v[136:137]
	v_mad_i32_i24 v63, v61, s61, v63
	v_mul_f32_e32 v46, v46, v251
	v_mul_f32_e32 v47, v47, v252
	v_mul_f32_e32 v48, v48, v253
	v_mul_f32_e32 v49, v49, v254
	v_cvt_pk_bf16_f32 v46, v46, v47
	v_cvt_pk_bf16_f32 v47, v48, v49
	global_store_dwordx2 v[62:63], v[46:47], off offset:64
	v_lshl_add_u64 v[56:57], v[134:135], 0, v[110:111]
	v_mad_u64_u32 v[58:59], s[18:19], v56, s61, v[136:137]
	v_mad_i32_i24 v59, v57, s61, v59
	v_mul_f32_e32 v42, v42, v251
	v_mul_f32_e32 v43, v43, v252
	v_mul_f32_e32 v44, v44, v253
	v_mul_f32_e32 v45, v45, v254
	v_cvt_pk_bf16_f32 v42, v42, v43
	v_cvt_pk_bf16_f32 v43, v44, v45
	global_store_dwordx2 v[58:59], v[42:43], off offset:64
	v_lshl_add_u64 v[52:53], v[134:135], 0, v[106:107]
	v_mad_u64_u32 v[54:55], s[18:19], v52, s61, v[136:137]
	v_mad_i32_i24 v55, v53, s61, v55
	v_mul_f32_e32 v38, v38, v251
	v_mul_f32_e32 v39, v39, v252
	v_mul_f32_e32 v40, v40, v253
	v_mul_f32_e32 v41, v41, v254
	v_cvt_pk_bf16_f32 v38, v38, v39
	v_cvt_pk_bf16_f32 v39, v40, v41
	global_store_dwordx2 v[54:55], v[38:39], off offset:64
	v_lshl_add_u64 v[48:49], v[134:135], 0, v[102:103]
	v_mad_u64_u32 v[50:51], s[18:19], v48, s61, v[136:137]
	v_mad_i32_i24 v51, v49, s61, v51
	v_mul_f32_e32 v34, v34, v251
	v_mul_f32_e32 v35, v35, v252
	v_mul_f32_e32 v36, v36, v253
	v_mul_f32_e32 v37, v37, v254
	v_cvt_pk_bf16_f32 v34, v34, v35
	v_cvt_pk_bf16_f32 v35, v36, v37
	global_store_dwordx2 v[50:51], v[34:35], off offset:64
	v_or_b32_e32 v34, 48, v142
	v_ashrrev_i32_e32 v35, 31, v34
	v_lshl_add_u64 v[34:35], v[98:99], 0, v[34:35]
	v_lshl_add_u64 v[34:35], v[34:35], 2, s[36:37]
	global_load_dwordx4 v[36:39], v[138:139], off offset:192
	global_load_dwordx4 v[40:43], v[34:35], off
	v_mov_b64_e32 v[44:45], s[48:49]
	v_lshl_add_u64 v[46:47], v[134:135], 0, v[140:141]
	v_mad_u64_u32 v[48:49], s[18:19], v46, s61, v[136:137]
	v_mad_i32_i24 v49, v47, s61, v49
	s_waitcnt vmcnt(0)
; __device__ __forceinline__ unsigned pack2(float a, float b) { unsigned r; asm("v_cvt_pk_bf16_f32 %0, %1, %2" : "=v"(r) : "v"(a), "v"(b)); return r; }
;   __device__ __forceinline__ void r4(int g, int rig, int col, f32x4 v) const {
;     const size_t row = (size_t)g * 2304 + rig;
;     const f32x4 t = *(const f32x4*)(part + row) + *(const f32x4*)(part + 18432 + row);
;     f32x4 s;
; #pragma unroll
;     for (int j = 0; j < 4; ++j) s[j] = rsqrtf(t[j] * (1.0f / 256.0f) + 1e-6f);
;     uint2 u; u.x = pack2(v[0] * s[0], v[1] * s[1]); u.y = pack2(v[2] * s[2], v[3] * s[3]);
;     *(uint2*)(out + ((size_t)g * 1024 + col) * 2304 + rig) = u;
;   }
; template <bool SWAP, class Epi, bool THIN = false> ...
;     ...
; #pragma unroll
;       for (int m = 0; m < 4; ++m) {
;         const int rig = rig0 + rw + m * 16 + fq_e * 4;
; #pragma unroll
;         for (int n = 0; n < 8; ++n) {
;           const int col = nt * 256 + wc_e * 128 + n * 16 + fr_e;
;           if (col < N) epi.r4(g, rig, col, acc[m][n]);
;         }
;       }
	v_pk_add_f32 v[36:37], v[36:37], v[40:41]
	v_pk_add_f32 v[38:39], v[38:39], v[42:43]
	v_pk_fma_f32 v[36:37], v[36:37], s[44:45], v[44:45] op_sel_hi:[1,0,0]
	v_pk_fma_f32 v[38:39], v[38:39], s[44:45], v[44:45] op_sel_hi:[1,0,0]
	v_mul_f32_e32 v40, 0x4b800000, v36
	v_mul_f32_e32 v41, 0x4b800000, v37
	v_cmp_gt_f32_e32 vcc, s60, v36
	v_cmp_gt_f32_e64 s[18:19], s60, v37
	v_mul_f32_e32 v42, 0x4b800000, v38
	v_mul_f32_e32 v43, 0x4b800000, v39
	v_cndmask_b32_e32 v36, v36, v40, vcc
	v_cndmask_b32_e64 v37, v37, v41, s[18:19]
	v_cmp_gt_f32_e64 s[20:21], s60, v38
	v_cmp_gt_f32_e64 s[22:23], s60, v39
	v_rsq_f32_e32 v36, v36
	v_cndmask_b32_e64 v38, v38, v42, s[20:21]
	v_cndmask_b32_e64 v39, v39, v43, s[22:23]
	v_rsq_f32_e32 v37, v37
	v_rsq_f32_e32 v38, v38
	v_rsq_f32_e32 v39, v39
	v_mul_f32_e32 v40, 0x45800000, v36
	v_mul_f32_e32 v41, 0x45800000, v37
	v_mul_f32_e32 v42, 0x45800000, v38
	v_mul_f32_e32 v43, 0x45800000, v39
	v_cndmask_b32_e32 v36, v36, v40, vcc
	v_cndmask_b32_e64 v37, v37, v41, s[18:19]
	v_cndmask_b32_e64 v38, v38, v42, s[20:21]
	v_cndmask_b32_e64 v39, v39, v43, s[22:23]
	v_mov_b32_e32 v251, v36
	v_mov_b32_e32 v252, v37
	v_mov_b32_e32 v253, v38
	v_mov_b32_e32 v254, v39
	v_mul_f32_e32 v30, v30, v36
	v_mul_f32_e32 v31, v31, v37
	v_mul_f32_e32 v32, v32, v38
	v_mul_f32_e32 v33, v33, v39
	v_cvt_pk_bf16_f32 v30, v30, v31
	v_cvt_pk_bf16_f32 v31, v32, v33
	global_store_dwordx2 v[48:49], v[30:31], off offset:96
	v_lshl_add_u64 v[42:43], v[134:135], 0, v[126:127]
	v_mad_u64_u32 v[44:45], s[4:5], v42, s61, v[136:137]
	v_mad_i32_i24 v45, v43, s61, v45
	v_mul_f32_e32 v26, v26, v251
	v_mul_f32_e32 v27, v27, v252
	v_mul_f32_e32 v28, v28, v253
	v_mul_f32_e32 v29, v29, v254
	v_cvt_pk_bf16_f32 v26, v26, v27
	v_cvt_pk_bf16_f32 v27, v28, v29
	global_store_dwordx2 v[44:45], v[26:27], off offset:96
	v_lshl_add_u64 v[38:39], v[134:135], 0, v[122:123]
	v_mad_u64_u32 v[40:41], s[4:5], v38, s61, v[136:137]
	v_mad_i32_i24 v41, v39, s61, v41
	v_mul_f32_e32 v22, v22, v251
	v_mul_f32_e32 v23, v23, v252
	v_mul_f32_e32 v24, v24, v253
	v_mul_f32_e32 v25, v25, v254
	v_cvt_pk_bf16_f32 v22, v22, v23
	v_cvt_pk_bf16_f32 v23, v24, v25
	global_store_dwordx2 v[40:41], v[22:23], off offset:96
	v_lshl_add_u64 v[32:33], v[134:135], 0, v[118:119]
	v_mad_u64_u32 v[36:37], s[4:5], v32, s61, v[136:137]
	v_mad_i32_i24 v37, v33, s61, v37
	v_mul_f32_e32 v18, v18, v251
	v_mul_f32_e32 v19, v19, v252
	v_mul_f32_e32 v20, v20, v253
	v_mul_f32_e32 v21, v21, v254
	v_cvt_pk_bf16_f32 v18, v18, v19
	v_cvt_pk_bf16_f32 v19, v20, v21
	global_store_dwordx2 v[36:37], v[18:19], off offset:96
	v_lshl_add_u64 v[28:29], v[134:135], 0, v[114:115]
	v_mad_u64_u32 v[30:31], s[4:5], v28, s61, v[136:137]
	v_mad_i32_i24 v31, v29, s61, v31
	v_mul_f32_e32 v14, v14, v251
	v_mul_f32_e32 v15, v15, v252
	v_mul_f32_e32 v16, v16, v253
	v_mul_f32_e32 v17, v17, v254
	v_cvt_pk_bf16_f32 v14, v14, v15
	v_cvt_pk_bf16_f32 v15, v16, v17
	global_store_dwordx2 v[30:31], v[14:15], off offset:96
	v_lshl_add_u64 v[24:25], v[134:135], 0, v[110:111]
	v_mad_u64_u32 v[26:27], s[4:5], v24, s61, v[136:137]
	v_mad_i32_i24 v27, v25, s61, v27
	v_mul_f32_e32 v10, v10, v251
	v_mul_f32_e32 v11, v11, v252
	v_mul_f32_e32 v12, v12, v253
	v_mul_f32_e32 v13, v13, v254
	v_cvt_pk_bf16_f32 v10, v10, v11
	v_cvt_pk_bf16_f32 v11, v12, v13
	global_store_dwordx2 v[26:27], v[10:11], off offset:96
	v_lshl_add_u64 v[20:21], v[134:135], 0, v[106:107]
	v_mad_u64_u32 v[22:23], s[4:5], v20, s61, v[136:137]
	v_mad_i32_i24 v23, v21, s61, v23
	v_mul_f32_e32 v6, v6, v251
	v_mul_f32_e32 v7, v7, v252
	v_mul_f32_e32 v8, v8, v253
	v_mul_f32_e32 v9, v9, v254
	v_cvt_pk_bf16_f32 v6, v6, v7
	v_cvt_pk_bf16_f32 v7, v8, v9
	global_store_dwordx2 v[22:23], v[6:7], off offset:96
	v_lshl_add_u64 v[16:17], v[134:135], 0, v[102:103]
	v_mad_u64_u32 v[18:19], s[4:5], v16, s61, v[136:137]
	v_mad_i32_i24 v19, v17, s61, v19
	v_mul_f32_e32 v2, v2, v251
	v_mul_f32_e32 v3, v3, v252
	v_mul_f32_e32 v4, v4, v253
	v_mul_f32_e32 v5, v5, v254
	v_cvt_pk_bf16_f32 v2, v2, v3
	v_cvt_pk_bf16_f32 v3, v4, v5
	global_store_dwordx2 v[18:19], v[2:3], off offset:96
	s_branch .LBB0_1886

; template <bool SWAP, class Epi, bool THIN = false> ...
;     ...
;   for (; v < voff + ntiles; v += grid) {
;     ...
;       __syncthreads();
;     }
;     asm volatile("s_waitcnt vmcnt(0)" ::: "memory");
;     __syncthreads();
.LBB0_2328:
	s_waitcnt lgkmcnt(0)
	s_or_b64 exec, exec, s[4:5]
	s_barrier
	s_waitcnt vmcnt(0)
	s_add_i32 s3, s3, s54
	s_cmpk_lt_i32 s3, 0x5d8
	s_barrier
	s_cbranch_scc0 .LBB0_2352

; template <bool SWAP, class Epi, bool THIN = false> ...
;     ...
;     for (int st = 0; st < ns; ++st) {
;       asm volatile("s_waitcnt vmcnt(0)" ::: "memory");
;       __builtin_amdgcn_s_barrier();
;       asm volatile("" ::: "memory");
;       if (st + 1 < ns) {
;         char* nb = smem + ((st + 1) & 1) * 65536;
;         const int ko = (st + 1) * 64;
; #pragma unroll
;         for (int i = 0; i < 4; ++i) { GLDS16(A + (size_t)(ap[i] + ko), nb + tid * 16 + i * 8192); GLDS16(Bt + (size_t)(bp[i] + ko), nb + 32768 + tid * 16 + i * 8192); }
;       }
;       const char* sa = smem + (st & 1) * 65536 + (wr * 64 + fr) * 128;
;       const char* sb = smem + (st & 1) * 65536 + 32768 + (wc * 128 + fr) * 128;
;       if constexpr (THIN) {
;         if (wc == 0) {
; #pragma unroll
;           for (int ks = 0; ks < 2; ++ks) {
;             bf16x8 af[4], bf[2];
; #pragma unroll
;             for (int m = 0; m < 4; ++m) af[m] = *(const bf16x8*)(sa + m * 2048 + (((ks * 4 + fq) ^ swz) << 4));
; #pragma unroll
;             for (int n = 0; n < 2; ++n) bf[n] = *(const bf16x8*)(sb + n * 2048 + (((ks * 4 + fq) ^ swz) << 4));
; #pragma unroll
;             for (int m = 0; m < 4; ++m)
; #pragma unroll
;               for (int n = 0; n < 2; ++n)
;                 acc[m][n] = SWAP ? __builtin_amdgcn_mfma_f32_16x16x32_bf16(bf[n], af[m], acc[m][n], 0, 0, 0)
;                                  : __builtin_amdgcn_mfma_f32_16x16x32_bf16(af[m], bf[n], acc[m][n], 0, 0, 0);
;           }
;         }
;       } else {
;       bf16x8 afA[4], afB[4], bfb[2][2];
; #pragma unroll
;       for (int m = 0; m < 4; ++m) afA[m] = *(const bf16x8*)(sa + m * 2048 + ((fq ^ swz) << 4));
; #pragma unroll
;       for (int n = 0; n < 2; ++n) bfb[0][n] = *(const bf16x8*)(sb + n * 2048 + ((fq ^ swz) << 4));
; #pragma unroll
;       for (int gq = 0; gq < 8; ++gq) {
;         const int ks = gq >> 2, nh = gq & 3;
;         if (gq < 7) {
;           const int ks2 = (gq + 1) >> 2, nh2 = (gq + 1) & 3;
; #pragma unroll
;           for (int n = 0; n < 2; ++n) bfb[(gq + 1) & 1][n] = *(const bf16x8*)(sb + (nh2 * 2 + n) * 2048 + (((ks2 * 4 + fq) ^ swz) << 4));
;         }
;         if (gq == 3) {
; #pragma unroll
;           for (int m = 0; m < 4; ++m) afB[m] = *(const bf16x8*)(sa + m * 2048 + (((4 + fq) ^ swz) << 4));
;         }
;         __builtin_amdgcn_sched_barrier(0);
; #pragma unroll
.LBB0_2334:
	s_add_i32 s8, s7, 0x10000
	s_and_b32 s9, s8, 0x10000
	v_add_u32_e32 v170, s9, v135
	s_nop 0
	v_readfirstlane_b32 s9, v170
	s_waitcnt vmcnt(0)
	s_barrier
	s_and_b32 s7, s7, 0x10000
	v_or_b32_e32 v204, s7, v139
	v_add_u32_e32 v205, v204, v140
	v_add_u32_e32 v136, s7, v138
	v_add_u32_e32 v180, v136, v140
	ds_read_b128 v[168:171], v180
	ds_read_b128 v[172:175], v180 offset:2048
	ds_read_b128 v[176:179], v180 offset:4096
	ds_read_b128 v[180:183], v180 offset:6144
	ds_read_b128 v[184:187], v205 offset:32768
	ds_read_b128 v[188:191], v205 offset:34816
	ds_read_b128 v[192:195], v205 offset:36864
	ds_read_b128 v[196:199], v205 offset:38912
	v_add_u32_e32 v136, v136, v141
	s_waitcnt lgkmcnt(3)
	v_mfma_f32_16x16x32_bf16 v[126:129], v[184:187], v[168:171], v[126:129]
	s_mov_b32 m0, s9
	v_mfma_f32_16x16x32_bf16 v[110:113], v[184:187], v[172:175], v[110:113]
	global_load_lds_dwordx4 v167, s[16:17]
	v_add_u32_e32 v167, 0x80, v167
	v_mfma_f32_16x16x32_bf16 v[82:85], v[184:187], v[176:179], v[82:85]
	v_mfma_f32_16x16x32_bf16 v[50:53], v[184:187], v[180:183], v[50:53]
	ds_read_b128 v[184:187], v205 offset:40960
	ds_read_b128 v[200:203], v205 offset:43008
	s_waitcnt lgkmcnt(4)
	v_mfma_f32_16x16x32_bf16 v[122:125], v[188:191], v[168:171], v[122:125]
	s_add_u32 m0, s9, 0x8000
	v_mfma_f32_16x16x32_bf16 v[106:109], v[188:191], v[172:175], v[106:109]
	global_load_lds_dwordx4 v166, s[18:19]
	v_add_u32_e32 v166, 0x80, v166
	v_mfma_f32_16x16x32_bf16 v[78:81], v[188:191], v[176:179], v[78:81]
	v_mfma_f32_16x16x32_bf16 v[42:45], v[188:191], v[180:183], v[42:45]
	s_waitcnt lgkmcnt(3)
	v_mfma_f32_16x16x32_bf16 v[118:121], v[192:195], v[168:171], v[118:121]
	s_add_u32 m0, s9, 0x2000
	v_mfma_f32_16x16x32_bf16 v[94:97], v[192:195], v[172:175], v[94:97]
	global_load_lds_dwordx4 v165, s[16:17]
	v_add_u32_e32 v165, 0x80, v165
	v_mfma_f32_16x16x32_bf16 v[58:61], v[192:195], v[176:179], v[58:61]
	v_mfma_f32_16x16x32_bf16 v[26:29], v[192:195], v[180:183], v[26:29]
	ds_read_b128 v[188:191], v205 offset:45056
	ds_read_b128 v[192:195], v205 offset:47104
	s_waitcnt lgkmcnt(4)
	v_mfma_f32_16x16x32_bf16 v[114:117], v[196:199], v[168:171], v[114:117]
	s_add_u32 m0, s9, 0xa000
	v_mfma_f32_16x16x32_bf16 v[90:93], v[196:199], v[172:175], v[90:93]
	global_load_lds_dwordx4 v164, s[18:19]
	v_add_u32_e32 v164, 0x80, v164
	v_mfma_f32_16x16x32_bf16 v[54:57], v[196:199], v[176:179], v[54:57]
	v_mfma_f32_16x16x32_bf16 v[22:25], v[196:199], v[180:183], v[22:25]
	v_add_u32_e32 v220, v204, v141
	s_waitcnt lgkmcnt(3)
	v_mfma_f32_16x16x32_bf16 v[102:105], v[184:187], v[168:171], v[102:105]
	ds_read_b128 v[196:199], v220 offset:32768
	ds_read_b128 v[204:207], v220 offset:34816
	s_add_u32 m0, s9, 0x4000
	v_mfma_f32_16x16x32_bf16 v[74:77], v[184:187], v[172:175], v[74:77]
	global_load_lds_dwordx4 v163, s[16:17]
	v_add_u32_e32 v163, 0x80, v163
	v_mfma_f32_16x16x32_bf16 v[46:49], v[184:187], v[176:179], v[46:49]
	v_mfma_f32_16x16x32_bf16 v[10:13], v[184:187], v[180:183], v[10:13]
	ds_read_b128 v[184:187], v136
	ds_read_b128 v[208:211], v136 offset:2048
	ds_read_b128 v[212:215], v136 offset:4096
	ds_read_b128 v[216:219], v136 offset:6144
	s_waitcnt lgkmcnt(8)
	v_mfma_f32_16x16x32_bf16 v[98:101], v[200:203], v[168:171], v[98:101]
	s_add_u32 m0, s9, 0xc000
	v_mfma_f32_16x16x32_bf16 v[66:69], v[200:203], v[172:175], v[66:69]
	global_load_lds_dwordx4 v162, s[18:19]
	v_add_u32_e32 v162, 0x80, v162
	v_mfma_f32_16x16x32_bf16 v[30:33], v[200:203], v[176:179], v[30:33]
	v_mfma_f32_16x16x32_bf16 v[6:9], v[200:203], v[180:183], v[6:9]
	s_waitcnt lgkmcnt(7)
	v_mfma_f32_16x16x32_bf16 v[70:73], v[188:191], v[168:171], v[70:73]
	s_add_u32 m0, s9, 0x6000
	s_waitcnt lgkmcnt(6)
	v_mfma_f32_16x16x32_bf16 v[62:65], v[192:195], v[168:171], v[62:65]
	global_load_lds_dwordx4 v161, s[16:17]
	v_add_u32_e32 v161, 0x80, v161
	v_mfma_f32_16x16x32_bf16 v[38:41], v[188:191], v[172:175], v[38:41]
	v_mfma_f32_16x16x32_bf16 v[34:37], v[192:195], v[172:175], v[34:37]
	ds_read_b128 v[168:171], v220 offset:36864
	ds_read_b128 v[172:175], v220 offset:38912
	v_mfma_f32_16x16x32_bf16 v[18:21], v[188:191], v[176:179], v[18:21]
	s_add_u32 m0, s9, 0xe000
	v_mfma_f32_16x16x32_bf16 v[14:17], v[192:195], v[176:179], v[14:17]
	global_load_lds_dwordx4 v160, s[18:19]
	v_add_u32_e32 v160, 0x80, v160
	v_mfma_f32_16x16x32_bf16 v[2:5], v[188:191], v[180:183], v[2:5]
	v_mfma_f32_16x16x32_bf16 v[86:89], v[192:195], v[180:183], v[86:89]
	ds_read_b128 v[176:179], v220 offset:40960
	ds_read_b128 v[180:183], v220 offset:43008
	s_waitcnt lgkmcnt(7)
	v_mfma_f32_16x16x32_bf16 v[126:129], v[196:199], v[184:187], v[126:129]
	v_mfma_f32_16x16x32_bf16 v[122:125], v[204:207], v[184:187], v[122:125]
	s_waitcnt lgkmcnt(6)
	v_mfma_f32_16x16x32_bf16 v[110:113], v[196:199], v[208:211], v[110:113]
	v_mfma_f32_16x16x32_bf16 v[106:109], v[204:207], v[208:211], v[106:109]
	s_waitcnt lgkmcnt(5)
	v_mfma_f32_16x16x32_bf16 v[82:85], v[196:199], v[212:215], v[82:85]
	v_mfma_f32_16x16x32_bf16 v[78:81], v[204:207], v[212:215], v[78:81]
	s_waitcnt lgkmcnt(4)
	v_mfma_f32_16x16x32_bf16 v[50:53], v[196:199], v[216:219], v[50:53]
	v_mfma_f32_16x16x32_bf16 v[42:45], v[204:207], v[216:219], v[42:45]
	s_waitcnt lgkmcnt(3)
	v_mfma_f32_16x16x32_bf16 v[118:121], v[168:171], v[184:187], v[118:121]
	v_mfma_f32_16x16x32_bf16 v[94:97], v[168:171], v[208:211], v[94:97]
	v_mfma_f32_16x16x32_bf16 v[58:61], v[168:171], v[212:215], v[58:61]
	v_mfma_f32_16x16x32_bf16 v[26:29], v[168:171], v[216:219], v[26:29]
	ds_read_b128 v[168:171], v220 offset:45056
	ds_read_b128 v[188:191], v220 offset:47104
	s_waitcnt lgkmcnt(4)
; template <bool SWAP, class Epi, bool THIN = false> ...
;     ...
;     for (int st = 0; st < ns; ++st) {
;       asm volatile("s_waitcnt vmcnt(0)" ::: "memory");
;       __builtin_amdgcn_s_barrier();
;       asm volatile("" ::: "memory");
;       if (st + 1 < ns) {
;         char* nb = smem + ((st + 1) & 1) * 65536;
;         const int ko = (st + 1) * 64;
; #pragma unroll
;         for (int i = 0; i < 4; ++i) { GLDS16(A + (size_t)(ap[i] + ko), nb + tid * 16 + i * 8192); GLDS16(Bt + (size_t)(bp[i] + ko), nb + 32768 + tid * 16 + i * 8192); }
;       }
;       const char* sa = smem + (st & 1) * 65536 + (wr * 64 + fr) * 128;
;       const char* sb = smem + (st & 1) * 65536 + 32768 + (wc * 128 + fr) * 128;
;       if constexpr (THIN) {
;         if (wc == 0) {
; #pragma unroll
;           for (int ks = 0; ks < 2; ++ks) {
;             bf16x8 af[4], bf[2];
; #pragma unroll
;             for (int m = 0; m < 4; ++m) af[m] = *(const bf16x8*)(sa + m * 2048 + (((ks * 4 + fq) ^ swz) << 4));
; #pragma unroll
;             for (int n = 0; n < 2; ++n) bf[n] = *(const bf16x8*)(sb + n * 2048 + (((ks * 4 + fq) ^ swz) << 4));
; #pragma unroll
;             for (int m = 0; m < 4; ++m)
; #pragma unroll
;               for (int n = 0; n < 2; ++n)
;                 acc[m][n] = SWAP ? __builtin_amdgcn_mfma_f32_16x16x32_bf16(bf[n], af[m], acc[m][n], 0, 0, 0)
;                                  : __builtin_amdgcn_mfma_f32_16x16x32_bf16(af[m], bf[n], acc[m][n], 0, 0, 0);
;           }
;         }
;       } else {
;       bf16x8 afA[4], afB[4], bfb[2][2];
; #pragma unroll
;       for (int m = 0; m < 4; ++m) afA[m] = *(const bf16x8*)(sa + m * 2048 + ((fq ^ swz) << 4));
; #pragma unroll
;       for (int n = 0; n < 2; ++n) bfb[0][n] = *(const bf16x8*)(sb + n * 2048 + ((fq ^ swz) << 4));
; #pragma unroll
;       for (int gq = 0; gq < 8; ++gq) {
;         const int ks = gq >> 2, nh = gq & 3;
;         if (gq < 7) {
;           const int ks2 = (gq + 1) >> 2, nh2 = (gq + 1) & 3;
; #pragma unroll
;           for (int n = 0; n < 2; ++n) bfb[(gq + 1) & 1][n] = *(const bf16x8*)(sb + (nh2 * 2 + n) * 2048 + (((ks2 * 4 + fq) ^ swz) << 4));
;         }
;         if (gq == 3) {
; #pragma unroll
;           for (int m = 0; m < 4; ++m) afB[m] = *(const bf16x8*)(sa + m * 2048 + (((4 + fq) ^ swz) << 4));
;         }
;         __builtin_amdgcn_sched_barrier(0);
; #pragma unroll
	v_mfma_f32_16x16x32_bf16 v[114:117], v[172:175], v[184:187], v[114:117]
	v_mfma_f32_16x16x32_bf16 v[90:93], v[172:175], v[208:211], v[90:93]
	v_mfma_f32_16x16x32_bf16 v[54:57], v[172:175], v[212:215], v[54:57]
	v_mfma_f32_16x16x32_bf16 v[22:25], v[172:175], v[216:219], v[22:25]
	s_waitcnt lgkmcnt(3)
	v_mfma_f32_16x16x32_bf16 v[102:105], v[176:179], v[184:187], v[102:105]
	s_waitcnt lgkmcnt(2)
	v_mfma_f32_16x16x32_bf16 v[98:101], v[180:183], v[184:187], v[98:101]
	v_mfma_f32_16x16x32_bf16 v[74:77], v[176:179], v[208:211], v[74:77]
	v_mfma_f32_16x16x32_bf16 v[66:69], v[180:183], v[208:211], v[66:69]
	v_mfma_f32_16x16x32_bf16 v[46:49], v[176:179], v[212:215], v[46:49]
	v_mfma_f32_16x16x32_bf16 v[30:33], v[180:183], v[212:215], v[30:33]
	v_mfma_f32_16x16x32_bf16 v[10:13], v[176:179], v[216:219], v[10:13]
	v_mfma_f32_16x16x32_bf16 v[6:9], v[180:183], v[216:219], v[6:9]
	s_waitcnt lgkmcnt(1)
	v_mfma_f32_16x16x32_bf16 v[70:73], v[168:171], v[184:187], v[70:73]
	s_add_i32 s5, s5, 64
	s_cmpk_eq_i32 s5, 0x3c0
	s_mov_b32 s7, s8
	s_waitcnt lgkmcnt(0)
	v_mfma_f32_16x16x32_bf16 v[62:65], v[188:191], v[184:187], v[62:65]
	v_mfma_f32_16x16x32_bf16 v[38:41], v[168:171], v[208:211], v[38:41]
	v_mfma_f32_16x16x32_bf16 v[34:37], v[188:191], v[208:211], v[34:37]
	v_mfma_f32_16x16x32_bf16 v[18:21], v[168:171], v[212:215], v[18:21]
	v_mfma_f32_16x16x32_bf16 v[14:17], v[188:191], v[212:215], v[14:17]
	v_mfma_f32_16x16x32_bf16 v[2:5], v[168:171], v[216:219], v[2:5]
	v_mfma_f32_16x16x32_bf16 v[86:89], v[188:191], v[216:219], v[86:89]
	s_cbranch_scc0 .LBB0_2334
	s_waitcnt vmcnt(0)
	s_barrier
	v_add_u32_e32 v136, v150, v140
	ds_read_b128 v[160:163], v136
	ds_read_b128 v[164:167], v136 offset:2048
	ds_read_b128 v[168:171], v136 offset:4096
	ds_read_b128 v[172:175], v136 offset:6144
	v_add_u32_e32 v136, v151, v140
	ds_read_b128 v[176:179], v136
	ds_read_b128 v[180:183], v136 offset:2048
	ds_read_b128 v[184:187], v136 offset:4096
	ds_read_b128 v[188:191], v136 offset:6144
	s_waitcnt lgkmcnt(0)
	v_mfma_f32_16x16x32_bf16 v[126:129], v[176:179], v[160:163], v[126:129]
	v_mfma_f32_16x16x32_bf16 v[110:113], v[176:179], v[164:167], v[110:113]
	v_mfma_f32_16x16x32_bf16 v[82:85], v[176:179], v[168:171], v[82:85]
	v_mfma_f32_16x16x32_bf16 v[50:53], v[176:179], v[172:175], v[50:53]
	ds_read_b128 v[176:179], v136 offset:8192
	ds_read_b128 v[192:195], v136 offset:10240
	v_mfma_f32_16x16x32_bf16 v[122:125], v[180:183], v[160:163], v[122:125]
	v_mfma_f32_16x16x32_bf16 v[106:109], v[180:183], v[164:167], v[106:109]
	v_mfma_f32_16x16x32_bf16 v[78:81], v[180:183], v[168:171], v[78:81]
	v_mfma_f32_16x16x32_bf16 v[42:45], v[180:183], v[172:175], v[42:45]
	v_mfma_f32_16x16x32_bf16 v[118:121], v[184:187], v[160:163], v[118:121]
	v_mfma_f32_16x16x32_bf16 v[94:97], v[184:187], v[164:167], v[94:97]
	v_mfma_f32_16x16x32_bf16 v[58:61], v[184:187], v[168:171], v[58:61]
	v_mfma_f32_16x16x32_bf16 v[26:29], v[184:187], v[172:175], v[26:29]
	ds_read_b128 v[180:183], v136 offset:12288
	ds_read_b128 v[184:187], v136 offset:14336
	v_mfma_f32_16x16x32_bf16 v[114:117], v[188:191], v[160:163], v[114:117]
	v_mfma_f32_16x16x32_bf16 v[90:93], v[188:191], v[164:167], v[90:93]
	v_mfma_f32_16x16x32_bf16 v[54:57], v[188:191], v[168:171], v[54:57]
	v_mfma_f32_16x16x32_bf16 v[22:25], v[188:191], v[172:175], v[22:25]
	v_add_u32_e32 v136, v151, v141
	v_add_u32_e32 v208, v150, v141
	s_waitcnt lgkmcnt(0)
	v_mfma_f32_16x16x32_bf16 v[102:105], v[176:179], v[160:163], v[102:105]
	v_mfma_f32_16x16x32_bf16 v[74:77], v[176:179], v[164:167], v[74:77]
	v_mfma_f32_16x16x32_bf16 v[188:191], v[192:195], v[164:167], v[66:69]
	v_mfma_f32_16x16x32_bf16 v[196:199], v[176:179], v[168:171], v[46:49]
	s_nop 2
	ds_read_b128 v[46:49], v136
	ds_read_b128 v[66:69], v136 offset:2048
	v_mfma_f32_16x16x32_bf16 v[10:13], v[176:179], v[172:175], v[10:13]
	ds_read_b128 v[176:179], v208
	ds_read_b128 v[200:203], v208 offset:2048
	ds_read_b128 v[204:207], v208 offset:4096
	ds_read_b128 v[208:211], v208 offset:6144
	v_mfma_f32_16x16x32_bf16 v[98:101], v[192:195], v[160:163], v[98:101]
	v_mfma_f32_16x16x32_bf16 v[30:33], v[192:195], v[168:171], v[30:33]
	v_mfma_f32_16x16x32_bf16 v[6:9], v[192:195], v[172:175], v[6:9]
	v_mfma_f32_16x16x32_bf16 v[192:195], v[180:183], v[164:167], v[38:41]
	v_mfma_f32_16x16x32_bf16 v[164:167], v[184:187], v[164:167], v[34:37]
	v_mfma_f32_16x16x32_bf16 v[18:21], v[180:183], v[168:171], v[18:21]
	v_mfma_f32_16x16x32_bf16 v[168:171], v[184:187], v[168:171], v[14:17]
	s_nop 2
	ds_read_b128 v[14:17], v136 offset:4096
	ds_read_b128 v[34:37], v136 offset:6144
	v_mfma_f32_16x16x32_bf16 v[70:73], v[180:183], v[160:163], v[70:73]
	v_mfma_f32_16x16x32_bf16 v[2:5], v[180:183], v[172:175], v[2:5]
	v_mfma_f32_16x16x32_bf16 v[160:163], v[184:187], v[160:163], v[62:65]
	v_mfma_f32_16x16x32_bf16 v[86:89], v[184:187], v[172:175], v[86:89]
	s_waitcnt lgkmcnt(0)
	v_mfma_f32_16x16x32_bf16 v[172:175], v[46:49], v[208:211], v[50:53]
	s_nop 2
	ds_read_b128 v[50:53], v136 offset:8192
	ds_read_b128 v[180:183], v136 offset:10240
	v_mfma_f32_16x16x32_bf16 v[126:129], v[46:49], v[176:179], v[126:129]
	v_mfma_f32_16x16x32_bf16 v[122:125], v[66:69], v[176:179], v[122:125]
	v_mfma_f32_16x16x32_bf16 v[110:113], v[46:49], v[200:203], v[110:113]
	v_mfma_f32_16x16x32_bf16 v[106:109], v[66:69], v[200:203], v[106:109]
	v_mfma_f32_16x16x32_bf16 v[82:85], v[46:49], v[204:207], v[82:85]
	v_mfma_f32_16x16x32_bf16 v[78:81], v[66:69], v[204:207], v[78:81]
	v_mfma_f32_16x16x32_bf16 v[184:187], v[66:69], v[208:211], v[42:45]
	ds_read_b128 v[224:227], v136 offset:12288
	ds_read_b128 v[228:231], v136 offset:14336
	v_mfma_f32_16x16x32_bf16 v[118:121], v[14:17], v[176:179], v[118:121]
	v_mfma_f32_16x16x32_bf16 v[114:117], v[34:37], v[176:179], v[114:117]
	v_mfma_f32_16x16x32_bf16 v[94:97], v[14:17], v[200:203], v[94:97]
	v_mfma_f32_16x16x32_bf16 v[90:93], v[34:37], v[200:203], v[90:93]
	v_mfma_f32_16x16x32_bf16 v[212:215], v[14:17], v[204:207], v[58:61]
	v_mfma_f32_16x16x32_bf16 v[216:219], v[34:37], v[204:207], v[54:57]
	v_mfma_f32_16x16x32_bf16 v[220:223], v[14:17], v[208:211], v[26:29]
	v_mfma_f32_16x16x32_bf16 v[66:69], v[34:37], v[208:211], v[22:25]
	s_waitcnt lgkmcnt(0)
	v_mfma_f32_16x16x32_bf16 v[38:41], v[180:183], v[204:207], v[30:33]
	v_mfma_f32_16x16x32_bf16 v[62:65], v[50:53], v[176:179], v[102:105]
	v_mfma_f32_16x16x32_bf16 v[46:49], v[180:183], v[176:179], v[98:101]
	v_mfma_f32_16x16x32_bf16 v[58:61], v[50:53], v[200:203], v[74:77]
	v_mfma_f32_16x16x32_bf16 v[42:45], v[180:183], v[200:203], v[188:191]
	v_mfma_f32_16x16x32_bf16 v[54:57], v[50:53], v[204:207], v[196:199]
	v_mfma_f32_16x16x32_bf16 v[50:53], v[50:53], v[208:211], v[10:13]
	v_mfma_f32_16x16x32_bf16 v[34:37], v[180:183], v[208:211], v[6:9]
	s_nop 2
	v_mov_b32_e32 v8, v1
	s_waitcnt vmcnt(0)
	v_mfma_f32_16x16x32_bf16 v[30:33], v[224:227], v[176:179], v[70:73]
	s_barrier
; template <bool SWAP, class Epi, bool THIN = false> ...
;     ...
;     __syncthreads();
;     const int te = get_tid512();
;     const int fr_e = te & 15, fq_e = (te & 63) >> 4, wr_e = te >> 7, wc_e = (te >> 6) & 1;
;     const int sub = 2 * mt + (wr_e >> 1);
;     const int g = sub / tpg, ti = sub - g * tpg;
;     const int rig0 = ti * step - halo;
;     const int rw = (wr_e & 1) * 64;
;     if constexpr (Epi::KIND == 0) {
; #pragma unroll
;       for (int m = 0; m < 4; ++m) {
;         const int rig = rig0 + rw + m * 16 + fr_e;
;         if constexpr (Epi::ROWSUM) {
;           float ss = 0.f;
; #pragma unroll
;           for (int n = 0; n < 8; ++n) {
;             const int col = nt * 256 + wc_e * 128 + n * 16 + fq_e * 4;
;             if (col < N) ss += epi.c4(g, rig, col, acc[m][n]);
;           }
;           ss += __shfl_xor(ss, 16); ss += __shfl_xor(ss, 32);
;           if (fq_e == 0) epi.rowsum(g, rig, nt * 2 + wc_e, ss);
;         } else {
; #pragma unroll
;           for (int n = 0; n < 8; ++n) {
;             const int col = nt * 256 + wc_e * 128 + n * 16 + fq_e * 4;
;             if (col < N) epi.c4(g, rig, col, acc[m][n]);
;           }
;         }
;       }
;     } else if constexpr (Epi::KIND == 1) {
; #pragma unroll
;       for (int m = 0; m < 4; ++m) {
;         const int rig = rig0 + rw + m * 16 + fq_e * 4;
; #pragma unroll
;         for (int n = 0; n < 8; ++n) {
;           const int col = nt * 256 + wc_e * 128 + n * 16 + fr_e;
;           if (col < N) epi.r4(g, rig, col, acc[m][n]);
;         }
;       }
;     } else {
;       bf16_t* Zw = (bf16_t*)smem + ((wr_e >> 1) * 2 + wc_e) * (128 * 132);
;       const int nt2w = nt * 2 + wc_e;
; #pragma unroll
;       for (int n = 0; n < 8; ++n) {
;         const int cl = n * 16 + fq_e * 4;
;         f32x4 b4 = {0.f, 0.f, 0.f, 0.f};
;         if (epi.pre_bias) b4 = *(const f32x4*)(epi.pre_bias + epi.norig(nt2w, cl));
; #pragma unroll
;         for (int m = 0; m < 4; ++m) {
;           const int rl = rw + m * 16 + fr_e;
;           const int pos = rig0 + rl;
;           const bool ok = pos >= 0 && pos < grows;
;           f32x4 vv = acc[m][n] + b4;
;           if (!ok) vv = (f32x4){0.f, 0.f, 0.f, 0.f};
;           uint2 u; u.x = pack2(vv[0], vv[1]); u.y = pack2(vv[2], vv[3]);
;           *(uint2*)(Zw + rl * 132 + cl) = u;
;         }
	v_mfma_f32_16x16x32_bf16 v[22:25], v[224:227], v[204:207], v[18:21]
	s_nop 0
	v_ashrrev_i32_e32 v71, 8, v8
	v_add_u32_e32 v6, s4, v71
	v_mul_hi_i32 v7, v6, s26
	v_lshrrev_b32_e32 v9, 31, v7
	v_ashrrev_i32_e32 v7, 3, v7
	v_add_u32_e32 v70, v7, v9
	v_and_b32_e32 v73, 15, v8
	v_mad_u64_u32 v[6:7], s[4:5], v70, s27, v[6:7]
	v_lshrrev_b32_e32 v75, 1, v8
	v_bfe_u32 v74, v8, 6, 1
	v_mul_lo_u32 v72, v6, s28
	v_and_or_b32 v73, v75, 64, v73
	v_add_u32_e32 v98, v72, v73
	v_lshl_or_b32 v74, v71, 1, v74
	v_mul_lo_u32 v74, v74, s29
	v_add_u32_e32 v99, -1, v98
	v_mfma_f32_16x16x32_bf16 v[18:21], v[224:227], v[208:211], v[2:5]
	v_add_f32_e64 v76, v126, 0
	v_add_f32_e64 v77, v127, 0
	v_cmp_gt_u32_e32 vcc, s30, v99
	s_lshl_b32 s24, s6, 7
	v_mfma_f32_16x16x32_bf16 v[2:5], v[228:231], v[208:211], v[86:89]
	v_add_f32_e64 v84, v84, 0
	v_add_f32_e64 v85, v85, 0
	v_pk_add_f32 v[82:83], v[82:83], 0 op_sel_hi:[1,0]
	v_pk_add_f32 v[66:67], v[66:67], 0 op_sel_hi:[1,0]
	v_and_or_b32 v86, v75, 24, v74
	v_pk_add_f32 v[74:75], v[128:129], 0 op_sel_hi:[1,0]
	v_add_u32_e32 v88, 15, v98
	v_cndmask_b32_e32 v87, 0, v74, vcc
	v_cndmask_b32_e32 v75, 0, v75, vcc
	v_cndmask_b32_e32 v74, 0, v76, vcc
	v_cndmask_b32_e32 v76, 0, v77, vcc
	v_cvt_pk_bf16_f32 v74, v74, v76
	v_cvt_pk_bf16_f32 v75, v87, v75
	v_mad_u32_u24 v73, v73, s31, v86
	v_pk_add_f32 v[76:77], v[112:113], 0 op_sel_hi:[1,0]
	v_pk_add_f32 v[86:87], v[110:111], 0 op_sel_hi:[1,0]
	v_cmp_gt_u32_e64 s[4:5], s30, v88
	v_mfma_f32_16x16x32_bf16 v[26:29], v[224:227], v[200:203], v[192:195]
	v_add_f32_e64 v62, v62, 0
	v_add_f32_e64 v63, v63, 0
	v_cndmask_b32_e64 v88, 0, v76, s[4:5]
	v_cndmask_b32_e64 v76, 0, v86, s[4:5]
	v_cndmask_b32_e64 v86, 0, v87, s[4:5]
	v_cvt_pk_bf16_f32 v76, v76, v86
	v_add_u32_e32 v86, 31, v98
	v_cndmask_b32_e64 v77, 0, v77, s[4:5]
	v_cmp_gt_u32_e64 s[6:7], s30, v86
	v_cvt_pk_bf16_f32 v77, v88, v77
	v_add_u32_e32 v88, 47, v98
	v_pk_add_f32 v[86:87], v[172:173], 0 op_sel_hi:[1,0]
	v_cndmask_b32_e64 v84, 0, v84, s[6:7]
	v_cndmask_b32_e64 v85, 0, v85, s[6:7]
	v_cndmask_b32_e64 v82, 0, v82, s[6:7]
	v_cndmask_b32_e64 v83, 0, v83, s[6:7]
	v_cvt_pk_bf16_f32 v82, v82, v83
	v_cvt_pk_bf16_f32 v83, v84, v85
	v_pk_add_f32 v[84:85], v[174:175], 0 op_sel_hi:[1,0]
	v_cmp_gt_u32_e64 s[8:9], s30, v88
	v_mfma_f32_16x16x32_bf16 v[14:17], v[228:231], v[176:179], v[160:163]
	v_add_f32_e64 v28, v28, 0
	v_add_f32_e64 v29, v29, 0
	v_cndmask_b32_e64 v88, 0, v84, s[8:9]
	v_cndmask_b32_e64 v85, 0, v85, s[8:9]
	v_cndmask_b32_e64 v84, 0, v86, s[8:9]
	v_cndmask_b32_e64 v86, 0, v87, s[8:9]
	v_cvt_pk_bf16_f32 v84, v84, v86
	v_cvt_pk_bf16_f32 v85, v88, v85
	v_pk_add_f32 v[86:87], v[124:125], 0 op_sel_hi:[1,0]
	v_pk_add_f32 v[88:89], v[122:123], 0 op_sel_hi:[1,0]
	v_cndmask_b32_e32 v98, 0, v86, vcc
	v_cndmask_b32_e32 v87, 0, v87, vcc
	v_cndmask_b32_e32 v86, 0, v88, vcc
	v_cndmask_b32_e32 v88, 0, v89, vcc
	v_cvt_pk_bf16_f32 v86, v86, v88
	v_cvt_pk_bf16_f32 v87, v98, v87
	ds_write2_b64 v73, v[74:75], v[86:87] offset1:4
	v_pk_add_f32 v[74:75], v[108:109], 0 op_sel_hi:[1,0]
	v_pk_add_f32 v[86:87], v[106:107], 0 op_sel_hi:[1,0]
	v_cndmask_b32_e64 v88, 0, v74, s[4:5]
	v_cndmask_b32_e64 v75, 0, v75, s[4:5]
	v_cndmask_b32_e64 v74, 0, v86, s[4:5]
	v_cndmask_b32_e64 v86, 0, v87, s[4:5]
	v_cvt_pk_bf16_f32 v74, v74, v86
	v_cvt_pk_bf16_f32 v75, v88, v75
	v_add_u32_e32 v86, 0x1000, v73
	ds_write2_b64 v86, v[76:77], v[74:75] offset0:16 offset1:20
	v_pk_add_f32 v[74:75], v[80:81], 0 op_sel_hi:[1,0]
	v_pk_add_f32 v[76:77], v[78:79], 0 op_sel_hi:[1,0]
	v_cndmask_b32_e64 v78, 0, v74, s[6:7]
	v_cndmask_b32_e64 v75, 0, v75, s[6:7]
	v_cndmask_b32_e64 v74, 0, v76, s[6:7]
	v_cndmask_b32_e64 v76, 0, v77, s[6:7]
	v_cvt_pk_bf16_f32 v74, v74, v76
	v_cvt_pk_bf16_f32 v75, v78, v75
	v_add_u32_e32 v87, 0x2000, v73
	ds_write2_b64 v87, v[82:83], v[74:75] offset0:32 offset1:36
	v_pk_add_f32 v[74:75], v[186:187], 0 op_sel_hi:[1,0]
	v_pk_add_f32 v[76:77], v[184:185], 0 op_sel_hi:[1,0]
	v_cndmask_b32_e64 v78, 0, v74, s[8:9]
	v_cndmask_b32_e64 v75, 0, v75, s[8:9]
	v_cndmask_b32_e64 v74, 0, v76, s[8:9]
	v_cndmask_b32_e64 v76, 0, v77, s[8:9]
	v_cvt_pk_bf16_f32 v74, v74, v76
	v_cvt_pk_bf16_f32 v75, v78, v75
	v_add_u32_e32 v88, 0x3000, v73
	ds_write2_b64 v88, v[84:85], v[74:75] offset0:48 offset1:52
	v_pk_add_f32 v[74:75], v[120:121], 0 op_sel_hi:[1,0]
	v_pk_add_f32 v[76:77], v[118:119], 0 op_sel_hi:[1,0]
	v_cndmask_b32_e32 v78, 0, v74, vcc
	v_cndmask_b32_e32 v75, 0, v75, vcc
	v_cndmask_b32_e32 v74, 0, v76, vcc
	v_cndmask_b32_e32 v76, 0, v77, vcc
	v_cvt_pk_bf16_f32 v74, v74, v76
	v_cvt_pk_bf16_f32 v75, v78, v75
	v_pk_add_f32 v[76:77], v[96:97], 0 op_sel_hi:[1,0]
	v_pk_add_f32 v[78:79], v[94:95], 0 op_sel_hi:[1,0]
	v_cndmask_b32_e64 v80, 0, v76, s[4:5]
	v_cndmask_b32_e64 v77, 0, v77, s[4:5]
	v_cndmask_b32_e64 v76, 0, v78, s[4:5]
	v_cndmask_b32_e64 v78, 0, v79, s[4:5]
	v_cvt_pk_bf16_f32 v76, v76, v78
	v_cvt_pk_bf16_f32 v77, v80, v77
	v_pk_add_f32 v[78:79], v[214:215], 0 op_sel_hi:[1,0]
	v_pk_add_f32 v[80:81], v[212:213], 0 op_sel_hi:[1,0]
	v_cndmask_b32_e64 v82, 0, v78, s[6:7]
	v_cndmask_b32_e64 v79, 0, v79, s[6:7]
	v_cndmask_b32_e64 v78, 0, v80, s[6:7]
	v_cndmask_b32_e64 v80, 0, v81, s[6:7]
	v_cvt_pk_bf16_f32 v78, v78, v80
	v_cvt_pk_bf16_f32 v79, v82, v79
	v_pk_add_f32 v[80:81], v[222:223], 0 op_sel_hi:[1,0]
	v_pk_add_f32 v[82:83], v[220:221], 0 op_sel_hi:[1,0]
	v_cndmask_b32_e64 v84, 0, v80, s[8:9]
	v_cndmask_b32_e64 v81, 0, v81, s[8:9]
	v_cndmask_b32_e64 v80, 0, v82, s[8:9]
	v_cndmask_b32_e64 v82, 0, v83, s[8:9]
	v_cvt_pk_bf16_f32 v80, v80, v82
	v_cvt_pk_bf16_f32 v81, v84, v81
	v_pk_add_f32 v[82:83], v[116:117], 0 op_sel_hi:[1,0]
	v_pk_add_f32 v[84:85], v[114:115], 0 op_sel_hi:[1,0]
; __device__ __forceinline__ unsigned pack2(float a, float b) { unsigned r; asm("v_cvt_pk_bf16_f32 %0, %1, %2" : "=v"(r) : "v"(a), "v"(b)); return r; }
; template <bool SWAP, class Epi, bool THIN = false> ...
;     ...
;     } else {
;       bf16_t* Zw = (bf16_t*)smem + ((wr_e >> 1) * 2 + wc_e) * (128 * 132);
;       const int nt2w = nt * 2 + wc_e;
; #pragma unroll
;       for (int n = 0; n < 8; ++n) {
;         const int cl = n * 16 + fq_e * 4;
;         f32x4 b4 = {0.f, 0.f, 0.f, 0.f};
;         if (epi.pre_bias) b4 = *(const f32x4*)(epi.pre_bias + epi.norig(nt2w, cl));
; #pragma unroll
;         for (int m = 0; m < 4; ++m) {
;           const int rl = rw + m * 16 + fr_e;
;           const int pos = rig0 + rl;
;           const bool ok = pos >= 0 && pos < grows;
;           f32x4 vv = acc[m][n] + b4;
;           if (!ok) vv = (f32x4){0.f, 0.f, 0.f, 0.f};
;           uint2 u; u.x = pack2(vv[0], vv[1]); u.y = pack2(vv[2], vv[3]);
;           *(uint2*)(Zw + rl * 132 + cl) = u;
;         }
;       }
	v_cndmask_b32_e32 v89, 0, v82, vcc
	v_cndmask_b32_e32 v83, 0, v83, vcc
	v_cndmask_b32_e32 v82, 0, v84, vcc
	v_mfma_f32_16x16x32_bf16 v[10:13], v[228:231], v[200:203], v[164:167]
	v_cndmask_b32_e32 v84, 0, v85, vcc
	v_cvt_pk_bf16_f32 v82, v82, v84
	v_cvt_pk_bf16_f32 v83, v89, v83
	v_mfma_f32_16x16x32_bf16 v[6:9], v[228:231], v[204:207], v[168:171]
	ds_write2_b64 v73, v[74:75], v[82:83] offset0:8 offset1:12
	v_pk_add_f32 v[74:75], v[92:93], 0 op_sel_hi:[1,0]
	v_pk_add_f32 v[82:83], v[90:91], 0 op_sel_hi:[1,0]
	v_cndmask_b32_e64 v84, 0, v74, s[4:5]
	v_cndmask_b32_e64 v75, 0, v75, s[4:5]
	v_cndmask_b32_e64 v74, 0, v82, s[4:5]
	v_cndmask_b32_e64 v82, 0, v83, s[4:5]
	v_cvt_pk_bf16_f32 v74, v74, v82
	v_cvt_pk_bf16_f32 v75, v84, v75
	v_pk_add_f32 v[26:27], v[26:27], 0 op_sel_hi:[1,0]
	ds_write2_b64 v86, v[76:77], v[74:75] offset0:24 offset1:28
	v_pk_add_f32 v[74:75], v[218:219], 0 op_sel_hi:[1,0]
	v_pk_add_f32 v[76:77], v[216:217], 0 op_sel_hi:[1,0]
	v_pk_add_f32 v[58:59], v[58:59], 0 op_sel_hi:[1,0]
	v_pk_add_f32 v[54:55], v[54:55], 0 op_sel_hi:[1,0]
	v_pk_add_f32 v[50:51], v[50:51], 0 op_sel_hi:[1,0]
	v_pk_add_f32 v[46:47], v[46:47], 0 op_sel_hi:[1,0]
	v_pk_add_f32 v[42:43], v[42:43], 0 op_sel_hi:[1,0]
	v_pk_add_f32 v[38:39], v[38:39], 0 op_sel_hi:[1,0]
	v_pk_add_f32 v[34:35], v[34:35], 0 op_sel_hi:[1,0]
	v_pk_add_f32 v[30:31], v[30:31], 0 op_sel_hi:[1,0]
	v_cndmask_b32_e64 v28, 0, v28, s[4:5]
	v_cndmask_b32_e64 v26, 0, v26, s[4:5]
	v_cndmask_b32_e64 v27, 0, v27, s[4:5]
	v_pk_add_f32 v[22:23], v[22:23], 0 op_sel_hi:[1,0]
	v_pk_add_f32 v[18:19], v[18:19], 0 op_sel_hi:[1,0]
	v_pk_add_f32 v[14:15], v[14:15], 0 op_sel_hi:[1,0]
	v_pk_add_f32 v[10:11], v[10:11], 0 op_sel_hi:[1,0]
	v_pk_add_f32 v[6:7], v[6:7], 0 op_sel_hi:[1,0]
	v_pk_add_f32 v[2:3], v[2:3], 0 op_sel_hi:[1,0]
	v_cndmask_b32_e64 v82, 0, v74, s[6:7]
	v_cndmask_b32_e64 v75, 0, v75, s[6:7]
	v_cndmask_b32_e64 v74, 0, v76, s[6:7]
	v_pk_add_f32 v[68:69], v[68:69], 0 op_sel_hi:[1,0]
	v_cndmask_b32_e64 v66, 0, v66, s[8:9]
	v_cndmask_b32_e64 v67, 0, v67, s[8:9]
	v_pk_add_f32 v[64:65], v[64:65], 0 op_sel_hi:[1,0]
	v_cndmask_b32_e32 v62, 0, v62, vcc
	v_cndmask_b32_e32 v63, 0, v63, vcc
	v_pk_add_f32 v[60:61], v[60:61], 0 op_sel_hi:[1,0]
	v_cndmask_b32_e64 v58, 0, v58, s[4:5]
	v_cndmask_b32_e64 v59, 0, v59, s[4:5]
	v_pk_add_f32 v[56:57], v[56:57], 0 op_sel_hi:[1,0]
	v_cndmask_b32_e64 v54, 0, v54, s[6:7]
	v_cndmask_b32_e64 v55, 0, v55, s[6:7]
	v_pk_add_f32 v[52:53], v[52:53], 0 op_sel_hi:[1,0]
	v_cndmask_b32_e64 v50, 0, v50, s[8:9]
	v_cndmask_b32_e64 v51, 0, v51, s[8:9]
	v_pk_add_f32 v[48:49], v[48:49], 0 op_sel_hi:[1,0]
	v_cndmask_b32_e32 v46, 0, v46, vcc
	v_cndmask_b32_e32 v47, 0, v47, vcc
	v_pk_add_f32 v[44:45], v[44:45], 0 op_sel_hi:[1,0]
	v_cndmask_b32_e64 v42, 0, v42, s[4:5]
	v_cndmask_b32_e64 v43, 0, v43, s[4:5]
	v_pk_add_f32 v[40:41], v[40:41], 0 op_sel_hi:[1,0]
	v_cndmask_b32_e64 v38, 0, v38, s[6:7]
	v_cndmask_b32_e64 v39, 0, v39, s[6:7]
	v_pk_add_f32 v[36:37], v[36:37], 0 op_sel_hi:[1,0]
	v_cndmask_b32_e64 v34, 0, v34, s[8:9]
	v_cndmask_b32_e64 v35, 0, v35, s[8:9]
	v_pk_add_f32 v[32:33], v[32:33], 0 op_sel_hi:[1,0]
	v_cndmask_b32_e32 v30, 0, v30, vcc
	v_cndmask_b32_e32 v31, 0, v31, vcc
	v_cndmask_b32_e64 v29, 0, v29, s[4:5]
	v_cvt_pk_bf16_f32 v26, v26, v27
	v_cvt_pk_bf16_f32 v27, v28, v29
	v_pk_add_f32 v[24:25], v[24:25], 0 op_sel_hi:[1,0]
	v_cndmask_b32_e64 v22, 0, v22, s[6:7]
	v_cndmask_b32_e64 v23, 0, v23, s[6:7]
	v_pk_add_f32 v[20:21], v[20:21], 0 op_sel_hi:[1,0]
	v_cndmask_b32_e64 v18, 0, v18, s[8:9]
	v_cndmask_b32_e64 v19, 0, v19, s[8:9]
	v_pk_add_f32 v[16:17], v[16:17], 0 op_sel_hi:[1,0]
	v_cndmask_b32_e32 v14, 0, v14, vcc
	v_cndmask_b32_e32 v15, 0, v15, vcc
	v_pk_add_f32 v[12:13], v[12:13], 0 op_sel_hi:[1,0]
	v_cndmask_b32_e64 v10, 0, v10, s[4:5]
	v_cndmask_b32_e64 v11, 0, v11, s[4:5]
	v_pk_add_f32 v[8:9], v[8:9], 0 op_sel_hi:[1,0]
	v_cndmask_b32_e64 v6, 0, v6, s[6:7]
	v_cndmask_b32_e64 v7, 0, v7, s[6:7]
	v_pk_add_f32 v[4:5], v[4:5], 0 op_sel_hi:[1,0]
	v_cndmask_b32_e64 v2, 0, v2, s[8:9]
	v_cndmask_b32_e64 v3, 0, v3, s[8:9]
	v_mov_b32_e32 v28, v142
	v_cndmask_b32_e64 v76, 0, v77, s[6:7]
	v_cvt_pk_bf16_f32 v74, v74, v76
	v_cvt_pk_bf16_f32 v75, v82, v75
	ds_write2_b64 v87, v[78:79], v[74:75] offset0:40 offset1:44
	v_cndmask_b32_e64 v68, 0, v68, s[8:9]
	v_cndmask_b32_e64 v69, 0, v69, s[8:9]
	v_cvt_pk_bf16_f32 v66, v66, v67
	v_cvt_pk_bf16_f32 v67, v68, v69
	ds_write2_b64 v88, v[80:81], v[66:67] offset0:56 offset1:60
	v_cndmask_b32_e32 v64, 0, v64, vcc
	v_cndmask_b32_e32 v65, 0, v65, vcc
	v_cvt_pk_bf16_f32 v62, v62, v63
	v_cvt_pk_bf16_f32 v63, v64, v65
	v_cndmask_b32_e64 v60, 0, v60, s[4:5]
	v_cndmask_b32_e64 v61, 0, v61, s[4:5]
	v_cvt_pk_bf16_f32 v58, v58, v59
	v_cvt_pk_bf16_f32 v59, v60, v61
	v_cndmask_b32_e64 v56, 0, v56, s[6:7]
	v_cndmask_b32_e64 v57, 0, v57, s[6:7]
	v_cvt_pk_bf16_f32 v54, v54, v55
	v_cvt_pk_bf16_f32 v55, v56, v57
	v_cndmask_b32_e64 v52, 0, v52, s[8:9]
	v_cndmask_b32_e64 v53, 0, v53, s[8:9]
	v_cvt_pk_bf16_f32 v50, v50, v51
	v_cvt_pk_bf16_f32 v51, v52, v53
	v_cndmask_b32_e32 v48, 0, v48, vcc
	v_cndmask_b32_e32 v49, 0, v49, vcc
	v_cvt_pk_bf16_f32 v46, v46, v47
	v_cvt_pk_bf16_f32 v47, v48, v49
	ds_write2_b64 v73, v[62:63], v[46:47] offset0:16 offset1:20
	v_cndmask_b32_e64 v44, 0, v44, s[4:5]
	v_cndmask_b32_e64 v45, 0, v45, s[4:5]
	v_cvt_pk_bf16_f32 v42, v42, v43
	v_cvt_pk_bf16_f32 v43, v44, v45
	ds_write2_b64 v86, v[58:59], v[42:43] offset0:32 offset1:36
; __device__ __forceinline__ int get_tid() { int t = threadIdx.x & 255; asm volatile("" : "+v"(t)); return t; }
;   template <class F>
;   __device__ __forceinline__ void finish(const bf16_t* Z, int g, int rig0, int nt, F&& pre) const {
;     typedef f32x2_t f32x2;
;     const int tid = get_tid();
;     if (MODE == 0 || nt < 8) {
;       if (MODE == 0) {
;         const int f2 = (tid & 31) * 2, q8 = tid >> 5;
;         const int q0 = 1 + 16 * q8, q1 = (q0 + 16 < 127) ? q0 + 16 : 127;
;         const int na = norig(nt, f2), ng = norig(nt, 64 + f2);
;         const f32x2 a0 = *(const f32x2*)(cw + na), a1 = *(const f32x2*)(cw + NC + na), a2 = *(const f32x2*)(cw + 2 * NC + na), ab = *(const f32x2*)(cb + na);
;         const f32x2 g0 = *(const f32x2*)(cw + ng), g1 = *(const f32x2*)(cw + NC + ng), g2 = *(const f32x2*)(cw + 2 * NC + ng), gb = *(const f32x2*)(cb + ng);
;         pre();
;         f32x2 am = ldz(Z, q0 - 1, f2), ac = ldz(Z, q0, f2);
;         f32x2 gm = ldz(Z, q0 - 1, 64 + f2), gc = ldz(Z, q0, 64 + f2);
; template <bool SWAP, class Epi, bool THIN = false> ...
;     ...
;       __syncthreads();
;       {
;         auto no_pre = []() {};
;         const bf16_t* Zr = (const bf16_t*)smem + ((wr_e >> 1) * 2) * (128 * 132);
;         epi.finish(Zr, g, rig0, nt * 2, no_pre);
;         epi.finish(Zr + 128 * 132, g, rig0, nt * 2 + 1, no_pre);
	v_cndmask_b32_e64 v40, 0, v40, s[6:7]
	v_cndmask_b32_e64 v41, 0, v41, s[6:7]
	v_cvt_pk_bf16_f32 v38, v38, v39
	v_cvt_pk_bf16_f32 v39, v40, v41
	ds_write2_b64 v87, v[54:55], v[38:39] offset0:48 offset1:52
	v_cndmask_b32_e64 v36, 0, v36, s[8:9]
	v_cndmask_b32_e64 v37, 0, v37, s[8:9]
	v_cvt_pk_bf16_f32 v34, v34, v35
	v_cvt_pk_bf16_f32 v35, v36, v37
	ds_write2_b64 v88, v[50:51], v[34:35] offset0:64 offset1:68
	v_cndmask_b32_e32 v32, 0, v32, vcc
	v_cndmask_b32_e32 v33, 0, v33, vcc
	v_cvt_pk_bf16_f32 v30, v30, v31
	v_cvt_pk_bf16_f32 v31, v32, v33
	v_cndmask_b32_e64 v24, 0, v24, s[6:7]
	v_cndmask_b32_e64 v25, 0, v25, s[6:7]
	v_cvt_pk_bf16_f32 v22, v22, v23
	v_cvt_pk_bf16_f32 v23, v24, v25
	v_cndmask_b32_e64 v20, 0, v20, s[8:9]
	v_cndmask_b32_e64 v21, 0, v21, s[8:9]
	v_cvt_pk_bf16_f32 v18, v18, v19
	v_cvt_pk_bf16_f32 v19, v20, v21
	v_cndmask_b32_e32 v16, 0, v16, vcc
	v_cndmask_b32_e32 v17, 0, v17, vcc
	v_cvt_pk_bf16_f32 v14, v14, v15
	v_cvt_pk_bf16_f32 v15, v16, v17
	ds_write2_b64 v73, v[30:31], v[14:15] offset0:24 offset1:28
	v_cndmask_b32_e64 v12, 0, v12, s[4:5]
	v_cndmask_b32_e64 v13, 0, v13, s[4:5]
	v_cvt_pk_bf16_f32 v10, v10, v11
	v_cvt_pk_bf16_f32 v11, v12, v13
	ds_write2_b64 v86, v[26:27], v[10:11] offset0:40 offset1:44
	v_cndmask_b32_e64 v8, 0, v8, s[6:7]
	v_cndmask_b32_e64 v9, 0, v9, s[6:7]
	v_cvt_pk_bf16_f32 v6, v6, v7
	v_cvt_pk_bf16_f32 v7, v8, v9
	ds_write2_b64 v87, v[22:23], v[6:7] offset0:56 offset1:60
	v_cndmask_b32_e64 v4, 0, v4, s[8:9]
	v_cndmask_b32_e64 v5, 0, v5, s[8:9]
	v_cvt_pk_bf16_f32 v2, v2, v3
	v_cvt_pk_bf16_f32 v3, v4, v5
	ds_write2_b64 v88, v[18:19], v[2:3] offset0:72 offset1:76
	s_waitcnt lgkmcnt(0)
	s_barrier
	s_nop 0
	v_ashrrev_i32_e32 v29, 1, v28
	v_and_b32_e32 v38, -16, v29
	v_min_i32_e32 v2, 0x6e, v38
	v_or_b32_e32 v20, 1, v38
	v_add_u32_e32 v3, 17, v2
	v_cmp_ge_i32_e32 vcc, v20, v3
	s_and_saveexec_b64 s[4:5], vcc
	s_xor_b64 s[4:5], exec, s[4:5]
	s_ashr_i32 s25, s24, 31
	s_or_saveexec_b64 s[4:5], s[4:5]
	v_mul_i32_i24_e32 v2, 0x10800, v71
	v_mov_b64_e32 v[22:23], s[24:25]
	v_ashrrev_i32_e32 v71, 31, v70
	s_xor_b64 exec, exec, s[4:5]
	s_cbranch_execz .LBB0_2345
	v_lshlrev_b32_e32 v4, 1, v28
	v_and_b32_e32 v21, 62, v4
	v_or_b32_e32 v4, s24, v21
	s_add_i32 s6, s24, 0xb00
	v_ashrrev_i32_e32 v5, 31, v4
	v_or_b32_e32 v12, s6, v21
	v_lshlrev_b64 v[10:11], 2, v[4:5]
	v_lshl_add_u64 v[14:15], s[12:13], 0, v[10:11]
	v_lshl_add_u64 v[18:19], s[22:23], 0, v[10:11]
	v_ashrrev_i32_e32 v13, 31, v12
	v_lshl_add_u64 v[16:17], s[20:21], 0, v[10:11]
	global_load_dwordx2 v[4:5], v[14:15], off
	global_load_dwordx2 v[6:7], v[16:17], off
	global_load_dwordx2 v[8:9], v[18:19], off
	v_lshlrev_b64 v[18:19], 2, v[12:13]
	v_lshl_add_u64 v[10:11], s[14:15], 0, v[10:11]
	v_lshl_add_u64 v[22:23], s[12:13], 0, v[18:19]
	global_load_dwordx2 v[10:11], v[10:11], off
	v_lshl_add_u64 v[24:25], s[20:21], 0, v[18:19]
	v_lshl_add_u64 v[26:27], s[22:23], 0, v[18:19]
	global_load_dwordx2 v[12:13], v[22:23], off
	global_load_dwordx2 v[14:15], v[24:25], off
	global_load_dwordx2 v[16:17], v[26:27], off
	v_lshl_add_u64 v[18:19], s[14:15], 0, v[18:19]
	global_load_dwordx2 v[18:19], v[18:19], off
	s_ashr_i32 s25, s24, 31
	v_mov_b64_e32 v[106:107], s[24:25]
	v_mov_b32_e32 v117, 0
	v_lshlrev_b32_e32 v88, 1, v142
	v_and_b32_e32 v116, 62, v88
	v_add3_u32 v88, v116, s24, 64
	s_add_i32 s38, s24, 0xb40
	v_ashrrev_i32_e32 v89, 31, v88
	v_lshl_add_u64 v[90:91], v[116:117], 0, v[106:107]
	v_or_b32_e32 v96, s38, v116
	v_lshlrev_b64 v[94:95], 2, v[90:91]
	v_lshlrev_b64 v[88:89], 2, v[88:89]
	v_lshl_add_u64 v[98:99], s[12:13], 0, v[94:95]
	v_lshl_add_u64 v[102:103], s[22:23], 0, v[88:89]
	v_ashrrev_i32_e32 v97, 31, v96
	v_lshl_add_u64 v[100:101], s[20:21], 0, v[88:89]
	global_load_dwordx2 v[88:89], v[98:99], off offset:256
	global_load_dwordx2 v[90:91], v[100:101], off
	global_load_dwordx2 v[92:93], v[102:103], off
	v_lshlrev_b64 v[102:103], 2, v[96:97]
	v_lshl_add_u64 v[94:95], s[14:15], 0, v[94:95]
	v_lshl_add_u64 v[108:109], s[12:13], 0, v[102:103]
	global_load_dwordx2 v[94:95], v[94:95], off offset:256
	v_lshl_add_u64 v[110:111], s[20:21], 0, v[102:103]
	v_lshl_add_u64 v[114:115], s[22:23], 0, v[102:103]
	global_load_dwordx2 v[96:97], v[108:109], off
	global_load_dwordx2 v[98:99], v[110:111], off
	global_load_dwordx2 v[100:101], v[114:115], off
	v_lshl_add_u64 v[102:103], s[14:15], 0, v[102:103]
	global_load_dwordx2 v[102:103], v[102:103], off
	v_lshlrev_b32_e32 v136, 1, v21
	v_mul_lo_u32 v22, v38, s31
	v_mul_lo_u32 v20, v20, s31
	v_add3_u32 v22, v2, v22, v136
	v_add3_u32 v20, v2, v20, v136
	ds_read2_b32 v[22:23], v22 offset1:32
	ds_read2_b32 v[20:21], v20 offset1:32
	s_ashr_i32 s25, s24, 31
	s_lshl_b64 s[6:7], s[24:25], 1
	s_add_u32 s6, s10, s6
	s_addc_u32 s7, s11, s7
	v_lshrrev_b32_e32 v29, 4, v29
	v_and_b32_e32 v28, 31, v28
	s_waitcnt lgkmcnt(1)
	v_lshlrev_b32_e32 v32, 16, v23
	v_and_b32_e32 v33, 0xffff0000, v23
	v_lshlrev_b32_e32 v34, 16, v22
	v_and_b32_e32 v35, 0xffff0000, v22
	v_lshl_add_u64 v[22:23], s[6:7], 0, v[136:137]
	v_mad_u64_u32 v[30:31], s[6:7], v29, s33, v[2:3]
	v_lshlrev_b32_e32 v28, 2, v28
	s_waitcnt lgkmcnt(0)
	v_lshlrev_b32_e32 v24, 16, v21
	v_and_b32_e32 v25, 0xffff0000, v21
	v_lshlrev_b32_e32 v26, 16, v20
	v_and_b32_e32 v27, 0xffff0000, v20
	v_lshlrev_b64 v[20:21], 11, v[70:71]
	v_add3_u32 v39, v30, v28, s34
	s_mov_b64 s[6:7], 0
	s_waitcnt vmcnt(0)
	ds_read2_b32 v[44:45], v39 offset1:32
	s_branch .LBB0_2340

; __device__ __forceinline__ unsigned pack2(float a, float b) { unsigned r; asm("v_cvt_pk_bf16_f32 %0, %1, %2" : "=v"(r) : "v"(a), "v"(b)); return r; }
;   template <class F>
;   __device__ __forceinline__ void finish(const bf16_t* Z, int g, int rig0, int nt, F&& pre) const {
;     ...
;         f32x2 am = ldz(Z, q0 - 1, f2), ac = ldz(Z, q0, f2);
;         f32x2 gm = ldz(Z, q0 - 1, 64 + f2), gc = ldz(Z, q0, 64 + f2);
; #pragma unroll 4
;         for (int pl = q0; pl < q1; ++pl) {
;           const f32x2 an = ldz(Z, pl + 1, f2), gn = ldz(Z, pl + 1, 64 + f2);
;           const int pos = rig0 + pl;
;           if (pos < 2048) {
;             const f32x2 av = a0 * am + a1 * ac + a2 * an + ab;
;             const f32x2 gv = g0 * gm + g1 * gc + g2 * gn + gb;
;             const float s0 = av[0] * gv[0] * __builtin_amdgcn_rcpf(1.f + __expf(-gv[0]));
;             const float s1 = av[1] * gv[1] * __builtin_amdgcn_rcpf(1.f + __expf(-gv[1]));
;             *(unsigned*)(o0 + ((size_t)g * 2048 + pos) * 2816 + nt * 64 + f2) = pack2(s0, s1);
;           }
;           am = ac; ac = an; gm = gc; gc = gn;
;         }
;       } else {
.LBB0_2340:
	ds_read2_b32 v[46:47], v39 offset0:66 offset1:98
	v_add_u32_e32 v36, v72, v38
	v_cmp_gt_i32_e32 vcc, s30, v36
	s_waitcnt lgkmcnt(1)
	v_lshlrev_b32_e32 v30, 16, v44
	v_and_b32_e32 v31, 0xffff0000, v44
	v_lshlrev_b32_e32 v28, 16, v45
	v_and_b32_e32 v29, 0xffff0000, v45
	s_and_saveexec_b64 s[8:9], vcc
	s_cbranch_execz .LBB0_2342
	v_pk_mul_f32 v[40:41], v[6:7], v[26:27]
	s_nop 0
	v_pk_fma_f32 v[34:35], v[4:5], v[34:35], v[40:41]
	v_pk_mul_f32 v[40:41], v[14:15], v[24:25]
	v_pk_fma_f32 v[34:35], v[8:9], v[30:31], v[34:35]
	v_pk_fma_f32 v[32:33], v[12:13], v[32:33], v[40:41]
	v_pk_add_f32 v[34:35], v[10:11], v[34:35]
	v_pk_fma_f32 v[32:33], v[16:17], v[28:29], v[32:33]
	s_nop 0
	v_pk_add_f32 v[32:33], v[18:19], v[32:33]
	s_nop 0
	v_mul_f32_e32 v37, 0xbfb8aa3b, v32
	v_mul_f32_e32 v40, 0xbfb8aa3b, v33
	v_exp_f32_e32 v37, v37
	v_exp_f32_e32 v40, v40
	v_pk_mul_f32 v[32:33], v[34:35], v[32:33]
	v_add_f32_e32 v37, 1.0, v37
	v_add_f32_e32 v40, 1.0, v40
	v_rcp_f32_e32 v37, v37
	v_rcp_f32_e32 v40, v40
	v_mul_f32_e32 v32, v32, v37
	v_mul_f32_e32 v33, v33, v40
	v_ashrrev_i32_e32 v37, 31, v36
	v_cvt_pk_bf16_f32 v40, v32, v33
	v_lshl_add_u64 v[32:33], v[20:21], 0, v[36:37]
	v_mad_u64_u32 v[34:35], s[38:39], v32, s35, v[22:23]
	v_mad_i32_i24 v35, v33, s35, v35
	global_store_dword v[34:35], v40, off
.LBB0_2342:
	s_or_b64 exec, exec, s[8:9]
	ds_read2_b32 v[44:45], v39 offset0:132 offset1:164
	v_add_u32_e32 v34, 1, v36
	v_cmp_gt_i32_e32 vcc, s30, v34
	s_waitcnt lgkmcnt(1)
	v_lshlrev_b32_e32 v32, 16, v46
	v_and_b32_e32 v33, 0xffff0000, v46
	v_lshlrev_b32_e32 v36, 16, v47
	v_and_b32_e32 v37, 0xffff0000, v47
	s_and_saveexec_b64 s[8:9], vcc
	s_cbranch_execz .LBB0_2339
	v_pk_mul_f32 v[40:41], v[6:7], v[30:31]
	s_nop 0
	v_pk_fma_f32 v[26:27], v[4:5], v[26:27], v[40:41]
	v_pk_mul_f32 v[40:41], v[14:15], v[28:29]
	v_pk_fma_f32 v[26:27], v[8:9], v[32:33], v[26:27]
	v_pk_fma_f32 v[24:25], v[12:13], v[24:25], v[40:41]
	v_pk_add_f32 v[26:27], v[10:11], v[26:27]
	v_pk_fma_f32 v[24:25], v[16:17], v[36:37], v[24:25]
	s_nop 0
	v_pk_add_f32 v[24:25], v[18:19], v[24:25]
	s_nop 0
	v_mul_f32_e32 v35, 0xbfb8aa3b, v24
	v_mul_f32_e32 v40, 0xbfb8aa3b, v25
	v_exp_f32_e32 v35, v35
	v_exp_f32_e32 v40, v40
	v_pk_mul_f32 v[24:25], v[26:27], v[24:25]
	v_add_f32_e32 v35, 1.0, v35
	v_add_f32_e32 v40, 1.0, v40
	v_rcp_f32_e32 v35, v35
	v_rcp_f32_e32 v40, v40
	v_mul_f32_e32 v24, v24, v35
	v_mul_f32_e32 v25, v25, v40
	v_ashrrev_i32_e32 v35, 31, v34
	v_cvt_pk_bf16_f32 v40, v24, v25
	v_lshl_add_u64 v[24:25], v[20:21], 0, v[34:35]
	v_mad_u64_u32 v[26:27], s[38:39], v24, s35, v[22:23]
	v_mad_i32_i24 v27, v25, s35, v27
	global_store_dword v[26:27], v40, off
	s_branch .LBB0_2339
.LBB0_2344:
	s_waitcnt lgkmcnt(0)
	s_or_b64 exec, exec, s[6:7]
	v_mov_b64_e32 v[22:23], s[24:25]
.LBB0_2345:
	s_or_b64 exec, exec, s[4:5]
	v_mov_b32_e32 v3, v142
	s_nop 0
	v_ashrrev_i32_e32 v28, 1, v3
	v_and_b32_e32 v37, -16, v28
	v_min_i32_e32 v4, 0x6e, v37
	v_or_b32_e32 v20, 1, v37
	v_add_u32_e32 v36, 17, v4
	v_cmp_lt_i32_e32 vcc, v20, v36
	s_and_saveexec_b64 s[4:5], vcc
	s_cbranch_execz .LBB0_2328
	v_lshlrev_b32_e32 v4, 1, v3
	v_and_b32_e32 v136, 62, v4
	v_add3_u32 v4, v136, s24, 64
	s_add_i32 s6, s24, 0xb40
	v_ashrrev_i32_e32 v5, 31, v4
	v_lshl_add_u64 v[6:7], v[136:137], 0, v[22:23]
	v_or_b32_e32 v12, s6, v136
	v_lshlrev_b64 v[10:11], 2, v[6:7]
	v_lshlrev_b64 v[4:5], 2, v[4:5]
	v_lshl_add_u64 v[14:15], s[12:13], 0, v[10:11]
	v_lshl_add_u64 v[18:19], s[22:23], 0, v[4:5]
	v_ashrrev_i32_e32 v13, 31, v12
	v_lshl_add_u64 v[16:17], s[20:21], 0, v[4:5]
	v_lshlrev_b64 v[18:19], 2, v[12:13]
	v_lshl_add_u64 v[10:11], s[14:15], 0, v[10:11]
	v_lshl_add_u64 v[24:25], s[12:13], 0, v[18:19]
	v_lshl_add_u64 v[26:27], s[20:21], 0, v[18:19]
	v_lshl_add_u64 v[30:31], s[22:23], 0, v[18:19]
	v_lshl_add_u64 v[18:19], s[14:15], 0, v[18:19]
	v_mul_lo_u32 v20, v20, s31
	v_lshlrev_b32_e32 v136, 1, v136
	v_mul_lo_u32 v24, v37, s31
	v_add3_u32 v20, v2, v20, v136
	v_add3_u32 v24, v2, v24, v136
	v_add_u32_e32 v20, 0x8400, v20
	v_add_u32_e32 v24, 0x8400, v24
	ds_read2_b32 v[20:21], v20 offset1:32
	ds_read2_b32 v[34:35], v24 offset1:32
	v_lshrrev_b32_e32 v28, 4, v28
	v_mad_u64_u32 v[28:29], s[6:7], v28, s33, v[2:3]
	v_and_b32_e32 v2, 31, v3
	v_lshl_add_u64 v[22:23], v[22:23], 1, s[10:11]
	v_lshlrev_b32_e32 v2, 2, v2
	s_waitcnt lgkmcnt(1)
	v_lshlrev_b32_e32 v24, 16, v21
	v_and_b32_e32 v25, 0xffff0000, v21
	s_waitcnt lgkmcnt(0)
	v_lshlrev_b32_e32 v30, 16, v35
	v_and_b32_e32 v31, 0xffff0000, v35
	v_lshlrev_b32_e32 v26, 16, v20
	v_and_b32_e32 v27, 0xffff0000, v20
	v_lshlrev_b32_e32 v32, 16, v34
	v_and_b32_e32 v33, 0xffff0000, v34
	v_lshlrev_b64 v[20:21], 11, v[70:71]
	v_lshl_add_u64 v[22:23], v[22:23], 0, v[136:137]
	v_add3_u32 v38, v28, v2, s36
	s_mov_b64 s[6:7], 0
	ds_read2_b32 v[44:45], v38 offset1:32
	s_branch .LBB0_2348

; __device__ __forceinline__ unsigned pack2(float a, float b) { unsigned r; asm("v_cvt_pk_bf16_f32 %0, %1, %2" : "=v"(r) : "v"(a), "v"(b)); return r; }
;   template <class F>
;   __device__ __forceinline__ void finish(const bf16_t* Z, int g, int rig0, int nt, F&& pre) const {
;     ...
;         f32x2 am = ldz(Z, q0 - 1, f2), ac = ldz(Z, q0, f2);
;         f32x2 gm = ldz(Z, q0 - 1, 64 + f2), gc = ldz(Z, q0, 64 + f2);
; #pragma unroll 4
;         for (int pl = q0; pl < q1; ++pl) {
;           const f32x2 an = ldz(Z, pl + 1, f2), gn = ldz(Z, pl + 1, 64 + f2);
;           const int pos = rig0 + pl;
;           if (pos < 2048) {
;             const f32x2 av = a0 * am + a1 * ac + a2 * an + ab;
;             const f32x2 gv = g0 * gm + g1 * gc + g2 * gn + gb;
;             const float s0 = av[0] * gv[0] * __builtin_amdgcn_rcpf(1.f + __expf(-gv[0]));
;             const float s1 = av[1] * gv[1] * __builtin_amdgcn_rcpf(1.f + __expf(-gv[1]));
;             *(unsigned*)(o0 + ((size_t)g * 2048 + pos) * 2816 + nt * 64 + f2) = pack2(s0, s1);
;           }
;           am = ac; ac = an; gm = gc; gc = gn;
;         }
.LBB0_2348:
	ds_read2_b32 v[46:47], v38 offset0:66 offset1:98
	v_add_u32_e32 v34, v72, v37
	v_cmp_gt_i32_e32 vcc, s30, v34
	s_waitcnt lgkmcnt(1)
	v_lshlrev_b32_e32 v28, 16, v44
	v_and_b32_e32 v29, 0xffff0000, v44
	v_lshlrev_b32_e32 v2, 16, v45
	v_and_b32_e32 v3, 0xffff0000, v45
	s_and_saveexec_b64 s[8:9], vcc
	s_cbranch_execz .LBB0_2350
	v_pk_mul_f32 v[40:41], v[90:91], v[26:27]
	s_nop 0
	v_pk_fma_f32 v[32:33], v[88:89], v[32:33], v[40:41]
	v_pk_mul_f32 v[40:41], v[98:99], v[24:25]
	v_pk_fma_f32 v[32:33], v[92:93], v[28:29], v[32:33]
	v_pk_fma_f32 v[30:31], v[96:97], v[30:31], v[40:41]
	v_pk_add_f32 v[32:33], v[94:95], v[32:33]
	v_pk_fma_f32 v[30:31], v[100:101], v[2:3], v[30:31]
	s_nop 0
	v_pk_add_f32 v[30:31], v[102:103], v[30:31]
	s_nop 0
	v_mul_f32_e32 v35, 0xbfb8aa3b, v30
	v_mul_f32_e32 v39, 0xbfb8aa3b, v31
	v_exp_f32_e32 v35, v35
	v_exp_f32_e32 v39, v39
	v_pk_mul_f32 v[30:31], v[32:33], v[30:31]
	v_add_f32_e32 v35, 1.0, v35
	v_add_f32_e32 v39, 1.0, v39
	v_rcp_f32_e32 v35, v35
	v_rcp_f32_e32 v39, v39
	v_mul_f32_e32 v30, v30, v35
	v_mul_f32_e32 v31, v31, v39
	v_ashrrev_i32_e32 v35, 31, v34
	v_cvt_pk_bf16_f32 v39, v30, v31
	v_lshl_add_u64 v[30:31], v[20:21], 0, v[34:35]
	v_mad_u64_u32 v[32:33], s[24:25], v30, s35, v[22:23]
	v_mad_i32_i24 v33, v31, s35, v33
	global_store_dword v[32:33], v39, off offset:128
.LBB0_2350:
	s_or_b64 exec, exec, s[8:9]
	ds_read2_b32 v[44:45], v38 offset0:132 offset1:164
	v_add_u32_e32 v32, 1, v34
	v_cmp_gt_i32_e32 vcc, s30, v32
	s_waitcnt lgkmcnt(1)
	v_lshlrev_b32_e32 v30, 16, v46
	v_and_b32_e32 v31, 0xffff0000, v46
	v_lshlrev_b32_e32 v34, 16, v47
	v_and_b32_e32 v35, 0xffff0000, v47
	s_and_saveexec_b64 s[8:9], vcc
	s_cbranch_execz .LBB0_2347
	v_pk_mul_f32 v[40:41], v[90:91], v[28:29]
	s_nop 0
	v_pk_fma_f32 v[26:27], v[88:89], v[26:27], v[40:41]
	v_pk_mul_f32 v[40:41], v[98:99], v[2:3]
	v_pk_fma_f32 v[26:27], v[92:93], v[30:31], v[26:27]
	v_pk_fma_f32 v[24:25], v[96:97], v[24:25], v[40:41]
	v_pk_add_f32 v[26:27], v[94:95], v[26:27]
	v_pk_fma_f32 v[24:25], v[100:101], v[34:35], v[24:25]
	s_nop 0
	v_pk_add_f32 v[24:25], v[102:103], v[24:25]
	s_nop 0
	v_mul_f32_e32 v33, 0xbfb8aa3b, v24
	v_mul_f32_e32 v39, 0xbfb8aa3b, v25
	v_exp_f32_e32 v33, v33
	v_exp_f32_e32 v39, v39
	v_pk_mul_f32 v[24:25], v[26:27], v[24:25]
	v_add_f32_e32 v33, 1.0, v33
	v_add_f32_e32 v39, 1.0, v39
	v_rcp_f32_e32 v33, v33
	v_rcp_f32_e32 v39, v39
	v_mul_f32_e32 v24, v24, v33
	v_mul_f32_e32 v25, v25, v39
	v_ashrrev_i32_e32 v33, 31, v32
	v_cvt_pk_bf16_f32 v39, v24, v25
	v_lshl_add_u64 v[24:25], v[20:21], 0, v[32:33]
	v_mad_u64_u32 v[26:27], s[24:25], v24, s35, v[22:23]
	v_mad_i32_i24 v27, v25, s35, v27
	global_store_dword v[26:27], v39, off offset:128
	s_branch .LBB0_2347

; template <bool SWAP, class Epi, bool THIN = false> ...
;     ...
;     for (int st = 0; st < ns; ++st) {
;       asm volatile("s_waitcnt vmcnt(0)" ::: "memory");
;       __builtin_amdgcn_s_barrier();
;       asm volatile("" ::: "memory");
;       if (st + 1 < ns) {
;         char* nb = smem + ((st + 1) & 1) * 65536;
;         const int ko = (st + 1) * 64;
; #pragma unroll
;         for (int i = 0; i < 4; ++i) { GLDS16(A + (size_t)(ap[i] + ko), nb + tid * 16 + i * 8192); GLDS16(Bt + (size_t)(bp[i] + ko), nb + 32768 + tid * 16 + i * 8192); }
;       }
;       const char* sa = smem + (st & 1) * 65536 + (wr * 64 + fr) * 128;
;       const char* sb = smem + (st & 1) * 65536 + 32768 + (wc * 128 + fr) * 128;
;       if constexpr (THIN) {
;         if (wc == 0) {
; #pragma unroll
;           for (int ks = 0; ks < 2; ++ks) {
;             bf16x8 af[4], bf[2];
; #pragma unroll
;             for (int m = 0; m < 4; ++m) af[m] = *(const bf16x8*)(sa + m * 2048 + (((ks * 4 + fq) ^ swz) << 4));
; #pragma unroll
;             for (int n = 0; n < 2; ++n) bf[n] = *(const bf16x8*)(sb + n * 2048 + (((ks * 4 + fq) ^ swz) << 4));
; #pragma unroll
;             for (int m = 0; m < 4; ++m)
; #pragma unroll
;               for (int n = 0; n < 2; ++n)
;                 acc[m][n] = SWAP ? __builtin_amdgcn_mfma_f32_16x16x32_bf16(bf[n], af[m], acc[m][n], 0, 0, 0)
;                                  : __builtin_amdgcn_mfma_f32_16x16x32_bf16(af[m], bf[n], acc[m][n], 0, 0, 0);
;           }
;         }
;       } else {
;       bf16x8 afA[4], afB[4], bfb[2][2];
; #pragma unroll
;       for (int m = 0; m < 4; ++m) afA[m] = *(const bf16x8*)(sa + m * 2048 + ((fq ^ swz) << 4));
; #pragma unroll
;       for (int n = 0; n < 2; ++n) bfb[0][n] = *(const bf16x8*)(sb + n * 2048 + ((fq ^ swz) << 4));
; #pragma unroll
;       for (int gq = 0; gq < 8; ++gq) {
;         const int ks = gq >> 2, nh = gq & 3;
;         if (gq < 7) {
;           const int ks2 = (gq + 1) >> 2, nh2 = (gq + 1) & 3;
; #pragma unroll
;           for (int n = 0; n < 2; ++n) bfb[(gq + 1) & 1][n] = *(const bf16x8*)(sb + (nh2 * 2 + n) * 2048 + (((ks2 * 4 + fq) ^ swz) << 4));
;         }
;         if (gq == 3) {
; #pragma unroll
;           for (int m = 0; m < 4; ++m) afB[m] = *(const bf16x8*)(sa + m * 2048 + (((4 + fq) ^ swz) << 4));
;         }
;         __builtin_amdgcn_sched_barrier(0);
; #pragma unroll
.LBB0_3424:
	s_add_i32 s8, s7, 0x10000
	s_and_b32 s9, s8, 0x10000
	v_add_u32_e32 v170, s9, v135
	s_nop 0
	v_readfirstlane_b32 s9, v170
	s_waitcnt vmcnt(0)
	s_barrier
	s_and_b32 s7, s7, 0x10000
	v_or_b32_e32 v204, s7, v139
	v_add_u32_e32 v205, v204, v140
	v_add_u32_e32 v136, s7, v138
	v_add_u32_e32 v180, v136, v140
	ds_read_b128 v[168:171], v180
	ds_read_b128 v[172:175], v180 offset:2048
	ds_read_b128 v[176:179], v180 offset:4096
	ds_read_b128 v[180:183], v180 offset:6144
	ds_read_b128 v[184:187], v205 offset:32768
	ds_read_b128 v[188:191], v205 offset:34816
	ds_read_b128 v[192:195], v205 offset:36864
	ds_read_b128 v[196:199], v205 offset:38912
	v_add_u32_e32 v136, v136, v141
	s_waitcnt lgkmcnt(3)
	v_mfma_f32_16x16x32_bf16 v[126:129], v[184:187], v[168:171], v[126:129]
	s_mov_b32 m0, s9
	v_mfma_f32_16x16x32_bf16 v[110:113], v[184:187], v[172:175], v[110:113]
	global_load_lds_dwordx4 v167, s[14:15]
	v_add_u32_e32 v167, 0x80, v167
	v_mfma_f32_16x16x32_bf16 v[82:85], v[184:187], v[176:179], v[82:85]
	v_mfma_f32_16x16x32_bf16 v[50:53], v[184:187], v[180:183], v[50:53]
	ds_read_b128 v[184:187], v205 offset:40960
	ds_read_b128 v[200:203], v205 offset:43008
	s_waitcnt lgkmcnt(4)
	v_mfma_f32_16x16x32_bf16 v[122:125], v[188:191], v[168:171], v[122:125]
	s_add_u32 m0, s9, 0x8000
	v_mfma_f32_16x16x32_bf16 v[106:109], v[188:191], v[172:175], v[106:109]
	global_load_lds_dwordx4 v166, s[10:11]
	v_add_u32_e32 v166, 0x80, v166
	v_mfma_f32_16x16x32_bf16 v[78:81], v[188:191], v[176:179], v[78:81]
	v_mfma_f32_16x16x32_bf16 v[42:45], v[188:191], v[180:183], v[42:45]
	s_waitcnt lgkmcnt(3)
	v_mfma_f32_16x16x32_bf16 v[118:121], v[192:195], v[168:171], v[118:121]
	s_add_u32 m0, s9, 0x2000
	v_mfma_f32_16x16x32_bf16 v[94:97], v[192:195], v[172:175], v[94:97]
	global_load_lds_dwordx4 v165, s[14:15]
	v_add_u32_e32 v165, 0x80, v165
	v_mfma_f32_16x16x32_bf16 v[58:61], v[192:195], v[176:179], v[58:61]
	v_mfma_f32_16x16x32_bf16 v[26:29], v[192:195], v[180:183], v[26:29]
	ds_read_b128 v[188:191], v205 offset:45056
	ds_read_b128 v[192:195], v205 offset:47104
	s_waitcnt lgkmcnt(4)
	v_mfma_f32_16x16x32_bf16 v[114:117], v[196:199], v[168:171], v[114:117]
	s_add_u32 m0, s9, 0xa000
	v_mfma_f32_16x16x32_bf16 v[90:93], v[196:199], v[172:175], v[90:93]
	global_load_lds_dwordx4 v164, s[10:11]
	v_add_u32_e32 v164, 0x80, v164
	v_mfma_f32_16x16x32_bf16 v[54:57], v[196:199], v[176:179], v[54:57]
	v_mfma_f32_16x16x32_bf16 v[22:25], v[196:199], v[180:183], v[22:25]
	v_add_u32_e32 v220, v204, v141
	s_waitcnt lgkmcnt(3)
	v_mfma_f32_16x16x32_bf16 v[102:105], v[184:187], v[168:171], v[102:105]
	ds_read_b128 v[196:199], v220 offset:32768
	ds_read_b128 v[204:207], v220 offset:34816
	s_add_u32 m0, s9, 0x4000
	v_mfma_f32_16x16x32_bf16 v[74:77], v[184:187], v[172:175], v[74:77]
	global_load_lds_dwordx4 v163, s[14:15]
	v_add_u32_e32 v163, 0x80, v163
	v_mfma_f32_16x16x32_bf16 v[46:49], v[184:187], v[176:179], v[46:49]
	v_mfma_f32_16x16x32_bf16 v[10:13], v[184:187], v[180:183], v[10:13]
	ds_read_b128 v[184:187], v136
	ds_read_b128 v[208:211], v136 offset:2048
	ds_read_b128 v[212:215], v136 offset:4096
	ds_read_b128 v[216:219], v136 offset:6144
	s_waitcnt lgkmcnt(8)
	v_mfma_f32_16x16x32_bf16 v[98:101], v[200:203], v[168:171], v[98:101]
	s_add_u32 m0, s9, 0xc000
	v_mfma_f32_16x16x32_bf16 v[66:69], v[200:203], v[172:175], v[66:69]
	global_load_lds_dwordx4 v162, s[10:11]
	v_add_u32_e32 v162, 0x80, v162
	v_mfma_f32_16x16x32_bf16 v[30:33], v[200:203], v[176:179], v[30:33]
	v_mfma_f32_16x16x32_bf16 v[6:9], v[200:203], v[180:183], v[6:9]
	s_waitcnt lgkmcnt(7)
	v_mfma_f32_16x16x32_bf16 v[70:73], v[188:191], v[168:171], v[70:73]
	s_add_u32 m0, s9, 0x6000
	s_waitcnt lgkmcnt(6)
	v_mfma_f32_16x16x32_bf16 v[62:65], v[192:195], v[168:171], v[62:65]
	global_load_lds_dwordx4 v161, s[14:15]
	v_add_u32_e32 v161, 0x80, v161
	v_mfma_f32_16x16x32_bf16 v[38:41], v[188:191], v[172:175], v[38:41]
	v_mfma_f32_16x16x32_bf16 v[34:37], v[192:195], v[172:175], v[34:37]
	ds_read_b128 v[168:171], v220 offset:36864
	ds_read_b128 v[172:175], v220 offset:38912
	v_mfma_f32_16x16x32_bf16 v[18:21], v[188:191], v[176:179], v[18:21]
	s_add_u32 m0, s9, 0xe000
	v_mfma_f32_16x16x32_bf16 v[14:17], v[192:195], v[176:179], v[14:17]
	global_load_lds_dwordx4 v160, s[10:11]
	v_add_u32_e32 v160, 0x80, v160
	v_mfma_f32_16x16x32_bf16 v[2:5], v[188:191], v[180:183], v[2:5]
	v_mfma_f32_16x16x32_bf16 v[86:89], v[192:195], v[180:183], v[86:89]
	ds_read_b128 v[176:179], v220 offset:40960
	ds_read_b128 v[180:183], v220 offset:43008
	s_waitcnt lgkmcnt(7)
	v_mfma_f32_16x16x32_bf16 v[126:129], v[196:199], v[184:187], v[126:129]
	v_mfma_f32_16x16x32_bf16 v[122:125], v[204:207], v[184:187], v[122:125]
	s_waitcnt lgkmcnt(6)
	v_mfma_f32_16x16x32_bf16 v[110:113], v[196:199], v[208:211], v[110:113]
	v_mfma_f32_16x16x32_bf16 v[106:109], v[204:207], v[208:211], v[106:109]
	s_waitcnt lgkmcnt(5)
	v_mfma_f32_16x16x32_bf16 v[82:85], v[196:199], v[212:215], v[82:85]
	v_mfma_f32_16x16x32_bf16 v[78:81], v[204:207], v[212:215], v[78:81]
	s_waitcnt lgkmcnt(4)
	v_mfma_f32_16x16x32_bf16 v[50:53], v[196:199], v[216:219], v[50:53]
	v_mfma_f32_16x16x32_bf16 v[42:45], v[204:207], v[216:219], v[42:45]
	s_waitcnt lgkmcnt(3)
	v_mfma_f32_16x16x32_bf16 v[118:121], v[168:171], v[184:187], v[118:121]
	v_mfma_f32_16x16x32_bf16 v[94:97], v[168:171], v[208:211], v[94:97]
	v_mfma_f32_16x16x32_bf16 v[58:61], v[168:171], v[212:215], v[58:61]
	v_mfma_f32_16x16x32_bf16 v[26:29], v[168:171], v[216:219], v[26:29]
	ds_read_b128 v[168:171], v220 offset:45056
	ds_read_b128 v[188:191], v220 offset:47104
	s_waitcnt lgkmcnt(4)
; template <bool SWAP, class Epi, bool THIN = false> ...
;     ...
;     for (int st = 0; st < ns; ++st) {
;       asm volatile("s_waitcnt vmcnt(0)" ::: "memory");
;       __builtin_amdgcn_s_barrier();
;       asm volatile("" ::: "memory");
;       if (st + 1 < ns) {
;         char* nb = smem + ((st + 1) & 1) * 65536;
;         const int ko = (st + 1) * 64;
; #pragma unroll
;         for (int i = 0; i < 4; ++i) { GLDS16(A + (size_t)(ap[i] + ko), nb + tid * 16 + i * 8192); GLDS16(Bt + (size_t)(bp[i] + ko), nb + 32768 + tid * 16 + i * 8192); }
;       }
;       const char* sa = smem + (st & 1) * 65536 + (wr * 64 + fr) * 128;
;       const char* sb = smem + (st & 1) * 65536 + 32768 + (wc * 128 + fr) * 128;
;       if constexpr (THIN) {
;         if (wc == 0) {
; #pragma unroll
;           for (int ks = 0; ks < 2; ++ks) {
;             bf16x8 af[4], bf[2];
; #pragma unroll
;             for (int m = 0; m < 4; ++m) af[m] = *(const bf16x8*)(sa + m * 2048 + (((ks * 4 + fq) ^ swz) << 4));
; #pragma unroll
;             for (int n = 0; n < 2; ++n) bf[n] = *(const bf16x8*)(sb + n * 2048 + (((ks * 4 + fq) ^ swz) << 4));
; #pragma unroll
;             for (int m = 0; m < 4; ++m)
; #pragma unroll
;               for (int n = 0; n < 2; ++n)
;                 acc[m][n] = SWAP ? __builtin_amdgcn_mfma_f32_16x16x32_bf16(bf[n], af[m], acc[m][n], 0, 0, 0)
;                                  : __builtin_amdgcn_mfma_f32_16x16x32_bf16(af[m], bf[n], acc[m][n], 0, 0, 0);
;           }
;         }
;       } else {
;       bf16x8 afA[4], afB[4], bfb[2][2];
; #pragma unroll
;       for (int m = 0; m < 4; ++m) afA[m] = *(const bf16x8*)(sa + m * 2048 + ((fq ^ swz) << 4));
; #pragma unroll
;       for (int n = 0; n < 2; ++n) bfb[0][n] = *(const bf16x8*)(sb + n * 2048 + ((fq ^ swz) << 4));
; #pragma unroll
;       for (int gq = 0; gq < 8; ++gq) {
;         const int ks = gq >> 2, nh = gq & 3;
;         if (gq < 7) {
;           const int ks2 = (gq + 1) >> 2, nh2 = (gq + 1) & 3;
; #pragma unroll
;           for (int n = 0; n < 2; ++n) bfb[(gq + 1) & 1][n] = *(const bf16x8*)(sb + (nh2 * 2 + n) * 2048 + (((ks2 * 4 + fq) ^ swz) << 4));
;         }
;         if (gq == 3) {
; #pragma unroll
;           for (int m = 0; m < 4; ++m) afB[m] = *(const bf16x8*)(sa + m * 2048 + (((4 + fq) ^ swz) << 4));
;         }
;         __builtin_amdgcn_sched_barrier(0);
; #pragma unroll
	v_mfma_f32_16x16x32_bf16 v[114:117], v[172:175], v[184:187], v[114:117]
	v_mfma_f32_16x16x32_bf16 v[90:93], v[172:175], v[208:211], v[90:93]
	v_mfma_f32_16x16x32_bf16 v[54:57], v[172:175], v[212:215], v[54:57]
	v_mfma_f32_16x16x32_bf16 v[22:25], v[172:175], v[216:219], v[22:25]
	s_waitcnt lgkmcnt(3)
	v_mfma_f32_16x16x32_bf16 v[102:105], v[176:179], v[184:187], v[102:105]
	s_waitcnt lgkmcnt(2)
	v_mfma_f32_16x16x32_bf16 v[98:101], v[180:183], v[184:187], v[98:101]
	v_mfma_f32_16x16x32_bf16 v[74:77], v[176:179], v[208:211], v[74:77]
	v_mfma_f32_16x16x32_bf16 v[66:69], v[180:183], v[208:211], v[66:69]
	v_mfma_f32_16x16x32_bf16 v[46:49], v[176:179], v[212:215], v[46:49]
	v_mfma_f32_16x16x32_bf16 v[30:33], v[180:183], v[212:215], v[30:33]
	v_mfma_f32_16x16x32_bf16 v[10:13], v[176:179], v[216:219], v[10:13]
	v_mfma_f32_16x16x32_bf16 v[6:9], v[180:183], v[216:219], v[6:9]
	s_waitcnt lgkmcnt(1)
	v_mfma_f32_16x16x32_bf16 v[70:73], v[168:171], v[184:187], v[70:73]
	s_add_i32 s5, s5, 64
	s_cmpk_eq_i32 s5, 0x3c0
	s_mov_b32 s7, s8
	s_waitcnt lgkmcnt(0)
	v_mfma_f32_16x16x32_bf16 v[62:65], v[188:191], v[184:187], v[62:65]
	v_mfma_f32_16x16x32_bf16 v[38:41], v[168:171], v[208:211], v[38:41]
	v_mfma_f32_16x16x32_bf16 v[34:37], v[188:191], v[208:211], v[34:37]
	v_mfma_f32_16x16x32_bf16 v[18:21], v[168:171], v[212:215], v[18:21]
	v_mfma_f32_16x16x32_bf16 v[14:17], v[188:191], v[212:215], v[14:17]
	v_mfma_f32_16x16x32_bf16 v[2:5], v[168:171], v[216:219], v[2:5]
	v_mfma_f32_16x16x32_bf16 v[86:89], v[188:191], v[216:219], v[86:89]
	s_cbranch_scc0 .LBB0_3424
	s_waitcnt vmcnt(0)
	s_barrier
	v_add_u32_e32 v136, v150, v140
	ds_read_b128 v[160:163], v136
	ds_read_b128 v[164:167], v136 offset:2048
	ds_read_b128 v[168:171], v136 offset:4096
	ds_read_b128 v[172:175], v136 offset:6144
	v_add_u32_e32 v136, v151, v140
	ds_read_b128 v[176:179], v136
	ds_read_b128 v[180:183], v136 offset:2048
	ds_read_b128 v[184:187], v136 offset:4096
	ds_read_b128 v[188:191], v136 offset:6144
	s_waitcnt lgkmcnt(0)
	v_mfma_f32_16x16x32_bf16 v[126:129], v[176:179], v[160:163], v[126:129]
	v_mfma_f32_16x16x32_bf16 v[110:113], v[176:179], v[164:167], v[110:113]
	v_mfma_f32_16x16x32_bf16 v[82:85], v[176:179], v[168:171], v[82:85]
	v_mfma_f32_16x16x32_bf16 v[50:53], v[176:179], v[172:175], v[50:53]
	ds_read_b128 v[176:179], v136 offset:8192
	ds_read_b128 v[192:195], v136 offset:10240
	v_mfma_f32_16x16x32_bf16 v[122:125], v[180:183], v[160:163], v[122:125]
	v_mfma_f32_16x16x32_bf16 v[106:109], v[180:183], v[164:167], v[106:109]
	v_mfma_f32_16x16x32_bf16 v[78:81], v[180:183], v[168:171], v[78:81]
	v_mfma_f32_16x16x32_bf16 v[42:45], v[180:183], v[172:175], v[42:45]
	v_mfma_f32_16x16x32_bf16 v[118:121], v[184:187], v[160:163], v[118:121]
	v_mfma_f32_16x16x32_bf16 v[94:97], v[184:187], v[164:167], v[94:97]
	v_mfma_f32_16x16x32_bf16 v[58:61], v[184:187], v[168:171], v[58:61]
	v_mfma_f32_16x16x32_bf16 v[26:29], v[184:187], v[172:175], v[26:29]
	ds_read_b128 v[180:183], v136 offset:12288
	ds_read_b128 v[184:187], v136 offset:14336
	v_mfma_f32_16x16x32_bf16 v[114:117], v[188:191], v[160:163], v[114:117]
	v_mfma_f32_16x16x32_bf16 v[90:93], v[188:191], v[164:167], v[90:93]
	v_mfma_f32_16x16x32_bf16 v[54:57], v[188:191], v[168:171], v[54:57]
	v_mfma_f32_16x16x32_bf16 v[22:25], v[188:191], v[172:175], v[22:25]
	v_add_u32_e32 v136, v151, v141
	v_add_u32_e32 v208, v150, v141
	s_waitcnt lgkmcnt(0)
	v_mfma_f32_16x16x32_bf16 v[102:105], v[176:179], v[160:163], v[102:105]
	v_mfma_f32_16x16x32_bf16 v[74:77], v[176:179], v[164:167], v[74:77]
	v_mfma_f32_16x16x32_bf16 v[188:191], v[192:195], v[164:167], v[66:69]
	v_mfma_f32_16x16x32_bf16 v[196:199], v[176:179], v[168:171], v[46:49]
	s_nop 2
	ds_read_b128 v[46:49], v136
	ds_read_b128 v[66:69], v136 offset:2048
	v_mfma_f32_16x16x32_bf16 v[10:13], v[176:179], v[172:175], v[10:13]
	ds_read_b128 v[176:179], v208
	ds_read_b128 v[200:203], v208 offset:2048
	ds_read_b128 v[204:207], v208 offset:4096
	ds_read_b128 v[208:211], v208 offset:6144
	v_mfma_f32_16x16x32_bf16 v[98:101], v[192:195], v[160:163], v[98:101]
	v_mfma_f32_16x16x32_bf16 v[30:33], v[192:195], v[168:171], v[30:33]
	v_mfma_f32_16x16x32_bf16 v[6:9], v[192:195], v[172:175], v[6:9]
	v_mfma_f32_16x16x32_bf16 v[192:195], v[180:183], v[164:167], v[38:41]
	v_mfma_f32_16x16x32_bf16 v[164:167], v[184:187], v[164:167], v[34:37]
	v_mfma_f32_16x16x32_bf16 v[18:21], v[180:183], v[168:171], v[18:21]
	v_mfma_f32_16x16x32_bf16 v[168:171], v[184:187], v[168:171], v[14:17]
	s_nop 2
	ds_read_b128 v[14:17], v136 offset:4096
	ds_read_b128 v[34:37], v136 offset:6144
	v_mfma_f32_16x16x32_bf16 v[70:73], v[180:183], v[160:163], v[70:73]
	v_mfma_f32_16x16x32_bf16 v[2:5], v[180:183], v[172:175], v[2:5]
	v_mfma_f32_16x16x32_bf16 v[160:163], v[184:187], v[160:163], v[62:65]
	v_mfma_f32_16x16x32_bf16 v[86:89], v[184:187], v[172:175], v[86:89]
	s_waitcnt lgkmcnt(0)
	v_mfma_f32_16x16x32_bf16 v[172:175], v[46:49], v[208:211], v[50:53]
	s_nop 2
	ds_read_b128 v[50:53], v136 offset:8192
	ds_read_b128 v[180:183], v136 offset:10240
	v_mfma_f32_16x16x32_bf16 v[126:129], v[46:49], v[176:179], v[126:129]
	v_mfma_f32_16x16x32_bf16 v[122:125], v[66:69], v[176:179], v[122:125]
	v_mfma_f32_16x16x32_bf16 v[110:113], v[46:49], v[200:203], v[110:113]
	v_mfma_f32_16x16x32_bf16 v[106:109], v[66:69], v[200:203], v[106:109]
	v_mfma_f32_16x16x32_bf16 v[82:85], v[46:49], v[204:207], v[82:85]
	v_mfma_f32_16x16x32_bf16 v[78:81], v[66:69], v[204:207], v[78:81]
	v_mfma_f32_16x16x32_bf16 v[184:187], v[66:69], v[208:211], v[42:45]
	ds_read_b128 v[224:227], v136 offset:12288
	ds_read_b128 v[228:231], v136 offset:14336
	v_mfma_f32_16x16x32_bf16 v[118:121], v[14:17], v[176:179], v[118:121]
	v_mfma_f32_16x16x32_bf16 v[114:117], v[34:37], v[176:179], v[114:117]
	v_mfma_f32_16x16x32_bf16 v[94:97], v[14:17], v[200:203], v[94:97]
	v_mfma_f32_16x16x32_bf16 v[90:93], v[34:37], v[200:203], v[90:93]
	v_mfma_f32_16x16x32_bf16 v[212:215], v[14:17], v[204:207], v[58:61]
	v_mfma_f32_16x16x32_bf16 v[216:219], v[34:37], v[204:207], v[54:57]
	v_mfma_f32_16x16x32_bf16 v[220:223], v[14:17], v[208:211], v[26:29]
	v_mfma_f32_16x16x32_bf16 v[66:69], v[34:37], v[208:211], v[22:25]
	s_waitcnt lgkmcnt(0)
	v_mfma_f32_16x16x32_bf16 v[38:41], v[180:183], v[204:207], v[30:33]
	v_mfma_f32_16x16x32_bf16 v[62:65], v[50:53], v[176:179], v[102:105]
	v_mfma_f32_16x16x32_bf16 v[46:49], v[180:183], v[176:179], v[98:101]
	v_mfma_f32_16x16x32_bf16 v[58:61], v[50:53], v[200:203], v[74:77]
	v_mfma_f32_16x16x32_bf16 v[42:45], v[180:183], v[200:203], v[188:191]
	v_mfma_f32_16x16x32_bf16 v[54:57], v[50:53], v[204:207], v[196:199]
	v_mfma_f32_16x16x32_bf16 v[50:53], v[50:53], v[208:211], v[10:13]
	v_mfma_f32_16x16x32_bf16 v[34:37], v[180:183], v[208:211], v[6:9]
	s_nop 2
	v_mov_b32_e32 v8, v1
	s_waitcnt vmcnt(0)
	s_barrier
; template <bool SWAP, class Epi, bool THIN = false> ...
;     ...
;     __syncthreads();
;     const int te = get_tid512();
;     const int fr_e = te & 15, fq_e = (te & 63) >> 4, wr_e = te >> 7, wc_e = (te >> 6) & 1;
;     const int sub = 2 * mt + (wr_e >> 1);
;     const int g = sub / tpg, ti = sub - g * tpg;
;     const int rig0 = ti * step - halo;
;     const int rw = (wr_e & 1) * 64;
;     if constexpr (Epi::KIND == 0) {
; #pragma unroll
;       for (int m = 0; m < 4; ++m) {
;         const int rig = rig0 + rw + m * 16 + fr_e;
;         if constexpr (Epi::ROWSUM) {
;           float ss = 0.f;
; #pragma unroll
;           for (int n = 0; n < 8; ++n) {
;             const int col = nt * 256 + wc_e * 128 + n * 16 + fq_e * 4;
;             if (col < N) ss += epi.c4(g, rig, col, acc[m][n]);
;           }
;           ss += __shfl_xor(ss, 16); ss += __shfl_xor(ss, 32);
;           if (fq_e == 0) epi.rowsum(g, rig, nt * 2 + wc_e, ss);
;         } else {
; #pragma unroll
;           for (int n = 0; n < 8; ++n) {
;             const int col = nt * 256 + wc_e * 128 + n * 16 + fq_e * 4;
;             if (col < N) epi.c4(g, rig, col, acc[m][n]);
;           }
;         }
;       }
;     } else if constexpr (Epi::KIND == 1) {
; #pragma unroll
;       for (int m = 0; m < 4; ++m) {
;         const int rig = rig0 + rw + m * 16 + fq_e * 4;
; #pragma unroll
;         for (int n = 0; n < 8; ++n) {
;           const int col = nt * 256 + wc_e * 128 + n * 16 + fr_e;
;           if (col < N) epi.r4(g, rig, col, acc[m][n]);
;         }
;       }
;     } else {
;       bf16_t* Zw = (bf16_t*)smem + ((wr_e >> 1) * 2 + wc_e) * (128 * 132);
;       const int nt2w = nt * 2 + wc_e;
; #pragma unroll
;       for (int n = 0; n < 8; ++n) {
;         const int cl = n * 16 + fq_e * 4;
;         f32x4 b4 = {0.f, 0.f, 0.f, 0.f};
;         if (epi.pre_bias) b4 = *(const f32x4*)(epi.pre_bias + epi.norig(nt2w, cl));
; #pragma unroll
;         for (int m = 0; m < 4; ++m) {
;           const int rl = rw + m * 16 + fr_e;
;           const int pos = rig0 + rl;
;           const bool ok = pos >= 0 && pos < grows;
;           f32x4 vv = acc[m][n] + b4;
;           if (!ok) vv = (f32x4){0.f, 0.f, 0.f, 0.f};
;           uint2 u; u.x = pack2(vv[0], vv[1]); u.y = pack2(vv[2], vv[3]);
;           *(uint2*)(Zw + rl * 132 + cl) = u;
;         }
	v_mfma_f32_16x16x32_bf16 v[30:33], v[224:227], v[176:179], v[70:73]
	v_ashrrev_i32_e32 v98, 8, v8
	v_add_u32_e32 v6, s4, v98
	v_mul_hi_i32 v7, v6, s26
	v_lshrrev_b32_e32 v9, 31, v7
	v_ashrrev_i32_e32 v7, 3, v7
	v_add_u32_e32 v70, v7, v9
	v_and_b32_e32 v71, 15, v8
	v_mad_u64_u32 v[6:7], s[4:5], v70, s27, v[6:7]
	v_lshrrev_b32_e32 v74, 1, v8
	v_bfe_u32 v73, v8, 6, 1
	v_mul_lo_u32 v72, v6, s28
	v_and_or_b32 v71, v74, 64, v71
	v_add_u32_e32 v99, v72, v71
	v_lshl_or_b32 v73, v98, 1, v73
	v_mul_lo_u32 v73, v73, s29
	v_add_u32_e32 v100, -1, v99
	v_and_or_b32 v73, v74, 24, v73
	v_pk_add_f32 v[74:75], v[128:129], 0 op_sel_hi:[1,0]
	v_pk_add_f32 v[76:77], v[126:127], 0 op_sel_hi:[1,0]
	v_cmp_gt_u32_e32 vcc, s30, v100
	v_mfma_f32_16x16x32_bf16 v[22:25], v[224:227], v[204:207], v[18:21]
	v_mad_u32_u24 v71, v71, s31, v73
	v_add_u32_e32 v73, 15, v99
	v_cmp_gt_u32_e64 s[4:5], s30, v73
	v_mfma_f32_16x16x32_bf16 v[18:21], v[224:227], v[208:211], v[2:5]
	s_lshl_b32 s24, s6, 7
	v_cndmask_b32_e32 v75, 0, v75, vcc
	v_pk_add_f32 v[84:85], v[84:85], 0 op_sel_hi:[1,0]
	v_mfma_f32_16x16x32_bf16 v[2:5], v[228:231], v[208:211], v[86:89]
	v_add_f32_e64 v82, v82, 0
	v_add_f32_e64 v83, v83, 0
	v_pk_add_f32 v[66:67], v[66:67], 0 op_sel_hi:[1,0]
	v_pk_add_f32 v[62:63], v[62:63], 0 op_sel_hi:[1,0]
	v_cndmask_b32_e32 v86, 0, v74, vcc
	v_cndmask_b32_e32 v74, 0, v76, vcc
	v_cndmask_b32_e32 v76, 0, v77, vcc
	v_cvt_pk_bf16_f32 v74, v74, v76
	v_pk_add_f32 v[76:77], v[112:113], 0 op_sel_hi:[1,0]
	v_cvt_pk_bf16_f32 v75, v86, v75
	v_pk_add_f32 v[86:87], v[110:111], 0 op_sel_hi:[1,0]
	v_cndmask_b32_e64 v73, 0, v76, s[4:5]
	v_cndmask_b32_e64 v77, 0, v77, s[4:5]
	v_cvt_pk_bf16_f32 v77, v73, v77
	v_add_u32_e32 v73, 31, v99
	v_cmp_gt_u32_e64 s[6:7], s30, v73
	v_cndmask_b32_e64 v76, 0, v86, s[4:5]
	v_cndmask_b32_e64 v86, 0, v87, s[4:5]
	v_cndmask_b32_e64 v73, 0, v84, s[6:7]
	v_cndmask_b32_e64 v82, 0, v82, s[6:7]
	v_cndmask_b32_e64 v83, 0, v83, s[6:7]
	v_cndmask_b32_e64 v84, 0, v85, s[6:7]
	v_cvt_pk_bf16_f32 v82, v82, v83
	v_cvt_pk_bf16_f32 v83, v73, v84
	v_add_u32_e32 v73, 47, v99
	v_cvt_pk_bf16_f32 v76, v76, v86
	v_pk_add_f32 v[84:85], v[174:175], 0 op_sel_hi:[1,0]
	v_pk_add_f32 v[86:87], v[172:173], 0 op_sel_hi:[1,0]
	v_cmp_gt_u32_e64 s[8:9], s30, v73
	v_pk_add_f32 v[88:89], v[122:123], 0 op_sel_hi:[1,0]
	v_mfma_f32_16x16x32_bf16 v[26:29], v[224:227], v[200:203], v[192:195]
	v_cndmask_b32_e64 v73, 0, v84, s[8:9]
	v_cndmask_b32_e64 v84, 0, v86, s[8:9]
	v_cndmask_b32_e64 v86, 0, v87, s[8:9]
	v_cndmask_b32_e64 v85, 0, v85, s[8:9]
	v_cvt_pk_bf16_f32 v84, v84, v86
	v_pk_add_f32 v[86:87], v[124:125], 0 op_sel_hi:[1,0]
	v_cvt_pk_bf16_f32 v85, v73, v85
	v_mfma_f32_16x16x32_bf16 v[14:17], v[228:231], v[176:179], v[160:163]
	v_cndmask_b32_e32 v73, 0, v86, vcc
	v_cndmask_b32_e32 v87, 0, v87, vcc
	v_cndmask_b32_e32 v86, 0, v88, vcc
	v_cndmask_b32_e32 v88, 0, v89, vcc
	v_cvt_pk_bf16_f32 v86, v86, v88
	v_cvt_pk_bf16_f32 v87, v73, v87
	ds_write2_b64 v71, v[74:75], v[86:87] offset1:4
	v_pk_add_f32 v[74:75], v[108:109], 0 op_sel_hi:[1,0]
	v_pk_add_f32 v[86:87], v[106:107], 0 op_sel_hi:[1,0]
	v_cndmask_b32_e64 v73, 0, v74, s[4:5]
	v_cndmask_b32_e64 v75, 0, v75, s[4:5]
	v_cndmask_b32_e64 v74, 0, v86, s[4:5]
	v_cndmask_b32_e64 v86, 0, v87, s[4:5]
	v_cvt_pk_bf16_f32 v74, v74, v86
	v_cvt_pk_bf16_f32 v75, v73, v75
	v_add_u32_e32 v73, 0x1000, v71
	ds_write2_b64 v73, v[76:77], v[74:75] offset0:16 offset1:20
	v_pk_add_f32 v[74:75], v[80:81], 0 op_sel_hi:[1,0]
	v_pk_add_f32 v[76:77], v[78:79], 0 op_sel_hi:[1,0]
	v_cndmask_b32_e64 v78, 0, v74, s[6:7]
	v_cndmask_b32_e64 v75, 0, v75, s[6:7]
	v_cndmask_b32_e64 v74, 0, v76, s[6:7]
	v_cndmask_b32_e64 v76, 0, v77, s[6:7]
	v_cvt_pk_bf16_f32 v74, v74, v76
	v_cvt_pk_bf16_f32 v75, v78, v75
	v_add_u32_e32 v86, 0x2000, v71
	ds_write2_b64 v86, v[82:83], v[74:75] offset0:32 offset1:36
	v_pk_add_f32 v[74:75], v[186:187], 0 op_sel_hi:[1,0]
	v_pk_add_f32 v[76:77], v[184:185], 0 op_sel_hi:[1,0]
	v_cndmask_b32_e64 v78, 0, v74, s[8:9]
	v_cndmask_b32_e64 v75, 0, v75, s[8:9]
	v_cndmask_b32_e64 v74, 0, v76, s[8:9]
	v_cndmask_b32_e64 v76, 0, v77, s[8:9]
	v_cvt_pk_bf16_f32 v74, v74, v76
	v_cvt_pk_bf16_f32 v75, v78, v75
	v_add_u32_e32 v87, 0x3000, v71
	ds_write2_b64 v87, v[84:85], v[74:75] offset0:48 offset1:52
	v_pk_add_f32 v[74:75], v[120:121], 0 op_sel_hi:[1,0]
	v_pk_add_f32 v[76:77], v[118:119], 0 op_sel_hi:[1,0]
	v_cndmask_b32_e32 v78, 0, v74, vcc
	v_cndmask_b32_e32 v75, 0, v75, vcc
	v_cndmask_b32_e32 v74, 0, v76, vcc
	v_cndmask_b32_e32 v76, 0, v77, vcc
	v_cvt_pk_bf16_f32 v74, v74, v76
	v_cvt_pk_bf16_f32 v75, v78, v75
	v_pk_add_f32 v[76:77], v[96:97], 0 op_sel_hi:[1,0]
	v_pk_add_f32 v[78:79], v[94:95], 0 op_sel_hi:[1,0]
	v_cndmask_b32_e64 v80, 0, v76, s[4:5]
	v_cndmask_b32_e64 v77, 0, v77, s[4:5]
	v_cndmask_b32_e64 v76, 0, v78, s[4:5]
	v_cndmask_b32_e64 v78, 0, v79, s[4:5]
	v_cvt_pk_bf16_f32 v76, v76, v78
	v_cvt_pk_bf16_f32 v77, v80, v77
	v_pk_add_f32 v[78:79], v[214:215], 0 op_sel_hi:[1,0]
	v_pk_add_f32 v[80:81], v[212:213], 0 op_sel_hi:[1,0]
	v_cndmask_b32_e64 v82, 0, v78, s[6:7]
	v_cndmask_b32_e64 v79, 0, v79, s[6:7]
	v_cndmask_b32_e64 v78, 0, v80, s[6:7]
	v_cndmask_b32_e64 v80, 0, v81, s[6:7]
	v_cvt_pk_bf16_f32 v78, v78, v80
	v_cvt_pk_bf16_f32 v79, v82, v79
	v_pk_add_f32 v[80:81], v[222:223], 0 op_sel_hi:[1,0]
	v_pk_add_f32 v[82:83], v[220:221], 0 op_sel_hi:[1,0]
	v_cndmask_b32_e64 v84, 0, v80, s[8:9]
	v_cndmask_b32_e64 v81, 0, v81, s[8:9]
	v_cndmask_b32_e64 v80, 0, v82, s[8:9]
	v_cndmask_b32_e64 v82, 0, v83, s[8:9]
	v_cvt_pk_bf16_f32 v80, v80, v82
	v_cvt_pk_bf16_f32 v81, v84, v81
	v_pk_add_f32 v[82:83], v[116:117], 0 op_sel_hi:[1,0]
	v_pk_add_f32 v[84:85], v[114:115], 0 op_sel_hi:[1,0]
; __device__ __forceinline__ unsigned pack2(float a, float b) { unsigned r; asm("v_cvt_pk_bf16_f32 %0, %1, %2" : "=v"(r) : "v"(a), "v"(b)); return r; }
; template <bool SWAP, class Epi, bool THIN = false> ...
;     ...
;     } else {
;       bf16_t* Zw = (bf16_t*)smem + ((wr_e >> 1) * 2 + wc_e) * (128 * 132);
;       const int nt2w = nt * 2 + wc_e;
; #pragma unroll
;       for (int n = 0; n < 8; ++n) {
;         const int cl = n * 16 + fq_e * 4;
;         f32x4 b4 = {0.f, 0.f, 0.f, 0.f};
;         if (epi.pre_bias) b4 = *(const f32x4*)(epi.pre_bias + epi.norig(nt2w, cl));
; #pragma unroll
;         for (int m = 0; m < 4; ++m) {
;           const int rl = rw + m * 16 + fr_e;
;           const int pos = rig0 + rl;
;           const bool ok = pos >= 0 && pos < grows;
;           f32x4 vv = acc[m][n] + b4;
;           if (!ok) vv = (f32x4){0.f, 0.f, 0.f, 0.f};
;           uint2 u; u.x = pack2(vv[0], vv[1]); u.y = pack2(vv[2], vv[3]);
;           *(uint2*)(Zw + rl * 132 + cl) = u;
;         }
;       }
	v_cndmask_b32_e32 v88, 0, v82, vcc
	v_cndmask_b32_e32 v83, 0, v83, vcc
	v_cndmask_b32_e32 v82, 0, v84, vcc
	v_mfma_f32_16x16x32_bf16 v[10:13], v[228:231], v[200:203], v[164:167]
	v_cndmask_b32_e32 v84, 0, v85, vcc
	v_cvt_pk_bf16_f32 v82, v82, v84
	v_cvt_pk_bf16_f32 v83, v88, v83
	v_mfma_f32_16x16x32_bf16 v[6:9], v[228:231], v[204:207], v[168:171]
	ds_write2_b64 v71, v[74:75], v[82:83] offset0:8 offset1:12
	v_pk_add_f32 v[74:75], v[92:93], 0 op_sel_hi:[1,0]
	v_pk_add_f32 v[82:83], v[90:91], 0 op_sel_hi:[1,0]
	v_cndmask_b32_e64 v84, 0, v74, s[4:5]
	v_cndmask_b32_e64 v75, 0, v75, s[4:5]
	v_cndmask_b32_e64 v74, 0, v82, s[4:5]
	v_cndmask_b32_e64 v82, 0, v83, s[4:5]
	v_cvt_pk_bf16_f32 v74, v74, v82
	v_cvt_pk_bf16_f32 v75, v84, v75
	v_pk_add_f32 v[28:29], v[28:29], 0 op_sel_hi:[1,0]
	v_pk_add_f32 v[26:27], v[26:27], 0 op_sel_hi:[1,0]
	ds_write2_b64 v73, v[76:77], v[74:75] offset0:24 offset1:28
	v_pk_add_f32 v[74:75], v[218:219], 0 op_sel_hi:[1,0]
	v_pk_add_f32 v[76:77], v[216:217], 0 op_sel_hi:[1,0]
	v_pk_add_f32 v[58:59], v[58:59], 0 op_sel_hi:[1,0]
	v_pk_add_f32 v[54:55], v[54:55], 0 op_sel_hi:[1,0]
	v_pk_add_f32 v[50:51], v[50:51], 0 op_sel_hi:[1,0]
	v_pk_add_f32 v[46:47], v[46:47], 0 op_sel_hi:[1,0]
	v_pk_add_f32 v[42:43], v[42:43], 0 op_sel_hi:[1,0]
	v_pk_add_f32 v[38:39], v[38:39], 0 op_sel_hi:[1,0]
	v_pk_add_f32 v[34:35], v[34:35], 0 op_sel_hi:[1,0]
	v_pk_add_f32 v[30:31], v[30:31], 0 op_sel_hi:[1,0]
	v_cndmask_b32_e64 v28, 0, v28, s[4:5]
	v_cndmask_b32_e64 v26, 0, v26, s[4:5]
	v_cndmask_b32_e64 v27, 0, v27, s[4:5]
	v_pk_add_f32 v[22:23], v[22:23], 0 op_sel_hi:[1,0]
	v_pk_add_f32 v[18:19], v[18:19], 0 op_sel_hi:[1,0]
	v_pk_add_f32 v[14:15], v[14:15], 0 op_sel_hi:[1,0]
	v_pk_add_f32 v[10:11], v[10:11], 0 op_sel_hi:[1,0]
	v_pk_add_f32 v[6:7], v[6:7], 0 op_sel_hi:[1,0]
	v_pk_add_f32 v[2:3], v[2:3], 0 op_sel_hi:[1,0]
	v_cndmask_b32_e64 v82, 0, v74, s[6:7]
	v_cndmask_b32_e64 v75, 0, v75, s[6:7]
	v_cndmask_b32_e64 v74, 0, v76, s[6:7]
	v_pk_add_f32 v[68:69], v[68:69], 0 op_sel_hi:[1,0]
	v_cndmask_b32_e64 v66, 0, v66, s[8:9]
	v_cndmask_b32_e64 v67, 0, v67, s[8:9]
	v_pk_add_f32 v[64:65], v[64:65], 0 op_sel_hi:[1,0]
	v_cndmask_b32_e32 v62, 0, v62, vcc
	v_cndmask_b32_e32 v63, 0, v63, vcc
	v_pk_add_f32 v[60:61], v[60:61], 0 op_sel_hi:[1,0]
	v_cndmask_b32_e64 v58, 0, v58, s[4:5]
	v_cndmask_b32_e64 v59, 0, v59, s[4:5]
	v_pk_add_f32 v[56:57], v[56:57], 0 op_sel_hi:[1,0]
	v_cndmask_b32_e64 v54, 0, v54, s[6:7]
	v_cndmask_b32_e64 v55, 0, v55, s[6:7]
	v_pk_add_f32 v[52:53], v[52:53], 0 op_sel_hi:[1,0]
	v_cndmask_b32_e64 v50, 0, v50, s[8:9]
	v_cndmask_b32_e64 v51, 0, v51, s[8:9]
	v_pk_add_f32 v[48:49], v[48:49], 0 op_sel_hi:[1,0]
	v_cndmask_b32_e32 v46, 0, v46, vcc
	v_cndmask_b32_e32 v47, 0, v47, vcc
	v_pk_add_f32 v[44:45], v[44:45], 0 op_sel_hi:[1,0]
	v_cndmask_b32_e64 v42, 0, v42, s[4:5]
	v_cndmask_b32_e64 v43, 0, v43, s[4:5]
	v_pk_add_f32 v[40:41], v[40:41], 0 op_sel_hi:[1,0]
	v_cndmask_b32_e64 v38, 0, v38, s[6:7]
	v_cndmask_b32_e64 v39, 0, v39, s[6:7]
	v_pk_add_f32 v[36:37], v[36:37], 0 op_sel_hi:[1,0]
	v_cndmask_b32_e64 v34, 0, v34, s[8:9]
	v_cndmask_b32_e64 v35, 0, v35, s[8:9]
	v_pk_add_f32 v[32:33], v[32:33], 0 op_sel_hi:[1,0]
	v_cndmask_b32_e32 v30, 0, v30, vcc
	v_cndmask_b32_e32 v31, 0, v31, vcc
	v_cndmask_b32_e64 v29, 0, v29, s[4:5]
	v_cvt_pk_bf16_f32 v26, v26, v27
	v_cvt_pk_bf16_f32 v27, v28, v29
	v_pk_add_f32 v[24:25], v[24:25], 0 op_sel_hi:[1,0]
	v_cndmask_b32_e64 v22, 0, v22, s[6:7]
	v_cndmask_b32_e64 v23, 0, v23, s[6:7]
	v_pk_add_f32 v[20:21], v[20:21], 0 op_sel_hi:[1,0]
	v_cndmask_b32_e64 v18, 0, v18, s[8:9]
	v_cndmask_b32_e64 v19, 0, v19, s[8:9]
	v_pk_add_f32 v[16:17], v[16:17], 0 op_sel_hi:[1,0]
	v_cndmask_b32_e32 v14, 0, v14, vcc
	v_cndmask_b32_e32 v15, 0, v15, vcc
	v_pk_add_f32 v[12:13], v[12:13], 0 op_sel_hi:[1,0]
	v_cndmask_b32_e64 v10, 0, v10, s[4:5]
	v_cndmask_b32_e64 v11, 0, v11, s[4:5]
	v_pk_add_f32 v[8:9], v[8:9], 0 op_sel_hi:[1,0]
	v_cndmask_b32_e64 v6, 0, v6, s[6:7]
	v_cndmask_b32_e64 v7, 0, v7, s[6:7]
	v_pk_add_f32 v[4:5], v[4:5], 0 op_sel_hi:[1,0]
	v_cndmask_b32_e64 v2, 0, v2, s[8:9]
	v_cndmask_b32_e64 v3, 0, v3, s[8:9]
	v_mov_b32_e32 v28, v142
	v_cndmask_b32_e64 v76, 0, v77, s[6:7]
	v_cvt_pk_bf16_f32 v74, v74, v76
	v_cvt_pk_bf16_f32 v75, v82, v75
	ds_write2_b64 v86, v[78:79], v[74:75] offset0:40 offset1:44
	v_cndmask_b32_e64 v68, 0, v68, s[8:9]
	v_cndmask_b32_e64 v69, 0, v69, s[8:9]
	v_cvt_pk_bf16_f32 v66, v66, v67
	v_cvt_pk_bf16_f32 v67, v68, v69
	ds_write2_b64 v87, v[80:81], v[66:67] offset0:56 offset1:60
	v_cndmask_b32_e32 v64, 0, v64, vcc
	v_cndmask_b32_e32 v65, 0, v65, vcc
	v_cvt_pk_bf16_f32 v62, v62, v63
	v_cvt_pk_bf16_f32 v63, v64, v65
	v_cndmask_b32_e64 v60, 0, v60, s[4:5]
	v_cndmask_b32_e64 v61, 0, v61, s[4:5]
	v_cvt_pk_bf16_f32 v58, v58, v59
	v_cvt_pk_bf16_f32 v59, v60, v61
	v_cndmask_b32_e64 v56, 0, v56, s[6:7]
	v_cndmask_b32_e64 v57, 0, v57, s[6:7]
	v_cvt_pk_bf16_f32 v54, v54, v55
	v_cvt_pk_bf16_f32 v55, v56, v57
	v_cndmask_b32_e64 v52, 0, v52, s[8:9]
	v_cndmask_b32_e64 v53, 0, v53, s[8:9]
	v_cvt_pk_bf16_f32 v50, v50, v51
	v_cvt_pk_bf16_f32 v51, v52, v53
	v_cndmask_b32_e32 v48, 0, v48, vcc
	v_cndmask_b32_e32 v49, 0, v49, vcc
	v_cvt_pk_bf16_f32 v46, v46, v47
	v_cvt_pk_bf16_f32 v47, v48, v49
	ds_write2_b64 v71, v[62:63], v[46:47] offset0:16 offset1:20
; __device__ __forceinline__ int get_tid() { int t = threadIdx.x & 255; asm volatile("" : "+v"(t)); return t; }
;   template <class F>
;   __device__ __forceinline__ void finish(const bf16_t* Z, int g, int rig0, int nt, F&& pre) const {
;     typedef f32x2_t f32x2;
;     const int tid = get_tid();
;     if (MODE == 0 || nt < 8) {
;       if (MODE == 0) {
;         const int f2 = (tid & 31) * 2, q8 = tid >> 5;
;         const int q0 = 1 + 16 * q8, q1 = (q0 + 16 < 127) ? q0 + 16 : 127;
;         const int na = norig(nt, f2), ng = norig(nt, 64 + f2);
;         const f32x2 a0 = *(const f32x2*)(cw + na), a1 = *(const f32x2*)(cw + NC + na), a2 = *(const f32x2*)(cw + 2 * NC + na), ab = *(const f32x2*)(cb + na);
;         const f32x2 g0 = *(const f32x2*)(cw + ng), g1 = *(const f32x2*)(cw + NC + ng), g2 = *(const f32x2*)(cw + 2 * NC + ng), gb = *(const f32x2*)(cb + ng);
;         pre();
;         f32x2 am = ldz(Z, q0 - 1, f2), ac = ldz(Z, q0, f2);
;         f32x2 gm = ldz(Z, q0 - 1, 64 + f2), gc = ldz(Z, q0, 64 + f2);
; template <bool SWAP, class Epi, bool THIN = false> ...
;     ...
;       __syncthreads();
;       {
;         auto no_pre = []() {};
;         const bf16_t* Zr = (const bf16_t*)smem + ((wr_e >> 1) * 2) * (128 * 132);
;         epi.finish(Zr, g, rig0, nt * 2, no_pre);
;         epi.finish(Zr + 128 * 132, g, rig0, nt * 2 + 1, no_pre);
	v_cndmask_b32_e64 v44, 0, v44, s[4:5]
	v_cndmask_b32_e64 v45, 0, v45, s[4:5]
	v_cvt_pk_bf16_f32 v42, v42, v43
	v_cvt_pk_bf16_f32 v43, v44, v45
	ds_write2_b64 v73, v[58:59], v[42:43] offset0:32 offset1:36
	v_cndmask_b32_e64 v40, 0, v40, s[6:7]
	v_cndmask_b32_e64 v41, 0, v41, s[6:7]
	v_cvt_pk_bf16_f32 v38, v38, v39
	v_cvt_pk_bf16_f32 v39, v40, v41
	ds_write2_b64 v86, v[54:55], v[38:39] offset0:48 offset1:52
	v_cndmask_b32_e64 v36, 0, v36, s[8:9]
	v_cndmask_b32_e64 v37, 0, v37, s[8:9]
	v_cvt_pk_bf16_f32 v34, v34, v35
	v_cvt_pk_bf16_f32 v35, v36, v37
	ds_write2_b64 v87, v[50:51], v[34:35] offset0:64 offset1:68
	v_cndmask_b32_e32 v32, 0, v32, vcc
	v_cndmask_b32_e32 v33, 0, v33, vcc
	v_cvt_pk_bf16_f32 v30, v30, v31
	v_cvt_pk_bf16_f32 v31, v32, v33
	v_cndmask_b32_e64 v24, 0, v24, s[6:7]
	v_cndmask_b32_e64 v25, 0, v25, s[6:7]
	v_cvt_pk_bf16_f32 v22, v22, v23
	v_cvt_pk_bf16_f32 v23, v24, v25
	v_cndmask_b32_e64 v20, 0, v20, s[8:9]
	v_cndmask_b32_e64 v21, 0, v21, s[8:9]
	v_cvt_pk_bf16_f32 v18, v18, v19
	v_cvt_pk_bf16_f32 v19, v20, v21
	v_cndmask_b32_e32 v16, 0, v16, vcc
	v_cndmask_b32_e32 v17, 0, v17, vcc
	v_cvt_pk_bf16_f32 v14, v14, v15
	v_cvt_pk_bf16_f32 v15, v16, v17
	ds_write2_b64 v71, v[30:31], v[14:15] offset0:24 offset1:28
	v_cndmask_b32_e64 v12, 0, v12, s[4:5]
	v_cndmask_b32_e64 v13, 0, v13, s[4:5]
	v_cvt_pk_bf16_f32 v10, v10, v11
	v_cvt_pk_bf16_f32 v11, v12, v13
	ds_write2_b64 v73, v[26:27], v[10:11] offset0:40 offset1:44
	v_cndmask_b32_e64 v8, 0, v8, s[6:7]
	v_cndmask_b32_e64 v9, 0, v9, s[6:7]
	v_cvt_pk_bf16_f32 v6, v6, v7
	v_cvt_pk_bf16_f32 v7, v8, v9
	ds_write2_b64 v86, v[22:23], v[6:7] offset0:56 offset1:60
	v_cndmask_b32_e64 v4, 0, v4, s[8:9]
	v_cndmask_b32_e64 v5, 0, v5, s[8:9]
	v_cvt_pk_bf16_f32 v2, v2, v3
	v_cvt_pk_bf16_f32 v3, v4, v5
	ds_write2_b64 v87, v[18:19], v[2:3] offset0:72 offset1:76
	s_waitcnt lgkmcnt(0)
	s_barrier
	v_mul_i32_i24_e32 v2, 0x10800, v98
	v_ashrrev_i32_e32 v29, 1, v28
	v_and_b32_e32 v38, -16, v29
	v_min_i32_e32 v3, 0x6e, v38
	v_or_b32_e32 v20, 1, v38
	v_add_u32_e32 v3, 17, v3
	v_cmp_lt_i32_e32 vcc, v20, v3
	v_ashrrev_i32_e32 v71, 31, v70
	s_and_saveexec_b64 s[4:5], vcc
	s_cbranch_execz .LBB0_3432
	v_lshlrev_b32_e32 v4, 1, v28
	v_and_b32_e32 v21, 62, v4
	v_or_b32_e32 v4, s24, v21
	s_add_i32 s6, s24, 0xb00
	v_ashrrev_i32_e32 v5, 31, v4
	v_or_b32_e32 v12, s6, v21
	v_lshlrev_b64 v[10:11], 2, v[4:5]
	v_lshl_add_u64 v[14:15], s[16:17], 0, v[10:11]
	v_lshl_add_u64 v[18:19], s[22:23], 0, v[10:11]
	v_ashrrev_i32_e32 v13, 31, v12
	v_lshl_add_u64 v[16:17], s[20:21], 0, v[10:11]
	global_load_dwordx2 v[4:5], v[14:15], off
	global_load_dwordx2 v[6:7], v[16:17], off
	global_load_dwordx2 v[8:9], v[18:19], off
	v_lshlrev_b64 v[18:19], 2, v[12:13]
	v_lshl_add_u64 v[10:11], s[18:19], 0, v[10:11]
	v_lshl_add_u64 v[22:23], s[16:17], 0, v[18:19]
	global_load_dwordx2 v[10:11], v[10:11], off
	v_lshl_add_u64 v[24:25], s[20:21], 0, v[18:19]
	v_lshl_add_u64 v[26:27], s[22:23], 0, v[18:19]
	global_load_dwordx2 v[12:13], v[22:23], off
	global_load_dwordx2 v[14:15], v[24:25], off
	global_load_dwordx2 v[16:17], v[26:27], off
	v_lshl_add_u64 v[18:19], s[18:19], 0, v[18:19]
	global_load_dwordx2 v[18:19], v[18:19], off
	v_mov_b32_e32 v117, 0
	v_lshlrev_b32_e32 v88, 1, v142
	v_and_b32_e32 v105, 62, v88
	v_add3_u32 v88, v105, s24, 64
	s_add_i32 s38, s24, 0xb40
	v_ashrrev_i32_e32 v89, 31, v88
	v_or_b32_e32 v96, s38, v105
	v_lshlrev_b64 v[94:95], 2, v[88:89]
	v_lshl_add_u64 v[98:99], s[16:17], 0, v[94:95]
	v_lshl_add_u64 v[102:103], s[22:23], 0, v[94:95]
	v_ashrrev_i32_e32 v97, 31, v96
	v_lshl_add_u64 v[100:101], s[20:21], 0, v[94:95]
	global_load_dwordx2 v[88:89], v[98:99], off
	global_load_dwordx2 v[90:91], v[100:101], off
	global_load_dwordx2 v[92:93], v[102:103], off
	v_lshlrev_b64 v[102:103], 2, v[96:97]
	v_lshl_add_u64 v[94:95], s[18:19], 0, v[94:95]
	v_lshl_add_u64 v[106:107], s[16:17], 0, v[102:103]
	global_load_dwordx2 v[94:95], v[94:95], off
	v_lshl_add_u64 v[108:109], s[20:21], 0, v[102:103]
	v_lshl_add_u64 v[110:111], s[22:23], 0, v[102:103]
	global_load_dwordx2 v[96:97], v[106:107], off
	global_load_dwordx2 v[98:99], v[108:109], off
	global_load_dwordx2 v[100:101], v[110:111], off
	v_lshl_add_u64 v[102:103], s[18:19], 0, v[102:103]
	global_load_dwordx2 v[102:103], v[102:103], off
	v_lshlrev_b32_e32 v136, 1, v21
	v_mul_lo_u32 v22, v38, s31
	v_mul_lo_u32 v20, v20, s31
	v_add3_u32 v22, v2, v22, v136
	v_add3_u32 v20, v2, v20, v136
	ds_read2_b32 v[22:23], v22 offset1:32
	ds_read2_b32 v[20:21], v20 offset1:32
	s_ashr_i32 s25, s24, 31
	s_lshl_b64 s[6:7], s[24:25], 1
	s_add_u32 s6, s12, s6
	s_addc_u32 s7, s13, s7
	v_lshrrev_b32_e32 v29, 4, v29
	v_and_b32_e32 v28, 31, v28
	s_waitcnt lgkmcnt(1)
	v_lshlrev_b32_e32 v32, 16, v23
	v_and_b32_e32 v33, 0xffff0000, v23
	v_lshlrev_b32_e32 v34, 16, v22
	v_and_b32_e32 v35, 0xffff0000, v22
	v_lshl_add_u64 v[22:23], s[6:7], 0, v[136:137]
	v_mad_u64_u32 v[30:31], s[6:7], v29, s33, v[2:3]
	v_lshlrev_b32_e32 v28, 2, v28
	s_waitcnt lgkmcnt(0)
	v_lshlrev_b32_e32 v24, 16, v21
	v_and_b32_e32 v25, 0xffff0000, v21
	v_lshlrev_b32_e32 v26, 16, v20
	v_and_b32_e32 v27, 0xffff0000, v20
	v_lshlrev_b64 v[20:21], 11, v[70:71]
	v_add3_u32 v39, v30, v28, s34
	s_mov_b64 s[6:7], 0
	s_waitcnt vmcnt(0)
	ds_read2_b32 v[44:45], v39 offset1:32
	s_branch .LBB0_3428

; __device__ __forceinline__ int get_tid() { int t = threadIdx.x & 255; asm volatile("" : "+v"(t)); return t; }
;   template <class F>
;   __device__ __forceinline__ void finish(const bf16_t* Z, int g, int rig0, int nt, F&& pre) const {
;     typedef f32x2_t f32x2;
;     const int tid = get_tid();
;     if (MODE == 0 || nt < 8) {
;       if (MODE == 0) {
;         const int f2 = (tid & 31) * 2, q8 = tid >> 5;
;         const int q0 = 1 + 16 * q8, q1 = (q0 + 16 < 127) ? q0 + 16 : 127;
;         const int na = norig(nt, f2), ng = norig(nt, 64 + f2);
;         const f32x2 a0 = *(const f32x2*)(cw + na), a1 = *(const f32x2*)(cw + NC + na), a2 = *(const f32x2*)(cw + 2 * NC + na), ab = *(const f32x2*)(cb + na);
;         const f32x2 g0 = *(const f32x2*)(cw + ng), g1 = *(const f32x2*)(cw + NC + ng), g2 = *(const f32x2*)(cw + 2 * NC + ng), gb = *(const f32x2*)(cb + ng);
;         pre();
;         f32x2 am = ldz(Z, q0 - 1, f2), ac = ldz(Z, q0, f2);
;         f32x2 gm = ldz(Z, q0 - 1, 64 + f2), gc = ldz(Z, q0, 64 + f2);
.LBB0_3432:
	s_waitcnt lgkmcnt(0)
	s_or_b64 exec, exec, s[4:5]
	v_mov_b32_e32 v3, v142
	s_nop 0
	v_ashrrev_i32_e32 v28, 1, v3
	v_and_b32_e32 v37, -16, v28
	v_min_i32_e32 v4, 0x6e, v37
	v_or_b32_e32 v20, 1, v37
	v_add_u32_e32 v36, 17, v4
	v_cmp_lt_i32_e32 vcc, v20, v36
	s_and_saveexec_b64 s[4:5], vcc
	s_cbranch_execz .LBB0_3418
	v_lshlrev_b32_e32 v4, 1, v3
	v_and_b32_e32 v21, 62, v4
	v_add3_u32 v4, v21, s24, 64
	s_add_i32 s6, s24, 0xb40
	v_ashrrev_i32_e32 v5, 31, v4
	v_or_b32_e32 v12, s6, v21
	v_lshlrev_b64 v[10:11], 2, v[4:5]
	v_lshl_add_u64 v[14:15], s[16:17], 0, v[10:11]
	v_lshl_add_u64 v[18:19], s[22:23], 0, v[10:11]
	v_ashrrev_i32_e32 v13, 31, v12
	v_lshl_add_u64 v[16:17], s[20:21], 0, v[10:11]
	v_lshlrev_b64 v[18:19], 2, v[12:13]
	v_lshl_add_u64 v[10:11], s[18:19], 0, v[10:11]
	v_lshl_add_u64 v[22:23], s[16:17], 0, v[18:19]
	v_lshl_add_u64 v[24:25], s[20:21], 0, v[18:19]
	v_lshl_add_u64 v[26:27], s[22:23], 0, v[18:19]
	v_lshl_add_u64 v[18:19], s[18:19], 0, v[18:19]
	v_lshlrev_b32_e32 v136, 1, v21
	v_mul_lo_u32 v22, v37, s31
	v_add3_u32 v22, v2, v22, v136
	v_mul_lo_u32 v20, v20, s31
	v_add_u32_e32 v22, 0x8400, v22
	v_add3_u32 v20, v2, v20, v136
	ds_read2_b32 v[22:23], v22 offset1:32
	v_add_u32_e32 v20, 0x8400, v20
	s_ashr_i32 s25, s24, 31
	ds_read2_b32 v[20:21], v20 offset1:32
	s_lshl_b64 s[6:7], s[24:25], 1
	s_add_u32 s6, s12, s6
	s_addc_u32 s7, s13, s7
	v_lshrrev_b32_e32 v28, 4, v28
	s_waitcnt lgkmcnt(1)
	v_lshlrev_b32_e32 v30, 16, v23
	v_and_b32_e32 v31, 0xffff0000, v23
	v_lshlrev_b32_e32 v32, 16, v22
	v_and_b32_e32 v33, 0xffff0000, v22
	v_lshl_add_u64 v[22:23], s[6:7], 0, v[136:137]
	v_mad_u64_u32 v[28:29], s[6:7], v28, s33, v[2:3]
	v_and_b32_e32 v2, 31, v3
	v_lshlrev_b32_e32 v2, 2, v2
	s_waitcnt lgkmcnt(0)
	v_lshlrev_b32_e32 v24, 16, v21
	v_and_b32_e32 v25, 0xffff0000, v21
	v_lshlrev_b32_e32 v26, 16, v20
	v_and_b32_e32 v27, 0xffff0000, v20
	v_lshlrev_b64 v[20:21], 11, v[70:71]
	v_add3_u32 v38, v28, v2, s36
	s_mov_b64 s[6:7], 0
	ds_read2_b32 v[44:45], v38 offset1:32
	s_branch .LBB0_3435
